# attention: K/V LDS-DMA issued one tile ahead (was two); waves 4-7 run the tile body rotated by one segment (previous tile's second PV half after the barrier, P kept in registers) so SIMD partners are
# baseline (speedup 1.0000x reference)
.LBB0_843:
	s_lshl_b32 s4, s63, 1
	s_and_b32 s14, s4, 0xe00
	s_and_b32 s78, s57, 7
	v_readfirstlane_b32 s4, v176
	s_xor_b32 s9, s78, 15
	s_ashr_i32 s4, s4, 6
	s_ashr_i32 s8, s57, 6
	s_lshl_b32 s87, s9, 8
	s_lshl_b32 s15, s4, 5
	s_lshl_b32 s82, s9, 2
	s_add_i32 s83, s15, s87
	s_ashr_i32 s9, s8, 31
	s_add_i32 s82, s82, 4
	s_or_b32 s84, s83, 31
	s_lshl_b64 s[40:41], s[8:9], 12
	s_lshl_b64 s[12:13], s[8:9], 26
	s_add_u32 s8, s2, s12
	s_addc_u32 s9, s3, s13
	s_lshl_b32 s10, s57, 5
	s_and_b32 s79, s10, 0x700
	s_lshl_b32 s10, s79, 1
	s_add_u32 s18, s8, s10
	s_addc_u32 s19, s9, 0
	s_add_u32 s38, s18, 0x1000
	s_addc_u32 s39, s19, 0
	s_add_u32 s16, s18, 0x2000
	s_addc_u32 s17, s19, 0
	s_add_u32 s8, s2, s10
	s_addc_u32 s9, s3, 0
	s_lshl_b32 s55, s4, 3
	s_lshl_b32 s54, s4, 11
	s_lshl_b32 s33, s4, 12
	s_add_u32 s10, s18, 0x102000
	s_addc_u32 s11, s19, 0
	s_or_b32 s22, s40, s87
	s_ashr_i32 s23, s15, 31
	s_add_u32 s80, s22, s15
	s_addc_u32 s81, s41, s23
	s_cmp_lg_u32 0, -1
	s_cselect_b32 s15, 0, 0
	s_add_i32 s22, s15, 0xc000
	s_add_i32 s85, s54, s15
	s_add_i32 s86, s33, s22
	v_mov_b32_e32 v4, v176
	v_mov_b32_e32 v181, v179
	v_bfe_u32 v0, v4, 4, 2
	v_or_b32_e32 v1, s55, v0
	v_bitop3_b32 v0, v0, v4, s55 bitop3:0x36
	v_lshlrev_b32_e32 v2, 14, v1
	v_lshlrev_b32_e32 v0, 4, v0
	v_and_or_b32 v178, v0, s67, v2
	v_or_b32_e32 v0, 4, v1
	v_bitop3_b32 v1, v1, v4, 4 bitop3:0x36
	v_lshlrev_b32_e32 v0, 14, v0
	v_lshlrev_b32_e32 v1, 4, v1
	v_and_or_b32 v180, v1, s67, v0
	v_bfe_u32 v0, v4, 5, 1
	v_or_b32_e32 v1, s55, v0
	v_and_b32_e32 v2, 31, v4
	v_lshlrev_b32_e32 v3, 14, v1
	v_lshlrev_b32_e32 v0, 6, v0
	v_lshlrev_b32_e32 v5, 4, v2
	v_bitop3_b32 v182, v0, v3, v5 bitop3:0xde
	v_or_b32_e32 v0, 2, v1
	v_lshlrev_b32_e32 v3, 2, v0
	v_bitop3_b32 v3, v3, v2, 12 bitop3:0x6c
	v_lshlrev_b32_e32 v0, 14, v0
	v_lshl_or_b32 v184, v3, 4, v0
	v_or_b32_e32 v0, 6, v1
	v_lshlrev_b32_e32 v1, 2, v0
	v_bitop3_b32 v1, v1, v2, 12 bitop3:0x6c
	v_lshlrev_b32_e32 v0, 14, v0
	v_lshl_or_b32 v188, v1, 4, v0
	v_lshl_add_u64 v[0:1], s[38:39], 0, v[178:179]
	s_mov_b32 s22, m0
	s_mov_b32 m0, s85
	s_nop 0
	global_load_lds_dwordx4 v[0:1], off
	s_mov_b32 m0, s22
	v_lshl_add_u64 v[0:1], s[38:39], 0, v[180:181]
	s_add_i32 s22, s85, 0x400
	s_mov_b32 s23, m0
	s_mov_b32 m0, s22
	s_nop 0
	global_load_lds_dwordx4 v[0:1], off
	s_mov_b32 m0, s23
	v_mov_b32_e32 v183, v179
	v_lshl_add_u64 v[0:1], s[16:17], 0, v[182:183]
	s_mov_b32 s22, m0
	s_mov_b32 m0, s86
	s_nop 0
	global_load_lds_dwordx4 v[0:1], off
	s_mov_b32 m0, s22
	s_add_i32 s15, s15, s33
	v_mov_b32_e32 v185, v179
	s_add_i32 s22, s15, 0xc400
	v_or_b32_e32 v186, 0x10000, v182
	v_lshl_add_u64 v[0:1], s[16:17], 0, v[184:185]
	s_mov_b32 s23, m0
	s_mov_b32 m0, s22
	s_nop 0
	global_load_lds_dwordx4 v[0:1], off
	s_mov_b32 m0, s23
	v_mov_b32_e32 v187, v179
	s_add_i32 s22, s15, 0xc800
	v_lshl_add_u64 v[0:1], s[16:17], 0, v[186:187]
	s_mov_b32 s23, m0
	s_mov_b32 m0, s22
	s_nop 0
	global_load_lds_dwordx4 v[0:1], off
	s_mov_b32 m0, s23
	s_add_i32 s22, s15, 0xcc00
	v_mov_b32_e32 v189, v179
	s_add_u32 s52, s18, 0x101000
	v_lshl_add_u64 v[0:1], s[16:17], 0, v[188:189]
	s_addc_u32 s53, s19, 0
	s_mov_b32 s23, m0
	s_mov_b32 m0, s22
	s_nop 0
	global_load_lds_dwordx4 v[0:1], off
	s_mov_b32 m0, s23
	v_lshl_add_u64 v[0:1], s[52:53], 0, v[178:179]
	s_add_i32 s18, s85, 0x4000
	s_mov_b32 s19, m0
	s_mov_b32 m0, s18
	s_nop 0
	global_load_lds_dwordx4 v[0:1], off
	s_mov_b32 m0, s19
	v_lshl_add_u64 v[0:1], s[52:53], 0, v[180:181]
	s_add_i32 s18, s85, 0x4400
	s_mov_b32 s19, m0
	s_mov_b32 m0, s18
	s_nop 0
	global_load_lds_dwordx4 v[0:1], off
	s_mov_b32 m0, s19
	v_lshl_add_u64 v[0:1], s[10:11], 0, v[182:183]
	s_add_i32 s18, s15, 0x14000
	s_mov_b32 s19, m0
	s_mov_b32 m0, s18
	s_nop 0
	global_load_lds_dwordx4 v[0:1], off
	s_mov_b32 m0, s19
	v_lshl_add_u64 v[0:1], s[10:11], 0, v[184:185]
	s_add_i32 s18, s15, 0x14400
	s_mov_b32 s19, m0
	s_mov_b32 m0, s18
	s_nop 0
	global_load_lds_dwordx4 v[0:1], off
	s_mov_b32 m0, s19
	v_lshl_add_u64 v[0:1], s[10:11], 0, v[186:187]
	s_add_i32 s18, s15, 0x14800
	s_mov_b32 s19, m0
	s_mov_b32 m0, s18
	s_nop 0
	global_load_lds_dwordx4 v[0:1], off
	s_mov_b32 m0, s19
	v_lshl_add_u64 v[0:1], s[10:11], 0, v[188:189]
	s_add_i32 s15, s15, 0x14c00
	s_mov_b32 s18, m0
	s_mov_b32 m0, s15
	s_nop 0
	global_load_lds_dwordx4 v[0:1], off
	s_mov_b32 m0, s18
	v_or_b32_e32 v0, s80, v2
	v_mov_b32_e32 v1, s81
	v_lshlrev_b64 v[0:1], 14, v[0:1]
	v_lshrrev_b32_e32 v2, 1, v4
	v_lshl_add_u64 v[0:1], s[8:9], 0, v[0:1]
	v_and_b32_e32 v2, 16, v2
	v_mov_b32_e32 v3, v179
	v_lshl_add_u64 v[0:1], v[0:1], 0, v[2:3]
	global_load_dwordx4 v[144:147], v[0:1], off
	global_load_dwordx4 v[148:151], v[0:1], off offset:32
	global_load_dwordx4 v[152:155], v[0:1], off offset:64
	global_load_dwordx4 v[156:159], v[0:1], off offset:96
	global_load_dwordx4 v[160:163], v[0:1], off offset:128
	global_load_dwordx4 v[164:167], v[0:1], off offset:160
	global_load_dwordx4 v[168:171], v[0:1], off offset:192
	global_load_dwordx4 v[172:175], v[0:1], off offset:224
	v_lshrrev_b32_e32 v0, 5, v4
	v_and_b32_e32 v1, 15, v4
	v_bitop3_b32 v0, v0, v1, 1 bitop3:0x6c
	v_lshlrev_b32_e32 v1, 8, v4
	s_addk_i32 s87, 0x100
	s_or_b32 s12, s12, s14
	v_lshlrev_b32_e32 v0, 4, v0
	v_and_b32_e32 v1, 0x1f00, v1
	s_add_u32 s22, s61, s12
	v_mov_b32_e32 v14, v179
	v_mov_b32_e32 v15, v179
	v_or_b32_e32 v194, v0, v1
	v_bitop3_b32 v195, v0, 32, v1 bitop3:0x36
	v_bitop3_b32 v196, v0, 64, v1 bitop3:0x36
	v_bitop3_b32 v197, v0, s68, v1 bitop3:0x36
	v_bitop3_b32 v198, v0, s69, v1 bitop3:0x36
	v_bitop3_b32 v199, v0, s70, v1 bitop3:0x36
	v_bitop3_b32 v200, v0, s71, v1 bitop3:0x36
	v_bitop3_b32 v201, v0, s72, v1 bitop3:0x36
	s_addc_u32 s23, s62, s13
	v_mov_b32_e32 v0, v179
	v_mov_b32_e32 v1, v179
	v_mov_b32_e32 v2, v179
	v_mov_b32_e32 v4, v179
	s_waitcnt vmcnt(7)
	s_waitcnt vmcnt(6)
	s_waitcnt vmcnt(5)
	s_waitcnt vmcnt(4)
	s_waitcnt vmcnt(3)
	s_waitcnt vmcnt(2)
	s_waitcnt vmcnt(1)
	s_waitcnt vmcnt(0)
	s_waitcnt vmcnt(0)
	v_mov_b32_e32 v5, v179
	v_mov_b32_e32 v6, v179
	v_mov_b32_e32 v7, v179
	v_mov_b32_e32 v8, v179
	v_mov_b32_e32 v9, v179
	v_mov_b32_e32 v10, v179
	v_mov_b32_e32 v11, v179
	v_mov_b32_e32 v12, v179
	v_mov_b32_e32 v13, v179
	v_mov_b64_e32 v[30:31], v[14:15]
	v_mov_b64_e32 v[46:47], v[14:15]
	v_mov_b64_e32 v[62:63], v[14:15]
	v_mov_b64_e32 v[78:79], v[14:15]
	v_mov_b64_e32 v[94:95], v[14:15]
	v_mov_b64_e32 v[110:111], v[14:15]
	v_mov_b64_e32 v[126:127], v[14:15]
	v_mov_b32_e32 v190, 0xf149f2ca
	s_mov_b32 s42, 2
	s_mov_b64 s[14:15], s[22:23]
	s_mov_b32 s43, 0
	v_mov_b64_e32 v[28:29], v[12:13]
	v_mov_b64_e32 v[26:27], v[10:11]
	v_mov_b64_e32 v[24:25], v[8:9]
	v_mov_b64_e32 v[22:23], v[6:7]
	v_mov_b64_e32 v[20:21], v[4:5]
	v_mov_b64_e32 v[18:19], v[2:3]
	v_mov_b64_e32 v[16:17], v[0:1]
	v_mov_b64_e32 v[44:45], v[12:13]
	v_mov_b64_e32 v[42:43], v[10:11]
	v_mov_b64_e32 v[40:41], v[8:9]
	v_mov_b64_e32 v[38:39], v[6:7]
	v_mov_b64_e32 v[36:37], v[4:5]
	v_mov_b64_e32 v[34:35], v[2:3]
	v_mov_b64_e32 v[32:33], v[0:1]
	v_mov_b64_e32 v[60:61], v[12:13]
	v_mov_b64_e32 v[58:59], v[10:11]
	v_mov_b64_e32 v[56:57], v[8:9]
	v_mov_b64_e32 v[54:55], v[6:7]
	v_mov_b64_e32 v[52:53], v[4:5]
	v_mov_b64_e32 v[50:51], v[2:3]
	v_mov_b64_e32 v[48:49], v[0:1]
	v_mov_b64_e32 v[76:77], v[12:13]
	v_mov_b64_e32 v[74:75], v[10:11]
	v_mov_b64_e32 v[72:73], v[8:9]
	v_mov_b64_e32 v[70:71], v[6:7]
	v_mov_b64_e32 v[68:69], v[4:5]
	v_mov_b64_e32 v[66:67], v[2:3]
	v_mov_b64_e32 v[64:65], v[0:1]
	v_mov_b64_e32 v[92:93], v[12:13]
	v_mov_b64_e32 v[90:91], v[10:11]
	v_mov_b64_e32 v[88:89], v[8:9]
	v_mov_b64_e32 v[86:87], v[6:7]
	v_mov_b64_e32 v[84:85], v[4:5]
	v_mov_b64_e32 v[82:83], v[2:3]
	v_mov_b64_e32 v[80:81], v[0:1]
	v_mov_b64_e32 v[108:109], v[12:13]
	v_mov_b64_e32 v[106:107], v[10:11]
	v_mov_b64_e32 v[104:105], v[8:9]
	v_mov_b64_e32 v[102:103], v[6:7]
	v_mov_b64_e32 v[100:101], v[4:5]
	v_mov_b64_e32 v[98:99], v[2:3]
	v_mov_b64_e32 v[96:97], v[0:1]
	v_mov_b64_e32 v[124:125], v[12:13]
	v_mov_b64_e32 v[122:123], v[10:11]
	v_mov_b64_e32 v[120:121], v[8:9]
	v_mov_b64_e32 v[118:119], v[6:7]
	v_mov_b64_e32 v[116:117], v[4:5]
	v_mov_b64_e32 v[114:115], v[2:3]
	v_mov_b64_e32 v[112:113], v[0:1]
	v_mov_b32_e32 v202, v179
	s_mov_b32 s88, 0
	s_sub_u32 s14, s14, 0x100000
	s_subb_u32 s15, s15, 0
	s_sub_i32 s42, s42, 1
	s_barrier
	s_branch .LBB0_845

.LBB0_845:
	s_cmp_ge_u32 s42, s82
	s_cselect_b64 s[18:19], -1, 0
	v_mov_b32_e32 v203, v176
	s_and_b64 vcc, exec, s[18:19]
	s_cbranch_vccnz .LBB0_847
	s_add_i32 s100, s43, 63
	s_cmp_le_i32 s100, s83
	s_cbranch_scc1 .LBB0_847
	s_add_i32 s34, s88, 1
	s_cmp_eq_u32 s34, 3
	s_cselect_b32 s34, 0, s34
	v_mov_b32_e32 v130, s34
	v_lshlrev_b32_e32 v128, 14, v130
	v_add_u32_e32 v131, s85, v128
	v_lshl_add_u64 v[128:129], s[14:15], 0, v[178:179]
	s_add_u32 s34, s14, 0x1000
	v_readfirstlane_b32 s89, v131
	s_mov_b32 s90, m0
	s_mov_b32 m0, s89
	s_nop 0
	global_load_lds_dwordx4 v[128:129], off
	s_mov_b32 m0, s90
	v_lshl_add_u64 v[128:129], s[14:15], 0, v[180:181]
	s_addc_u32 s35, s15, 0
	s_addk_i32 s89, 0x400
	s_mov_b32 s90, m0
	s_mov_b32 m0, s89
	s_nop 0
	global_load_lds_dwordx4 v[128:129], off
	s_mov_b32 m0, s90
	v_lshlrev_b32_e32 v128, 15, v130
	v_add_u32_e32 v130, s86, v128
	v_lshl_add_u64 v[128:129], s[34:35], 0, v[182:183]
	v_readfirstlane_b32 s89, v130
	s_mov_b32 s90, m0
	s_mov_b32 m0, s89
	s_nop 0
	global_load_lds_dwordx4 v[128:129], off
	s_mov_b32 m0, s90
	v_lshl_add_u64 v[128:129], s[34:35], 0, v[184:185]
	s_add_i32 s90, s89, 0x400
	s_mov_b32 s91, m0
	s_mov_b32 m0, s90
	s_nop 0
	global_load_lds_dwordx4 v[128:129], off
	s_mov_b32 m0, s91
	v_lshl_add_u64 v[128:129], s[34:35], 0, v[186:187]
	s_add_i32 s90, s89, 0x800
	s_mov_b32 s91, m0
	s_mov_b32 m0, s90
	s_nop 0
	global_load_lds_dwordx4 v[128:129], off
	s_mov_b32 m0, s91
	v_lshl_add_u64 v[128:129], s[34:35], 0, v[188:189]
	s_add_i32 s34, s89, 0xc00
	s_mov_b32 s35, m0
	s_mov_b32 m0, s34
	s_nop 0
	global_load_lds_dwordx4 v[128:129], off
	s_mov_b32 m0, s35
.LBB0_847:
	s_cmp_gt_i32 s43, s84
	s_cbranch_scc1 .LBB0_858
	s_add_i32 s100, s43, 63
	s_cmp_le_i32 s100, s83
	s_cbranch_scc0 .Latt_slow_0
	v_lshrrev_b32_e32 v246, 8, v220
	s_nop 0
	v_readfirstlane_b32 s100, v246
	s_nop 0
	s_cmp_eq_u32 s100, 0
	s_cbranch_scc1 .Latt_A_0
	s_cmp_eq_u32 s43, 0
	s_cbranch_scc1 .Latt_B0_0
	s_add_i32 s99, s88, 2
	s_sub_i32 s101, s99, 3
	s_cmp_lt_u32 s99, 3
	s_cselect_b32 s99, s99, s101
	s_lshl_b32 s99, s99, 15
	s_add_i32 s99, s99, 0xc000
	v_bfe_u32 v246, v203, 2, 2
	v_bfe_u32 v247, v203, 5, 1
	v_lshl_or_b32 v247, v247, 2, v246
	v_and_b32_e32 v249, 3, v203
	v_and_b32_e32 v254, 16, v203
	v_lshl_or_b32 v249, v249, 2, v254
	v_lshlrev_b32_e32 v249, 1, v249
	v_lshl_add_u32 v247, v247, 9, v249
	v_add_u32_e32 v247, s99, v247
	v_lshlrev_b32_e32 v246, 6, v246
	v_add_u32_e32 v205, v247, v246
	v_xor_b32_e32 v249, 64, v246
	v_add_u32_e32 v218, v247, v249
	v_xor_b32_e32 v249, 0x80, v246
	v_add_u32_e32 v219, v247, v249
	v_xor_b32_e32 v249, 0xc0, v246
	v_add_u32_e32 v221, v247, v249
	s_lshl_b32 s98, s88, 14
	s_lshl_b32 s99, s88, 15
	s_add_i32 s99, s99, 0xc000
	ds_read_b64_tr_b16 v[206:207], v205 offset:16384
	ds_read_b64_tr_b16 v[208:209], v205 offset:20480
	ds_read_b64_tr_b16 v[210:211], v218 offset:16384
	ds_read_b64_tr_b16 v[212:213], v218 offset:20480
	ds_read_b64_tr_b16 v[214:215], v219 offset:16384
	ds_read_b64_tr_b16 v[216:217], v219 offset:20480
	ds_read_b64_tr_b16 v[238:239], v221 offset:16384
	ds_read_b64_tr_b16 v[240:241], v221 offset:20480
	ds_read_b64_tr_b16 v[222:223], v205 offset:16640
	ds_read_b64_tr_b16 v[224:225], v205 offset:20736
	s_waitcnt lgkmcnt(8)
	v_mfma_f32_32x32x16_bf16 v[112:127], v[206:209], v[242:245], v[112:127]
	ds_read_b64_tr_b16 v[206:207], v218 offset:16640
	ds_read_b64_tr_b16 v[208:209], v218 offset:20736
	s_cmp_lg_u64 s[18:19], 0
	s_cbranch_scc1 .Latt_nd0_0B1
	s_add_i32 s100, s88, 1
	s_cmp_eq_u32 s88, 2
	s_cselect_b32 s100, 0, s100
	s_lshl_b32 s101, s100, 14
	s_add_i32 m0, s85, s101
	s_nop 0
	global_load_lds_dwordx4 v178, s[14:15]
.Latt_nd0_0B1:
	s_waitcnt lgkmcnt(8)
	v_mfma_f32_32x32x16_bf16 v[96:111], v[210:213], v[242:245], v[96:111]
	ds_read_b64_tr_b16 v[210:211], v219 offset:16640
	ds_read_b64_tr_b16 v[212:213], v219 offset:20736
	s_cmp_lg_u64 s[18:19], 0
	s_cbranch_scc1 .Latt_nd1_0B1
	s_add_i32 m0, m0, 0x400
	s_nop 0
	global_load_lds_dwordx4 v180, s[14:15]
.Latt_nd1_0B1:
	s_waitcnt lgkmcnt(8)
	v_mfma_f32_32x32x16_bf16 v[80:95], v[214:217], v[242:245], v[80:95]
	ds_read_b64_tr_b16 v[214:215], v221 offset:16640
	ds_read_b64_tr_b16 v[216:217], v221 offset:20736
	s_cmp_lg_u64 s[18:19], 0
	s_cbranch_scc1 .Latt_nd2_0B1
	s_lshl_b32 s101, s100, 15
	s_add_i32 m0, s86, s101
	s_add_u32 s100, s14, 0x1000
	s_addc_u32 s101, s15, 0
	global_load_lds_dwordx4 v182, s[100:101]
.Latt_nd2_0B1:
	s_waitcnt lgkmcnt(8)
	v_mfma_f32_32x32x16_bf16 v[64:79], v[238:241], v[242:245], v[64:79]
	ds_read_b64_tr_b16 v[238:239], v205 offset:24576
	ds_read_b64_tr_b16 v[240:241], v205 offset:28672
	s_cmp_lg_u64 s[18:19], 0
	s_cbranch_scc1 .Latt_nd3_0B1
	s_add_i32 m0, m0, 0x400
	s_nop 0
	global_load_lds_dwordx4 v184, s[100:101]
.Latt_nd3_0B1:
	s_waitcnt lgkmcnt(8)
	v_mfma_f32_32x32x16_bf16 v[48:63], v[222:225], v[242:245], v[48:63]
	ds_read_b64_tr_b16 v[222:223], v218 offset:24576
	ds_read_b64_tr_b16 v[224:225], v218 offset:28672
	s_cmp_lg_u64 s[18:19], 0
	s_cbranch_scc1 .Latt_nd4_0B1
	s_add_i32 m0, m0, 0x400
	s_nop 0
	global_load_lds_dwordx4 v186, s[100:101]
.Latt_nd4_0B1:
	s_waitcnt lgkmcnt(8)
	v_mfma_f32_32x32x16_bf16 v[32:47], v[206:209], v[242:245], v[32:47]
	ds_read_b64_tr_b16 v[206:207], v219 offset:24576
	ds_read_b64_tr_b16 v[208:209], v219 offset:28672
	s_cmp_lg_u64 s[18:19], 0
	s_cbranch_scc1 .Latt_nd5_0B1
	s_add_i32 m0, m0, 0x400
	s_nop 0
	global_load_lds_dwordx4 v188, s[100:101]
.Latt_nd5_0B1:
	s_waitcnt lgkmcnt(8)
	v_mfma_f32_32x32x16_bf16 v[16:31], v[210:213], v[242:245], v[16:31]
	ds_read_b64_tr_b16 v[210:211], v221 offset:24576
	ds_read_b64_tr_b16 v[212:213], v221 offset:28672
	s_waitcnt lgkmcnt(8)
	v_mfma_f32_32x32x16_bf16 v[0:15], v[214:217], v[242:245], v[0:15]
	ds_read_b64_tr_b16 v[214:215], v205 offset:24832
	ds_read_b64_tr_b16 v[216:217], v205 offset:28928
	s_waitcnt lgkmcnt(8)
	v_mfma_f32_32x32x16_bf16 v[112:127], v[238:241], v[250:253], v[112:127]
	ds_read_b64_tr_b16 v[238:239], v218 offset:24832
	ds_read_b64_tr_b16 v[240:241], v218 offset:28928
	s_waitcnt lgkmcnt(8)
	v_mfma_f32_32x32x16_bf16 v[96:111], v[222:225], v[250:253], v[96:111]
	ds_read_b64_tr_b16 v[222:223], v219 offset:24832
	ds_read_b64_tr_b16 v[224:225], v219 offset:28928
	s_waitcnt lgkmcnt(8)
	v_mfma_f32_32x32x16_bf16 v[80:95], v[206:209], v[250:253], v[80:95]
	ds_read_b64_tr_b16 v[206:207], v221 offset:24832
	ds_read_b64_tr_b16 v[208:209], v221 offset:28928
	v_bfe_u32 v246, v203, 2, 2
	v_bfe_u32 v247, v203, 5, 1
	v_lshl_or_b32 v247, v247, 2, v246
	v_and_b32_e32 v249, 3, v203
	v_and_b32_e32 v254, 16, v203
	v_lshl_or_b32 v249, v249, 2, v254
	v_lshlrev_b32_e32 v249, 1, v249
	v_lshl_add_u32 v247, v247, 9, v249
	v_add_u32_e32 v247, s99, v247
	v_lshlrev_b32_e32 v246, 6, v246
	v_add_u32_e32 v205, v247, v246
	v_xor_b32_e32 v249, 64, v246
	v_add_u32_e32 v218, v247, v249
	v_xor_b32_e32 v249, 0x80, v246
	v_add_u32_e32 v219, v247, v249
	v_xor_b32_e32 v249, 0xc0, v246
	v_add_u32_e32 v221, v247, v249
	s_waitcnt lgkmcnt(8)
	v_mfma_f32_32x32x16_bf16 v[64:79], v[210:213], v[250:253], v[64:79]
	v_add_u32_e32 v210, s98, v194
	ds_read_b128 v[210:213], v210
	v_add_u32_e32 v226, s98, v195
	ds_read_b128 v[226:229], v226
	s_waitcnt lgkmcnt(8)
	v_mfma_f32_32x32x16_bf16 v[48:63], v[214:217], v[250:253], v[48:63]
	v_add_u32_e32 v214, s98, v196
	ds_read_b128 v[214:217], v214
	v_add_u32_e32 v230, s98, v197
	ds_read_b128 v[230:233], v230
	s_waitcnt lgkmcnt(8)
	v_mfma_f32_32x32x16_bf16 v[32:47], v[238:241], v[250:253], v[32:47]
	v_add_u32_e32 v238, s98, v198
	ds_read_b128 v[238:241], v238
	v_add_u32_e32 v234, s98, v199
	ds_read_b128 v[234:237], v234
	s_waitcnt lgkmcnt(8)
	v_mfma_f32_32x32x16_bf16 v[16:31], v[222:225], v[250:253], v[16:31]
	v_add_u32_e32 v222, s98, v200
	ds_read_b128 v[222:225], v222
	s_waitcnt lgkmcnt(7)
	v_mfma_f32_32x32x16_bf16 v[0:15], v[206:209], v[250:253], v[0:15]
	v_add_u32_e32 v206, s98, v201
	ds_read_b128 v[206:209], v206
	v_add_u32_e32 v242, s98, v194
	ds_read_b128 v[242:245], v242 offset:8192
	s_waitcnt lgkmcnt(8)
	v_mfma_f32_32x32x16_bf16 v[128:143], v[210:213], v[144:147], 0
	v_add_u32_e32 v210, s98, v195
	ds_read_b128 v[210:213], v210 offset:8192
	v_add_u32_e32 v250, s98, v196
	ds_read_b128 v[250:253], v250 offset:8192
	s_waitcnt lgkmcnt(9)
	v_mfma_f32_32x32x16_bf16 v[128:143], v[226:229], v[148:151], v[128:143]
	s_waitcnt lgkmcnt(8)
	v_mfma_f32_32x32x16_bf16 v[128:143], v[214:217], v[152:155], v[128:143]
	v_add_u32_e32 v214, s98, v197
	ds_read_b128 v[214:217], v214 offset:8192
	s_waitcnt lgkmcnt(8)
	v_mfma_f32_32x32x16_bf16 v[128:143], v[230:233], v[156:159], v[128:143]
	s_waitcnt lgkmcnt(7)
	v_mfma_f32_32x32x16_bf16 v[128:143], v[238:241], v[160:163], v[128:143]
	v_add_u32_e32 v238, s98, v198
	ds_read_b128 v[238:241], v238 offset:8192
	s_waitcnt lgkmcnt(7)
	v_mfma_f32_32x32x16_bf16 v[128:143], v[234:237], v[164:167], v[128:143]
	s_waitcnt lgkmcnt(6)
	v_mfma_f32_32x32x16_bf16 v[128:143], v[222:225], v[168:171], v[128:143]
	s_waitcnt lgkmcnt(5)
	v_mfma_f32_32x32x16_bf16 v[128:143], v[206:209], v[172:175], v[128:143]
	v_add_u32_e32 v206, s98, v199
	ds_read_b128 v[206:209], v206 offset:8192
	s_waitcnt lgkmcnt(5)
	v_mfma_f32_32x32x16_bf16 v[222:237], v[242:245], v[144:147], 0
	v_add_u32_e32 v242, s98, v200
	ds_read_b128 v[242:245], v242 offset:8192
	s_nop 5
	v_max3_f32 v246, v128, v129, v130
	v_max3_f32 v247, v131, v132, v133
	v_max3_f32 v246, v246, v134, v135
	v_max3_f32 v247, v247, v136, v137
	v_max3_f32 v246, v246, v138, v139
	v_max3_f32 v247, v247, v140, v141
	v_max3_f32 v246, v246, v142, v143
	s_waitcnt lgkmcnt(5)
	v_mfma_f32_32x32x16_bf16 v[222:237], v[210:213], v[148:151], v[222:237]
	v_add_u32_e32 v210, s98, v201
	ds_read_b128 v[210:213], v210 offset:8192
	v_max_f32_e32 v246, v246, v247
	v_mov_b32_e32 v247, v246
	v_add_f32_e32 v249, 0x41000000, v190
	s_nop 1
	v_permlane32_swap_b32_e32 v246, v247
	v_max_f32_e32 v246, v246, v247
	v_cmp_gt_f32_e32 vcc, v246, v249
	s_cbranch_vccz .Latt_nr0_0B1
	v_max_f32_e32 v246, v190, v246
	v_sub_f32_e32 v190, v190, v246
	v_exp_f32_e32 v190, v190
	s_nop 0
	v_pk_mul_f32 v[126:127], v[126:127], v[190:191] op_sel_hi:[1,0]
	v_pk_mul_f32 v[124:125], v[124:125], v[190:191] op_sel_hi:[1,0]
	v_pk_mul_f32 v[122:123], v[122:123], v[190:191] op_sel_hi:[1,0]
	v_pk_mul_f32 v[120:121], v[120:121], v[190:191] op_sel_hi:[1,0]
	v_pk_mul_f32 v[118:119], v[118:119], v[190:191] op_sel_hi:[1,0]
	v_pk_mul_f32 v[116:117], v[116:117], v[190:191] op_sel_hi:[1,0]
	v_pk_mul_f32 v[114:115], v[114:115], v[190:191] op_sel_hi:[1,0]
	v_pk_mul_f32 v[112:113], v[112:113], v[190:191] op_sel_hi:[1,0]
	v_pk_mul_f32 v[110:111], v[110:111], v[190:191] op_sel_hi:[1,0]
	v_pk_mul_f32 v[108:109], v[108:109], v[190:191] op_sel_hi:[1,0]
	v_pk_mul_f32 v[106:107], v[106:107], v[190:191] op_sel_hi:[1,0]
	v_pk_mul_f32 v[104:105], v[104:105], v[190:191] op_sel_hi:[1,0]
	v_pk_mul_f32 v[102:103], v[102:103], v[190:191] op_sel_hi:[1,0]
	v_pk_mul_f32 v[100:101], v[100:101], v[190:191] op_sel_hi:[1,0]
	v_pk_mul_f32 v[98:99], v[98:99], v[190:191] op_sel_hi:[1,0]
	v_pk_mul_f32 v[96:97], v[96:97], v[190:191] op_sel_hi:[1,0]
	v_pk_mul_f32 v[94:95], v[94:95], v[190:191] op_sel_hi:[1,0]
	v_pk_mul_f32 v[92:93], v[92:93], v[190:191] op_sel_hi:[1,0]
	v_pk_mul_f32 v[90:91], v[90:91], v[190:191] op_sel_hi:[1,0]
	v_pk_mul_f32 v[88:89], v[88:89], v[190:191] op_sel_hi:[1,0]
	v_pk_mul_f32 v[86:87], v[86:87], v[190:191] op_sel_hi:[1,0]
	v_pk_mul_f32 v[84:85], v[84:85], v[190:191] op_sel_hi:[1,0]
	v_pk_mul_f32 v[82:83], v[82:83], v[190:191] op_sel_hi:[1,0]
	v_pk_mul_f32 v[80:81], v[80:81], v[190:191] op_sel_hi:[1,0]
	v_pk_mul_f32 v[78:79], v[78:79], v[190:191] op_sel_hi:[1,0]
	v_pk_mul_f32 v[76:77], v[76:77], v[190:191] op_sel_hi:[1,0]
	v_pk_mul_f32 v[74:75], v[74:75], v[190:191] op_sel_hi:[1,0]
	v_pk_mul_f32 v[72:73], v[72:73], v[190:191] op_sel_hi:[1,0]
	v_pk_mul_f32 v[70:71], v[70:71], v[190:191] op_sel_hi:[1,0]
	v_pk_mul_f32 v[68:69], v[68:69], v[190:191] op_sel_hi:[1,0]
	v_pk_mul_f32 v[66:67], v[66:67], v[190:191] op_sel_hi:[1,0]
	v_pk_mul_f32 v[64:65], v[64:65], v[190:191] op_sel_hi:[1,0]
	v_pk_mul_f32 v[62:63], v[62:63], v[190:191] op_sel_hi:[1,0]
	v_pk_mul_f32 v[60:61], v[60:61], v[190:191] op_sel_hi:[1,0]
	v_pk_mul_f32 v[58:59], v[58:59], v[190:191] op_sel_hi:[1,0]
	v_pk_mul_f32 v[56:57], v[56:57], v[190:191] op_sel_hi:[1,0]
	v_pk_mul_f32 v[54:55], v[54:55], v[190:191] op_sel_hi:[1,0]
	v_pk_mul_f32 v[52:53], v[52:53], v[190:191] op_sel_hi:[1,0]
	v_pk_mul_f32 v[50:51], v[50:51], v[190:191] op_sel_hi:[1,0]
	v_pk_mul_f32 v[48:49], v[48:49], v[190:191] op_sel_hi:[1,0]
	v_pk_mul_f32 v[46:47], v[46:47], v[190:191] op_sel_hi:[1,0]
	v_pk_mul_f32 v[44:45], v[44:45], v[190:191] op_sel_hi:[1,0]
	v_pk_mul_f32 v[42:43], v[42:43], v[190:191] op_sel_hi:[1,0]
	v_pk_mul_f32 v[40:41], v[40:41], v[190:191] op_sel_hi:[1,0]
	v_pk_mul_f32 v[38:39], v[38:39], v[190:191] op_sel_hi:[1,0]
	v_pk_mul_f32 v[36:37], v[36:37], v[190:191] op_sel_hi:[1,0]
	v_pk_mul_f32 v[34:35], v[34:35], v[190:191] op_sel_hi:[1,0]
	v_pk_mul_f32 v[32:33], v[32:33], v[190:191] op_sel_hi:[1,0]
	v_pk_mul_f32 v[30:31], v[30:31], v[190:191] op_sel_hi:[1,0]
	v_pk_mul_f32 v[28:29], v[28:29], v[190:191] op_sel_hi:[1,0]
	v_pk_mul_f32 v[26:27], v[26:27], v[190:191] op_sel_hi:[1,0]
	v_pk_mul_f32 v[24:25], v[24:25], v[190:191] op_sel_hi:[1,0]
	v_pk_mul_f32 v[22:23], v[22:23], v[190:191] op_sel_hi:[1,0]
	v_pk_mul_f32 v[20:21], v[20:21], v[190:191] op_sel_hi:[1,0]
	v_pk_mul_f32 v[18:19], v[18:19], v[190:191] op_sel_hi:[1,0]
	v_pk_mul_f32 v[16:17], v[16:17], v[190:191] op_sel_hi:[1,0]
	v_pk_mul_f32 v[14:15], v[14:15], v[190:191] op_sel_hi:[1,0]
	v_pk_mul_f32 v[12:13], v[12:13], v[190:191] op_sel_hi:[1,0]
	v_pk_mul_f32 v[10:11], v[10:11], v[190:191] op_sel_hi:[1,0]
	v_pk_mul_f32 v[8:9], v[8:9], v[190:191] op_sel_hi:[1,0]
	v_pk_mul_f32 v[6:7], v[6:7], v[190:191] op_sel_hi:[1,0]
	v_pk_mul_f32 v[4:5], v[4:5], v[190:191] op_sel_hi:[1,0]
	v_pk_mul_f32 v[2:3], v[2:3], v[190:191] op_sel_hi:[1,0]
	v_pk_mul_f32 v[0:1], v[0:1], v[190:191] op_sel_hi:[1,0]
	v_mul_f32_e32 v202, v202, v190
	v_mov_b32_e32 v190, v246
.Latt_nr0_0B1:
	s_waitcnt lgkmcnt(5)
	v_mfma_f32_32x32x16_bf16 v[222:237], v[250:253], v[152:155], v[222:237]
	v_sub_f32_e32 v128, v128, v190
	v_exp_f32_e32 v128, v128
	v_sub_f32_e32 v129, v129, v190
	v_exp_f32_e32 v129, v129
	v_sub_f32_e32 v130, v130, v190
	v_add_f32_e32 v254, 0, v128
	v_exp_f32_e32 v130, v130
	v_sub_f32_e32 v131, v131, v190
	s_waitcnt lgkmcnt(4)
	v_mfma_f32_32x32x16_bf16 v[222:237], v[214:217], v[156:159], v[222:237]
	ds_read_b64_tr_b16 v[214:215], v205
	ds_read_b64_tr_b16 v[216:217], v205 offset:4096
	v_add_f32_e32 v254, v129, v254
	v_exp_f32_e32 v131, v131
	v_sub_f32_e32 v132, v132, v190
	v_add_f32_e32 v254, v130, v254
	v_exp_f32_e32 v132, v132
	v_sub_f32_e32 v133, v133, v190
	v_add_f32_e32 v254, v131, v254
	v_exp_f32_e32 v133, v133
	s_waitcnt lgkmcnt(5)
	v_mfma_f32_32x32x16_bf16 v[222:237], v[238:241], v[160:163], v[222:237]
	ds_read_b64_tr_b16 v[238:239], v218
	ds_read_b64_tr_b16 v[240:241], v218 offset:4096
	v_sub_f32_e32 v134, v134, v190
	v_add_f32_e32 v254, v132, v254
	v_exp_f32_e32 v134, v134
	v_sub_f32_e32 v135, v135, v190
	v_add_f32_e32 v254, v133, v254
	v_exp_f32_e32 v135, v135
	v_sub_f32_e32 v136, v136, v190
	v_add_f32_e32 v254, v134, v254
	s_waitcnt lgkmcnt(6)
	v_mfma_f32_32x32x16_bf16 v[222:237], v[206:209], v[164:167], v[222:237]
	ds_read_b64_tr_b16 v[206:207], v219
	ds_read_b64_tr_b16 v[208:209], v219 offset:4096
	v_exp_f32_e32 v136, v136
	v_sub_f32_e32 v137, v137, v190
	v_add_f32_e32 v254, v135, v254
	v_exp_f32_e32 v137, v137
	v_sub_f32_e32 v138, v138, v190
	v_add_f32_e32 v254, v136, v254
	v_exp_f32_e32 v138, v138
	v_sub_f32_e32 v139, v139, v190
	s_waitcnt lgkmcnt(7)
	v_mfma_f32_32x32x16_bf16 v[222:237], v[242:245], v[168:171], v[222:237]
	v_add_f32_e32 v254, v137, v254
	v_exp_f32_e32 v139, v139
	v_sub_f32_e32 v140, v140, v190
	v_add_f32_e32 v254, v138, v254
	v_exp_f32_e32 v140, v140
	v_sub_f32_e32 v141, v141, v190
	v_add_f32_e32 v254, v139, v254
	v_exp_f32_e32 v141, v141
	s_waitcnt lgkmcnt(6)
	v_mfma_f32_32x32x16_bf16 v[222:237], v[210:213], v[172:175], v[222:237]
	ds_read_b64_tr_b16 v[210:211], v221
	ds_read_b64_tr_b16 v[212:213], v221 offset:4096
	v_sub_f32_e32 v142, v142, v190
	v_add_f32_e32 v254, v140, v254
	v_exp_f32_e32 v142, v142
	v_sub_f32_e32 v143, v143, v190
	v_add_f32_e32 v254, v141, v254
	v_exp_f32_e32 v143, v143
	v_add_f32_e32 v254, v142, v254
	v_add_f32_e32 v254, v143, v254
	v_cvt_pk_bf16_f32 v242, v128, v129
	v_cvt_pk_bf16_f32 v243, v130, v131
	v_cvt_pk_bf16_f32 v244, v132, v133
	v_cvt_pk_bf16_f32 v245, v134, v135
	v_cvt_pk_bf16_f32 v250, v136, v137
	v_cvt_pk_bf16_f32 v251, v138, v139
	v_cvt_pk_bf16_f32 v252, v140, v141
	v_cvt_pk_bf16_f32 v253, v142, v143
	v_add_f32_e32 v202, v202, v254
	s_nop 1
	ds_read_b64_tr_b16 v[128:129], v205 offset:256
	ds_read_b64_tr_b16 v[130:131], v205 offset:4352
	s_waitcnt lgkmcnt(8)
	v_mfma_f32_32x32x16_bf16 v[112:127], v[214:217], v[242:245], v[112:127]
	ds_read_b64_tr_b16 v[214:215], v218 offset:256
	ds_read_b64_tr_b16 v[216:217], v218 offset:4352
	s_waitcnt lgkmcnt(8)
	v_mfma_f32_32x32x16_bf16 v[96:111], v[238:241], v[242:245], v[96:111]
	ds_read_b64_tr_b16 v[238:239], v219 offset:256
	ds_read_b64_tr_b16 v[240:241], v219 offset:4352
	s_waitcnt lgkmcnt(8)
	v_mfma_f32_32x32x16_bf16 v[80:95], v[206:209], v[242:245], v[80:95]
	ds_read_b64_tr_b16 v[206:207], v221 offset:256
	ds_read_b64_tr_b16 v[208:209], v221 offset:4352
	v_max3_f32 v246, v222, v223, v224
	v_max3_f32 v247, v225, v226, v227
	v_max3_f32 v246, v246, v228, v229
	v_max3_f32 v247, v247, v230, v231
	v_max3_f32 v246, v246, v232, v233
	v_max3_f32 v247, v247, v234, v235
	s_waitcnt lgkmcnt(8)
	v_mfma_f32_32x32x16_bf16 v[64:79], v[210:213], v[242:245], v[64:79]
	ds_read_b64_tr_b16 v[210:211], v205 offset:8192
	ds_read_b64_tr_b16 v[212:213], v205 offset:12288
	v_max3_f32 v246, v246, v236, v237
	v_max_f32_e32 v246, v246, v247
	v_mov_b32_e32 v247, v246
	v_add_f32_e32 v249, 0x41000000, v190
	s_nop 1
	s_waitcnt lgkmcnt(8)
	v_mfma_f32_32x32x16_bf16 v[48:63], v[128:131], v[242:245], v[48:63]
	ds_read_b64_tr_b16 v[128:129], v218 offset:8192
	ds_read_b64_tr_b16 v[130:131], v218 offset:12288
	v_permlane32_swap_b32_e32 v246, v247
	v_max_f32_e32 v246, v246, v247
	v_cmp_gt_f32_e32 vcc, v246, v249
	s_cbranch_vccnz .Latt_rs1_0B1
	s_waitcnt lgkmcnt(8)
	v_mfma_f32_32x32x16_bf16 v[32:47], v[214:217], v[242:245], v[32:47]
	ds_read_b64_tr_b16 v[214:215], v219 offset:8192
	ds_read_b64_tr_b16 v[216:217], v219 offset:12288
	v_sub_f32_e32 v222, v222, v190
	v_exp_f32_e32 v222, v222
	v_sub_f32_e32 v223, v223, v190
	v_exp_f32_e32 v223, v223
	v_sub_f32_e32 v224, v224, v190
	s_waitcnt lgkmcnt(8)
	v_mfma_f32_32x32x16_bf16 v[16:31], v[238:241], v[242:245], v[16:31]
	ds_read_b64_tr_b16 v[238:239], v221 offset:8192
	ds_read_b64_tr_b16 v[240:241], v221 offset:12288
	v_add_f32_e32 v254, 0, v222
	v_exp_f32_e32 v224, v224
	v_sub_f32_e32 v225, v225, v190
	v_add_f32_e32 v254, v223, v254
	v_exp_f32_e32 v225, v225
	s_waitcnt lgkmcnt(8)
	v_mfma_f32_32x32x16_bf16 v[0:15], v[206:209], v[242:245], v[0:15]
	ds_read_b64_tr_b16 v[206:207], v205 offset:8448
	ds_read_b64_tr_b16 v[208:209], v205 offset:12544
	v_sub_f32_e32 v226, v226, v190
	v_add_f32_e32 v254, v224, v254
	v_exp_f32_e32 v226, v226
	v_sub_f32_e32 v227, v227, v190
	v_add_f32_e32 v254, v225, v254
	s_waitcnt lgkmcnt(8)
	v_mfma_f32_32x32x16_bf16 v[112:127], v[210:213], v[250:253], v[112:127]
	ds_read_b64_tr_b16 v[210:211], v218 offset:8448
	ds_read_b64_tr_b16 v[212:213], v218 offset:12544
	v_exp_f32_e32 v227, v227
	v_sub_f32_e32 v228, v228, v190
	v_add_f32_e32 v254, v226, v254
	v_exp_f32_e32 v228, v228
	v_sub_f32_e32 v229, v229, v190
	s_waitcnt lgkmcnt(8)
	v_mfma_f32_32x32x16_bf16 v[96:111], v[128:131], v[250:253], v[96:111]
	ds_read_b64_tr_b16 v[128:129], v219 offset:8448
	ds_read_b64_tr_b16 v[130:131], v219 offset:12544
	v_add_f32_e32 v254, v227, v254
	v_exp_f32_e32 v229, v229
	v_sub_f32_e32 v230, v230, v190
	v_add_f32_e32 v254, v228, v254
	s_waitcnt lgkmcnt(8)
	v_mfma_f32_32x32x16_bf16 v[80:95], v[214:217], v[250:253], v[80:95]
	ds_read_b64_tr_b16 v[214:215], v221 offset:8448
	ds_read_b64_tr_b16 v[216:217], v221 offset:12544
	v_exp_f32_e32 v230, v230
	v_sub_f32_e32 v231, v231, v190
	v_add_f32_e32 v254, v229, v254
	v_exp_f32_e32 v231, v231
	s_waitcnt lgkmcnt(8)
	v_mfma_f32_32x32x16_bf16 v[64:79], v[238:241], v[250:253], v[64:79]
	v_sub_f32_e32 v232, v232, v190
	v_add_f32_e32 v254, v230, v254
	v_exp_f32_e32 v232, v232
	v_sub_f32_e32 v233, v233, v190
	s_waitcnt lgkmcnt(6)
	v_mfma_f32_32x32x16_bf16 v[48:63], v[206:209], v[250:253], v[48:63]
	v_add_f32_e32 v254, v231, v254
	v_exp_f32_e32 v233, v233
	v_sub_f32_e32 v234, v234, v190
	v_add_f32_e32 v254, v232, v254
	s_waitcnt lgkmcnt(4)
	v_mfma_f32_32x32x16_bf16 v[32:47], v[210:213], v[250:253], v[32:47]
	v_exp_f32_e32 v234, v234
	v_sub_f32_e32 v235, v235, v190
	v_add_f32_e32 v254, v233, v254
	v_exp_f32_e32 v235, v235
	s_waitcnt lgkmcnt(2)
	v_mfma_f32_32x32x16_bf16 v[16:31], v[128:131], v[250:253], v[16:31]
	v_sub_f32_e32 v236, v236, v190
	v_add_f32_e32 v254, v234, v254
	v_exp_f32_e32 v236, v236
	v_sub_f32_e32 v237, v237, v190
	s_waitcnt lgkmcnt(0)
	v_mfma_f32_32x32x16_bf16 v[0:15], v[214:217], v[250:253], v[0:15]
	v_add_f32_e32 v254, v235, v254
	v_exp_f32_e32 v237, v237
	v_add_f32_e32 v254, v236, v254
	v_add_f32_e32 v254, v237, v254
	v_cvt_pk_bf16_f32 v242, v222, v223
	v_cvt_pk_bf16_f32 v243, v224, v225
	v_cvt_pk_bf16_f32 v244, v226, v227
	v_cvt_pk_bf16_f32 v245, v228, v229
	v_cvt_pk_bf16_f32 v250, v230, v231
	v_cvt_pk_bf16_f32 v251, v232, v233
	v_cvt_pk_bf16_f32 v252, v234, v235
	v_cvt_pk_bf16_f32 v253, v236, v237
	v_add_f32_e32 v202, v202, v254
	s_nop 1
.Latt_pv1_0B1:
	s_branch .LBB0_858
.Latt_rs1_0B1:
	s_waitcnt lgkmcnt(8)
	v_mfma_f32_32x32x16_bf16 v[32:47], v[214:217], v[242:245], v[32:47]
	ds_read_b64_tr_b16 v[214:215], v219 offset:8192
	ds_read_b64_tr_b16 v[216:217], v219 offset:12288
	s_waitcnt lgkmcnt(8)
	v_mfma_f32_32x32x16_bf16 v[16:31], v[238:241], v[242:245], v[16:31]
	ds_read_b64_tr_b16 v[238:239], v221 offset:8192
	ds_read_b64_tr_b16 v[240:241], v221 offset:12288
	s_waitcnt lgkmcnt(8)
	v_mfma_f32_32x32x16_bf16 v[0:15], v[206:209], v[242:245], v[0:15]
	ds_read_b64_tr_b16 v[206:207], v205 offset:8448
	ds_read_b64_tr_b16 v[208:209], v205 offset:12544
	s_waitcnt lgkmcnt(8)
	v_mfma_f32_32x32x16_bf16 v[112:127], v[210:213], v[250:253], v[112:127]
	ds_read_b64_tr_b16 v[210:211], v218 offset:8448
	ds_read_b64_tr_b16 v[212:213], v218 offset:12544
	s_waitcnt lgkmcnt(8)
	v_mfma_f32_32x32x16_bf16 v[96:111], v[128:131], v[250:253], v[96:111]
	ds_read_b64_tr_b16 v[128:129], v219 offset:8448
	ds_read_b64_tr_b16 v[130:131], v219 offset:12544
	s_waitcnt lgkmcnt(8)
	v_mfma_f32_32x32x16_bf16 v[80:95], v[214:217], v[250:253], v[80:95]
	ds_read_b64_tr_b16 v[214:215], v221 offset:8448
	ds_read_b64_tr_b16 v[216:217], v221 offset:12544
	s_waitcnt lgkmcnt(8)
	v_mfma_f32_32x32x16_bf16 v[64:79], v[238:241], v[250:253], v[64:79]
	s_waitcnt lgkmcnt(6)
	v_mfma_f32_32x32x16_bf16 v[48:63], v[206:209], v[250:253], v[48:63]
	s_waitcnt lgkmcnt(4)
	v_mfma_f32_32x32x16_bf16 v[32:47], v[210:213], v[250:253], v[32:47]
	s_waitcnt lgkmcnt(2)
	v_mfma_f32_32x32x16_bf16 v[16:31], v[128:131], v[250:253], v[16:31]
	s_waitcnt lgkmcnt(0)
	v_mfma_f32_32x32x16_bf16 v[0:15], v[214:217], v[250:253], v[0:15]
	s_nop 11
	v_max_f32_e32 v246, v190, v246
	v_sub_f32_e32 v190, v190, v246
	v_exp_f32_e32 v190, v190
	s_nop 0
	v_pk_mul_f32 v[126:127], v[126:127], v[190:191] op_sel_hi:[1,0]
	v_pk_mul_f32 v[124:125], v[124:125], v[190:191] op_sel_hi:[1,0]
	v_pk_mul_f32 v[122:123], v[122:123], v[190:191] op_sel_hi:[1,0]
	v_pk_mul_f32 v[120:121], v[120:121], v[190:191] op_sel_hi:[1,0]
	v_pk_mul_f32 v[118:119], v[118:119], v[190:191] op_sel_hi:[1,0]
	v_pk_mul_f32 v[116:117], v[116:117], v[190:191] op_sel_hi:[1,0]
	v_pk_mul_f32 v[114:115], v[114:115], v[190:191] op_sel_hi:[1,0]
	v_pk_mul_f32 v[112:113], v[112:113], v[190:191] op_sel_hi:[1,0]
	v_pk_mul_f32 v[110:111], v[110:111], v[190:191] op_sel_hi:[1,0]
	v_pk_mul_f32 v[108:109], v[108:109], v[190:191] op_sel_hi:[1,0]
	v_pk_mul_f32 v[106:107], v[106:107], v[190:191] op_sel_hi:[1,0]
	v_pk_mul_f32 v[104:105], v[104:105], v[190:191] op_sel_hi:[1,0]
	v_pk_mul_f32 v[102:103], v[102:103], v[190:191] op_sel_hi:[1,0]
	v_pk_mul_f32 v[100:101], v[100:101], v[190:191] op_sel_hi:[1,0]
	v_pk_mul_f32 v[98:99], v[98:99], v[190:191] op_sel_hi:[1,0]
	v_pk_mul_f32 v[96:97], v[96:97], v[190:191] op_sel_hi:[1,0]
	v_pk_mul_f32 v[94:95], v[94:95], v[190:191] op_sel_hi:[1,0]
	v_pk_mul_f32 v[92:93], v[92:93], v[190:191] op_sel_hi:[1,0]
	v_pk_mul_f32 v[90:91], v[90:91], v[190:191] op_sel_hi:[1,0]
	v_pk_mul_f32 v[88:89], v[88:89], v[190:191] op_sel_hi:[1,0]
	v_pk_mul_f32 v[86:87], v[86:87], v[190:191] op_sel_hi:[1,0]
	v_pk_mul_f32 v[84:85], v[84:85], v[190:191] op_sel_hi:[1,0]
	v_pk_mul_f32 v[82:83], v[82:83], v[190:191] op_sel_hi:[1,0]
	v_pk_mul_f32 v[80:81], v[80:81], v[190:191] op_sel_hi:[1,0]
	v_pk_mul_f32 v[78:79], v[78:79], v[190:191] op_sel_hi:[1,0]
	v_pk_mul_f32 v[76:77], v[76:77], v[190:191] op_sel_hi:[1,0]
	v_pk_mul_f32 v[74:75], v[74:75], v[190:191] op_sel_hi:[1,0]
	v_pk_mul_f32 v[72:73], v[72:73], v[190:191] op_sel_hi:[1,0]
	v_pk_mul_f32 v[70:71], v[70:71], v[190:191] op_sel_hi:[1,0]
	v_pk_mul_f32 v[68:69], v[68:69], v[190:191] op_sel_hi:[1,0]
	v_pk_mul_f32 v[66:67], v[66:67], v[190:191] op_sel_hi:[1,0]
	v_pk_mul_f32 v[64:65], v[64:65], v[190:191] op_sel_hi:[1,0]
	v_pk_mul_f32 v[62:63], v[62:63], v[190:191] op_sel_hi:[1,0]
	v_pk_mul_f32 v[60:61], v[60:61], v[190:191] op_sel_hi:[1,0]
	v_pk_mul_f32 v[58:59], v[58:59], v[190:191] op_sel_hi:[1,0]
	v_pk_mul_f32 v[56:57], v[56:57], v[190:191] op_sel_hi:[1,0]
	v_pk_mul_f32 v[54:55], v[54:55], v[190:191] op_sel_hi:[1,0]
	v_pk_mul_f32 v[52:53], v[52:53], v[190:191] op_sel_hi:[1,0]
	v_pk_mul_f32 v[50:51], v[50:51], v[190:191] op_sel_hi:[1,0]
	v_pk_mul_f32 v[48:49], v[48:49], v[190:191] op_sel_hi:[1,0]
	v_pk_mul_f32 v[46:47], v[46:47], v[190:191] op_sel_hi:[1,0]
	v_pk_mul_f32 v[44:45], v[44:45], v[190:191] op_sel_hi:[1,0]
	v_pk_mul_f32 v[42:43], v[42:43], v[190:191] op_sel_hi:[1,0]
	v_pk_mul_f32 v[40:41], v[40:41], v[190:191] op_sel_hi:[1,0]
	v_pk_mul_f32 v[38:39], v[38:39], v[190:191] op_sel_hi:[1,0]
	v_pk_mul_f32 v[36:37], v[36:37], v[190:191] op_sel_hi:[1,0]
	v_pk_mul_f32 v[34:35], v[34:35], v[190:191] op_sel_hi:[1,0]
	v_pk_mul_f32 v[32:33], v[32:33], v[190:191] op_sel_hi:[1,0]
	v_pk_mul_f32 v[30:31], v[30:31], v[190:191] op_sel_hi:[1,0]
	v_pk_mul_f32 v[28:29], v[28:29], v[190:191] op_sel_hi:[1,0]
	v_pk_mul_f32 v[26:27], v[26:27], v[190:191] op_sel_hi:[1,0]
	v_pk_mul_f32 v[24:25], v[24:25], v[190:191] op_sel_hi:[1,0]
	v_pk_mul_f32 v[22:23], v[22:23], v[190:191] op_sel_hi:[1,0]
	v_pk_mul_f32 v[20:21], v[20:21], v[190:191] op_sel_hi:[1,0]
	v_pk_mul_f32 v[18:19], v[18:19], v[190:191] op_sel_hi:[1,0]
	v_pk_mul_f32 v[16:17], v[16:17], v[190:191] op_sel_hi:[1,0]
	v_pk_mul_f32 v[14:15], v[14:15], v[190:191] op_sel_hi:[1,0]
	v_pk_mul_f32 v[12:13], v[12:13], v[190:191] op_sel_hi:[1,0]
	v_pk_mul_f32 v[10:11], v[10:11], v[190:191] op_sel_hi:[1,0]
	v_pk_mul_f32 v[8:9], v[8:9], v[190:191] op_sel_hi:[1,0]
	v_pk_mul_f32 v[6:7], v[6:7], v[190:191] op_sel_hi:[1,0]
	v_pk_mul_f32 v[4:5], v[4:5], v[190:191] op_sel_hi:[1,0]
	v_pk_mul_f32 v[2:3], v[2:3], v[190:191] op_sel_hi:[1,0]
	v_pk_mul_f32 v[0:1], v[0:1], v[190:191] op_sel_hi:[1,0]
	v_mul_f32_e32 v202, v202, v190
	v_mov_b32_e32 v190, v246
	v_sub_f32_e32 v222, v222, v190
	v_exp_f32_e32 v222, v222
	v_sub_f32_e32 v223, v223, v190
	v_exp_f32_e32 v223, v223
	v_sub_f32_e32 v224, v224, v190
	v_add_f32_e32 v254, 0, v222
	v_exp_f32_e32 v224, v224
	v_sub_f32_e32 v225, v225, v190
	v_add_f32_e32 v254, v223, v254
	v_exp_f32_e32 v225, v225
	v_sub_f32_e32 v226, v226, v190
	v_add_f32_e32 v254, v224, v254
	v_exp_f32_e32 v226, v226
	v_sub_f32_e32 v227, v227, v190
	v_add_f32_e32 v254, v225, v254
	v_exp_f32_e32 v227, v227
	v_sub_f32_e32 v228, v228, v190
	v_add_f32_e32 v254, v226, v254
	v_exp_f32_e32 v228, v228
	v_sub_f32_e32 v229, v229, v190
	v_add_f32_e32 v254, v227, v254
	v_exp_f32_e32 v229, v229
	v_sub_f32_e32 v230, v230, v190
	v_add_f32_e32 v254, v228, v254
	v_exp_f32_e32 v230, v230
	v_sub_f32_e32 v231, v231, v190
	v_add_f32_e32 v254, v229, v254
	v_exp_f32_e32 v231, v231
	v_sub_f32_e32 v232, v232, v190
	v_add_f32_e32 v254, v230, v254
	v_exp_f32_e32 v232, v232
	v_sub_f32_e32 v233, v233, v190
	v_add_f32_e32 v254, v231, v254
	v_exp_f32_e32 v233, v233
	v_sub_f32_e32 v234, v234, v190
	v_add_f32_e32 v254, v232, v254
	v_exp_f32_e32 v234, v234
	v_sub_f32_e32 v235, v235, v190
	v_add_f32_e32 v254, v233, v254
	v_exp_f32_e32 v235, v235
	v_sub_f32_e32 v236, v236, v190
	v_add_f32_e32 v254, v234, v254
	v_exp_f32_e32 v236, v236
	v_sub_f32_e32 v237, v237, v190
	v_add_f32_e32 v254, v235, v254
	v_exp_f32_e32 v237, v237
	v_add_f32_e32 v254, v236, v254
	v_add_f32_e32 v254, v237, v254
	v_cvt_pk_bf16_f32 v242, v222, v223
	v_cvt_pk_bf16_f32 v243, v224, v225
	v_cvt_pk_bf16_f32 v244, v226, v227
	v_cvt_pk_bf16_f32 v245, v228, v229
	v_cvt_pk_bf16_f32 v250, v230, v231
	v_cvt_pk_bf16_f32 v251, v232, v233
	v_cvt_pk_bf16_f32 v252, v234, v235
	v_cvt_pk_bf16_f32 v253, v236, v237
	v_add_f32_e32 v202, v202, v254
	s_nop 1
	s_branch .Latt_pv1_0B1
.Latt_B0_0:
	s_lshl_b32 s98, s88, 14
	s_lshl_b32 s99, s88, 15
	s_add_i32 s99, s99, 0xc000
	v_add_u32_e32 v206, s98, v194
	ds_read_b128 v[206:209], v206
	v_add_u32_e32 v210, s98, v195
	ds_read_b128 v[210:213], v210
	v_add_u32_e32 v214, s98, v196
	ds_read_b128 v[214:217], v214
	v_add_u32_e32 v238, s98, v197
	ds_read_b128 v[238:241], v238
	v_add_u32_e32 v242, s98, v198
	ds_read_b128 v[242:245], v242
	v_add_u32_e32 v250, s98, v199
	ds_read_b128 v[250:253], v250
	v_add_u32_e32 v222, s98, v200
	ds_read_b128 v[222:225], v222
	v_add_u32_e32 v226, s98, v201
	ds_read_b128 v[226:229], v226
	v_bfe_u32 v246, v203, 2, 2
	v_bfe_u32 v247, v203, 5, 1
	v_lshl_or_b32 v247, v247, 2, v246
	v_and_b32_e32 v249, 3, v203
	v_and_b32_e32 v254, 16, v203
	v_lshl_or_b32 v249, v249, 2, v254
	v_lshlrev_b32_e32 v249, 1, v249
	v_lshl_add_u32 v247, v247, 9, v249
	v_add_u32_e32 v247, s99, v247
	v_lshlrev_b32_e32 v246, 6, v246
	v_add_u32_e32 v205, v247, v246
	v_xor_b32_e32 v249, 64, v246
	v_add_u32_e32 v218, v247, v249
	v_xor_b32_e32 v249, 0x80, v246
	v_add_u32_e32 v219, v247, v249
	v_xor_b32_e32 v249, 0xc0, v246
	v_add_u32_e32 v221, v247, v249
	s_waitcnt lgkmcnt(7)
	v_mfma_f32_32x32x16_bf16 v[128:143], v[206:209], v[144:147], 0
	v_add_u32_e32 v206, s98, v194
	ds_read_b128 v[206:209], v206 offset:8192
	s_cmp_lg_u64 s[18:19], 0
	s_cbranch_scc1 .Latt_nd0_0B0
	s_add_i32 s100, s88, 1
	s_cmp_eq_u32 s88, 2
	s_cselect_b32 s100, 0, s100
	s_lshl_b32 s101, s100, 14
	s_add_i32 m0, s85, s101
	s_nop 0
	global_load_lds_dwordx4 v178, s[14:15]
.Latt_nd0_0B0:
	s_waitcnt lgkmcnt(7)
	v_mfma_f32_32x32x16_bf16 v[128:143], v[210:213], v[148:151], v[128:143]
	v_add_u32_e32 v210, s98, v195
	ds_read_b128 v[210:213], v210 offset:8192
	s_cmp_lg_u64 s[18:19], 0
	s_cbranch_scc1 .Latt_nd1_0B0
	s_add_i32 m0, m0, 0x400
	s_nop 0
	global_load_lds_dwordx4 v180, s[14:15]
.Latt_nd1_0B0:
	s_waitcnt lgkmcnt(7)
	v_mfma_f32_32x32x16_bf16 v[128:143], v[214:217], v[152:155], v[128:143]
	v_add_u32_e32 v214, s98, v196
	ds_read_b128 v[214:217], v214 offset:8192
	s_cmp_lg_u64 s[18:19], 0
	s_cbranch_scc1 .Latt_nd2_0B0
	s_lshl_b32 s101, s100, 15
	s_add_i32 m0, s86, s101
	s_add_u32 s100, s14, 0x1000
	s_addc_u32 s101, s15, 0
	global_load_lds_dwordx4 v182, s[100:101]
.Latt_nd2_0B0:
	s_waitcnt lgkmcnt(7)
	v_mfma_f32_32x32x16_bf16 v[128:143], v[238:241], v[156:159], v[128:143]
	v_add_u32_e32 v238, s98, v197
	ds_read_b128 v[238:241], v238 offset:8192
	s_cmp_lg_u64 s[18:19], 0
	s_cbranch_scc1 .Latt_nd3_0B0
	s_add_i32 m0, m0, 0x400
	s_nop 0
	global_load_lds_dwordx4 v184, s[100:101]
.Latt_nd3_0B0:
	s_waitcnt lgkmcnt(7)
	v_mfma_f32_32x32x16_bf16 v[128:143], v[242:245], v[160:163], v[128:143]
	v_add_u32_e32 v242, s98, v198
	ds_read_b128 v[242:245], v242 offset:8192
	s_cmp_lg_u64 s[18:19], 0
	s_cbranch_scc1 .Latt_nd4_0B0
	s_add_i32 m0, m0, 0x400
	s_nop 0
	global_load_lds_dwordx4 v186, s[100:101]
.Latt_nd4_0B0:
	s_waitcnt lgkmcnt(7)
	v_mfma_f32_32x32x16_bf16 v[128:143], v[250:253], v[164:167], v[128:143]
	v_add_u32_e32 v250, s98, v199
	ds_read_b128 v[250:253], v250 offset:8192
	s_cmp_lg_u64 s[18:19], 0
	s_cbranch_scc1 .Latt_nd5_0B0
	s_add_i32 m0, m0, 0x400
	s_nop 0
	global_load_lds_dwordx4 v188, s[100:101]
.Latt_nd5_0B0:
	s_waitcnt lgkmcnt(7)
	v_mfma_f32_32x32x16_bf16 v[128:143], v[222:225], v[168:171], v[128:143]
	s_waitcnt lgkmcnt(6)
	v_mfma_f32_32x32x16_bf16 v[128:143], v[226:229], v[172:175], v[128:143]
	s_waitcnt lgkmcnt(5)
	v_mfma_f32_32x32x16_bf16 v[222:237], v[206:209], v[144:147], 0
	v_add_u32_e32 v206, s98, v200
	ds_read_b128 v[206:209], v206 offset:8192
	s_nop 7
	v_max3_f32 v246, v128, v129, v130
	v_max3_f32 v247, v131, v132, v133
	v_max3_f32 v246, v246, v134, v135
	v_max3_f32 v247, v247, v136, v137
	v_max3_f32 v246, v246, v138, v139
	v_max3_f32 v247, v247, v140, v141
	v_max3_f32 v246, v246, v142, v143
	s_waitcnt lgkmcnt(5)
	v_mfma_f32_32x32x16_bf16 v[222:237], v[210:213], v[148:151], v[222:237]
	v_add_u32_e32 v210, s98, v201
	ds_read_b128 v[210:213], v210 offset:8192
	v_max_f32_e32 v246, v246, v247
	v_mov_b32_e32 v247, v246
	v_add_f32_e32 v249, 0x41000000, v190
	s_nop 1
	v_permlane32_swap_b32_e32 v246, v247
	v_max_f32_e32 v246, v246, v247
	v_cmp_gt_f32_e32 vcc, v246, v249
	s_cbranch_vccz .Latt_nr0_0B0
	v_max_f32_e32 v246, v190, v246
	v_sub_f32_e32 v190, v190, v246
	v_exp_f32_e32 v190, v190
	s_nop 0
	v_pk_mul_f32 v[126:127], v[126:127], v[190:191] op_sel_hi:[1,0]
	v_pk_mul_f32 v[124:125], v[124:125], v[190:191] op_sel_hi:[1,0]
	v_pk_mul_f32 v[122:123], v[122:123], v[190:191] op_sel_hi:[1,0]
	v_pk_mul_f32 v[120:121], v[120:121], v[190:191] op_sel_hi:[1,0]
	v_pk_mul_f32 v[118:119], v[118:119], v[190:191] op_sel_hi:[1,0]
	v_pk_mul_f32 v[116:117], v[116:117], v[190:191] op_sel_hi:[1,0]
	v_pk_mul_f32 v[114:115], v[114:115], v[190:191] op_sel_hi:[1,0]
	v_pk_mul_f32 v[112:113], v[112:113], v[190:191] op_sel_hi:[1,0]
	v_pk_mul_f32 v[110:111], v[110:111], v[190:191] op_sel_hi:[1,0]
	v_pk_mul_f32 v[108:109], v[108:109], v[190:191] op_sel_hi:[1,0]
	v_pk_mul_f32 v[106:107], v[106:107], v[190:191] op_sel_hi:[1,0]
	v_pk_mul_f32 v[104:105], v[104:105], v[190:191] op_sel_hi:[1,0]
	v_pk_mul_f32 v[102:103], v[102:103], v[190:191] op_sel_hi:[1,0]
	v_pk_mul_f32 v[100:101], v[100:101], v[190:191] op_sel_hi:[1,0]
	v_pk_mul_f32 v[98:99], v[98:99], v[190:191] op_sel_hi:[1,0]
	v_pk_mul_f32 v[96:97], v[96:97], v[190:191] op_sel_hi:[1,0]
	v_pk_mul_f32 v[94:95], v[94:95], v[190:191] op_sel_hi:[1,0]
	v_pk_mul_f32 v[92:93], v[92:93], v[190:191] op_sel_hi:[1,0]
	v_pk_mul_f32 v[90:91], v[90:91], v[190:191] op_sel_hi:[1,0]
	v_pk_mul_f32 v[88:89], v[88:89], v[190:191] op_sel_hi:[1,0]
	v_pk_mul_f32 v[86:87], v[86:87], v[190:191] op_sel_hi:[1,0]
	v_pk_mul_f32 v[84:85], v[84:85], v[190:191] op_sel_hi:[1,0]
	v_pk_mul_f32 v[82:83], v[82:83], v[190:191] op_sel_hi:[1,0]
	v_pk_mul_f32 v[80:81], v[80:81], v[190:191] op_sel_hi:[1,0]
	v_pk_mul_f32 v[78:79], v[78:79], v[190:191] op_sel_hi:[1,0]
	v_pk_mul_f32 v[76:77], v[76:77], v[190:191] op_sel_hi:[1,0]
	v_pk_mul_f32 v[74:75], v[74:75], v[190:191] op_sel_hi:[1,0]
	v_pk_mul_f32 v[72:73], v[72:73], v[190:191] op_sel_hi:[1,0]
	v_pk_mul_f32 v[70:71], v[70:71], v[190:191] op_sel_hi:[1,0]
	v_pk_mul_f32 v[68:69], v[68:69], v[190:191] op_sel_hi:[1,0]
	v_pk_mul_f32 v[66:67], v[66:67], v[190:191] op_sel_hi:[1,0]
	v_pk_mul_f32 v[64:65], v[64:65], v[190:191] op_sel_hi:[1,0]
	v_pk_mul_f32 v[62:63], v[62:63], v[190:191] op_sel_hi:[1,0]
	v_pk_mul_f32 v[60:61], v[60:61], v[190:191] op_sel_hi:[1,0]
	v_pk_mul_f32 v[58:59], v[58:59], v[190:191] op_sel_hi:[1,0]
	v_pk_mul_f32 v[56:57], v[56:57], v[190:191] op_sel_hi:[1,0]
	v_pk_mul_f32 v[54:55], v[54:55], v[190:191] op_sel_hi:[1,0]
	v_pk_mul_f32 v[52:53], v[52:53], v[190:191] op_sel_hi:[1,0]
	v_pk_mul_f32 v[50:51], v[50:51], v[190:191] op_sel_hi:[1,0]
	v_pk_mul_f32 v[48:49], v[48:49], v[190:191] op_sel_hi:[1,0]
	v_pk_mul_f32 v[46:47], v[46:47], v[190:191] op_sel_hi:[1,0]
	v_pk_mul_f32 v[44:45], v[44:45], v[190:191] op_sel_hi:[1,0]
	v_pk_mul_f32 v[42:43], v[42:43], v[190:191] op_sel_hi:[1,0]
	v_pk_mul_f32 v[40:41], v[40:41], v[190:191] op_sel_hi:[1,0]
	v_pk_mul_f32 v[38:39], v[38:39], v[190:191] op_sel_hi:[1,0]
	v_pk_mul_f32 v[36:37], v[36:37], v[190:191] op_sel_hi:[1,0]
	v_pk_mul_f32 v[34:35], v[34:35], v[190:191] op_sel_hi:[1,0]
	v_pk_mul_f32 v[32:33], v[32:33], v[190:191] op_sel_hi:[1,0]
	v_pk_mul_f32 v[30:31], v[30:31], v[190:191] op_sel_hi:[1,0]
	v_pk_mul_f32 v[28:29], v[28:29], v[190:191] op_sel_hi:[1,0]
	v_pk_mul_f32 v[26:27], v[26:27], v[190:191] op_sel_hi:[1,0]
	v_pk_mul_f32 v[24:25], v[24:25], v[190:191] op_sel_hi:[1,0]
	v_pk_mul_f32 v[22:23], v[22:23], v[190:191] op_sel_hi:[1,0]
	v_pk_mul_f32 v[20:21], v[20:21], v[190:191] op_sel_hi:[1,0]
	v_pk_mul_f32 v[18:19], v[18:19], v[190:191] op_sel_hi:[1,0]
	v_pk_mul_f32 v[16:17], v[16:17], v[190:191] op_sel_hi:[1,0]
	v_pk_mul_f32 v[14:15], v[14:15], v[190:191] op_sel_hi:[1,0]
	v_pk_mul_f32 v[12:13], v[12:13], v[190:191] op_sel_hi:[1,0]
	v_pk_mul_f32 v[10:11], v[10:11], v[190:191] op_sel_hi:[1,0]
	v_pk_mul_f32 v[8:9], v[8:9], v[190:191] op_sel_hi:[1,0]
	v_pk_mul_f32 v[6:7], v[6:7], v[190:191] op_sel_hi:[1,0]
	v_pk_mul_f32 v[4:5], v[4:5], v[190:191] op_sel_hi:[1,0]
	v_pk_mul_f32 v[2:3], v[2:3], v[190:191] op_sel_hi:[1,0]
	v_pk_mul_f32 v[0:1], v[0:1], v[190:191] op_sel_hi:[1,0]
	v_mul_f32_e32 v202, v202, v190
	v_mov_b32_e32 v190, v246
.Latt_nr0_0B0:
	s_waitcnt lgkmcnt(5)
	v_mfma_f32_32x32x16_bf16 v[222:237], v[214:217], v[152:155], v[222:237]
	ds_read_b64_tr_b16 v[214:215], v205
	ds_read_b64_tr_b16 v[216:217], v205 offset:4096
	v_sub_f32_e32 v128, v128, v190
	v_exp_f32_e32 v128, v128
	v_sub_f32_e32 v129, v129, v190
	v_exp_f32_e32 v129, v129
	v_sub_f32_e32 v130, v130, v190
	v_add_f32_e32 v254, 0, v128
	v_exp_f32_e32 v130, v130
	v_sub_f32_e32 v131, v131, v190
	s_waitcnt lgkmcnt(6)
	v_mfma_f32_32x32x16_bf16 v[222:237], v[238:241], v[156:159], v[222:237]
	ds_read_b64_tr_b16 v[238:239], v218
	ds_read_b64_tr_b16 v[240:241], v218 offset:4096
	v_add_f32_e32 v254, v129, v254
	v_exp_f32_e32 v131, v131
	v_sub_f32_e32 v132, v132, v190
	v_add_f32_e32 v254, v130, v254
	v_exp_f32_e32 v132, v132
	v_sub_f32_e32 v133, v133, v190
	v_add_f32_e32 v254, v131, v254
	v_exp_f32_e32 v133, v133
	s_waitcnt lgkmcnt(7)
	v_mfma_f32_32x32x16_bf16 v[222:237], v[242:245], v[160:163], v[222:237]
	v_sub_f32_e32 v134, v134, v190
	v_add_f32_e32 v254, v132, v254
	v_exp_f32_e32 v134, v134
	v_sub_f32_e32 v135, v135, v190
	v_add_f32_e32 v254, v133, v254
	v_exp_f32_e32 v135, v135
	v_sub_f32_e32 v136, v136, v190
	v_add_f32_e32 v254, v134, v254
	s_waitcnt lgkmcnt(6)
	v_mfma_f32_32x32x16_bf16 v[222:237], v[250:253], v[164:167], v[222:237]
	v_exp_f32_e32 v136, v136
	v_sub_f32_e32 v137, v137, v190
	v_add_f32_e32 v254, v135, v254
	v_exp_f32_e32 v137, v137
	v_sub_f32_e32 v138, v138, v190
	v_add_f32_e32 v254, v136, v254
	v_exp_f32_e32 v138, v138
	v_sub_f32_e32 v139, v139, v190
	s_waitcnt lgkmcnt(5)
	v_mfma_f32_32x32x16_bf16 v[222:237], v[206:209], v[168:171], v[222:237]
	ds_read_b64_tr_b16 v[206:207], v219
	ds_read_b64_tr_b16 v[208:209], v219 offset:4096
	v_add_f32_e32 v254, v137, v254
	v_exp_f32_e32 v139, v139
	v_sub_f32_e32 v140, v140, v190
	v_add_f32_e32 v254, v138, v254
	v_exp_f32_e32 v140, v140
	v_sub_f32_e32 v141, v141, v190
	v_add_f32_e32 v254, v139, v254
	v_exp_f32_e32 v141, v141
	s_waitcnt lgkmcnt(6)
	v_mfma_f32_32x32x16_bf16 v[222:237], v[210:213], v[172:175], v[222:237]
	ds_read_b64_tr_b16 v[210:211], v221
	ds_read_b64_tr_b16 v[212:213], v221 offset:4096
	v_sub_f32_e32 v142, v142, v190
	v_add_f32_e32 v254, v140, v254
	v_exp_f32_e32 v142, v142
	v_sub_f32_e32 v143, v143, v190
	v_add_f32_e32 v254, v141, v254
	v_exp_f32_e32 v143, v143
	v_add_f32_e32 v254, v142, v254
	v_add_f32_e32 v254, v143, v254
	v_cvt_pk_bf16_f32 v242, v128, v129
	v_cvt_pk_bf16_f32 v243, v130, v131
	v_cvt_pk_bf16_f32 v244, v132, v133
	v_cvt_pk_bf16_f32 v245, v134, v135
	v_cvt_pk_bf16_f32 v250, v136, v137
	v_cvt_pk_bf16_f32 v251, v138, v139
	v_cvt_pk_bf16_f32 v252, v140, v141
	v_cvt_pk_bf16_f32 v253, v142, v143
	v_add_f32_e32 v202, v202, v254
	s_nop 1
	ds_read_b64_tr_b16 v[128:129], v205 offset:256
	ds_read_b64_tr_b16 v[130:131], v205 offset:4352
	s_waitcnt lgkmcnt(8)
	v_mfma_f32_32x32x16_bf16 v[112:127], v[214:217], v[242:245], v[112:127]
	ds_read_b64_tr_b16 v[214:215], v218 offset:256
	ds_read_b64_tr_b16 v[216:217], v218 offset:4352
	s_waitcnt lgkmcnt(8)
	v_mfma_f32_32x32x16_bf16 v[96:111], v[238:241], v[242:245], v[96:111]
	ds_read_b64_tr_b16 v[238:239], v219 offset:256
	ds_read_b64_tr_b16 v[240:241], v219 offset:4352
	s_waitcnt lgkmcnt(8)
	v_mfma_f32_32x32x16_bf16 v[80:95], v[206:209], v[242:245], v[80:95]
	ds_read_b64_tr_b16 v[206:207], v221 offset:256
	ds_read_b64_tr_b16 v[208:209], v221 offset:4352
	v_max3_f32 v246, v222, v223, v224
	v_max3_f32 v247, v225, v226, v227
	v_max3_f32 v246, v246, v228, v229
	v_max3_f32 v247, v247, v230, v231
	v_max3_f32 v246, v246, v232, v233
	v_max3_f32 v247, v247, v234, v235
	s_waitcnt lgkmcnt(8)
	v_mfma_f32_32x32x16_bf16 v[64:79], v[210:213], v[242:245], v[64:79]
	ds_read_b64_tr_b16 v[210:211], v205 offset:8192
	ds_read_b64_tr_b16 v[212:213], v205 offset:12288
	v_max3_f32 v246, v246, v236, v237
	v_max_f32_e32 v246, v246, v247
	v_mov_b32_e32 v247, v246
	v_add_f32_e32 v249, 0x41000000, v190
	s_nop 1
	s_waitcnt lgkmcnt(8)
	v_mfma_f32_32x32x16_bf16 v[48:63], v[128:131], v[242:245], v[48:63]
	ds_read_b64_tr_b16 v[128:129], v218 offset:8192
	ds_read_b64_tr_b16 v[130:131], v218 offset:12288
	v_permlane32_swap_b32_e32 v246, v247
	v_max_f32_e32 v246, v246, v247
	v_cmp_gt_f32_e32 vcc, v246, v249
	s_cbranch_vccnz .Latt_rs1_0B0
	s_waitcnt lgkmcnt(8)
	v_mfma_f32_32x32x16_bf16 v[32:47], v[214:217], v[242:245], v[32:47]
	ds_read_b64_tr_b16 v[214:215], v219 offset:8192
	ds_read_b64_tr_b16 v[216:217], v219 offset:12288
	v_sub_f32_e32 v222, v222, v190
	v_exp_f32_e32 v222, v222
	v_sub_f32_e32 v223, v223, v190
	v_exp_f32_e32 v223, v223
	v_sub_f32_e32 v224, v224, v190
	s_waitcnt lgkmcnt(8)
	v_mfma_f32_32x32x16_bf16 v[16:31], v[238:241], v[242:245], v[16:31]
	ds_read_b64_tr_b16 v[238:239], v221 offset:8192
	ds_read_b64_tr_b16 v[240:241], v221 offset:12288
	v_add_f32_e32 v254, 0, v222
	v_exp_f32_e32 v224, v224
	v_sub_f32_e32 v225, v225, v190
	v_add_f32_e32 v254, v223, v254
	v_exp_f32_e32 v225, v225
	s_waitcnt lgkmcnt(8)
	v_mfma_f32_32x32x16_bf16 v[0:15], v[206:209], v[242:245], v[0:15]
	ds_read_b64_tr_b16 v[206:207], v205 offset:8448
	ds_read_b64_tr_b16 v[208:209], v205 offset:12544
	v_sub_f32_e32 v226, v226, v190
	v_add_f32_e32 v254, v224, v254
	v_exp_f32_e32 v226, v226
	v_sub_f32_e32 v227, v227, v190
	v_add_f32_e32 v254, v225, v254
	s_waitcnt lgkmcnt(8)
	v_mfma_f32_32x32x16_bf16 v[112:127], v[210:213], v[250:253], v[112:127]
	ds_read_b64_tr_b16 v[210:211], v218 offset:8448
	ds_read_b64_tr_b16 v[212:213], v218 offset:12544
	v_exp_f32_e32 v227, v227
	v_sub_f32_e32 v228, v228, v190
	v_add_f32_e32 v254, v226, v254
	v_exp_f32_e32 v228, v228
	v_sub_f32_e32 v229, v229, v190
	s_waitcnt lgkmcnt(8)
	v_mfma_f32_32x32x16_bf16 v[96:111], v[128:131], v[250:253], v[96:111]
	ds_read_b64_tr_b16 v[128:129], v219 offset:8448
	ds_read_b64_tr_b16 v[130:131], v219 offset:12544
	v_add_f32_e32 v254, v227, v254
	v_exp_f32_e32 v229, v229
	v_sub_f32_e32 v230, v230, v190
	v_add_f32_e32 v254, v228, v254
	s_waitcnt lgkmcnt(8)
	v_mfma_f32_32x32x16_bf16 v[80:95], v[214:217], v[250:253], v[80:95]
	ds_read_b64_tr_b16 v[214:215], v221 offset:8448
	ds_read_b64_tr_b16 v[216:217], v221 offset:12544
	v_exp_f32_e32 v230, v230
	v_sub_f32_e32 v231, v231, v190
	v_add_f32_e32 v254, v229, v254
	v_exp_f32_e32 v231, v231
	s_waitcnt lgkmcnt(8)
	v_mfma_f32_32x32x16_bf16 v[64:79], v[238:241], v[250:253], v[64:79]
	v_sub_f32_e32 v232, v232, v190
	v_add_f32_e32 v254, v230, v254
	v_exp_f32_e32 v232, v232
	v_sub_f32_e32 v233, v233, v190
	s_waitcnt lgkmcnt(6)
	v_mfma_f32_32x32x16_bf16 v[48:63], v[206:209], v[250:253], v[48:63]
	v_add_f32_e32 v254, v231, v254
	v_exp_f32_e32 v233, v233
	v_sub_f32_e32 v234, v234, v190
	v_add_f32_e32 v254, v232, v254
	s_waitcnt lgkmcnt(4)
	v_mfma_f32_32x32x16_bf16 v[32:47], v[210:213], v[250:253], v[32:47]
	v_exp_f32_e32 v234, v234
	v_sub_f32_e32 v235, v235, v190
	v_add_f32_e32 v254, v233, v254
	v_exp_f32_e32 v235, v235
	s_waitcnt lgkmcnt(2)
	v_mfma_f32_32x32x16_bf16 v[16:31], v[128:131], v[250:253], v[16:31]
	v_sub_f32_e32 v236, v236, v190
	v_add_f32_e32 v254, v234, v254
	v_exp_f32_e32 v236, v236
	v_sub_f32_e32 v237, v237, v190
	s_waitcnt lgkmcnt(0)
	v_mfma_f32_32x32x16_bf16 v[0:15], v[214:217], v[250:253], v[0:15]
	v_add_f32_e32 v254, v235, v254
	v_exp_f32_e32 v237, v237
	v_add_f32_e32 v254, v236, v254
	v_add_f32_e32 v254, v237, v254
	v_cvt_pk_bf16_f32 v242, v222, v223
	v_cvt_pk_bf16_f32 v243, v224, v225
	v_cvt_pk_bf16_f32 v244, v226, v227
	v_cvt_pk_bf16_f32 v245, v228, v229
	v_cvt_pk_bf16_f32 v250, v230, v231
	v_cvt_pk_bf16_f32 v251, v232, v233
	v_cvt_pk_bf16_f32 v252, v234, v235
	v_cvt_pk_bf16_f32 v253, v236, v237
	v_add_f32_e32 v202, v202, v254
	s_nop 1

.Latt_pv1_0A:
	s_waitcnt lgkmcnt(8)
	v_mfma_f32_32x32x16_bf16 v[112:127], v[238:241], v[242:245], v[112:127]
	ds_read_b64_tr_b16 v[238:239], v218 offset:16640
	ds_read_b64_tr_b16 v[240:241], v218 offset:20736
	s_waitcnt lgkmcnt(8)
	v_mfma_f32_32x32x16_bf16 v[96:111], v[206:209], v[242:245], v[96:111]
	ds_read_b64_tr_b16 v[206:207], v219 offset:16640
	ds_read_b64_tr_b16 v[208:209], v219 offset:20736
	s_waitcnt lgkmcnt(8)
	v_mfma_f32_32x32x16_bf16 v[80:95], v[210:213], v[242:245], v[80:95]
	ds_read_b64_tr_b16 v[210:211], v221 offset:16640
	ds_read_b64_tr_b16 v[212:213], v221 offset:20736
	s_waitcnt lgkmcnt(8)
	v_mfma_f32_32x32x16_bf16 v[64:79], v[128:131], v[242:245], v[64:79]
	ds_read_b64_tr_b16 v[222:223], v205 offset:24576
	ds_read_b64_tr_b16 v[224:225], v205 offset:28672
	s_waitcnt lgkmcnt(8)
	v_mfma_f32_32x32x16_bf16 v[48:63], v[214:217], v[242:245], v[48:63]
	ds_read_b64_tr_b16 v[214:215], v218 offset:24576
	ds_read_b64_tr_b16 v[216:217], v218 offset:28672
	s_waitcnt lgkmcnt(8)
	v_mfma_f32_32x32x16_bf16 v[32:47], v[238:241], v[242:245], v[32:47]
	ds_read_b64_tr_b16 v[238:239], v219 offset:24576
	ds_read_b64_tr_b16 v[240:241], v219 offset:28672
	s_waitcnt lgkmcnt(8)
	v_mfma_f32_32x32x16_bf16 v[16:31], v[206:209], v[242:245], v[16:31]
	ds_read_b64_tr_b16 v[206:207], v221 offset:24576
	ds_read_b64_tr_b16 v[208:209], v221 offset:28672
	s_waitcnt lgkmcnt(8)
	v_mfma_f32_32x32x16_bf16 v[0:15], v[210:213], v[242:245], v[0:15]
	ds_read_b64_tr_b16 v[210:211], v205 offset:24832
	ds_read_b64_tr_b16 v[212:213], v205 offset:28928
	s_waitcnt lgkmcnt(8)
	v_mfma_f32_32x32x16_bf16 v[112:127], v[222:225], v[250:253], v[112:127]
	ds_read_b64_tr_b16 v[222:223], v218 offset:24832
	ds_read_b64_tr_b16 v[224:225], v218 offset:28928
	s_waitcnt lgkmcnt(8)
	v_mfma_f32_32x32x16_bf16 v[96:111], v[214:217], v[250:253], v[96:111]
	ds_read_b64_tr_b16 v[214:215], v219 offset:24832
	ds_read_b64_tr_b16 v[216:217], v219 offset:28928
	s_waitcnt lgkmcnt(8)
	v_mfma_f32_32x32x16_bf16 v[80:95], v[238:241], v[250:253], v[80:95]
	ds_read_b64_tr_b16 v[238:239], v221 offset:24832
	ds_read_b64_tr_b16 v[240:241], v221 offset:28928
	s_waitcnt lgkmcnt(8)
	v_mfma_f32_32x32x16_bf16 v[64:79], v[206:209], v[250:253], v[64:79]
	s_waitcnt lgkmcnt(6)
	v_mfma_f32_32x32x16_bf16 v[48:63], v[210:213], v[250:253], v[48:63]
	s_waitcnt lgkmcnt(4)
	v_mfma_f32_32x32x16_bf16 v[32:47], v[222:225], v[250:253], v[32:47]
	s_waitcnt lgkmcnt(2)
	v_mfma_f32_32x32x16_bf16 v[16:31], v[214:217], v[250:253], v[16:31]
	s_waitcnt lgkmcnt(0)
	v_mfma_f32_32x32x16_bf16 v[0:15], v[238:241], v[250:253], v[0:15]
	s_branch .LBB0_858

.Latt_slow_0:
	v_lshrrev_b32_e32 v246, 8, v220
	s_nop 0
	v_readfirstlane_b32 s100, v246
	s_nop 0
	s_cmp_eq_u32 s100, 0
	s_cbranch_scc1 .Latt_slow2_0
	s_cmp_eq_u32 s43, 0
	s_cbranch_scc1 .Latt_slow2_0
	s_add_i32 s99, s88, 2
	s_sub_i32 s101, s99, 3
	s_cmp_lt_u32 s99, 3
	s_cselect_b32 s99, s99, s101
	s_lshl_b32 s99, s99, 15
	s_add_i32 s99, s99, 0xc000
	v_bfe_u32 v246, v203, 2, 2
	v_bfe_u32 v247, v203, 5, 1
	v_lshl_or_b32 v247, v247, 2, v246
	v_and_b32_e32 v249, 3, v203
	v_and_b32_e32 v254, 16, v203
	v_lshl_or_b32 v249, v249, 2, v254
	v_lshlrev_b32_e32 v249, 1, v249
	v_lshl_add_u32 v247, v247, 9, v249
	v_add_u32_e32 v247, s99, v247
	v_lshlrev_b32_e32 v246, 6, v246
	v_add_u32_e32 v205, v247, v246
	v_xor_b32_e32 v249, 64, v246
	v_add_u32_e32 v218, v247, v249
	v_xor_b32_e32 v249, 0x80, v246
	v_add_u32_e32 v219, v247, v249
	v_xor_b32_e32 v249, 0xc0, v246
	v_add_u32_e32 v221, v247, v249
	ds_read_b64_tr_b16 v[206:207], v205 offset:16384
	ds_read_b64_tr_b16 v[208:209], v205 offset:20480
	ds_read_b64_tr_b16 v[210:211], v218 offset:16384
	ds_read_b64_tr_b16 v[212:213], v218 offset:20480
	ds_read_b64_tr_b16 v[214:215], v219 offset:16384
	ds_read_b64_tr_b16 v[216:217], v219 offset:20480
	ds_read_b64_tr_b16 v[238:239], v221 offset:16384
	ds_read_b64_tr_b16 v[240:241], v221 offset:20480
	ds_read_b64_tr_b16 v[222:223], v205 offset:16640
	ds_read_b64_tr_b16 v[224:225], v205 offset:20736
	s_waitcnt lgkmcnt(8)
	v_mfma_f32_32x32x16_bf16 v[112:127], v[206:209], v[242:245], v[112:127]
	ds_read_b64_tr_b16 v[206:207], v218 offset:16640
	ds_read_b64_tr_b16 v[208:209], v218 offset:20736
	s_waitcnt lgkmcnt(8)
	v_mfma_f32_32x32x16_bf16 v[96:111], v[210:213], v[242:245], v[96:111]
	ds_read_b64_tr_b16 v[210:211], v219 offset:16640
	ds_read_b64_tr_b16 v[212:213], v219 offset:20736
	s_waitcnt lgkmcnt(8)
	v_mfma_f32_32x32x16_bf16 v[80:95], v[214:217], v[242:245], v[80:95]
	ds_read_b64_tr_b16 v[214:215], v221 offset:16640
	ds_read_b64_tr_b16 v[216:217], v221 offset:20736
	s_waitcnt lgkmcnt(8)
	v_mfma_f32_32x32x16_bf16 v[64:79], v[238:241], v[242:245], v[64:79]
	ds_read_b64_tr_b16 v[238:239], v205 offset:24576
	ds_read_b64_tr_b16 v[240:241], v205 offset:28672
	s_waitcnt lgkmcnt(8)
	v_mfma_f32_32x32x16_bf16 v[48:63], v[222:225], v[242:245], v[48:63]
	ds_read_b64_tr_b16 v[222:223], v218 offset:24576
	ds_read_b64_tr_b16 v[224:225], v218 offset:28672
	s_waitcnt lgkmcnt(8)
	v_mfma_f32_32x32x16_bf16 v[32:47], v[206:209], v[242:245], v[32:47]
	ds_read_b64_tr_b16 v[206:207], v219 offset:24576
	ds_read_b64_tr_b16 v[208:209], v219 offset:28672
	s_waitcnt lgkmcnt(8)
	v_mfma_f32_32x32x16_bf16 v[16:31], v[210:213], v[242:245], v[16:31]
	ds_read_b64_tr_b16 v[210:211], v221 offset:24576
	ds_read_b64_tr_b16 v[212:213], v221 offset:28672
	s_waitcnt lgkmcnt(8)
	v_mfma_f32_32x32x16_bf16 v[0:15], v[214:217], v[242:245], v[0:15]
	ds_read_b64_tr_b16 v[214:215], v205 offset:24832
	ds_read_b64_tr_b16 v[216:217], v205 offset:28928
	s_waitcnt lgkmcnt(8)
	v_mfma_f32_32x32x16_bf16 v[112:127], v[238:241], v[250:253], v[112:127]
	ds_read_b64_tr_b16 v[238:239], v218 offset:24832
	ds_read_b64_tr_b16 v[240:241], v218 offset:28928
	s_waitcnt lgkmcnt(8)
	v_mfma_f32_32x32x16_bf16 v[96:111], v[222:225], v[250:253], v[96:111]
	ds_read_b64_tr_b16 v[222:223], v219 offset:24832
	ds_read_b64_tr_b16 v[224:225], v219 offset:28928
	s_waitcnt lgkmcnt(8)
	v_mfma_f32_32x32x16_bf16 v[80:95], v[206:209], v[250:253], v[80:95]
	ds_read_b64_tr_b16 v[206:207], v221 offset:24832
	ds_read_b64_tr_b16 v[208:209], v221 offset:28928
	s_waitcnt lgkmcnt(8)
	v_mfma_f32_32x32x16_bf16 v[64:79], v[210:213], v[250:253], v[64:79]
	s_waitcnt lgkmcnt(6)
	v_mfma_f32_32x32x16_bf16 v[48:63], v[214:217], v[250:253], v[48:63]
	s_waitcnt lgkmcnt(4)
	v_mfma_f32_32x32x16_bf16 v[32:47], v[238:241], v[250:253], v[32:47]
	s_waitcnt lgkmcnt(2)
	v_mfma_f32_32x32x16_bf16 v[16:31], v[222:225], v[250:253], v[16:31]
	s_waitcnt lgkmcnt(0)
	v_mfma_f32_32x32x16_bf16 v[0:15], v[206:209], v[250:253], v[0:15]

.LBB0_860:
	s_andn2_b64 vcc, exec, s[34:35]
	s_cbranch_vccnz .LBB0_844
	s_waitcnt vmcnt(0)
	s_branch .LBB0_844
.LBB0_862:
	v_and_b32_e32 v129, 64, v193
	v_xor_b32_e32 v128, 32, v193
	v_add_u32_e32 v129, 64, v129
	v_cmp_lt_i32_e32 vcc, v128, v129
	s_add_i32 s4, s4, s60
	s_lshl_b64 s[14:15], s[4:5], 14
	v_cndmask_b32_e32 v128, v193, v128, vcc
	v_lshlrev_b32_e32 v194, 2, v128
	ds_bpermute_b32 v128, v194, v202
	s_add_u32 s14, s58, s14
	s_addc_u32 s15, s59, s15
	s_mov_b32 s4, 0
	s_mov_b32 s88, 2
	s_waitcnt lgkmcnt(0)
	v_add_f32_e32 v128, v202, v128
	v_rcp_f32_e32 v130, v128
	v_mov_b32_e32 v128, v176
	v_mul_f32_e32 v112, v112, v130
	v_lshlrev_b32_e32 v128, 4, v128
	v_mul_f32_e32 v113, v113, v130
	v_mul_f32_e32 v114, v114, v130
	v_mul_f32_e32 v115, v115, v130
	v_and_b32_e32 v178, 0x3f0, v128
	v_mul_f32_e32 v116, v116, v130
	v_mul_f32_e32 v117, v117, v130
	v_mul_f32_e32 v118, v118, v130
	v_mul_f32_e32 v119, v119, v130
	v_cvt_pk_bf16_f32 v112, v112, v113
	v_cvt_pk_bf16_f32 v113, v114, v115
	v_cvt_pk_bf16_f32 v114, v116, v117
	v_cvt_pk_bf16_f32 v115, v118, v119
	v_mul_f32_e32 v96, v96, v130
	v_mul_f32_e32 v97, v97, v130
	v_mul_f32_e32 v98, v98, v130
	v_mul_f32_e32 v99, v99, v130
	v_lshl_add_u64 v[128:129], s[14:15], 0, v[178:179]
	v_mul_f32_e32 v120, v120, v130
	v_mul_f32_e32 v121, v121, v130
	v_mul_f32_e32 v122, v122, v130
	v_mul_f32_e32 v123, v123, v130
	v_mul_f32_e32 v124, v124, v130
	v_mul_f32_e32 v125, v125, v130
	v_mul_f32_e32 v126, v126, v130
	v_mul_f32_e32 v127, v127, v130
	v_cvt_pk_bf16_f32 v116, v120, v121
	v_cvt_pk_bf16_f32 v117, v122, v123
	v_cvt_pk_bf16_f32 v118, v124, v125
	v_cvt_pk_bf16_f32 v119, v126, v127
	global_store_dwordx4 v178, v[112:115], s[14:15]
	global_store_dwordx4 v178, v[116:119], s[14:15] offset:1024
	v_mul_f32_e32 v100, v100, v130
	v_mul_f32_e32 v101, v101, v130
	v_mul_f32_e32 v102, v102, v130
	v_mul_f32_e32 v103, v103, v130
	v_cvt_pk_bf16_f32 v96, v96, v97
	v_cvt_pk_bf16_f32 v97, v98, v99
	v_cvt_pk_bf16_f32 v98, v100, v101
	v_cvt_pk_bf16_f32 v99, v102, v103
	v_mul_f32_e32 v80, v80, v130
	v_mul_f32_e32 v81, v81, v130
	v_mul_f32_e32 v82, v82, v130
	v_mul_f32_e32 v83, v83, v130
	v_mul_f32_e32 v84, v84, v130
	v_mul_f32_e32 v88, v88, v130
	v_mul_f32_e32 v104, v104, v130
	v_mul_f32_e32 v105, v105, v130
	v_mul_f32_e32 v106, v106, v130
	v_mul_f32_e32 v107, v107, v130
	v_mul_f32_e32 v108, v108, v130
	v_mul_f32_e32 v109, v109, v130
	v_mul_f32_e32 v110, v110, v130
	v_mul_f32_e32 v111, v111, v130
	v_cvt_pk_bf16_f32 v100, v104, v105
	v_cvt_pk_bf16_f32 v101, v106, v107
	v_cvt_pk_bf16_f32 v102, v108, v109
	v_cvt_pk_bf16_f32 v103, v110, v111
	global_store_dwordx4 v178, v[96:99], s[14:15] offset:2048
	global_store_dwordx4 v178, v[100:103], s[14:15] offset:3072
	v_mul_f32_e32 v85, v85, v130
	v_mul_f32_e32 v86, v86, v130
	v_mul_f32_e32 v87, v87, v130
	v_mul_f32_e32 v89, v89, v130
	v_cvt_pk_bf16_f32 v80, v80, v81
	v_cvt_pk_bf16_f32 v81, v82, v83
	v_cvt_pk_bf16_f32 v82, v84, v85
	v_cvt_pk_bf16_f32 v83, v86, v87
	v_cvt_pk_bf16_f32 v84, v88, v89
	v_add_co_u32_e32 v88, vcc, s73, v128
	v_mul_f32_e32 v90, v90, v130
	s_nop 0
	v_addc_co_u32_e32 v89, vcc, 0, v129, vcc
	v_mul_f32_e32 v91, v91, v130
	v_cvt_pk_bf16_f32 v85, v90, v91
	v_add_co_u32_e32 v90, vcc, s74, v128
	v_mul_f32_e32 v64, v64, v130
	s_nop 0
	v_addc_co_u32_e32 v91, vcc, 0, v129, vcc
	v_mul_f32_e32 v65, v65, v130
	v_mul_f32_e32 v66, v66, v130
	v_mul_f32_e32 v67, v67, v130
	v_mul_f32_e32 v92, v92, v130
	v_mul_f32_e32 v93, v93, v130
	v_mul_f32_e32 v94, v94, v130
	v_mul_f32_e32 v95, v95, v130
	v_cvt_pk_bf16_f32 v86, v92, v93
	v_cvt_pk_bf16_f32 v87, v94, v95
	global_store_dwordx4 v[90:91], v[80:83], off offset:-4096
	global_store_dwordx4 v[88:89], v[84:87], off offset:1024
	v_mul_f32_e32 v68, v68, v130
	v_mul_f32_e32 v69, v69, v130
	v_mul_f32_e32 v70, v70, v130
	v_mul_f32_e32 v71, v71, v130
	v_cvt_pk_bf16_f32 v64, v64, v65
	v_cvt_pk_bf16_f32 v65, v66, v67
	v_cvt_pk_bf16_f32 v66, v68, v69
	v_cvt_pk_bf16_f32 v67, v70, v71
	v_mul_f32_e32 v48, v48, v130
	v_mul_f32_e32 v49, v49, v130
	v_mul_f32_e32 v50, v50, v130
	v_mul_f32_e32 v51, v51, v130
	v_mul_f32_e32 v72, v72, v130
	v_mul_f32_e32 v73, v73, v130
	v_mul_f32_e32 v74, v74, v130
	v_mul_f32_e32 v75, v75, v130
	v_mul_f32_e32 v76, v76, v130
	v_mul_f32_e32 v77, v77, v130
	v_mul_f32_e32 v78, v78, v130
	v_mul_f32_e32 v79, v79, v130
	v_cvt_pk_bf16_f32 v68, v72, v73
	v_cvt_pk_bf16_f32 v69, v74, v75
	v_cvt_pk_bf16_f32 v70, v76, v77
	v_cvt_pk_bf16_f32 v71, v78, v79
	global_store_dwordx4 v[88:89], v[64:67], off offset:2048
	global_store_dwordx4 v[88:89], v[68:71], off offset:3072
	v_mul_f32_e32 v52, v52, v130
	v_mul_f32_e32 v53, v53, v130
	v_mul_f32_e32 v54, v54, v130
	v_mul_f32_e32 v55, v55, v130
	v_cvt_pk_bf16_f32 v48, v48, v49
	v_cvt_pk_bf16_f32 v49, v50, v51
	v_cvt_pk_bf16_f32 v50, v52, v53
	v_cvt_pk_bf16_f32 v51, v54, v55
	v_mul_f32_e32 v32, v32, v130
	v_mul_f32_e32 v33, v33, v130
	v_mul_f32_e32 v34, v34, v130
	v_mul_f32_e32 v35, v35, v130
	v_mul_f32_e32 v56, v56, v130
	v_mul_f32_e32 v57, v57, v130
	v_mul_f32_e32 v58, v58, v130
	v_mul_f32_e32 v59, v59, v130
	v_mul_f32_e32 v60, v60, v130
	v_mul_f32_e32 v61, v61, v130
	v_mul_f32_e32 v62, v62, v130
	v_mul_f32_e32 v63, v63, v130
	v_cvt_pk_bf16_f32 v52, v56, v57
	v_cvt_pk_bf16_f32 v53, v58, v59
	v_cvt_pk_bf16_f32 v54, v60, v61
	v_cvt_pk_bf16_f32 v55, v62, v63
	global_store_dwordx4 v[90:91], v[48:51], off
	global_store_dwordx4 v[90:91], v[52:55], off offset:1024
	v_mul_f32_e32 v36, v36, v130
	v_mul_f32_e32 v37, v37, v130
	v_mul_f32_e32 v38, v38, v130
	v_mul_f32_e32 v39, v39, v130
	v_cvt_pk_bf16_f32 v32, v32, v33
	v_cvt_pk_bf16_f32 v33, v34, v35
	v_cvt_pk_bf16_f32 v34, v36, v37
	v_cvt_pk_bf16_f32 v35, v38, v39
	v_mul_f32_e32 v16, v16, v130
	v_mul_f32_e32 v17, v17, v130
	v_mul_f32_e32 v18, v18, v130
	v_mul_f32_e32 v19, v19, v130
	v_mul_f32_e32 v20, v20, v130
	v_mul_f32_e32 v24, v24, v130
	v_mul_f32_e32 v40, v40, v130
	v_mul_f32_e32 v41, v41, v130
	v_mul_f32_e32 v42, v42, v130
	v_mul_f32_e32 v43, v43, v130
	v_mul_f32_e32 v44, v44, v130
	v_mul_f32_e32 v45, v45, v130
	v_mul_f32_e32 v46, v46, v130
	v_mul_f32_e32 v47, v47, v130
	v_cvt_pk_bf16_f32 v36, v40, v41
	v_cvt_pk_bf16_f32 v37, v42, v43
	v_cvt_pk_bf16_f32 v38, v44, v45
	v_cvt_pk_bf16_f32 v39, v46, v47
	global_store_dwordx4 v[90:91], v[32:35], off offset:2048
	global_store_dwordx4 v[90:91], v[36:39], off offset:3072
	v_mul_f32_e32 v21, v21, v130
	v_mul_f32_e32 v22, v22, v130
	v_mul_f32_e32 v23, v23, v130
	v_mul_f32_e32 v25, v25, v130
	v_cvt_pk_bf16_f32 v16, v16, v17
	v_cvt_pk_bf16_f32 v17, v18, v19
	v_cvt_pk_bf16_f32 v18, v20, v21
	v_cvt_pk_bf16_f32 v19, v22, v23
	v_cvt_pk_bf16_f32 v20, v24, v25
	v_add_co_u32_e32 v24, vcc, s75, v128
	v_mul_f32_e32 v0, v0, v130
	s_nop 0
	v_addc_co_u32_e32 v25, vcc, 0, v129, vcc
	v_mul_f32_e32 v1, v1, v130
	v_mul_f32_e32 v2, v2, v130
	v_mul_f32_e32 v3, v3, v130
	v_mul_f32_e32 v26, v26, v130
	v_mul_f32_e32 v27, v27, v130
	v_mul_f32_e32 v28, v28, v130
	v_mul_f32_e32 v29, v29, v130
	v_mul_f32_e32 v30, v30, v130
	v_mul_f32_e32 v31, v31, v130
	v_cvt_pk_bf16_f32 v21, v26, v27
	v_cvt_pk_bf16_f32 v22, v28, v29
	v_cvt_pk_bf16_f32 v23, v30, v31
	global_store_dwordx4 v[24:25], v[16:19], off
	global_store_dwordx4 v[24:25], v[20:23], off offset:1024
	v_mul_f32_e32 v4, v4, v130
	v_mul_f32_e32 v5, v5, v130
	v_mul_f32_e32 v6, v6, v130
	v_mul_f32_e32 v7, v7, v130
	v_mul_f32_e32 v8, v8, v130
	v_mul_f32_e32 v9, v9, v130
	v_mul_f32_e32 v10, v10, v130
	v_mul_f32_e32 v11, v11, v130
	v_mul_f32_e32 v12, v12, v130
	v_mul_f32_e32 v13, v13, v130
	v_mul_f32_e32 v14, v14, v130
	v_mul_f32_e32 v15, v15, v130
	v_cvt_pk_bf16_f32 v0, v0, v1
	v_cvt_pk_bf16_f32 v1, v2, v3
	v_cvt_pk_bf16_f32 v2, v4, v5
	v_cvt_pk_bf16_f32 v3, v6, v7
	v_cvt_pk_bf16_f32 v4, v8, v9
	v_cvt_pk_bf16_f32 v5, v10, v11
	v_cvt_pk_bf16_f32 v6, v12, v13
	v_cvt_pk_bf16_f32 v7, v14, v15
	global_store_dwordx4 v[24:25], v[0:3], off offset:2048
	global_store_dwordx4 v[24:25], v[4:7], off offset:3072
	s_nop 1
	v_mov_b32_e32 v4, v176
	s_add_u32 s42, s38, 0x100
	v_bfe_u32 v0, v4, 4, 2
	v_or_b32_e32 v1, s55, v0
	v_bitop3_b32 v0, v0, v4, s55 bitop3:0x36
	v_lshlrev_b32_e32 v2, 14, v1
	v_lshlrev_b32_e32 v0, 4, v0
	v_and_or_b32 v178, v0, s67, v2
	v_or_b32_e32 v0, 4, v1
	v_bitop3_b32 v1, v1, v4, 4 bitop3:0x36
	v_lshlrev_b32_e32 v0, 14, v0
	v_lshlrev_b32_e32 v1, 4, v1
	v_and_or_b32 v180, v1, s67, v0
	v_bfe_u32 v0, v4, 5, 1
	v_or_b32_e32 v1, s55, v0
	v_and_b32_e32 v2, 31, v4
	v_lshlrev_b32_e32 v3, 14, v1
	v_lshlrev_b32_e32 v0, 6, v0
	v_lshlrev_b32_e32 v5, 4, v2
	v_bitop3_b32 v182, v0, v3, v5 bitop3:0xde
	v_or_b32_e32 v0, 2, v1
	v_lshlrev_b32_e32 v3, 2, v0
	v_bitop3_b32 v3, v3, v2, 12 bitop3:0x6c
	v_lshlrev_b32_e32 v0, 14, v0
	s_addc_u32 s43, s39, 0
	v_lshl_or_b32 v184, v3, 4, v0
	v_or_b32_e32 v0, 6, v1
	v_lshlrev_b32_e32 v1, 2, v0
	s_cmp_lg_u32 0, -1
	v_bitop3_b32 v1, v1, v2, 12 bitop3:0x6c
	v_lshlrev_b32_e32 v0, 14, v0
	s_cselect_b32 s18, 0, 0
	v_lshl_or_b32 v188, v1, 4, v0
	v_lshl_add_u64 v[0:1], s[42:43], 0, v[178:179]
	s_add_i32 s19, s54, s18
	s_mov_b32 s34, m0
	s_mov_b32 m0, s19
	s_nop 0
	global_load_lds_dwordx4 v[0:1], off
	s_mov_b32 m0, s34
	v_mov_b32_e32 v181, v179
	s_add_i32 s18, s18, s33
	v_lshl_add_u64 v[0:1], s[42:43], 0, v[180:181]
	s_add_i32 s34, s19, 0x400
	s_mov_b32 s35, m0
	s_mov_b32 m0, s34
	s_nop 0
	global_load_lds_dwordx4 v[0:1], off
	s_mov_b32 m0, s35
	v_mov_b32_e32 v183, v179
	s_add_i32 s33, s18, 0xc000
	v_lshl_add_u64 v[0:1], s[16:17], 0, v[182:183]
	s_mov_b32 s34, m0
	s_mov_b32 m0, s33
	s_nop 0
	global_load_lds_dwordx4 v[0:1], off
	s_mov_b32 m0, s34
	v_mov_b32_e32 v185, v179
	s_add_i32 s33, s18, 0xc400
	v_or_b32_e32 v186, 0x10000, v182
	v_lshl_add_u64 v[0:1], s[16:17], 0, v[184:185]
	s_mov_b32 s34, m0
	s_mov_b32 m0, s33
	s_nop 0
	global_load_lds_dwordx4 v[0:1], off
	s_mov_b32 m0, s34
	v_mov_b32_e32 v187, v179
	s_add_i32 s33, s18, 0xc800
	v_lshl_add_u64 v[0:1], s[16:17], 0, v[186:187]
	s_mov_b32 s34, m0
	s_mov_b32 m0, s33
	s_nop 0
	global_load_lds_dwordx4 v[0:1], off
	s_mov_b32 m0, s34
	s_add_i32 s33, s18, 0xcc00
	v_mov_b32_e32 v189, v179
	s_add_u32 s54, s38, 0x100100
	v_lshl_add_u64 v[0:1], s[16:17], 0, v[188:189]
	s_addc_u32 s55, s39, 0
	s_mov_b32 s34, m0
	s_mov_b32 m0, s33
	s_nop 0
	global_load_lds_dwordx4 v[0:1], off
	s_mov_b32 m0, s34
	v_lshl_add_u64 v[0:1], s[54:55], 0, v[178:179]
	s_add_i32 s33, s19, 0x4000
	s_mov_b32 s34, m0
	s_mov_b32 m0, s33
	s_nop 0
	global_load_lds_dwordx4 v[0:1], off
	s_mov_b32 m0, s34
	v_lshl_add_u64 v[0:1], s[54:55], 0, v[180:181]
	s_addk_i32 s19, 0x4400
	s_mov_b32 s33, m0
	s_mov_b32 m0, s19
	s_nop 0
	global_load_lds_dwordx4 v[0:1], off
	s_mov_b32 m0, s33
	v_lshl_add_u64 v[0:1], s[10:11], 0, v[182:183]
	s_add_i32 s19, s18, 0x14000
	s_mov_b32 s33, m0
	s_mov_b32 m0, s19
	s_nop 0
	global_load_lds_dwordx4 v[0:1], off
	s_mov_b32 m0, s33
	v_lshl_add_u64 v[0:1], s[10:11], 0, v[184:185]
	s_add_i32 s19, s18, 0x14400
	s_mov_b32 s33, m0
	s_mov_b32 m0, s19
	s_nop 0
	global_load_lds_dwordx4 v[0:1], off
	s_mov_b32 m0, s33
	v_lshl_add_u64 v[0:1], s[10:11], 0, v[186:187]
	s_add_i32 s19, s18, 0x14800
	s_mov_b32 s33, m0
	s_mov_b32 m0, s19
	s_nop 0
	global_load_lds_dwordx4 v[0:1], off
	s_mov_b32 m0, s33
	v_lshl_add_u64 v[0:1], s[10:11], 0, v[188:189]
	s_add_i32 s18, s18, 0x14c00
	s_mov_b32 s19, m0
	s_mov_b32 m0, s18
	s_nop 0
	global_load_lds_dwordx4 v[0:1], off
	s_mov_b32 m0, s19
	v_or_b32_e32 v0, s80, v2
	v_mov_b32_e32 v1, s81
	v_lshlrev_b64 v[0:1], 14, v[0:1]
	v_lshrrev_b32_e32 v2, 1, v4
	v_lshl_add_u64 v[0:1], s[8:9], 0, v[0:1]
	v_and_b32_e32 v2, 16, v2
	v_mov_b32_e32 v3, v179
	v_lshl_add_u64 v[0:1], v[0:1], 0, v[2:3]
	global_load_dwordx4 v[144:147], v[0:1], off offset:256
	global_load_dwordx4 v[148:151], v[0:1], off offset:288
	global_load_dwordx4 v[152:155], v[0:1], off offset:320
	global_load_dwordx4 v[156:159], v[0:1], off offset:352
	global_load_dwordx4 v[160:163], v[0:1], off offset:384
	global_load_dwordx4 v[164:167], v[0:1], off offset:416
	global_load_dwordx4 v[168:171], v[0:1], off offset:448
	global_load_dwordx4 v[172:175], v[0:1], off offset:480
	v_lshrrev_b32_e32 v0, 5, v4
	v_and_b32_e32 v1, 15, v4
	v_bitop3_b32 v0, v0, v1, 1 bitop3:0x6c
	v_lshlrev_b32_e32 v1, 8, v4
	v_lshlrev_b32_e32 v0, 4, v0
	v_and_b32_e32 v1, 0x1f00, v1
	s_add_u32 s34, s65, s12
	v_mov_b32_e32 v14, v179
	v_mov_b32_e32 v15, v179
	v_or_b32_e32 v196, v0, v1
	v_bitop3_b32 v197, v0, 32, v1 bitop3:0x36
	v_bitop3_b32 v198, v0, 64, v1 bitop3:0x36
	v_bitop3_b32 v199, v0, s68, v1 bitop3:0x36
	v_bitop3_b32 v200, v0, s69, v1 bitop3:0x36
	v_bitop3_b32 v201, v0, s70, v1 bitop3:0x36
	v_bitop3_b32 v202, v0, s71, v1 bitop3:0x36
	v_bitop3_b32 v203, v0, s72, v1 bitop3:0x36
	s_waitcnt vmcnt(7)
	s_waitcnt vmcnt(6)
	s_waitcnt vmcnt(5)
	s_waitcnt vmcnt(4)
	s_waitcnt vmcnt(3)
	s_waitcnt vmcnt(2)
	s_waitcnt vmcnt(1)
	s_waitcnt vmcnt(0)
	s_waitcnt vmcnt(0)
	s_addc_u32 s35, s66, s13
	v_mov_b32_e32 v0, v179
	v_mov_b32_e32 v1, v179
	v_mov_b32_e32 v2, v179
	v_mov_b32_e32 v4, v179
	v_mov_b32_e32 v5, v179
	v_mov_b32_e32 v6, v179
	v_mov_b32_e32 v7, v179
	v_mov_b32_e32 v8, v179
	v_mov_b32_e32 v9, v179
	v_mov_b32_e32 v10, v179
	v_mov_b32_e32 v11, v179
	v_mov_b32_e32 v12, v179
	v_mov_b32_e32 v13, v179
	v_mov_b64_e32 v[30:31], v[14:15]
	v_mov_b64_e32 v[46:47], v[14:15]
	v_mov_b64_e32 v[62:63], v[14:15]
	v_mov_b64_e32 v[78:79], v[14:15]
	v_mov_b64_e32 v[94:95], v[14:15]
	v_mov_b64_e32 v[110:111], v[14:15]
	v_mov_b64_e32 v[126:127], v[14:15]
	v_mov_b32_e32 v190, 0xf149f2ca
	v_mov_b32_e32 v195, 0
	s_mov_b64 s[12:13], s[34:35]
	v_mov_b64_e32 v[28:29], v[12:13]
	v_mov_b64_e32 v[26:27], v[10:11]
	v_mov_b64_e32 v[24:25], v[8:9]
	v_mov_b64_e32 v[22:23], v[6:7]
	v_mov_b64_e32 v[20:21], v[4:5]
	v_mov_b64_e32 v[18:19], v[2:3]
	v_mov_b64_e32 v[16:17], v[0:1]
	v_mov_b64_e32 v[44:45], v[12:13]
	v_mov_b64_e32 v[42:43], v[10:11]
	v_mov_b64_e32 v[40:41], v[8:9]
	v_mov_b64_e32 v[38:39], v[6:7]
	v_mov_b64_e32 v[36:37], v[4:5]
	v_mov_b64_e32 v[34:35], v[2:3]
	v_mov_b64_e32 v[32:33], v[0:1]
	v_mov_b64_e32 v[60:61], v[12:13]
	v_mov_b64_e32 v[58:59], v[10:11]
	v_mov_b64_e32 v[56:57], v[8:9]
	v_mov_b64_e32 v[54:55], v[6:7]
	v_mov_b64_e32 v[52:53], v[4:5]
	v_mov_b64_e32 v[50:51], v[2:3]
	v_mov_b64_e32 v[48:49], v[0:1]
	v_mov_b64_e32 v[76:77], v[12:13]
	v_mov_b64_e32 v[74:75], v[10:11]
	v_mov_b64_e32 v[72:73], v[8:9]
	v_mov_b64_e32 v[70:71], v[6:7]
	v_mov_b64_e32 v[68:69], v[4:5]
	v_mov_b64_e32 v[66:67], v[2:3]
	v_mov_b64_e32 v[64:65], v[0:1]
	v_mov_b64_e32 v[92:93], v[12:13]
	v_mov_b64_e32 v[90:91], v[10:11]
	v_mov_b64_e32 v[88:89], v[8:9]
	v_mov_b64_e32 v[86:87], v[6:7]
	v_mov_b64_e32 v[84:85], v[4:5]
	v_mov_b64_e32 v[82:83], v[2:3]
	v_mov_b64_e32 v[80:81], v[0:1]
	v_mov_b64_e32 v[108:109], v[12:13]
	v_mov_b64_e32 v[106:107], v[10:11]
	v_mov_b64_e32 v[104:105], v[8:9]
	v_mov_b64_e32 v[102:103], v[6:7]
	v_mov_b64_e32 v[100:101], v[4:5]
	v_mov_b64_e32 v[98:99], v[2:3]
	v_mov_b64_e32 v[96:97], v[0:1]
	v_mov_b64_e32 v[124:125], v[12:13]
	v_mov_b64_e32 v[122:123], v[10:11]
	v_mov_b64_e32 v[120:121], v[8:9]
	v_mov_b64_e32 v[118:119], v[6:7]
	v_mov_b64_e32 v[116:117], v[4:5]
	v_mov_b64_e32 v[114:115], v[2:3]
	v_mov_b64_e32 v[112:113], v[0:1]
	s_mov_b32 s33, 0
	s_sub_u32 s12, s12, 0x100000
	s_subb_u32 s13, s13, 0
	s_sub_i32 s88, s88, 1
	s_barrier
	s_branch .LBB0_864

.LBB0_864:
	s_cmp_ge_u32 s88, s82
	s_cselect_b64 s[18:19], -1, 0
	v_mov_b32_e32 v204, v176
	s_and_b64 vcc, exec, s[18:19]
	s_cbranch_vccnz .LBB0_866
	s_add_i32 s100, s4, 63
	s_cmp_le_i32 s100, s83
	s_cbranch_scc1 .LBB0_866
	s_add_i32 s90, s33, 1
	s_cmp_eq_u32 s90, 3
	s_cselect_b32 s90, 0, s90
	v_mov_b32_e32 v130, s90
	v_lshlrev_b32_e32 v128, 14, v130
	v_add_u32_e32 v131, s85, v128
	v_lshl_add_u64 v[128:129], s[12:13], 0, v[178:179]
	s_add_u32 s90, s12, 0xf00
	v_readfirstlane_b32 s89, v131
	s_mov_b32 s92, m0
	s_mov_b32 m0, s89
	s_nop 0
	global_load_lds_dwordx4 v[128:129], off
	s_mov_b32 m0, s92
	v_lshl_add_u64 v[128:129], s[12:13], 0, v[180:181]
	s_addc_u32 s91, s13, 0
	s_addk_i32 s89, 0x400
	s_mov_b32 s92, m0
	s_mov_b32 m0, s89
	s_nop 0
	global_load_lds_dwordx4 v[128:129], off
	s_mov_b32 m0, s92
	v_lshlrev_b32_e32 v128, 15, v130
	v_add_u32_e32 v130, s86, v128
	v_lshl_add_u64 v[128:129], s[90:91], 0, v[182:183]
	v_readfirstlane_b32 s89, v130
	s_mov_b32 s92, m0
	s_mov_b32 m0, s89
	s_nop 0
	global_load_lds_dwordx4 v[128:129], off
	s_mov_b32 m0, s92
	v_lshl_add_u64 v[128:129], s[90:91], 0, v[184:185]
	s_add_i32 s92, s89, 0x400
	s_mov_b32 s93, m0
	s_mov_b32 m0, s92
	s_nop 0
	global_load_lds_dwordx4 v[128:129], off
	s_mov_b32 m0, s93
	v_lshl_add_u64 v[128:129], s[90:91], 0, v[186:187]
	s_add_i32 s92, s89, 0x800
	s_mov_b32 s93, m0
	s_mov_b32 m0, s92
	s_nop 0
	global_load_lds_dwordx4 v[128:129], off
	s_mov_b32 m0, s93
	v_lshl_add_u64 v[128:129], s[90:91], 0, v[188:189]
	s_addk_i32 s89, 0xc00
	s_mov_b32 s90, m0
	s_mov_b32 m0, s89
	s_nop 0
	global_load_lds_dwordx4 v[128:129], off
	s_mov_b32 m0, s90
.LBB0_866:
	s_cmp_gt_i32 s4, s84
	s_cbranch_scc1 .LBB0_877
	s_add_i32 s100, s4, 63
	s_cmp_le_i32 s100, s83
	s_cbranch_scc0 .Latt_slow_1
	v_lshrrev_b32_e32 v246, 8, v220
	s_nop 0
	v_readfirstlane_b32 s100, v246
	s_nop 0
	s_cmp_eq_u32 s100, 0
	s_cbranch_scc1 .Latt_A_1
	s_cmp_eq_u32 s4, 0
	s_cbranch_scc1 .Latt_B0_1
	s_add_i32 s99, s33, 2
	s_sub_i32 s101, s99, 3
	s_cmp_lt_u32 s99, 3
	s_cselect_b32 s99, s99, s101
	s_lshl_b32 s99, s99, 15
	s_add_i32 s99, s99, 0xc000
	v_bfe_u32 v246, v204, 2, 2
	v_bfe_u32 v247, v204, 5, 1
	v_lshl_or_b32 v247, v247, 2, v246
	v_and_b32_e32 v249, 3, v204
	v_and_b32_e32 v254, 16, v204
	v_lshl_or_b32 v249, v249, 2, v254
	v_lshlrev_b32_e32 v249, 1, v249
	v_lshl_add_u32 v247, v247, 9, v249
	v_add_u32_e32 v247, s99, v247
	v_lshlrev_b32_e32 v246, 6, v246
	v_add_u32_e32 v205, v247, v246
	v_xor_b32_e32 v249, 64, v246
	v_add_u32_e32 v218, v247, v249
	v_xor_b32_e32 v249, 0x80, v246
	v_add_u32_e32 v219, v247, v249
	v_xor_b32_e32 v249, 0xc0, v246
	v_add_u32_e32 v221, v247, v249
	s_lshl_b32 s98, s33, 14
	s_lshl_b32 s99, s33, 15
	s_add_i32 s99, s99, 0xc000
	ds_read_b64_tr_b16 v[206:207], v205 offset:16384
	ds_read_b64_tr_b16 v[208:209], v205 offset:20480
	ds_read_b64_tr_b16 v[210:211], v218 offset:16384
	ds_read_b64_tr_b16 v[212:213], v218 offset:20480
	ds_read_b64_tr_b16 v[214:215], v219 offset:16384
	ds_read_b64_tr_b16 v[216:217], v219 offset:20480
	ds_read_b64_tr_b16 v[238:239], v221 offset:16384
	ds_read_b64_tr_b16 v[240:241], v221 offset:20480
	ds_read_b64_tr_b16 v[222:223], v205 offset:16640
	ds_read_b64_tr_b16 v[224:225], v205 offset:20736
	s_waitcnt lgkmcnt(8)
	v_mfma_f32_32x32x16_bf16 v[112:127], v[206:209], v[242:245], v[112:127]
	ds_read_b64_tr_b16 v[206:207], v218 offset:16640
	ds_read_b64_tr_b16 v[208:209], v218 offset:20736
	s_cmp_lg_u64 s[18:19], 0
	s_cbranch_scc1 .Latt_nd0_1B1
	s_add_i32 s100, s33, 1
	s_cmp_eq_u32 s33, 2
	s_cselect_b32 s100, 0, s100
	s_lshl_b32 s101, s100, 14
	s_add_i32 m0, s85, s101
	s_nop 0
	global_load_lds_dwordx4 v178, s[12:13]
.Latt_nd0_1B1:
	s_waitcnt lgkmcnt(8)
	v_mfma_f32_32x32x16_bf16 v[96:111], v[210:213], v[242:245], v[96:111]
	ds_read_b64_tr_b16 v[210:211], v219 offset:16640
	ds_read_b64_tr_b16 v[212:213], v219 offset:20736
	s_cmp_lg_u64 s[18:19], 0
	s_cbranch_scc1 .Latt_nd1_1B1
	s_add_i32 m0, m0, 0x400
	s_nop 0
	global_load_lds_dwordx4 v180, s[12:13]
.Latt_nd1_1B1:
	s_waitcnt lgkmcnt(8)
	v_mfma_f32_32x32x16_bf16 v[80:95], v[214:217], v[242:245], v[80:95]
	ds_read_b64_tr_b16 v[214:215], v221 offset:16640
	ds_read_b64_tr_b16 v[216:217], v221 offset:20736
	s_cmp_lg_u64 s[18:19], 0
	s_cbranch_scc1 .Latt_nd2_1B1
	s_lshl_b32 s101, s100, 15
	s_add_i32 m0, s86, s101
	s_add_u32 s100, s12, 0xf00
	s_addc_u32 s101, s13, 0
	global_load_lds_dwordx4 v182, s[100:101]

.Latt_nd5_1B1:
	s_waitcnt lgkmcnt(8)
	v_mfma_f32_32x32x16_bf16 v[16:31], v[210:213], v[242:245], v[16:31]
	ds_read_b64_tr_b16 v[210:211], v221 offset:24576
	ds_read_b64_tr_b16 v[212:213], v221 offset:28672
	s_waitcnt lgkmcnt(8)
	v_mfma_f32_32x32x16_bf16 v[0:15], v[214:217], v[242:245], v[0:15]
	ds_read_b64_tr_b16 v[214:215], v205 offset:24832
	ds_read_b64_tr_b16 v[216:217], v205 offset:28928
	s_waitcnt lgkmcnt(8)
	v_mfma_f32_32x32x16_bf16 v[112:127], v[238:241], v[250:253], v[112:127]
	ds_read_b64_tr_b16 v[238:239], v218 offset:24832
	ds_read_b64_tr_b16 v[240:241], v218 offset:28928
	s_waitcnt lgkmcnt(8)
	v_mfma_f32_32x32x16_bf16 v[96:111], v[222:225], v[250:253], v[96:111]
	ds_read_b64_tr_b16 v[222:223], v219 offset:24832
	ds_read_b64_tr_b16 v[224:225], v219 offset:28928
	s_waitcnt lgkmcnt(8)
	v_mfma_f32_32x32x16_bf16 v[80:95], v[206:209], v[250:253], v[80:95]
	ds_read_b64_tr_b16 v[206:207], v221 offset:24832
	ds_read_b64_tr_b16 v[208:209], v221 offset:28928
	v_bfe_u32 v246, v204, 2, 2
	v_bfe_u32 v247, v204, 5, 1
	v_lshl_or_b32 v247, v247, 2, v246
	v_and_b32_e32 v249, 3, v204
	v_and_b32_e32 v254, 16, v204
	v_lshl_or_b32 v249, v249, 2, v254
	v_lshlrev_b32_e32 v249, 1, v249
	v_lshl_add_u32 v247, v247, 9, v249
	v_add_u32_e32 v247, s99, v247
	v_lshlrev_b32_e32 v246, 6, v246
	v_add_u32_e32 v205, v247, v246
	v_xor_b32_e32 v249, 64, v246
	v_add_u32_e32 v218, v247, v249
	v_xor_b32_e32 v249, 0x80, v246
	v_add_u32_e32 v219, v247, v249
	v_xor_b32_e32 v249, 0xc0, v246
	v_add_u32_e32 v221, v247, v249
	s_waitcnt lgkmcnt(8)
	v_mfma_f32_32x32x16_bf16 v[64:79], v[210:213], v[250:253], v[64:79]
	v_add_u32_e32 v210, s98, v196
	ds_read_b128 v[210:213], v210
	v_add_u32_e32 v226, s98, v197
	ds_read_b128 v[226:229], v226
	s_waitcnt lgkmcnt(8)
	v_mfma_f32_32x32x16_bf16 v[48:63], v[214:217], v[250:253], v[48:63]
	v_add_u32_e32 v214, s98, v198
	ds_read_b128 v[214:217], v214
	v_add_u32_e32 v230, s98, v199
	ds_read_b128 v[230:233], v230
	s_waitcnt lgkmcnt(8)
	v_mfma_f32_32x32x16_bf16 v[32:47], v[238:241], v[250:253], v[32:47]
	v_add_u32_e32 v238, s98, v200
	ds_read_b128 v[238:241], v238
	v_add_u32_e32 v234, s98, v201
	ds_read_b128 v[234:237], v234
	s_waitcnt lgkmcnt(8)
	v_mfma_f32_32x32x16_bf16 v[16:31], v[222:225], v[250:253], v[16:31]
	v_add_u32_e32 v222, s98, v202
	ds_read_b128 v[222:225], v222
	s_waitcnt lgkmcnt(7)
	v_mfma_f32_32x32x16_bf16 v[0:15], v[206:209], v[250:253], v[0:15]
	v_add_u32_e32 v206, s98, v203
	ds_read_b128 v[206:209], v206
	v_add_u32_e32 v242, s98, v196
	ds_read_b128 v[242:245], v242 offset:8192
	s_waitcnt lgkmcnt(8)
	v_mfma_f32_32x32x16_bf16 v[128:143], v[210:213], v[144:147], 0
	v_add_u32_e32 v210, s98, v197
	ds_read_b128 v[210:213], v210 offset:8192
	v_add_u32_e32 v250, s98, v198
	ds_read_b128 v[250:253], v250 offset:8192
	s_waitcnt lgkmcnt(9)
	v_mfma_f32_32x32x16_bf16 v[128:143], v[226:229], v[148:151], v[128:143]
	s_waitcnt lgkmcnt(8)
	v_mfma_f32_32x32x16_bf16 v[128:143], v[214:217], v[152:155], v[128:143]
	v_add_u32_e32 v214, s98, v199
	ds_read_b128 v[214:217], v214 offset:8192
	s_waitcnt lgkmcnt(8)
	v_mfma_f32_32x32x16_bf16 v[128:143], v[230:233], v[156:159], v[128:143]
	s_waitcnt lgkmcnt(7)
	v_mfma_f32_32x32x16_bf16 v[128:143], v[238:241], v[160:163], v[128:143]
	v_add_u32_e32 v238, s98, v200
	ds_read_b128 v[238:241], v238 offset:8192
	s_waitcnt lgkmcnt(7)
	v_mfma_f32_32x32x16_bf16 v[128:143], v[234:237], v[164:167], v[128:143]
	s_waitcnt lgkmcnt(6)
	v_mfma_f32_32x32x16_bf16 v[128:143], v[222:225], v[168:171], v[128:143]
	s_waitcnt lgkmcnt(5)
	v_mfma_f32_32x32x16_bf16 v[128:143], v[206:209], v[172:175], v[128:143]
	v_add_u32_e32 v206, s98, v201
	ds_read_b128 v[206:209], v206 offset:8192
	s_waitcnt lgkmcnt(5)
	v_mfma_f32_32x32x16_bf16 v[222:237], v[242:245], v[144:147], 0
	v_add_u32_e32 v242, s98, v202
	ds_read_b128 v[242:245], v242 offset:8192
	s_nop 5
	v_max3_f32 v246, v128, v129, v130
	v_max3_f32 v247, v131, v132, v133
	v_max3_f32 v246, v246, v134, v135
	v_max3_f32 v247, v247, v136, v137
	v_max3_f32 v246, v246, v138, v139
	v_max3_f32 v247, v247, v140, v141
	v_max3_f32 v246, v246, v142, v143
	s_waitcnt lgkmcnt(5)
	v_mfma_f32_32x32x16_bf16 v[222:237], v[210:213], v[148:151], v[222:237]
	v_add_u32_e32 v210, s98, v203
	ds_read_b128 v[210:213], v210 offset:8192
	v_max_f32_e32 v246, v246, v247
	v_mov_b32_e32 v247, v246
	v_add_f32_e32 v249, 0x41000000, v190
	s_nop 1
	v_permlane32_swap_b32_e32 v246, v247
	v_max_f32_e32 v246, v246, v247
	v_cmp_gt_f32_e32 vcc, v246, v249
	s_cbranch_vccz .Latt_nr0_1B1
	v_max_f32_e32 v246, v190, v246
	v_sub_f32_e32 v190, v190, v246
	v_exp_f32_e32 v190, v190
	s_nop 0
	v_pk_mul_f32 v[126:127], v[126:127], v[190:191] op_sel_hi:[1,0]
	v_pk_mul_f32 v[124:125], v[124:125], v[190:191] op_sel_hi:[1,0]
	v_pk_mul_f32 v[122:123], v[122:123], v[190:191] op_sel_hi:[1,0]
	v_pk_mul_f32 v[120:121], v[120:121], v[190:191] op_sel_hi:[1,0]
	v_pk_mul_f32 v[118:119], v[118:119], v[190:191] op_sel_hi:[1,0]
	v_pk_mul_f32 v[116:117], v[116:117], v[190:191] op_sel_hi:[1,0]
	v_pk_mul_f32 v[114:115], v[114:115], v[190:191] op_sel_hi:[1,0]
	v_pk_mul_f32 v[112:113], v[112:113], v[190:191] op_sel_hi:[1,0]
	v_pk_mul_f32 v[110:111], v[110:111], v[190:191] op_sel_hi:[1,0]
	v_pk_mul_f32 v[108:109], v[108:109], v[190:191] op_sel_hi:[1,0]
	v_pk_mul_f32 v[106:107], v[106:107], v[190:191] op_sel_hi:[1,0]
	v_pk_mul_f32 v[104:105], v[104:105], v[190:191] op_sel_hi:[1,0]
	v_pk_mul_f32 v[102:103], v[102:103], v[190:191] op_sel_hi:[1,0]
	v_pk_mul_f32 v[100:101], v[100:101], v[190:191] op_sel_hi:[1,0]
	v_pk_mul_f32 v[98:99], v[98:99], v[190:191] op_sel_hi:[1,0]
	v_pk_mul_f32 v[96:97], v[96:97], v[190:191] op_sel_hi:[1,0]
	v_pk_mul_f32 v[94:95], v[94:95], v[190:191] op_sel_hi:[1,0]
	v_pk_mul_f32 v[92:93], v[92:93], v[190:191] op_sel_hi:[1,0]
	v_pk_mul_f32 v[90:91], v[90:91], v[190:191] op_sel_hi:[1,0]
	v_pk_mul_f32 v[88:89], v[88:89], v[190:191] op_sel_hi:[1,0]
	v_pk_mul_f32 v[86:87], v[86:87], v[190:191] op_sel_hi:[1,0]
	v_pk_mul_f32 v[84:85], v[84:85], v[190:191] op_sel_hi:[1,0]
	v_pk_mul_f32 v[82:83], v[82:83], v[190:191] op_sel_hi:[1,0]
	v_pk_mul_f32 v[80:81], v[80:81], v[190:191] op_sel_hi:[1,0]
	v_pk_mul_f32 v[78:79], v[78:79], v[190:191] op_sel_hi:[1,0]
	v_pk_mul_f32 v[76:77], v[76:77], v[190:191] op_sel_hi:[1,0]
	v_pk_mul_f32 v[74:75], v[74:75], v[190:191] op_sel_hi:[1,0]
	v_pk_mul_f32 v[72:73], v[72:73], v[190:191] op_sel_hi:[1,0]
	v_pk_mul_f32 v[70:71], v[70:71], v[190:191] op_sel_hi:[1,0]
	v_pk_mul_f32 v[68:69], v[68:69], v[190:191] op_sel_hi:[1,0]
	v_pk_mul_f32 v[66:67], v[66:67], v[190:191] op_sel_hi:[1,0]
	v_pk_mul_f32 v[64:65], v[64:65], v[190:191] op_sel_hi:[1,0]
	v_pk_mul_f32 v[62:63], v[62:63], v[190:191] op_sel_hi:[1,0]
	v_pk_mul_f32 v[60:61], v[60:61], v[190:191] op_sel_hi:[1,0]
	v_pk_mul_f32 v[58:59], v[58:59], v[190:191] op_sel_hi:[1,0]
	v_pk_mul_f32 v[56:57], v[56:57], v[190:191] op_sel_hi:[1,0]
	v_pk_mul_f32 v[54:55], v[54:55], v[190:191] op_sel_hi:[1,0]
	v_pk_mul_f32 v[52:53], v[52:53], v[190:191] op_sel_hi:[1,0]
	v_pk_mul_f32 v[50:51], v[50:51], v[190:191] op_sel_hi:[1,0]
	v_pk_mul_f32 v[48:49], v[48:49], v[190:191] op_sel_hi:[1,0]
	v_pk_mul_f32 v[46:47], v[46:47], v[190:191] op_sel_hi:[1,0]
	v_pk_mul_f32 v[44:45], v[44:45], v[190:191] op_sel_hi:[1,0]
	v_pk_mul_f32 v[42:43], v[42:43], v[190:191] op_sel_hi:[1,0]
	v_pk_mul_f32 v[40:41], v[40:41], v[190:191] op_sel_hi:[1,0]
	v_pk_mul_f32 v[38:39], v[38:39], v[190:191] op_sel_hi:[1,0]
	v_pk_mul_f32 v[36:37], v[36:37], v[190:191] op_sel_hi:[1,0]
	v_pk_mul_f32 v[34:35], v[34:35], v[190:191] op_sel_hi:[1,0]
	v_pk_mul_f32 v[32:33], v[32:33], v[190:191] op_sel_hi:[1,0]
	v_pk_mul_f32 v[30:31], v[30:31], v[190:191] op_sel_hi:[1,0]
	v_pk_mul_f32 v[28:29], v[28:29], v[190:191] op_sel_hi:[1,0]
	v_pk_mul_f32 v[26:27], v[26:27], v[190:191] op_sel_hi:[1,0]
	v_pk_mul_f32 v[24:25], v[24:25], v[190:191] op_sel_hi:[1,0]
	v_pk_mul_f32 v[22:23], v[22:23], v[190:191] op_sel_hi:[1,0]
	v_pk_mul_f32 v[20:21], v[20:21], v[190:191] op_sel_hi:[1,0]
	v_pk_mul_f32 v[18:19], v[18:19], v[190:191] op_sel_hi:[1,0]
	v_pk_mul_f32 v[16:17], v[16:17], v[190:191] op_sel_hi:[1,0]
	v_pk_mul_f32 v[14:15], v[14:15], v[190:191] op_sel_hi:[1,0]
	v_pk_mul_f32 v[12:13], v[12:13], v[190:191] op_sel_hi:[1,0]
	v_pk_mul_f32 v[10:11], v[10:11], v[190:191] op_sel_hi:[1,0]
	v_pk_mul_f32 v[8:9], v[8:9], v[190:191] op_sel_hi:[1,0]
	v_pk_mul_f32 v[6:7], v[6:7], v[190:191] op_sel_hi:[1,0]
	v_pk_mul_f32 v[4:5], v[4:5], v[190:191] op_sel_hi:[1,0]
	v_pk_mul_f32 v[2:3], v[2:3], v[190:191] op_sel_hi:[1,0]
	v_pk_mul_f32 v[0:1], v[0:1], v[190:191] op_sel_hi:[1,0]
	v_mul_f32_e32 v195, v195, v190
	v_mov_b32_e32 v190, v246
.Latt_nr0_1B1:
	s_waitcnt lgkmcnt(5)
	v_mfma_f32_32x32x16_bf16 v[222:237], v[250:253], v[152:155], v[222:237]
	v_sub_f32_e32 v128, v128, v190
	v_exp_f32_e32 v128, v128
	v_sub_f32_e32 v129, v129, v190
	v_exp_f32_e32 v129, v129
	v_sub_f32_e32 v130, v130, v190
	v_add_f32_e32 v254, 0, v128
	v_exp_f32_e32 v130, v130
	v_sub_f32_e32 v131, v131, v190
	s_waitcnt lgkmcnt(4)
	v_mfma_f32_32x32x16_bf16 v[222:237], v[214:217], v[156:159], v[222:237]
	ds_read_b64_tr_b16 v[214:215], v205
	ds_read_b64_tr_b16 v[216:217], v205 offset:4096
	v_add_f32_e32 v254, v129, v254
	v_exp_f32_e32 v131, v131
	v_sub_f32_e32 v132, v132, v190
	v_add_f32_e32 v254, v130, v254
	v_exp_f32_e32 v132, v132
	v_sub_f32_e32 v133, v133, v190
	v_add_f32_e32 v254, v131, v254
	v_exp_f32_e32 v133, v133
	s_waitcnt lgkmcnt(5)
	v_mfma_f32_32x32x16_bf16 v[222:237], v[238:241], v[160:163], v[222:237]
	ds_read_b64_tr_b16 v[238:239], v218
	ds_read_b64_tr_b16 v[240:241], v218 offset:4096
	v_sub_f32_e32 v134, v134, v190
	v_add_f32_e32 v254, v132, v254
	v_exp_f32_e32 v134, v134
	v_sub_f32_e32 v135, v135, v190
	v_add_f32_e32 v254, v133, v254
	v_exp_f32_e32 v135, v135
	v_sub_f32_e32 v136, v136, v190
	v_add_f32_e32 v254, v134, v254
	s_waitcnt lgkmcnt(6)
	v_mfma_f32_32x32x16_bf16 v[222:237], v[206:209], v[164:167], v[222:237]
	ds_read_b64_tr_b16 v[206:207], v219
	ds_read_b64_tr_b16 v[208:209], v219 offset:4096
	v_exp_f32_e32 v136, v136
	v_sub_f32_e32 v137, v137, v190
	v_add_f32_e32 v254, v135, v254
	v_exp_f32_e32 v137, v137
	v_sub_f32_e32 v138, v138, v190
	v_add_f32_e32 v254, v136, v254
	v_exp_f32_e32 v138, v138
	v_sub_f32_e32 v139, v139, v190
	s_waitcnt lgkmcnt(7)
	v_mfma_f32_32x32x16_bf16 v[222:237], v[242:245], v[168:171], v[222:237]
	v_add_f32_e32 v254, v137, v254
	v_exp_f32_e32 v139, v139
	v_sub_f32_e32 v140, v140, v190
	v_add_f32_e32 v254, v138, v254
	v_exp_f32_e32 v140, v140
	v_sub_f32_e32 v141, v141, v190
	v_add_f32_e32 v254, v139, v254
	v_exp_f32_e32 v141, v141
	s_waitcnt lgkmcnt(6)
	v_mfma_f32_32x32x16_bf16 v[222:237], v[210:213], v[172:175], v[222:237]
	ds_read_b64_tr_b16 v[210:211], v221
	ds_read_b64_tr_b16 v[212:213], v221 offset:4096
	v_sub_f32_e32 v142, v142, v190
	v_add_f32_e32 v254, v140, v254
	v_exp_f32_e32 v142, v142
	v_sub_f32_e32 v143, v143, v190
	v_add_f32_e32 v254, v141, v254
	v_exp_f32_e32 v143, v143
	v_add_f32_e32 v254, v142, v254
	v_add_f32_e32 v254, v143, v254
	v_cvt_pk_bf16_f32 v242, v128, v129
	v_cvt_pk_bf16_f32 v243, v130, v131
	v_cvt_pk_bf16_f32 v244, v132, v133
	v_cvt_pk_bf16_f32 v245, v134, v135
	v_cvt_pk_bf16_f32 v250, v136, v137
	v_cvt_pk_bf16_f32 v251, v138, v139
	v_cvt_pk_bf16_f32 v252, v140, v141
	v_cvt_pk_bf16_f32 v253, v142, v143
	v_add_f32_e32 v195, v195, v254
	s_nop 1
	ds_read_b64_tr_b16 v[128:129], v205 offset:256
	ds_read_b64_tr_b16 v[130:131], v205 offset:4352
	s_waitcnt lgkmcnt(8)
	v_mfma_f32_32x32x16_bf16 v[112:127], v[214:217], v[242:245], v[112:127]
	ds_read_b64_tr_b16 v[214:215], v218 offset:256
	ds_read_b64_tr_b16 v[216:217], v218 offset:4352
	s_waitcnt lgkmcnt(8)
	v_mfma_f32_32x32x16_bf16 v[96:111], v[238:241], v[242:245], v[96:111]
	ds_read_b64_tr_b16 v[238:239], v219 offset:256
	ds_read_b64_tr_b16 v[240:241], v219 offset:4352
	s_waitcnt lgkmcnt(8)
	v_mfma_f32_32x32x16_bf16 v[80:95], v[206:209], v[242:245], v[80:95]
	ds_read_b64_tr_b16 v[206:207], v221 offset:256
	ds_read_b64_tr_b16 v[208:209], v221 offset:4352
	v_max3_f32 v246, v222, v223, v224
	v_max3_f32 v247, v225, v226, v227
	v_max3_f32 v246, v246, v228, v229
	v_max3_f32 v247, v247, v230, v231
	v_max3_f32 v246, v246, v232, v233
	v_max3_f32 v247, v247, v234, v235
	s_waitcnt lgkmcnt(8)
	v_mfma_f32_32x32x16_bf16 v[64:79], v[210:213], v[242:245], v[64:79]
	ds_read_b64_tr_b16 v[210:211], v205 offset:8192
	ds_read_b64_tr_b16 v[212:213], v205 offset:12288
	v_max3_f32 v246, v246, v236, v237
	v_max_f32_e32 v246, v246, v247
	v_mov_b32_e32 v247, v246
	v_add_f32_e32 v249, 0x41000000, v190
	s_nop 1
	s_waitcnt lgkmcnt(8)
	v_mfma_f32_32x32x16_bf16 v[48:63], v[128:131], v[242:245], v[48:63]
	ds_read_b64_tr_b16 v[128:129], v218 offset:8192
	ds_read_b64_tr_b16 v[130:131], v218 offset:12288
	v_permlane32_swap_b32_e32 v246, v247
	v_max_f32_e32 v246, v246, v247
	v_cmp_gt_f32_e32 vcc, v246, v249
	s_cbranch_vccnz .Latt_rs1_1B1
	s_waitcnt lgkmcnt(8)
	v_mfma_f32_32x32x16_bf16 v[32:47], v[214:217], v[242:245], v[32:47]
	ds_read_b64_tr_b16 v[214:215], v219 offset:8192
	ds_read_b64_tr_b16 v[216:217], v219 offset:12288
	v_sub_f32_e32 v222, v222, v190
	v_exp_f32_e32 v222, v222
	v_sub_f32_e32 v223, v223, v190
	v_exp_f32_e32 v223, v223
	v_sub_f32_e32 v224, v224, v190
	s_waitcnt lgkmcnt(8)
	v_mfma_f32_32x32x16_bf16 v[16:31], v[238:241], v[242:245], v[16:31]
	ds_read_b64_tr_b16 v[238:239], v221 offset:8192
	ds_read_b64_tr_b16 v[240:241], v221 offset:12288
	v_add_f32_e32 v254, 0, v222
	v_exp_f32_e32 v224, v224
	v_sub_f32_e32 v225, v225, v190
	v_add_f32_e32 v254, v223, v254
	v_exp_f32_e32 v225, v225
	s_waitcnt lgkmcnt(8)
	v_mfma_f32_32x32x16_bf16 v[0:15], v[206:209], v[242:245], v[0:15]
	ds_read_b64_tr_b16 v[206:207], v205 offset:8448
	ds_read_b64_tr_b16 v[208:209], v205 offset:12544
	v_sub_f32_e32 v226, v226, v190
	v_add_f32_e32 v254, v224, v254
	v_exp_f32_e32 v226, v226
	v_sub_f32_e32 v227, v227, v190
	v_add_f32_e32 v254, v225, v254
	s_waitcnt lgkmcnt(8)
	v_mfma_f32_32x32x16_bf16 v[112:127], v[210:213], v[250:253], v[112:127]
	ds_read_b64_tr_b16 v[210:211], v218 offset:8448
	ds_read_b64_tr_b16 v[212:213], v218 offset:12544
	v_exp_f32_e32 v227, v227
	v_sub_f32_e32 v228, v228, v190
	v_add_f32_e32 v254, v226, v254
	v_exp_f32_e32 v228, v228
	v_sub_f32_e32 v229, v229, v190
	s_waitcnt lgkmcnt(8)
	v_mfma_f32_32x32x16_bf16 v[96:111], v[128:131], v[250:253], v[96:111]
	ds_read_b64_tr_b16 v[128:129], v219 offset:8448
	ds_read_b64_tr_b16 v[130:131], v219 offset:12544
	v_add_f32_e32 v254, v227, v254
	v_exp_f32_e32 v229, v229
	v_sub_f32_e32 v230, v230, v190
	v_add_f32_e32 v254, v228, v254
	s_waitcnt lgkmcnt(8)
	v_mfma_f32_32x32x16_bf16 v[80:95], v[214:217], v[250:253], v[80:95]
	ds_read_b64_tr_b16 v[214:215], v221 offset:8448
	ds_read_b64_tr_b16 v[216:217], v221 offset:12544
	v_exp_f32_e32 v230, v230
	v_sub_f32_e32 v231, v231, v190
	v_add_f32_e32 v254, v229, v254
	v_exp_f32_e32 v231, v231
	s_waitcnt lgkmcnt(8)
	v_mfma_f32_32x32x16_bf16 v[64:79], v[238:241], v[250:253], v[64:79]
	v_sub_f32_e32 v232, v232, v190
	v_add_f32_e32 v254, v230, v254
	v_exp_f32_e32 v232, v232
	v_sub_f32_e32 v233, v233, v190
	s_waitcnt lgkmcnt(6)
	v_mfma_f32_32x32x16_bf16 v[48:63], v[206:209], v[250:253], v[48:63]
	v_add_f32_e32 v254, v231, v254
	v_exp_f32_e32 v233, v233
	v_sub_f32_e32 v234, v234, v190
	v_add_f32_e32 v254, v232, v254
	s_waitcnt lgkmcnt(4)
	v_mfma_f32_32x32x16_bf16 v[32:47], v[210:213], v[250:253], v[32:47]
	v_exp_f32_e32 v234, v234
	v_sub_f32_e32 v235, v235, v190
	v_add_f32_e32 v254, v233, v254
	v_exp_f32_e32 v235, v235
	s_waitcnt lgkmcnt(2)
	v_mfma_f32_32x32x16_bf16 v[16:31], v[128:131], v[250:253], v[16:31]
	v_sub_f32_e32 v236, v236, v190
	v_add_f32_e32 v254, v234, v254
	v_exp_f32_e32 v236, v236
	v_sub_f32_e32 v237, v237, v190
	s_waitcnt lgkmcnt(0)
	v_mfma_f32_32x32x16_bf16 v[0:15], v[214:217], v[250:253], v[0:15]
	v_add_f32_e32 v254, v235, v254
	v_exp_f32_e32 v237, v237
	v_add_f32_e32 v254, v236, v254
	v_add_f32_e32 v254, v237, v254
	v_cvt_pk_bf16_f32 v242, v222, v223
	v_cvt_pk_bf16_f32 v243, v224, v225
	v_cvt_pk_bf16_f32 v244, v226, v227
	v_cvt_pk_bf16_f32 v245, v228, v229
	v_cvt_pk_bf16_f32 v250, v230, v231
	v_cvt_pk_bf16_f32 v251, v232, v233
	v_cvt_pk_bf16_f32 v252, v234, v235
	v_cvt_pk_bf16_f32 v253, v236, v237
	v_add_f32_e32 v195, v195, v254
	s_nop 1

.Latt_rs1_1B1:
	s_waitcnt lgkmcnt(8)
	v_mfma_f32_32x32x16_bf16 v[32:47], v[214:217], v[242:245], v[32:47]
	ds_read_b64_tr_b16 v[214:215], v219 offset:8192
	ds_read_b64_tr_b16 v[216:217], v219 offset:12288
	s_waitcnt lgkmcnt(8)
	v_mfma_f32_32x32x16_bf16 v[16:31], v[238:241], v[242:245], v[16:31]
	ds_read_b64_tr_b16 v[238:239], v221 offset:8192
	ds_read_b64_tr_b16 v[240:241], v221 offset:12288
	s_waitcnt lgkmcnt(8)
	v_mfma_f32_32x32x16_bf16 v[0:15], v[206:209], v[242:245], v[0:15]
	ds_read_b64_tr_b16 v[206:207], v205 offset:8448
	ds_read_b64_tr_b16 v[208:209], v205 offset:12544
	s_waitcnt lgkmcnt(8)
	v_mfma_f32_32x32x16_bf16 v[112:127], v[210:213], v[250:253], v[112:127]
	ds_read_b64_tr_b16 v[210:211], v218 offset:8448
	ds_read_b64_tr_b16 v[212:213], v218 offset:12544
	s_waitcnt lgkmcnt(8)
	v_mfma_f32_32x32x16_bf16 v[96:111], v[128:131], v[250:253], v[96:111]
	ds_read_b64_tr_b16 v[128:129], v219 offset:8448
	ds_read_b64_tr_b16 v[130:131], v219 offset:12544
	s_waitcnt lgkmcnt(8)
	v_mfma_f32_32x32x16_bf16 v[80:95], v[214:217], v[250:253], v[80:95]
	ds_read_b64_tr_b16 v[214:215], v221 offset:8448
	ds_read_b64_tr_b16 v[216:217], v221 offset:12544
	s_waitcnt lgkmcnt(8)
	v_mfma_f32_32x32x16_bf16 v[64:79], v[238:241], v[250:253], v[64:79]
	s_waitcnt lgkmcnt(6)
	v_mfma_f32_32x32x16_bf16 v[48:63], v[206:209], v[250:253], v[48:63]
	s_waitcnt lgkmcnt(4)
	v_mfma_f32_32x32x16_bf16 v[32:47], v[210:213], v[250:253], v[32:47]
	s_waitcnt lgkmcnt(2)
	v_mfma_f32_32x32x16_bf16 v[16:31], v[128:131], v[250:253], v[16:31]
	s_waitcnt lgkmcnt(0)
	v_mfma_f32_32x32x16_bf16 v[0:15], v[214:217], v[250:253], v[0:15]
	s_nop 11
	v_max_f32_e32 v246, v190, v246
	v_sub_f32_e32 v190, v190, v246
	v_exp_f32_e32 v190, v190
	s_nop 0
	v_pk_mul_f32 v[126:127], v[126:127], v[190:191] op_sel_hi:[1,0]
	v_pk_mul_f32 v[124:125], v[124:125], v[190:191] op_sel_hi:[1,0]
	v_pk_mul_f32 v[122:123], v[122:123], v[190:191] op_sel_hi:[1,0]
	v_pk_mul_f32 v[120:121], v[120:121], v[190:191] op_sel_hi:[1,0]
	v_pk_mul_f32 v[118:119], v[118:119], v[190:191] op_sel_hi:[1,0]
	v_pk_mul_f32 v[116:117], v[116:117], v[190:191] op_sel_hi:[1,0]
	v_pk_mul_f32 v[114:115], v[114:115], v[190:191] op_sel_hi:[1,0]
	v_pk_mul_f32 v[112:113], v[112:113], v[190:191] op_sel_hi:[1,0]
	v_pk_mul_f32 v[110:111], v[110:111], v[190:191] op_sel_hi:[1,0]
	v_pk_mul_f32 v[108:109], v[108:109], v[190:191] op_sel_hi:[1,0]
	v_pk_mul_f32 v[106:107], v[106:107], v[190:191] op_sel_hi:[1,0]
	v_pk_mul_f32 v[104:105], v[104:105], v[190:191] op_sel_hi:[1,0]
	v_pk_mul_f32 v[102:103], v[102:103], v[190:191] op_sel_hi:[1,0]
	v_pk_mul_f32 v[100:101], v[100:101], v[190:191] op_sel_hi:[1,0]
	v_pk_mul_f32 v[98:99], v[98:99], v[190:191] op_sel_hi:[1,0]
	v_pk_mul_f32 v[96:97], v[96:97], v[190:191] op_sel_hi:[1,0]
	v_pk_mul_f32 v[94:95], v[94:95], v[190:191] op_sel_hi:[1,0]
	v_pk_mul_f32 v[92:93], v[92:93], v[190:191] op_sel_hi:[1,0]
	v_pk_mul_f32 v[90:91], v[90:91], v[190:191] op_sel_hi:[1,0]
	v_pk_mul_f32 v[88:89], v[88:89], v[190:191] op_sel_hi:[1,0]
	v_pk_mul_f32 v[86:87], v[86:87], v[190:191] op_sel_hi:[1,0]
	v_pk_mul_f32 v[84:85], v[84:85], v[190:191] op_sel_hi:[1,0]
	v_pk_mul_f32 v[82:83], v[82:83], v[190:191] op_sel_hi:[1,0]
	v_pk_mul_f32 v[80:81], v[80:81], v[190:191] op_sel_hi:[1,0]
	v_pk_mul_f32 v[78:79], v[78:79], v[190:191] op_sel_hi:[1,0]
	v_pk_mul_f32 v[76:77], v[76:77], v[190:191] op_sel_hi:[1,0]
	v_pk_mul_f32 v[74:75], v[74:75], v[190:191] op_sel_hi:[1,0]
	v_pk_mul_f32 v[72:73], v[72:73], v[190:191] op_sel_hi:[1,0]
	v_pk_mul_f32 v[70:71], v[70:71], v[190:191] op_sel_hi:[1,0]
	v_pk_mul_f32 v[68:69], v[68:69], v[190:191] op_sel_hi:[1,0]
	v_pk_mul_f32 v[66:67], v[66:67], v[190:191] op_sel_hi:[1,0]
	v_pk_mul_f32 v[64:65], v[64:65], v[190:191] op_sel_hi:[1,0]
	v_pk_mul_f32 v[62:63], v[62:63], v[190:191] op_sel_hi:[1,0]
	v_pk_mul_f32 v[60:61], v[60:61], v[190:191] op_sel_hi:[1,0]
	v_pk_mul_f32 v[58:59], v[58:59], v[190:191] op_sel_hi:[1,0]
	v_pk_mul_f32 v[56:57], v[56:57], v[190:191] op_sel_hi:[1,0]
	v_pk_mul_f32 v[54:55], v[54:55], v[190:191] op_sel_hi:[1,0]
	v_pk_mul_f32 v[52:53], v[52:53], v[190:191] op_sel_hi:[1,0]
	v_pk_mul_f32 v[50:51], v[50:51], v[190:191] op_sel_hi:[1,0]
	v_pk_mul_f32 v[48:49], v[48:49], v[190:191] op_sel_hi:[1,0]
	v_pk_mul_f32 v[46:47], v[46:47], v[190:191] op_sel_hi:[1,0]
	v_pk_mul_f32 v[44:45], v[44:45], v[190:191] op_sel_hi:[1,0]
	v_pk_mul_f32 v[42:43], v[42:43], v[190:191] op_sel_hi:[1,0]
	v_pk_mul_f32 v[40:41], v[40:41], v[190:191] op_sel_hi:[1,0]
	v_pk_mul_f32 v[38:39], v[38:39], v[190:191] op_sel_hi:[1,0]
	v_pk_mul_f32 v[36:37], v[36:37], v[190:191] op_sel_hi:[1,0]
	v_pk_mul_f32 v[34:35], v[34:35], v[190:191] op_sel_hi:[1,0]
	v_pk_mul_f32 v[32:33], v[32:33], v[190:191] op_sel_hi:[1,0]
	v_pk_mul_f32 v[30:31], v[30:31], v[190:191] op_sel_hi:[1,0]
	v_pk_mul_f32 v[28:29], v[28:29], v[190:191] op_sel_hi:[1,0]
	v_pk_mul_f32 v[26:27], v[26:27], v[190:191] op_sel_hi:[1,0]
	v_pk_mul_f32 v[24:25], v[24:25], v[190:191] op_sel_hi:[1,0]
	v_pk_mul_f32 v[22:23], v[22:23], v[190:191] op_sel_hi:[1,0]
	v_pk_mul_f32 v[20:21], v[20:21], v[190:191] op_sel_hi:[1,0]
	v_pk_mul_f32 v[18:19], v[18:19], v[190:191] op_sel_hi:[1,0]
	v_pk_mul_f32 v[16:17], v[16:17], v[190:191] op_sel_hi:[1,0]
	v_pk_mul_f32 v[14:15], v[14:15], v[190:191] op_sel_hi:[1,0]
	v_pk_mul_f32 v[12:13], v[12:13], v[190:191] op_sel_hi:[1,0]
	v_pk_mul_f32 v[10:11], v[10:11], v[190:191] op_sel_hi:[1,0]
	v_pk_mul_f32 v[8:9], v[8:9], v[190:191] op_sel_hi:[1,0]
	v_pk_mul_f32 v[6:7], v[6:7], v[190:191] op_sel_hi:[1,0]
	v_pk_mul_f32 v[4:5], v[4:5], v[190:191] op_sel_hi:[1,0]
	v_pk_mul_f32 v[2:3], v[2:3], v[190:191] op_sel_hi:[1,0]
	v_pk_mul_f32 v[0:1], v[0:1], v[190:191] op_sel_hi:[1,0]
	v_mul_f32_e32 v195, v195, v190
	v_mov_b32_e32 v190, v246
	v_sub_f32_e32 v222, v222, v190
	v_exp_f32_e32 v222, v222
	v_sub_f32_e32 v223, v223, v190
	v_exp_f32_e32 v223, v223
	v_sub_f32_e32 v224, v224, v190
	v_add_f32_e32 v254, 0, v222
	v_exp_f32_e32 v224, v224
	v_sub_f32_e32 v225, v225, v190
	v_add_f32_e32 v254, v223, v254
	v_exp_f32_e32 v225, v225
	v_sub_f32_e32 v226, v226, v190
	v_add_f32_e32 v254, v224, v254
	v_exp_f32_e32 v226, v226
	v_sub_f32_e32 v227, v227, v190
	v_add_f32_e32 v254, v225, v254
	v_exp_f32_e32 v227, v227
	v_sub_f32_e32 v228, v228, v190
	v_add_f32_e32 v254, v226, v254
	v_exp_f32_e32 v228, v228
	v_sub_f32_e32 v229, v229, v190
	v_add_f32_e32 v254, v227, v254
	v_exp_f32_e32 v229, v229
	v_sub_f32_e32 v230, v230, v190
	v_add_f32_e32 v254, v228, v254
	v_exp_f32_e32 v230, v230
	v_sub_f32_e32 v231, v231, v190
	v_add_f32_e32 v254, v229, v254
	v_exp_f32_e32 v231, v231
	v_sub_f32_e32 v232, v232, v190
	v_add_f32_e32 v254, v230, v254
	v_exp_f32_e32 v232, v232
	v_sub_f32_e32 v233, v233, v190
	v_add_f32_e32 v254, v231, v254
	v_exp_f32_e32 v233, v233
	v_sub_f32_e32 v234, v234, v190
	v_add_f32_e32 v254, v232, v254
	v_exp_f32_e32 v234, v234
	v_sub_f32_e32 v235, v235, v190
	v_add_f32_e32 v254, v233, v254
	v_exp_f32_e32 v235, v235
	v_sub_f32_e32 v236, v236, v190
	v_add_f32_e32 v254, v234, v254
	v_exp_f32_e32 v236, v236
	v_sub_f32_e32 v237, v237, v190
	v_add_f32_e32 v254, v235, v254
	v_exp_f32_e32 v237, v237
	v_add_f32_e32 v254, v236, v254
	v_add_f32_e32 v254, v237, v254
	v_cvt_pk_bf16_f32 v242, v222, v223
	v_cvt_pk_bf16_f32 v243, v224, v225
	v_cvt_pk_bf16_f32 v244, v226, v227
	v_cvt_pk_bf16_f32 v245, v228, v229
	v_cvt_pk_bf16_f32 v250, v230, v231
	v_cvt_pk_bf16_f32 v251, v232, v233
	v_cvt_pk_bf16_f32 v252, v234, v235
	v_cvt_pk_bf16_f32 v253, v236, v237
	v_add_f32_e32 v195, v195, v254
	s_nop 1
	s_branch .Latt_pv1_1B1
.Latt_B0_1:
	s_lshl_b32 s98, s33, 14
	s_lshl_b32 s99, s33, 15
	s_add_i32 s99, s99, 0xc000
	v_add_u32_e32 v206, s98, v196
	ds_read_b128 v[206:209], v206
	v_add_u32_e32 v210, s98, v197
	ds_read_b128 v[210:213], v210
	v_add_u32_e32 v214, s98, v198
	ds_read_b128 v[214:217], v214
	v_add_u32_e32 v238, s98, v199
	ds_read_b128 v[238:241], v238
	v_add_u32_e32 v242, s98, v200
	ds_read_b128 v[242:245], v242
	v_add_u32_e32 v250, s98, v201
	ds_read_b128 v[250:253], v250
	v_add_u32_e32 v222, s98, v202
	ds_read_b128 v[222:225], v222
	v_add_u32_e32 v226, s98, v203
	ds_read_b128 v[226:229], v226
	v_bfe_u32 v246, v204, 2, 2
	v_bfe_u32 v247, v204, 5, 1
	v_lshl_or_b32 v247, v247, 2, v246
	v_and_b32_e32 v249, 3, v204
	v_and_b32_e32 v254, 16, v204
	v_lshl_or_b32 v249, v249, 2, v254
	v_lshlrev_b32_e32 v249, 1, v249
	v_lshl_add_u32 v247, v247, 9, v249
	v_add_u32_e32 v247, s99, v247
	v_lshlrev_b32_e32 v246, 6, v246
	v_add_u32_e32 v205, v247, v246
	v_xor_b32_e32 v249, 64, v246
	v_add_u32_e32 v218, v247, v249
	v_xor_b32_e32 v249, 0x80, v246
	v_add_u32_e32 v219, v247, v249
	v_xor_b32_e32 v249, 0xc0, v246
	v_add_u32_e32 v221, v247, v249
	s_waitcnt lgkmcnt(7)
	v_mfma_f32_32x32x16_bf16 v[128:143], v[206:209], v[144:147], 0
	v_add_u32_e32 v206, s98, v196
	ds_read_b128 v[206:209], v206 offset:8192
	s_cmp_lg_u64 s[18:19], 0
	s_cbranch_scc1 .Latt_nd0_1B0
	s_add_i32 s100, s33, 1
	s_cmp_eq_u32 s33, 2
	s_cselect_b32 s100, 0, s100
	s_lshl_b32 s101, s100, 14
	s_add_i32 m0, s85, s101
	s_nop 0
	global_load_lds_dwordx4 v178, s[12:13]
.Latt_nd0_1B0:
	s_waitcnt lgkmcnt(7)
	v_mfma_f32_32x32x16_bf16 v[128:143], v[210:213], v[148:151], v[128:143]
	v_add_u32_e32 v210, s98, v197
	ds_read_b128 v[210:213], v210 offset:8192
	s_cmp_lg_u64 s[18:19], 0
	s_cbranch_scc1 .Latt_nd1_1B0
	s_add_i32 m0, m0, 0x400
	s_nop 0
	global_load_lds_dwordx4 v180, s[12:13]
.Latt_nd1_1B0:
	s_waitcnt lgkmcnt(7)
	v_mfma_f32_32x32x16_bf16 v[128:143], v[214:217], v[152:155], v[128:143]
	v_add_u32_e32 v214, s98, v198
	ds_read_b128 v[214:217], v214 offset:8192
	s_cmp_lg_u64 s[18:19], 0
	s_cbranch_scc1 .Latt_nd2_1B0
	s_lshl_b32 s101, s100, 15
	s_add_i32 m0, s86, s101
	s_add_u32 s100, s12, 0xf00
	s_addc_u32 s101, s13, 0
	global_load_lds_dwordx4 v182, s[100:101]
.Latt_nd2_1B0:
	s_waitcnt lgkmcnt(7)
	v_mfma_f32_32x32x16_bf16 v[128:143], v[238:241], v[156:159], v[128:143]
	v_add_u32_e32 v238, s98, v199
	ds_read_b128 v[238:241], v238 offset:8192
	s_cmp_lg_u64 s[18:19], 0
	s_cbranch_scc1 .Latt_nd3_1B0
	s_add_i32 m0, m0, 0x400
	s_nop 0
	global_load_lds_dwordx4 v184, s[100:101]
.Latt_nd3_1B0:
	s_waitcnt lgkmcnt(7)
	v_mfma_f32_32x32x16_bf16 v[128:143], v[242:245], v[160:163], v[128:143]
	v_add_u32_e32 v242, s98, v200
	ds_read_b128 v[242:245], v242 offset:8192
	s_cmp_lg_u64 s[18:19], 0
	s_cbranch_scc1 .Latt_nd4_1B0
	s_add_i32 m0, m0, 0x400
	s_nop 0
	global_load_lds_dwordx4 v186, s[100:101]
.Latt_nd4_1B0:
	s_waitcnt lgkmcnt(7)
	v_mfma_f32_32x32x16_bf16 v[128:143], v[250:253], v[164:167], v[128:143]
	v_add_u32_e32 v250, s98, v201
	ds_read_b128 v[250:253], v250 offset:8192
	s_cmp_lg_u64 s[18:19], 0
	s_cbranch_scc1 .Latt_nd5_1B0
	s_add_i32 m0, m0, 0x400
	s_nop 0
	global_load_lds_dwordx4 v188, s[100:101]
.Latt_nd5_1B0:
	s_waitcnt lgkmcnt(7)
	v_mfma_f32_32x32x16_bf16 v[128:143], v[222:225], v[168:171], v[128:143]
	s_waitcnt lgkmcnt(6)
	v_mfma_f32_32x32x16_bf16 v[128:143], v[226:229], v[172:175], v[128:143]
	s_waitcnt lgkmcnt(5)
	v_mfma_f32_32x32x16_bf16 v[222:237], v[206:209], v[144:147], 0
	v_add_u32_e32 v206, s98, v202
	ds_read_b128 v[206:209], v206 offset:8192
	s_nop 7
	v_max3_f32 v246, v128, v129, v130
	v_max3_f32 v247, v131, v132, v133
	v_max3_f32 v246, v246, v134, v135
	v_max3_f32 v247, v247, v136, v137
	v_max3_f32 v246, v246, v138, v139
	v_max3_f32 v247, v247, v140, v141
	v_max3_f32 v246, v246, v142, v143
	s_waitcnt lgkmcnt(5)
	v_mfma_f32_32x32x16_bf16 v[222:237], v[210:213], v[148:151], v[222:237]
	v_add_u32_e32 v210, s98, v203
	ds_read_b128 v[210:213], v210 offset:8192
	v_max_f32_e32 v246, v246, v247
	v_mov_b32_e32 v247, v246
	v_add_f32_e32 v249, 0x41000000, v190
	s_nop 1
	v_permlane32_swap_b32_e32 v246, v247
	v_max_f32_e32 v246, v246, v247
	v_cmp_gt_f32_e32 vcc, v246, v249
	s_cbranch_vccz .Latt_nr0_1B0
	v_max_f32_e32 v246, v190, v246
	v_sub_f32_e32 v190, v190, v246
	v_exp_f32_e32 v190, v190
	s_nop 0
	v_pk_mul_f32 v[126:127], v[126:127], v[190:191] op_sel_hi:[1,0]
	v_pk_mul_f32 v[124:125], v[124:125], v[190:191] op_sel_hi:[1,0]
	v_pk_mul_f32 v[122:123], v[122:123], v[190:191] op_sel_hi:[1,0]
	v_pk_mul_f32 v[120:121], v[120:121], v[190:191] op_sel_hi:[1,0]
	v_pk_mul_f32 v[118:119], v[118:119], v[190:191] op_sel_hi:[1,0]
	v_pk_mul_f32 v[116:117], v[116:117], v[190:191] op_sel_hi:[1,0]
	v_pk_mul_f32 v[114:115], v[114:115], v[190:191] op_sel_hi:[1,0]
	v_pk_mul_f32 v[112:113], v[112:113], v[190:191] op_sel_hi:[1,0]
	v_pk_mul_f32 v[110:111], v[110:111], v[190:191] op_sel_hi:[1,0]
	v_pk_mul_f32 v[108:109], v[108:109], v[190:191] op_sel_hi:[1,0]
	v_pk_mul_f32 v[106:107], v[106:107], v[190:191] op_sel_hi:[1,0]
	v_pk_mul_f32 v[104:105], v[104:105], v[190:191] op_sel_hi:[1,0]
	v_pk_mul_f32 v[102:103], v[102:103], v[190:191] op_sel_hi:[1,0]
	v_pk_mul_f32 v[100:101], v[100:101], v[190:191] op_sel_hi:[1,0]
	v_pk_mul_f32 v[98:99], v[98:99], v[190:191] op_sel_hi:[1,0]
	v_pk_mul_f32 v[96:97], v[96:97], v[190:191] op_sel_hi:[1,0]
	v_pk_mul_f32 v[94:95], v[94:95], v[190:191] op_sel_hi:[1,0]
	v_pk_mul_f32 v[92:93], v[92:93], v[190:191] op_sel_hi:[1,0]
	v_pk_mul_f32 v[90:91], v[90:91], v[190:191] op_sel_hi:[1,0]
	v_pk_mul_f32 v[88:89], v[88:89], v[190:191] op_sel_hi:[1,0]
	v_pk_mul_f32 v[86:87], v[86:87], v[190:191] op_sel_hi:[1,0]
	v_pk_mul_f32 v[84:85], v[84:85], v[190:191] op_sel_hi:[1,0]
	v_pk_mul_f32 v[82:83], v[82:83], v[190:191] op_sel_hi:[1,0]
	v_pk_mul_f32 v[80:81], v[80:81], v[190:191] op_sel_hi:[1,0]
	v_pk_mul_f32 v[78:79], v[78:79], v[190:191] op_sel_hi:[1,0]
	v_pk_mul_f32 v[76:77], v[76:77], v[190:191] op_sel_hi:[1,0]
	v_pk_mul_f32 v[74:75], v[74:75], v[190:191] op_sel_hi:[1,0]
	v_pk_mul_f32 v[72:73], v[72:73], v[190:191] op_sel_hi:[1,0]
	v_pk_mul_f32 v[70:71], v[70:71], v[190:191] op_sel_hi:[1,0]
	v_pk_mul_f32 v[68:69], v[68:69], v[190:191] op_sel_hi:[1,0]
	v_pk_mul_f32 v[66:67], v[66:67], v[190:191] op_sel_hi:[1,0]
	v_pk_mul_f32 v[64:65], v[64:65], v[190:191] op_sel_hi:[1,0]
	v_pk_mul_f32 v[62:63], v[62:63], v[190:191] op_sel_hi:[1,0]
	v_pk_mul_f32 v[60:61], v[60:61], v[190:191] op_sel_hi:[1,0]
	v_pk_mul_f32 v[58:59], v[58:59], v[190:191] op_sel_hi:[1,0]
	v_pk_mul_f32 v[56:57], v[56:57], v[190:191] op_sel_hi:[1,0]
	v_pk_mul_f32 v[54:55], v[54:55], v[190:191] op_sel_hi:[1,0]
	v_pk_mul_f32 v[52:53], v[52:53], v[190:191] op_sel_hi:[1,0]
	v_pk_mul_f32 v[50:51], v[50:51], v[190:191] op_sel_hi:[1,0]
	v_pk_mul_f32 v[48:49], v[48:49], v[190:191] op_sel_hi:[1,0]
	v_pk_mul_f32 v[46:47], v[46:47], v[190:191] op_sel_hi:[1,0]
	v_pk_mul_f32 v[44:45], v[44:45], v[190:191] op_sel_hi:[1,0]
	v_pk_mul_f32 v[42:43], v[42:43], v[190:191] op_sel_hi:[1,0]
	v_pk_mul_f32 v[40:41], v[40:41], v[190:191] op_sel_hi:[1,0]
	v_pk_mul_f32 v[38:39], v[38:39], v[190:191] op_sel_hi:[1,0]
	v_pk_mul_f32 v[36:37], v[36:37], v[190:191] op_sel_hi:[1,0]
	v_pk_mul_f32 v[34:35], v[34:35], v[190:191] op_sel_hi:[1,0]
	v_pk_mul_f32 v[32:33], v[32:33], v[190:191] op_sel_hi:[1,0]
	v_pk_mul_f32 v[30:31], v[30:31], v[190:191] op_sel_hi:[1,0]
	v_pk_mul_f32 v[28:29], v[28:29], v[190:191] op_sel_hi:[1,0]
	v_pk_mul_f32 v[26:27], v[26:27], v[190:191] op_sel_hi:[1,0]
	v_pk_mul_f32 v[24:25], v[24:25], v[190:191] op_sel_hi:[1,0]
	v_pk_mul_f32 v[22:23], v[22:23], v[190:191] op_sel_hi:[1,0]
	v_pk_mul_f32 v[20:21], v[20:21], v[190:191] op_sel_hi:[1,0]
	v_pk_mul_f32 v[18:19], v[18:19], v[190:191] op_sel_hi:[1,0]
	v_pk_mul_f32 v[16:17], v[16:17], v[190:191] op_sel_hi:[1,0]
	v_pk_mul_f32 v[14:15], v[14:15], v[190:191] op_sel_hi:[1,0]
	v_pk_mul_f32 v[12:13], v[12:13], v[190:191] op_sel_hi:[1,0]
	v_pk_mul_f32 v[10:11], v[10:11], v[190:191] op_sel_hi:[1,0]
	v_pk_mul_f32 v[8:9], v[8:9], v[190:191] op_sel_hi:[1,0]
	v_pk_mul_f32 v[6:7], v[6:7], v[190:191] op_sel_hi:[1,0]
	v_pk_mul_f32 v[4:5], v[4:5], v[190:191] op_sel_hi:[1,0]
	v_pk_mul_f32 v[2:3], v[2:3], v[190:191] op_sel_hi:[1,0]
	v_pk_mul_f32 v[0:1], v[0:1], v[190:191] op_sel_hi:[1,0]
	v_mul_f32_e32 v195, v195, v190
	v_mov_b32_e32 v190, v246
.Latt_nr0_1B0:
	s_waitcnt lgkmcnt(5)
	v_mfma_f32_32x32x16_bf16 v[222:237], v[214:217], v[152:155], v[222:237]
	ds_read_b64_tr_b16 v[214:215], v205
	ds_read_b64_tr_b16 v[216:217], v205 offset:4096
	v_sub_f32_e32 v128, v128, v190
	v_exp_f32_e32 v128, v128
	v_sub_f32_e32 v129, v129, v190
	v_exp_f32_e32 v129, v129
	v_sub_f32_e32 v130, v130, v190
	v_add_f32_e32 v254, 0, v128
	v_exp_f32_e32 v130, v130
	v_sub_f32_e32 v131, v131, v190
	s_waitcnt lgkmcnt(6)
	v_mfma_f32_32x32x16_bf16 v[222:237], v[238:241], v[156:159], v[222:237]
	ds_read_b64_tr_b16 v[238:239], v218
	ds_read_b64_tr_b16 v[240:241], v218 offset:4096
	v_add_f32_e32 v254, v129, v254
	v_exp_f32_e32 v131, v131
	v_sub_f32_e32 v132, v132, v190
	v_add_f32_e32 v254, v130, v254
	v_exp_f32_e32 v132, v132
	v_sub_f32_e32 v133, v133, v190
	v_add_f32_e32 v254, v131, v254
	v_exp_f32_e32 v133, v133
	s_waitcnt lgkmcnt(7)
	v_mfma_f32_32x32x16_bf16 v[222:237], v[242:245], v[160:163], v[222:237]
	v_sub_f32_e32 v134, v134, v190
	v_add_f32_e32 v254, v132, v254
	v_exp_f32_e32 v134, v134
	v_sub_f32_e32 v135, v135, v190
	v_add_f32_e32 v254, v133, v254
	v_exp_f32_e32 v135, v135
	v_sub_f32_e32 v136, v136, v190
	v_add_f32_e32 v254, v134, v254
	s_waitcnt lgkmcnt(6)
	v_mfma_f32_32x32x16_bf16 v[222:237], v[250:253], v[164:167], v[222:237]
	v_exp_f32_e32 v136, v136
	v_sub_f32_e32 v137, v137, v190
	v_add_f32_e32 v254, v135, v254
	v_exp_f32_e32 v137, v137
	v_sub_f32_e32 v138, v138, v190
	v_add_f32_e32 v254, v136, v254
	v_exp_f32_e32 v138, v138
	v_sub_f32_e32 v139, v139, v190
	s_waitcnt lgkmcnt(5)
	v_mfma_f32_32x32x16_bf16 v[222:237], v[206:209], v[168:171], v[222:237]
	ds_read_b64_tr_b16 v[206:207], v219
	ds_read_b64_tr_b16 v[208:209], v219 offset:4096
	v_add_f32_e32 v254, v137, v254
	v_exp_f32_e32 v139, v139
	v_sub_f32_e32 v140, v140, v190
	v_add_f32_e32 v254, v138, v254
	v_exp_f32_e32 v140, v140
	v_sub_f32_e32 v141, v141, v190
	v_add_f32_e32 v254, v139, v254
	v_exp_f32_e32 v141, v141
	s_waitcnt lgkmcnt(6)
	v_mfma_f32_32x32x16_bf16 v[222:237], v[210:213], v[172:175], v[222:237]
	ds_read_b64_tr_b16 v[210:211], v221
	ds_read_b64_tr_b16 v[212:213], v221 offset:4096
	v_sub_f32_e32 v142, v142, v190
	v_add_f32_e32 v254, v140, v254
	v_exp_f32_e32 v142, v142
	v_sub_f32_e32 v143, v143, v190
	v_add_f32_e32 v254, v141, v254
	v_exp_f32_e32 v143, v143
	v_add_f32_e32 v254, v142, v254
	v_add_f32_e32 v254, v143, v254
	v_cvt_pk_bf16_f32 v242, v128, v129
	v_cvt_pk_bf16_f32 v243, v130, v131
	v_cvt_pk_bf16_f32 v244, v132, v133
	v_cvt_pk_bf16_f32 v245, v134, v135
	v_cvt_pk_bf16_f32 v250, v136, v137
	v_cvt_pk_bf16_f32 v251, v138, v139
	v_cvt_pk_bf16_f32 v252, v140, v141
	v_cvt_pk_bf16_f32 v253, v142, v143
	v_add_f32_e32 v195, v195, v254
	s_nop 1
	ds_read_b64_tr_b16 v[128:129], v205 offset:256
	ds_read_b64_tr_b16 v[130:131], v205 offset:4352
	s_waitcnt lgkmcnt(8)
	v_mfma_f32_32x32x16_bf16 v[112:127], v[214:217], v[242:245], v[112:127]
	ds_read_b64_tr_b16 v[214:215], v218 offset:256
	ds_read_b64_tr_b16 v[216:217], v218 offset:4352
	s_waitcnt lgkmcnt(8)
	v_mfma_f32_32x32x16_bf16 v[96:111], v[238:241], v[242:245], v[96:111]
	ds_read_b64_tr_b16 v[238:239], v219 offset:256
	ds_read_b64_tr_b16 v[240:241], v219 offset:4352
	s_waitcnt lgkmcnt(8)
	v_mfma_f32_32x32x16_bf16 v[80:95], v[206:209], v[242:245], v[80:95]
	ds_read_b64_tr_b16 v[206:207], v221 offset:256
	ds_read_b64_tr_b16 v[208:209], v221 offset:4352
	v_max3_f32 v246, v222, v223, v224
	v_max3_f32 v247, v225, v226, v227
	v_max3_f32 v246, v246, v228, v229
	v_max3_f32 v247, v247, v230, v231
	v_max3_f32 v246, v246, v232, v233
	v_max3_f32 v247, v247, v234, v235
	s_waitcnt lgkmcnt(8)
	v_mfma_f32_32x32x16_bf16 v[64:79], v[210:213], v[242:245], v[64:79]
	ds_read_b64_tr_b16 v[210:211], v205 offset:8192
	ds_read_b64_tr_b16 v[212:213], v205 offset:12288
	v_max3_f32 v246, v246, v236, v237
	v_max_f32_e32 v246, v246, v247
	v_mov_b32_e32 v247, v246
	v_add_f32_e32 v249, 0x41000000, v190
	s_nop 1
	s_waitcnt lgkmcnt(8)
	v_mfma_f32_32x32x16_bf16 v[48:63], v[128:131], v[242:245], v[48:63]
	ds_read_b64_tr_b16 v[128:129], v218 offset:8192
	ds_read_b64_tr_b16 v[130:131], v218 offset:12288
	v_permlane32_swap_b32_e32 v246, v247
	v_max_f32_e32 v246, v246, v247
	v_cmp_gt_f32_e32 vcc, v246, v249
	s_cbranch_vccnz .Latt_rs1_1B0
	s_waitcnt lgkmcnt(8)
	v_mfma_f32_32x32x16_bf16 v[32:47], v[214:217], v[242:245], v[32:47]
	ds_read_b64_tr_b16 v[214:215], v219 offset:8192
	ds_read_b64_tr_b16 v[216:217], v219 offset:12288
	v_sub_f32_e32 v222, v222, v190
	v_exp_f32_e32 v222, v222
	v_sub_f32_e32 v223, v223, v190
	v_exp_f32_e32 v223, v223
	v_sub_f32_e32 v224, v224, v190
	s_waitcnt lgkmcnt(8)
	v_mfma_f32_32x32x16_bf16 v[16:31], v[238:241], v[242:245], v[16:31]
	ds_read_b64_tr_b16 v[238:239], v221 offset:8192
	ds_read_b64_tr_b16 v[240:241], v221 offset:12288
	v_add_f32_e32 v254, 0, v222
	v_exp_f32_e32 v224, v224
	v_sub_f32_e32 v225, v225, v190
	v_add_f32_e32 v254, v223, v254
	v_exp_f32_e32 v225, v225
	s_waitcnt lgkmcnt(8)
	v_mfma_f32_32x32x16_bf16 v[0:15], v[206:209], v[242:245], v[0:15]
	ds_read_b64_tr_b16 v[206:207], v205 offset:8448
	ds_read_b64_tr_b16 v[208:209], v205 offset:12544
	v_sub_f32_e32 v226, v226, v190
	v_add_f32_e32 v254, v224, v254
	v_exp_f32_e32 v226, v226
	v_sub_f32_e32 v227, v227, v190
	v_add_f32_e32 v254, v225, v254
	s_waitcnt lgkmcnt(8)
	v_mfma_f32_32x32x16_bf16 v[112:127], v[210:213], v[250:253], v[112:127]
	ds_read_b64_tr_b16 v[210:211], v218 offset:8448
	ds_read_b64_tr_b16 v[212:213], v218 offset:12544
	v_exp_f32_e32 v227, v227
	v_sub_f32_e32 v228, v228, v190
	v_add_f32_e32 v254, v226, v254
	v_exp_f32_e32 v228, v228
	v_sub_f32_e32 v229, v229, v190
	s_waitcnt lgkmcnt(8)
	v_mfma_f32_32x32x16_bf16 v[96:111], v[128:131], v[250:253], v[96:111]
	ds_read_b64_tr_b16 v[128:129], v219 offset:8448
	ds_read_b64_tr_b16 v[130:131], v219 offset:12544
	v_add_f32_e32 v254, v227, v254
	v_exp_f32_e32 v229, v229
	v_sub_f32_e32 v230, v230, v190
	v_add_f32_e32 v254, v228, v254
	s_waitcnt lgkmcnt(8)
	v_mfma_f32_32x32x16_bf16 v[80:95], v[214:217], v[250:253], v[80:95]
	ds_read_b64_tr_b16 v[214:215], v221 offset:8448
	ds_read_b64_tr_b16 v[216:217], v221 offset:12544
	v_exp_f32_e32 v230, v230
	v_sub_f32_e32 v231, v231, v190
	v_add_f32_e32 v254, v229, v254
	v_exp_f32_e32 v231, v231
	s_waitcnt lgkmcnt(8)
	v_mfma_f32_32x32x16_bf16 v[64:79], v[238:241], v[250:253], v[64:79]
	v_sub_f32_e32 v232, v232, v190
	v_add_f32_e32 v254, v230, v254
	v_exp_f32_e32 v232, v232
	v_sub_f32_e32 v233, v233, v190
	s_waitcnt lgkmcnt(6)
	v_mfma_f32_32x32x16_bf16 v[48:63], v[206:209], v[250:253], v[48:63]
	v_add_f32_e32 v254, v231, v254
	v_exp_f32_e32 v233, v233
	v_sub_f32_e32 v234, v234, v190
	v_add_f32_e32 v254, v232, v254
	s_waitcnt lgkmcnt(4)
	v_mfma_f32_32x32x16_bf16 v[32:47], v[210:213], v[250:253], v[32:47]
	v_exp_f32_e32 v234, v234
	v_sub_f32_e32 v235, v235, v190
	v_add_f32_e32 v254, v233, v254
	v_exp_f32_e32 v235, v235
	s_waitcnt lgkmcnt(2)
	v_mfma_f32_32x32x16_bf16 v[16:31], v[128:131], v[250:253], v[16:31]
	v_sub_f32_e32 v236, v236, v190
	v_add_f32_e32 v254, v234, v254
	v_exp_f32_e32 v236, v236
	v_sub_f32_e32 v237, v237, v190
	s_waitcnt lgkmcnt(0)
	v_mfma_f32_32x32x16_bf16 v[0:15], v[214:217], v[250:253], v[0:15]
	v_add_f32_e32 v254, v235, v254
	v_exp_f32_e32 v237, v237
	v_add_f32_e32 v254, v236, v254
	v_add_f32_e32 v254, v237, v254
	v_cvt_pk_bf16_f32 v242, v222, v223
	v_cvt_pk_bf16_f32 v243, v224, v225
	v_cvt_pk_bf16_f32 v244, v226, v227
	v_cvt_pk_bf16_f32 v245, v228, v229
	v_cvt_pk_bf16_f32 v250, v230, v231
	v_cvt_pk_bf16_f32 v251, v232, v233
	v_cvt_pk_bf16_f32 v252, v234, v235
	v_cvt_pk_bf16_f32 v253, v236, v237
	v_add_f32_e32 v195, v195, v254
	s_nop 1

.Latt_slow_1:
	v_lshrrev_b32_e32 v246, 8, v220
	s_nop 0
	v_readfirstlane_b32 s100, v246
	s_nop 0
	s_cmp_eq_u32 s100, 0
	s_cbranch_scc1 .Latt_slow2_1
	s_cmp_eq_u32 s4, 0
	s_cbranch_scc1 .Latt_slow2_1
	s_add_i32 s99, s33, 2
	s_sub_i32 s101, s99, 3
	s_cmp_lt_u32 s99, 3
	s_cselect_b32 s99, s99, s101
	s_lshl_b32 s99, s99, 15
	s_add_i32 s99, s99, 0xc000
	v_bfe_u32 v246, v204, 2, 2
	v_bfe_u32 v247, v204, 5, 1
	v_lshl_or_b32 v247, v247, 2, v246
	v_and_b32_e32 v249, 3, v204
	v_and_b32_e32 v254, 16, v204
	v_lshl_or_b32 v249, v249, 2, v254
	v_lshlrev_b32_e32 v249, 1, v249
	v_lshl_add_u32 v247, v247, 9, v249
	v_add_u32_e32 v247, s99, v247
	v_lshlrev_b32_e32 v246, 6, v246
	v_add_u32_e32 v205, v247, v246
	v_xor_b32_e32 v249, 64, v246
	v_add_u32_e32 v218, v247, v249
	v_xor_b32_e32 v249, 0x80, v246
	v_add_u32_e32 v219, v247, v249
	v_xor_b32_e32 v249, 0xc0, v246
	v_add_u32_e32 v221, v247, v249
	ds_read_b64_tr_b16 v[206:207], v205 offset:16384
	ds_read_b64_tr_b16 v[208:209], v205 offset:20480
	ds_read_b64_tr_b16 v[210:211], v218 offset:16384
	ds_read_b64_tr_b16 v[212:213], v218 offset:20480
	ds_read_b64_tr_b16 v[214:215], v219 offset:16384
	ds_read_b64_tr_b16 v[216:217], v219 offset:20480
	ds_read_b64_tr_b16 v[238:239], v221 offset:16384
	ds_read_b64_tr_b16 v[240:241], v221 offset:20480
	ds_read_b64_tr_b16 v[222:223], v205 offset:16640
	ds_read_b64_tr_b16 v[224:225], v205 offset:20736
	s_waitcnt lgkmcnt(8)
	v_mfma_f32_32x32x16_bf16 v[112:127], v[206:209], v[242:245], v[112:127]
	ds_read_b64_tr_b16 v[206:207], v218 offset:16640
	ds_read_b64_tr_b16 v[208:209], v218 offset:20736
	s_waitcnt lgkmcnt(8)
	v_mfma_f32_32x32x16_bf16 v[96:111], v[210:213], v[242:245], v[96:111]
	ds_read_b64_tr_b16 v[210:211], v219 offset:16640
	ds_read_b64_tr_b16 v[212:213], v219 offset:20736
	s_waitcnt lgkmcnt(8)
	v_mfma_f32_32x32x16_bf16 v[80:95], v[214:217], v[242:245], v[80:95]
	ds_read_b64_tr_b16 v[214:215], v221 offset:16640
	ds_read_b64_tr_b16 v[216:217], v221 offset:20736
	s_waitcnt lgkmcnt(8)
	v_mfma_f32_32x32x16_bf16 v[64:79], v[238:241], v[242:245], v[64:79]
	ds_read_b64_tr_b16 v[238:239], v205 offset:24576
	ds_read_b64_tr_b16 v[240:241], v205 offset:28672
	s_waitcnt lgkmcnt(8)
	v_mfma_f32_32x32x16_bf16 v[48:63], v[222:225], v[242:245], v[48:63]
	ds_read_b64_tr_b16 v[222:223], v218 offset:24576
	ds_read_b64_tr_b16 v[224:225], v218 offset:28672
	s_waitcnt lgkmcnt(8)
	v_mfma_f32_32x32x16_bf16 v[32:47], v[206:209], v[242:245], v[32:47]
	ds_read_b64_tr_b16 v[206:207], v219 offset:24576
	ds_read_b64_tr_b16 v[208:209], v219 offset:28672
	s_waitcnt lgkmcnt(8)
	v_mfma_f32_32x32x16_bf16 v[16:31], v[210:213], v[242:245], v[16:31]
	ds_read_b64_tr_b16 v[210:211], v221 offset:24576
	ds_read_b64_tr_b16 v[212:213], v221 offset:28672
	s_waitcnt lgkmcnt(8)
	v_mfma_f32_32x32x16_bf16 v[0:15], v[214:217], v[242:245], v[0:15]
	ds_read_b64_tr_b16 v[214:215], v205 offset:24832
	ds_read_b64_tr_b16 v[216:217], v205 offset:28928
	s_waitcnt lgkmcnt(8)
	v_mfma_f32_32x32x16_bf16 v[112:127], v[238:241], v[250:253], v[112:127]
	ds_read_b64_tr_b16 v[238:239], v218 offset:24832
	ds_read_b64_tr_b16 v[240:241], v218 offset:28928
	s_waitcnt lgkmcnt(8)
	v_mfma_f32_32x32x16_bf16 v[96:111], v[222:225], v[250:253], v[96:111]
	ds_read_b64_tr_b16 v[222:223], v219 offset:24832
	ds_read_b64_tr_b16 v[224:225], v219 offset:28928
	s_waitcnt lgkmcnt(8)
	v_mfma_f32_32x32x16_bf16 v[80:95], v[206:209], v[250:253], v[80:95]
	ds_read_b64_tr_b16 v[206:207], v221 offset:24832
	ds_read_b64_tr_b16 v[208:209], v221 offset:28928
	s_waitcnt lgkmcnt(8)
	v_mfma_f32_32x32x16_bf16 v[64:79], v[210:213], v[250:253], v[64:79]
	s_waitcnt lgkmcnt(6)
	v_mfma_f32_32x32x16_bf16 v[48:63], v[214:217], v[250:253], v[48:63]
	s_waitcnt lgkmcnt(4)
	v_mfma_f32_32x32x16_bf16 v[32:47], v[238:241], v[250:253], v[32:47]
	s_waitcnt lgkmcnt(2)
	v_mfma_f32_32x32x16_bf16 v[16:31], v[222:225], v[250:253], v[16:31]
	s_waitcnt lgkmcnt(0)
	v_mfma_f32_32x32x16_bf16 v[0:15], v[206:209], v[250:253], v[0:15]

.LBB0_879:
	s_andn2_b64 vcc, exec, s[18:19]
	s_cbranch_vccnz .LBB0_863
	s_waitcnt vmcnt(0)
	s_branch .LBB0_863
.LBB0_881:
	ds_bpermute_b32 v138, v194, v195
	v_mov_b32_e32 v153, v176
	v_mov_b32_e32 v149, s81
	v_lshlrev_b32_e32 v128, 4, v153
	v_and_b32_e32 v178, 0x3f0, v128
	v_lshl_add_u64 v[136:137], s[14:15], 0, v[178:179]
	s_waitcnt lgkmcnt(0)
	v_add_f32_e32 v152, v195, v138
	v_add_co_u32_e32 v138, vcc, s73, v136
	global_load_dwordx4 v[132:135], v178, s[14:15]
	global_load_dwordx4 v[128:131], v178, s[14:15] offset:1024
	global_load_dwordx4 v[144:147], v178, s[14:15] offset:2048
	global_load_dwordx4 v[140:143], v178, s[14:15] offset:3072
	v_addc_co_u32_e32 v139, vcc, 0, v137, vcc
	v_add_co_u32_e32 v150, vcc, s74, v136
	v_rcp_f32_e32 v152, v152
	s_nop 0
	v_addc_co_u32_e32 v151, vcc, 0, v137, vcc
	v_add_co_u32_e32 v154, vcc, s75, v136
	v_mul_f32_e32 v152, v177, v152
	s_nop 0
	v_addc_co_u32_e32 v155, vcc, 0, v137, vcc
	global_load_dwordx4 v[196:199], v[150:151], off offset:-4096
	global_load_dwordx4 v[200:203], v[138:139], off offset:1024
	global_load_dwordx4 v[204:207], v[138:139], off offset:2048
	global_load_dwordx4 v[208:211], v[138:139], off offset:3072
	s_nop 0
	global_load_dwordx4 v[136:139], v[154:155], off offset:3072
	v_and_or_b32 v148, v153, 31, s80
	s_lshl_b32 s4, s79, 1
	s_and_b32 s12, s77, 7
	s_lshl_b32 s79, s12, 8
	v_readfirstlane_b32 s12, v176
	s_ashr_i32 s86, s12, 6
	s_lshl_b32 s12, s78, 8
	s_lshl_b32 s13, s86, 5
	s_lshl_b32 s78, s78, 2
	s_add_i32 s80, s13, s12
	s_addk_i32 s79, 0x100
	s_add_i32 s78, s78, 4
	s_or_b32 s81, s80, 31
	s_lshl_b32 s83, s86, 3
	s_lshl_b32 s82, s86, 11
	s_lshl_b32 s33, s86, 12
	s_or_b32 s12, s40, s12
	s_ashr_i32 s14, s13, 31
	s_add_u32 s18, s12, s13
	s_addc_u32 s19, s41, s14
	s_cmp_lg_u32 0, -1
	s_cselect_b32 s12, 0, 0
	s_add_i32 s13, s12, 0xc000
	s_mov_b32 s84, 0
	s_mov_b32 s85, 2
	s_add_i32 s40, s82, s12
	s_add_i32 s41, s33, s13
	s_waitcnt vmcnt(8)
	v_lshlrev_b32_e32 v157, 16, v133
	v_lshlrev_b32_e32 v159, 16, v135
	s_waitcnt vmcnt(6)
	v_lshlrev_b32_e32 v164, 16, v144
	v_and_b32_e32 v144, 0xffff0000, v144
	v_lshlrev_b32_e32 v165, 16, v145
	v_lshlrev_b32_e32 v162, 16, v130
	v_and_b32_e32 v145, 0xffff0000, v145
	v_lshlrev_b32_e32 v168, 16, v146
	v_lshlrev_b32_e32 v169, 16, v147
	v_and_b32_e32 v147, 0xffff0000, v147
	v_fma_f32 v171, -v96, v152, v164
	v_fma_f32 v170, -v97, v152, v144
	v_fma_f32 v167, -v98, v152, v165
	s_waitcnt vmcnt(4)
	v_lshlrev_b32_e32 v96, 16, v196
	v_and_b32_e32 v97, 0xffff0000, v196
	v_lshlrev_b32_e32 v98, 16, v197
	v_fma_f32 v212, -v114, v152, v157
	v_fma_f32 v185, -v118, v152, v159
	v_fma_f32 v175, -v124, v152, v162
	v_fma_f32 v166, -v99, v152, v145
	v_fma_f32 v162, -v100, v152, v168
	v_fma_f32 v168, -v103, v152, v147
	v_fma_f32 v159, -v80, v152, v96
	v_fma_f32 v157, -v81, v152, v97
	v_fma_f32 v147, -v82, v152, v98
	global_load_dwordx4 v[96:99], v[150:151], off
	v_lshlrev_b32_e32 v160, 16, v128
	v_and_b32_e32 v146, 0xffff0000, v146
	v_lshlrev_b32_e32 v156, 16, v132
	v_lshlrev_b32_e32 v178, 16, v140
	v_lshlrev_b32_e32 v188, 16, v142
	v_and_b32_e32 v142, 0xffff0000, v142
	v_lshlrev_b32_e32 v189, 16, v143
	v_and_b32_e32 v143, 0xffff0000, v143
	v_fma_f32 v183, -v120, v152, v160
	v_fma_f32 v160, -v101, v152, v146
	v_fma_f32 v169, -v102, v152, v169
	v_lshlrev_b32_e32 v101, 16, v198
	v_and_b32_e32 v102, 0xffff0000, v198
	v_lshlrev_b32_e32 v161, 16, v129
	v_and_b32_e32 v130, 0xffff0000, v130
	v_lshlrev_b32_e32 v163, 16, v131
	v_and_b32_e32 v131, 0xffff0000, v131
	v_and_b32_e32 v140, 0xffff0000, v140
	v_lshlrev_b32_e32 v187, 16, v141
	v_and_b32_e32 v141, 0xffff0000, v141
	v_fma_f32 v190, -v112, v152, v156
	v_fma_f32 v165, -v104, v152, v178
	v_fma_f32 v156, -v109, v152, v142
	v_fma_f32 v144, -v111, v152, v143
	v_lshlrev_b32_e32 v103, 16, v199
	v_and_b32_e32 v104, 0xffff0000, v199
	v_fma_f32 v143, -v84, v152, v101
	v_fma_f32 v142, -v85, v152, v102
	s_waitcnt vmcnt(3)
	v_lshlrev_b32_e32 v84, 16, v204
	v_and_b32_e32 v85, 0xffff0000, v204
	v_fma_f32 v181, -v122, v152, v161
	v_fma_f32 v174, -v125, v152, v130
	v_fma_f32 v172, -v127, v152, v131
	v_fma_f32 v164, -v105, v152, v140
	v_fma_f32 v161, -v107, v152, v141
	v_fma_f32 v141, -v86, v152, v103
	v_fma_f32 v140, -v87, v152, v104
	v_fma_f32 v131, -v64, v152, v84
	v_fma_f32 v130, -v65, v152, v85
	global_load_dwordx4 v[84:87], v[150:151], off offset:2048
	v_and_b32_e32 v100, 0xffff0000, v197
	v_fma_f32 v146, -v83, v152, v100
	global_load_dwordx4 v[80:83], v[150:151], off offset:1024
	v_and_b32_e32 v132, 0xffff0000, v132
	v_fma_f32 v195, -v113, v152, v132
	v_mul_f32_e32 v215, v195, v195
	v_and_b32_e32 v133, 0xffff0000, v133
	v_fmac_f32_e32 v215, v190, v190
	v_lshlrev_b32_e32 v158, 16, v134
	v_fma_f32 v213, -v115, v152, v133
	v_fmac_f32_e32 v215, v212, v212
	v_and_b32_e32 v134, 0xffff0000, v134
	v_fma_f32 v214, -v116, v152, v158
	v_fmac_f32_e32 v215, v213, v213
	v_and_b32_e32 v135, 0xffff0000, v135
	v_fma_f32 v186, -v117, v152, v134
	v_fma_f32 v173, -v126, v152, v163
	v_fmac_f32_e32 v215, v214, v214
	v_fma_f32 v163, -v106, v152, v187
	v_lshlrev_b32_e32 v105, 16, v200
	v_and_b32_e32 v106, 0xffff0000, v200
	v_and_b32_e32 v128, 0xffff0000, v128
	v_fma_f32 v184, -v119, v152, v135
	v_fmac_f32_e32 v215, v186, v186
	v_fma_f32 v135, -v88, v152, v105
	v_fma_f32 v134, -v89, v152, v106
	v_lshlrev_b32_e32 v88, 16, v205
	v_and_b32_e32 v89, 0xffff0000, v205
	v_fma_f32 v182, -v121, v152, v128
	v_fmac_f32_e32 v215, v185, v185
	v_fma_f32 v128, -v66, v152, v88
	v_fma_f32 v126, -v67, v152, v89
	global_load_dwordx4 v[64:67], v[150:151], off offset:3072
	v_fmac_f32_e32 v215, v184, v184
	v_fmac_f32_e32 v215, v183, v183
	v_and_b32_e32 v129, 0xffff0000, v129
	v_fmac_f32_e32 v215, v182, v182
	v_fma_f32 v180, -v123, v152, v129
	v_fmac_f32_e32 v215, v181, v181
	v_fmac_f32_e32 v215, v180, v180
	v_fmac_f32_e32 v215, v175, v175
	v_fmac_f32_e32 v215, v174, v174
	v_fmac_f32_e32 v215, v173, v173
	global_load_dwordx4 v[196:199], v[154:155], off
	v_fmac_f32_e32 v215, v172, v172
	v_fmac_f32_e32 v215, v171, v171
	v_fmac_f32_e32 v215, v170, v170
	v_fmac_f32_e32 v215, v167, v167
	v_fmac_f32_e32 v215, v166, v166
	v_fma_f32 v158, -v108, v152, v188
	v_fma_f32 v145, -v110, v152, v189
	v_lshlrev_b32_e32 v107, 16, v201
	v_and_b32_e32 v108, 0xffff0000, v201
	v_lshlrev_b32_e32 v109, 16, v202
	v_and_b32_e32 v110, 0xffff0000, v202
	v_fmac_f32_e32 v215, v162, v162
	v_fma_f32 v133, -v90, v152, v107
	v_fma_f32 v132, -v91, v152, v108
	v_fma_f32 v129, -v92, v152, v109
	v_fma_f32 v127, -v93, v152, v110
	v_lshlrev_b32_e32 v90, 16, v206
	v_and_b32_e32 v91, 0xffff0000, v206
	v_lshlrev_b32_e32 v92, 16, v207
	v_and_b32_e32 v93, 0xffff0000, v207
	v_fmac_f32_e32 v215, v160, v160
	v_lshlrev_b32_e32 v111, 16, v203
	v_fma_f32 v123, -v68, v152, v90
	v_fma_f32 v122, -v69, v152, v91
	v_fma_f32 v121, -v70, v152, v92
	v_fma_f32 v120, -v71, v152, v93
	s_waitcnt vmcnt(4)
	v_lshlrev_b32_e32 v68, 16, v96
	v_and_b32_e32 v69, 0xffff0000, v96
	v_lshlrev_b32_e32 v70, 16, v97
	v_and_b32_e32 v71, 0xffff0000, v97
	v_fmac_f32_e32 v215, v169, v169
	v_fma_f32 v125, -v94, v152, v111
	v_fma_f32 v115, -v48, v152, v68
	v_fma_f32 v113, -v49, v152, v69
	v_fma_f32 v111, -v50, v152, v70
	v_fma_f32 v109, -v51, v152, v71
	global_load_dwordx4 v[48:51], v[154:155], off offset:1024
	v_fmac_f32_e32 v215, v168, v168
	v_fmac_f32_e32 v215, v165, v165
	v_fmac_f32_e32 v215, v164, v164
	v_fmac_f32_e32 v215, v163, v163
	v_fmac_f32_e32 v215, v161, v161
	v_and_b32_e32 v112, 0xffff0000, v203
	v_lshlrev_b32_e32 v94, 16, v208
	v_fmac_f32_e32 v215, v158, v158
	v_fma_f32 v124, -v95, v152, v112
	v_and_b32_e32 v95, 0xffff0000, v208
	v_lshlrev_b32_e32 v100, 16, v209
	v_and_b32_e32 v101, 0xffff0000, v209
	v_fma_f32 v119, -v72, v152, v94
	v_lshlrev_b32_e32 v72, 16, v98
	v_fmac_f32_e32 v215, v156, v156
	v_lshlrev_b32_e32 v104, 16, v211
	v_and_b32_e32 v105, 0xffff0000, v211
	v_fma_f32 v118, -v73, v152, v95
	v_fma_f32 v117, -v74, v152, v100
	v_fma_f32 v116, -v75, v152, v101
	v_and_b32_e32 v73, 0xffff0000, v98
	v_lshlrev_b32_e32 v74, 16, v99
	v_and_b32_e32 v75, 0xffff0000, v99
	v_fma_f32 v107, -v52, v152, v72
	s_waitcnt vmcnt(4)
	v_lshlrev_b32_e32 v52, 16, v84
	v_fmac_f32_e32 v215, v145, v145
	v_fma_f32 v110, -v78, v152, v104
	v_fma_f32 v108, -v79, v152, v105
	v_fma_f32 v106, -v53, v152, v73
	v_fma_f32 v105, -v54, v152, v74
	v_fma_f32 v104, -v55, v152, v75
	v_fma_f32 v99, -v32, v152, v52
	global_load_dwordx4 v[52:55], v[154:155], off offset:2048
	v_fmac_f32_e32 v215, v144, v144
	v_fmac_f32_e32 v215, v159, v159
	v_fmac_f32_e32 v215, v157, v157
	v_fmac_f32_e32 v215, v147, v147
	v_fmac_f32_e32 v215, v146, v146
	v_fmac_f32_e32 v215, v143, v143
	v_fmac_f32_e32 v215, v142, v142
	v_fmac_f32_e32 v215, v141, v141
	v_fmac_f32_e32 v215, v140, v140
	v_fmac_f32_e32 v215, v135, v135
	v_fmac_f32_e32 v215, v134, v134
	v_fmac_f32_e32 v215, v133, v133
	v_fmac_f32_e32 v215, v132, v132
	v_fmac_f32_e32 v215, v129, v129
	v_fmac_f32_e32 v215, v127, v127
	v_fmac_f32_e32 v215, v125, v125
	v_fmac_f32_e32 v215, v124, v124
	v_fmac_f32_e32 v215, v131, v131
	v_fmac_f32_e32 v215, v130, v130
	v_fmac_f32_e32 v215, v128, v128
	v_fmac_f32_e32 v215, v126, v126
	v_fmac_f32_e32 v215, v123, v123
	v_fmac_f32_e32 v215, v122, v122
	v_fmac_f32_e32 v215, v121, v121
	v_fmac_f32_e32 v215, v120, v120
	v_fmac_f32_e32 v215, v119, v119
	v_fmac_f32_e32 v215, v118, v118
	v_lshlrev_b32_e32 v102, 16, v210
	v_fmac_f32_e32 v215, v117, v117
	v_and_b32_e32 v103, 0xffff0000, v210
	v_fmac_f32_e32 v215, v116, v116
	v_fma_f32 v114, -v76, v152, v102
	v_fmac_f32_e32 v215, v114, v114
	v_fma_f32 v112, -v77, v152, v103
	v_fmac_f32_e32 v215, v112, v112
	v_fmac_f32_e32 v215, v110, v110
	v_fmac_f32_e32 v215, v108, v108
	v_fmac_f32_e32 v215, v115, v115
	v_fmac_f32_e32 v215, v113, v113
	v_fmac_f32_e32 v215, v111, v111
	v_fmac_f32_e32 v215, v109, v109
	v_fmac_f32_e32 v215, v107, v107
	v_fmac_f32_e32 v215, v106, v106
	s_waitcnt vmcnt(4)
	v_lshlrev_b32_e32 v76, 16, v80
	v_fmac_f32_e32 v215, v105, v105
	v_and_b32_e32 v77, 0xffff0000, v80
	v_fmac_f32_e32 v215, v104, v104
	v_fma_f32 v103, -v56, v152, v76
	v_lshlrev_b32_e32 v78, 16, v81
	v_fmac_f32_e32 v215, v103, v103
	v_fma_f32 v102, -v57, v152, v77
	v_and_b32_e32 v79, 0xffff0000, v81
	v_fmac_f32_e32 v215, v102, v102
	v_fma_f32 v101, -v58, v152, v78
	v_lshlrev_b32_e32 v80, 16, v82
	v_fmac_f32_e32 v215, v101, v101
	v_fma_f32 v100, -v59, v152, v79
	v_and_b32_e32 v81, 0xffff0000, v82
	v_fmac_f32_e32 v215, v100, v100
	v_fma_f32 v96, -v60, v152, v80
	v_lshlrev_b32_e32 v82, 16, v83
	v_fmac_f32_e32 v215, v96, v96
	v_fma_f32 v95, -v61, v152, v81
	v_and_b32_e32 v83, 0xffff0000, v83
	v_fmac_f32_e32 v215, v95, v95
	v_fma_f32 v92, -v62, v152, v82
	v_fmac_f32_e32 v215, v92, v92
	v_fma_f32 v91, -v63, v152, v83
	v_fmac_f32_e32 v215, v91, v91
	v_and_b32_e32 v56, 0xffff0000, v84
	v_lshlrev_b32_e32 v57, 16, v85
	v_fmac_f32_e32 v215, v99, v99
	v_fma_f32 v97, -v33, v152, v56
	v_and_b32_e32 v58, 0xffff0000, v85
	v_fmac_f32_e32 v215, v97, v97
	v_fma_f32 v94, -v34, v152, v57
	v_lshlrev_b32_e32 v59, 16, v86
	v_fmac_f32_e32 v215, v94, v94
	v_fma_f32 v93, -v35, v152, v58
	v_and_b32_e32 v60, 0xffff0000, v86
	v_fmac_f32_e32 v215, v93, v93
	v_fma_f32 v89, -v36, v152, v59
	v_lshlrev_b32_e32 v61, 16, v87
	v_fmac_f32_e32 v215, v89, v89
	v_fma_f32 v88, -v37, v152, v60
	v_and_b32_e32 v62, 0xffff0000, v87
	v_fmac_f32_e32 v215, v88, v88
	v_fma_f32 v87, -v38, v152, v61
	s_waitcnt vmcnt(3)
	v_lshlrev_b32_e32 v63, 16, v64
	v_fmac_f32_e32 v215, v87, v87
	v_fma_f32 v86, -v39, v152, v62
	v_and_b32_e32 v64, 0xffff0000, v64
	v_fmac_f32_e32 v215, v86, v86
	v_fma_f32 v85, -v40, v152, v63
	v_lshlrev_b32_e32 v68, 16, v65
	v_fmac_f32_e32 v215, v85, v85
	v_fma_f32 v84, -v41, v152, v64
	v_and_b32_e32 v65, 0xffff0000, v65
	v_fmac_f32_e32 v215, v84, v84
	v_fma_f32 v83, -v42, v152, v68
	v_lshlrev_b32_e32 v69, 16, v66
	v_fmac_f32_e32 v215, v83, v83
	v_fma_f32 v82, -v43, v152, v65
	v_and_b32_e32 v66, 0xffff0000, v66
	v_fmac_f32_e32 v215, v82, v82
	v_fma_f32 v80, -v44, v152, v69
	v_lshlrev_b32_e32 v70, 16, v67
	v_fmac_f32_e32 v215, v80, v80
	v_fma_f32 v78, -v45, v152, v66
	v_and_b32_e32 v67, 0xffff0000, v67
	v_fmac_f32_e32 v215, v78, v78
	v_fma_f32 v76, -v46, v152, v70
	v_fmac_f32_e32 v215, v76, v76
	v_fma_f32 v74, -v47, v152, v67
	s_waitcnt vmcnt(2)
	v_lshlrev_b32_e32 v32, 16, v196
	v_fmac_f32_e32 v215, v74, v74
	v_and_b32_e32 v33, 0xffff0000, v196
	v_fma_f32 v81, -v16, v152, v32
	v_lshlrev_b32_e32 v34, 16, v197
	v_fmac_f32_e32 v215, v81, v81
	v_fma_f32 v79, -v17, v152, v33
	v_and_b32_e32 v35, 0xffff0000, v197
	v_fmac_f32_e32 v215, v79, v79
	v_fma_f32 v77, -v18, v152, v34
	v_lshlrev_b32_e32 v36, 16, v198
	v_fmac_f32_e32 v215, v77, v77
	v_fma_f32 v75, -v19, v152, v35
	v_and_b32_e32 v37, 0xffff0000, v198
	v_fmac_f32_e32 v215, v75, v75
	v_fma_f32 v73, -v20, v152, v36
	v_lshlrev_b32_e32 v38, 16, v199
	v_fmac_f32_e32 v215, v73, v73
	v_fma_f32 v72, -v21, v152, v37
	v_and_b32_e32 v39, 0xffff0000, v199
	v_fmac_f32_e32 v215, v72, v72
	v_fma_f32 v71, -v22, v152, v38
	s_waitcnt vmcnt(1)
	v_lshlrev_b32_e32 v40, 16, v48
	v_fmac_f32_e32 v215, v71, v71
	v_fma_f32 v70, -v23, v152, v39
	v_and_b32_e32 v41, 0xffff0000, v48
	v_fmac_f32_e32 v215, v70, v70
	v_fma_f32 v69, -v24, v152, v40
	v_lshlrev_b32_e32 v42, 16, v49
	v_fmac_f32_e32 v215, v69, v69
	v_fma_f32 v68, -v25, v152, v41
	v_and_b32_e32 v43, 0xffff0000, v49
	v_fmac_f32_e32 v215, v68, v68
	v_fma_f32 v67, -v26, v152, v42
	v_lshlrev_b32_e32 v44, 16, v50
	v_fmac_f32_e32 v215, v67, v67
	v_fma_f32 v66, -v27, v152, v43
	v_and_b32_e32 v45, 0xffff0000, v50
	v_fmac_f32_e32 v215, v66, v66
	v_fma_f32 v65, -v28, v152, v44
	v_lshlrev_b32_e32 v46, 16, v51
	v_fmac_f32_e32 v215, v65, v65
	v_fma_f32 v64, -v29, v152, v45
	v_and_b32_e32 v47, 0xffff0000, v51
	v_fmac_f32_e32 v215, v64, v64
	v_fma_f32 v63, -v30, v152, v46
	v_fmac_f32_e32 v215, v63, v63
	v_fma_f32 v62, -v31, v152, v47
	s_waitcnt vmcnt(0)
	v_lshlrev_b32_e32 v16, 16, v52
	v_fmac_f32_e32 v215, v62, v62
	v_and_b32_e32 v17, 0xffff0000, v52
	v_fma_f32 v61, -v0, v152, v16
	v_lshlrev_b32_e32 v18, 16, v53
	v_lshlrev_b32_e32 v20, 16, v54
	v_and_b32_e32 v21, 0xffff0000, v54
	v_fmac_f32_e32 v215, v61, v61
	v_fma_f32 v60, -v1, v152, v17
	v_and_b32_e32 v1, 0xffff0000, v55
	v_lshlrev_b32_e32 v0, 16, v55
	v_and_b32_e32 v19, 0xffff0000, v53
	v_fmac_f32_e32 v215, v60, v60
	v_fma_f32 v59, -v2, v152, v18
	v_fma_f32 v57, -v4, v152, v20
	v_fma_f32 v56, -v5, v152, v21
	v_pk_fma_f32 v[0:1], v[6:7], v[152:153], v[0:1] op_sel_hi:[1,0,1] neg_lo:[1,0,0] neg_hi:[1,0,0]
	v_lshlrev_b64 v[4:5], 14, v[148:149]
	v_lshrrev_b32_e32 v6, 3, v153
	v_fmac_f32_e32 v215, v59, v59
	v_fma_f32 v58, -v3, v152, v19
	v_lshl_add_u64 v[4:5], s[2:3], 0, v[4:5]
	v_and_b32_e32 v90, 4, v6
	v_fmac_f32_e32 v215, v58, v58
	v_lshl_add_u64 v[4:5], v[4:5], 0, s[4:5]
	v_lshlrev_b32_e32 v178, 1, v90
	v_fmac_f32_e32 v215, v57, v57
	v_lshl_add_u64 v[4:5], v[4:5], 0, v[178:179]
	v_fmac_f32_e32 v215, v56, v56
	v_pk_mul_f32 v[2:3], v[0:1], v[0:1]
	v_add_co_u32_e32 v148, vcc, s75, v4
	v_add_f32_e32 v2, v2, v215
	s_waitcnt vmcnt(0)
	s_nop 0
	v_addc_co_u32_e32 v149, vcc, 0, v5, vcc
	global_load_dwordx2 v[150:151], v[148:149], off
	v_add_f32_e32 v6, v3, v2
	v_and_b32_e32 v3, 0xffff0000, v136
	v_lshlrev_b32_e32 v2, 16, v136
	v_pk_fma_f32 v[16:17], v[8:9], v[152:153], v[2:3] op_sel_hi:[1,0,1] neg_lo:[1,0,0] neg_hi:[1,0,0]
	s_nop 0
	v_pk_mul_f32 v[2:3], v[16:17], v[16:17]
	s_nop 0
	v_add_f32_e32 v2, v2, v6
	v_add_f32_e32 v6, v3, v2
	v_and_b32_e32 v3, 0xffff0000, v137
	v_lshlrev_b32_e32 v2, 16, v137
	v_pk_fma_f32 v[8:9], v[10:11], v[152:153], v[2:3] op_sel_hi:[1,0,1] neg_lo:[1,0,0] neg_hi:[1,0,0]
	v_and_b32_e32 v11, 0xffff0000, v139
	v_pk_mul_f32 v[2:3], v[8:9], v[8:9]
	s_nop 0
	v_add_f32_e32 v2, v2, v6
	v_add_f32_e32 v10, v3, v2
	v_and_b32_e32 v3, 0xffff0000, v138
	v_lshlrev_b32_e32 v2, 16, v138
	v_pk_fma_f32 v[6:7], v[12:13], v[152:153], v[2:3] op_sel_hi:[1,0,1] neg_lo:[1,0,0] neg_hi:[1,0,0]
	s_nop 0
	v_pk_mul_f32 v[2:3], v[6:7], v[6:7]
	s_nop 0
	v_add_f32_e32 v2, v2, v10
	v_add_f32_e32 v12, v3, v2
	v_lshl_add_u64 v[2:3], v[4:5], 0, s[6:7]
	global_load_dwordx2 v[154:155], v[2:3], off offset:16
	v_lshlrev_b32_e32 v10, 16, v139
	v_pk_fma_f32 v[4:5], v[14:15], v[152:153], v[10:11] op_sel_hi:[1,0,1] neg_lo:[1,0,0] neg_hi:[1,0,0]
	global_load_dwordx2 v[152:153], v[2:3], off offset:32
	global_load_dwordx2 v[188:189], v[2:3], off offset:48
	global_load_dwordx2 v[196:197], v[2:3], off offset:64
	global_load_dwordx2 v[198:199], v[2:3], off offset:80
	global_load_dwordx2 v[200:201], v[2:3], off offset:96
	global_load_dwordx2 v[202:203], v[2:3], off offset:112
	global_load_dwordx2 v[204:205], v[2:3], off offset:128
	global_load_dwordx2 v[206:207], v[2:3], off offset:144
	global_load_dwordx2 v[54:55], v[2:3], off offset:160
	global_load_dwordx2 v[52:53], v[2:3], off offset:176
	global_load_dwordx2 v[50:51], v[2:3], off offset:192
	global_load_dwordx2 v[48:49], v[2:3], off offset:208
	global_load_dwordx2 v[46:47], v[2:3], off offset:224
	global_load_dwordx2 v[44:45], v[2:3], off offset:240
	global_load_dwordx2 v[42:43], v[2:3], off offset:256
	global_load_dwordx2 v[40:41], v[2:3], off offset:272
	global_load_dwordx2 v[38:39], v[2:3], off offset:288
	global_load_dwordx2 v[36:37], v[2:3], off offset:304
	global_load_dwordx2 v[34:35], v[2:3], off offset:320
	global_load_dwordx2 v[32:33], v[2:3], off offset:336
	global_load_dwordx2 v[30:31], v[2:3], off offset:352
	global_load_dwordx2 v[28:29], v[2:3], off offset:368
	global_load_dwordx2 v[26:27], v[2:3], off offset:384
	global_load_dwordx2 v[24:25], v[2:3], off offset:400
	global_load_dwordx2 v[22:23], v[2:3], off offset:416
	global_load_dwordx2 v[20:21], v[2:3], off offset:432
	global_load_dwordx2 v[18:19], v[2:3], off offset:448
	v_pk_mul_f32 v[10:11], v[4:5], v[4:5]
	s_nop 0
	v_add_f32_e32 v10, v10, v12
	v_add_f32_e32 v10, v11, v10
	ds_bpermute_b32 v11, v194, v10
	s_waitcnt lgkmcnt(0)
	v_add_f32_e32 v10, v10, v11
	v_fmamk_f32 v10, v10, 0x3b800000, v191
	v_mul_f32_e32 v11, 0x4b800000, v10
	v_cmp_gt_f32_e32 vcc, s76, v10
	s_nop 1
	v_cndmask_b32_e32 v10, v10, v11, vcc
	v_rsq_f32_e32 v10, v10
	s_nop 0
	v_mul_f32_e32 v11, 0x45800000, v10
	v_cndmask_b32_e32 v178, v10, v11, vcc
	v_lshl_add_u32 v10, v90, 2, 0
	v_add_u32_e32 v98, 0x24000, v10
	ds_read_b128 v[136:139], v98
	v_mul_f32_e32 v90, 0x3f24fd5c, v178
	v_mul_f32_e32 v178, v190, v90
	global_load_dwordx2 v[14:15], v[2:3], off offset:464
	global_load_dwordx2 v[12:13], v[2:3], off offset:480
	global_load_dwordx2 v[10:11], v[2:3], off offset:496
	v_mul_f32_e32 v143, v143, v90
	s_waitcnt lgkmcnt(0)
	v_mul_f32_e32 v136, v136, v178
	v_mul_f32_e32 v142, v142, v90
	v_mul_f32_e32 v135, v135, v90
	v_mul_f32_e32 v134, v134, v90
	v_mul_f32_e32 v133, v133, v90
	v_mul_f32_e32 v132, v132, v90
	v_mul_f32_e32 v0, v0, v90
	v_mul_f32_e32 v1, v1, v90
	s_waitcnt vmcnt(31)
	v_lshlrev_b32_e32 v178, 16, v150
	v_mul_f32_e32 v136, v136, v178
	v_mul_f32_e32 v178, v195, v90
	v_mul_f32_e32 v137, v137, v178
	v_and_b32_e32 v150, 0xffff0000, v150
	v_mul_f32_e32 v137, v137, v150
	v_cvt_pk_bf16_f32 v150, v136, v137
	v_mul_f32_e32 v136, v212, v90
	v_mul_f32_e32 v136, v138, v136
	v_lshlrev_b32_e32 v137, 16, v151
	v_mul_f32_e32 v136, v136, v137
	v_mul_f32_e32 v137, v213, v90
	v_mul_f32_e32 v137, v139, v137
	v_and_b32_e32 v138, 0xffff0000, v151
	v_mul_f32_e32 v137, v137, v138
	v_cvt_pk_bf16_f32 v151, v136, v137
	ds_read_b128 v[136:139], v98 offset:32
	global_store_dwordx2 v[148:149], v[150:151], off
	v_mul_f32_e32 v148, v214, v90
	s_waitcnt lgkmcnt(0)
	v_mul_f32_e32 v136, v136, v148
	s_waitcnt vmcnt(31)
	v_lshlrev_b32_e32 v148, 16, v154
	v_mul_f32_e32 v136, v136, v148
	v_mul_f32_e32 v148, v186, v90
	v_mul_f32_e32 v137, v137, v148
	v_and_b32_e32 v148, 0xffff0000, v154
	v_mul_f32_e32 v137, v137, v148
	v_cvt_pk_bf16_f32 v148, v136, v137
	v_mul_f32_e32 v136, v185, v90
	v_mul_f32_e32 v136, v138, v136
	v_lshlrev_b32_e32 v137, 16, v155
	v_mul_f32_e32 v136, v136, v137
	v_mul_f32_e32 v137, v184, v90
	v_mul_f32_e32 v137, v139, v137
	v_and_b32_e32 v138, 0xffff0000, v155
	v_mul_f32_e32 v137, v137, v138
	v_cvt_pk_bf16_f32 v149, v136, v137
	ds_read_b128 v[136:139], v98 offset:64
	global_store_dwordx2 v[2:3], v[148:149], off offset:16
	v_mul_f32_e32 v148, v183, v90
	s_waitcnt lgkmcnt(0)
	v_mul_f32_e32 v136, v136, v148
	s_waitcnt vmcnt(31)
	v_lshlrev_b32_e32 v148, 16, v152
	v_mul_f32_e32 v136, v136, v148
	v_mul_f32_e32 v148, v182, v90
	v_mul_f32_e32 v137, v137, v148
	v_and_b32_e32 v148, 0xffff0000, v152
	v_mul_f32_e32 v137, v137, v148
	v_cvt_pk_bf16_f32 v148, v136, v137
	v_mul_f32_e32 v136, v181, v90
	v_mul_f32_e32 v136, v138, v136
	v_lshlrev_b32_e32 v137, 16, v153
	v_mul_f32_e32 v136, v136, v137
	v_mul_f32_e32 v137, v180, v90
	v_mul_f32_e32 v137, v139, v137
	v_and_b32_e32 v138, 0xffff0000, v153
	v_mul_f32_e32 v137, v137, v138
	v_cvt_pk_bf16_f32 v149, v136, v137
	ds_read_b128 v[136:139], v98 offset:96
	global_store_dwordx2 v[2:3], v[148:149], off offset:32
	v_mul_f32_e32 v148, v175, v90
	s_waitcnt lgkmcnt(0)
	v_mul_f32_e32 v136, v136, v148
	s_waitcnt vmcnt(31)
	v_lshlrev_b32_e32 v148, 16, v188
	v_mul_f32_e32 v136, v136, v148
	v_mul_f32_e32 v148, v174, v90
	v_mul_f32_e32 v137, v137, v148
	v_and_b32_e32 v148, 0xffff0000, v188
	v_mul_f32_e32 v137, v137, v148
	v_cvt_pk_bf16_f32 v148, v136, v137
	v_mul_f32_e32 v136, v173, v90
	v_mul_f32_e32 v136, v138, v136
	v_lshlrev_b32_e32 v137, 16, v189
	v_mul_f32_e32 v136, v136, v137
	v_mul_f32_e32 v137, v172, v90
	v_mul_f32_e32 v137, v139, v137
	v_and_b32_e32 v138, 0xffff0000, v189
	v_mul_f32_e32 v137, v137, v138
	v_cvt_pk_bf16_f32 v149, v136, v137
	ds_read_b128 v[136:139], v98 offset:128
	global_store_dwordx2 v[2:3], v[148:149], off offset:48
	v_mul_f32_e32 v148, v171, v90
	s_waitcnt lgkmcnt(0)
	v_mul_f32_e32 v136, v136, v148
	s_waitcnt vmcnt(31)
	v_lshlrev_b32_e32 v148, 16, v196
	v_mul_f32_e32 v136, v136, v148
	v_mul_f32_e32 v148, v170, v90
	v_mul_f32_e32 v137, v137, v148
	v_and_b32_e32 v148, 0xffff0000, v196
	v_mul_f32_e32 v137, v137, v148
	v_cvt_pk_bf16_f32 v148, v136, v137
	v_mul_f32_e32 v136, v167, v90
	v_mul_f32_e32 v136, v138, v136
	v_lshlrev_b32_e32 v137, 16, v197
	v_mul_f32_e32 v136, v136, v137
	v_mul_f32_e32 v137, v166, v90
	v_mul_f32_e32 v137, v139, v137
	v_and_b32_e32 v138, 0xffff0000, v197
	v_mul_f32_e32 v137, v137, v138
	v_cvt_pk_bf16_f32 v149, v136, v137
	ds_read_b128 v[136:139], v98 offset:160
	global_store_dwordx2 v[2:3], v[148:149], off offset:64
	v_mul_f32_e32 v148, v162, v90
	s_waitcnt lgkmcnt(0)
	v_mul_f32_e32 v136, v136, v148
	s_waitcnt vmcnt(31)
	v_lshlrev_b32_e32 v148, 16, v198
	v_mul_f32_e32 v136, v136, v148
	v_mul_f32_e32 v148, v160, v90
	v_mul_f32_e32 v137, v137, v148
	v_and_b32_e32 v148, 0xffff0000, v198
	v_mul_f32_e32 v137, v137, v148
	v_cvt_pk_bf16_f32 v148, v136, v137
	v_mul_f32_e32 v136, v169, v90
	v_mul_f32_e32 v136, v138, v136
	v_lshlrev_b32_e32 v137, 16, v199
	v_mul_f32_e32 v136, v136, v137
	v_mul_f32_e32 v137, v168, v90
	v_mul_f32_e32 v137, v139, v137
	v_and_b32_e32 v138, 0xffff0000, v199
	v_mul_f32_e32 v137, v137, v138
	v_cvt_pk_bf16_f32 v149, v136, v137
	ds_read_b128 v[136:139], v98 offset:192
	global_store_dwordx2 v[2:3], v[148:149], off offset:80
	v_mul_f32_e32 v148, v165, v90
	s_waitcnt lgkmcnt(0)
	v_mul_f32_e32 v136, v136, v148
	s_waitcnt vmcnt(31)
	v_lshlrev_b32_e32 v148, 16, v200
	v_mul_f32_e32 v136, v136, v148
	v_mul_f32_e32 v148, v164, v90
	v_mul_f32_e32 v137, v137, v148
	v_and_b32_e32 v148, 0xffff0000, v200
	v_mul_f32_e32 v137, v137, v148
	v_cvt_pk_bf16_f32 v148, v136, v137
	v_mul_f32_e32 v136, v163, v90
	v_mul_f32_e32 v136, v138, v136
	v_lshlrev_b32_e32 v137, 16, v201
	v_mul_f32_e32 v136, v136, v137
	v_mul_f32_e32 v137, v161, v90
	v_mul_f32_e32 v137, v139, v137
	v_and_b32_e32 v138, 0xffff0000, v201
	v_mul_f32_e32 v137, v137, v138
	v_cvt_pk_bf16_f32 v149, v136, v137
	ds_read_b128 v[136:139], v98 offset:224
	global_store_dwordx2 v[2:3], v[148:149], off offset:96
	v_mul_f32_e32 v148, v158, v90
	s_waitcnt lgkmcnt(0)
	v_mul_f32_e32 v136, v136, v148
	s_waitcnt vmcnt(31)
	v_lshlrev_b32_e32 v148, 16, v202
	v_mul_f32_e32 v136, v136, v148
	v_mul_f32_e32 v148, v156, v90
	v_mul_f32_e32 v137, v137, v148
	v_and_b32_e32 v148, 0xffff0000, v202
	v_mul_f32_e32 v137, v137, v148
	v_cvt_pk_bf16_f32 v148, v136, v137
	v_mul_f32_e32 v136, v145, v90
	v_mul_f32_e32 v136, v138, v136
	v_lshlrev_b32_e32 v137, 16, v203
	v_mul_f32_e32 v136, v136, v137
	v_mul_f32_e32 v137, v144, v90
	v_mul_f32_e32 v137, v139, v137
	v_and_b32_e32 v138, 0xffff0000, v203
	v_mul_f32_e32 v137, v137, v138
	v_cvt_pk_bf16_f32 v149, v136, v137
	ds_read_b128 v[136:139], v98 offset:256
	v_mul_f32_e32 v144, v159, v90
	global_store_dwordx2 v[2:3], v[148:149], off offset:112
	s_waitcnt lgkmcnt(0)
	v_mul_f32_e32 v136, v136, v144
	s_waitcnt vmcnt(31)
	v_lshlrev_b32_e32 v144, 16, v204
	v_mul_f32_e32 v136, v136, v144
	v_mul_f32_e32 v144, v157, v90
	v_mul_f32_e32 v137, v137, v144
	v_and_b32_e32 v144, 0xffff0000, v204
	v_mul_f32_e32 v137, v137, v144
	v_cvt_pk_bf16_f32 v144, v136, v137
	v_mul_f32_e32 v136, v147, v90
	v_mul_f32_e32 v136, v138, v136
	v_lshlrev_b32_e32 v137, 16, v205
	v_mul_f32_e32 v136, v136, v137
	v_mul_f32_e32 v137, v146, v90
	v_mul_f32_e32 v137, v139, v137
	v_and_b32_e32 v138, 0xffff0000, v205
	v_mul_f32_e32 v137, v137, v138
	v_cvt_pk_bf16_f32 v145, v136, v137
	ds_read_b128 v[136:139], v98 offset:288
	global_store_dwordx2 v[2:3], v[144:145], off offset:128
	s_waitcnt lgkmcnt(0)
	v_mul_f32_e32 v136, v136, v143
	s_waitcnt vmcnt(31)
	v_lshlrev_b32_e32 v143, 16, v206
	v_mul_f32_e32 v136, v136, v143
	v_mul_f32_e32 v137, v137, v142
	v_and_b32_e32 v142, 0xffff0000, v206
	v_mul_f32_e32 v137, v137, v142
	v_cvt_pk_bf16_f32 v142, v136, v137
	v_mul_f32_e32 v136, v141, v90
	v_mul_f32_e32 v136, v138, v136
	v_lshlrev_b32_e32 v137, 16, v207
	v_mul_f32_e32 v136, v136, v137
	v_mul_f32_e32 v137, v140, v90
	v_mul_f32_e32 v137, v139, v137
	v_and_b32_e32 v138, 0xffff0000, v207
	v_mul_f32_e32 v137, v137, v138
	v_cvt_pk_bf16_f32 v143, v136, v137
	ds_read_b128 v[136:139], v98 offset:320
	global_store_dwordx2 v[2:3], v[142:143], off offset:144
	s_waitcnt lgkmcnt(0)
	v_mul_f32_e32 v135, v136, v135
	s_waitcnt vmcnt(31)
	v_lshlrev_b32_e32 v136, 16, v54
	v_mul_f32_e32 v134, v137, v134
	v_and_b32_e32 v54, 0xffff0000, v54
	v_mul_f32_e32 v54, v134, v54
	v_mul_f32_e32 v133, v138, v133
	v_lshlrev_b32_e32 v134, 16, v55
	v_mul_f32_e32 v132, v139, v132
	v_and_b32_e32 v55, 0xffff0000, v55
	v_mul_f32_e32 v135, v135, v136
	v_mul_f32_e32 v133, v133, v134
	v_mul_f32_e32 v55, v132, v55
	v_cvt_pk_bf16_f32 v54, v135, v54
	v_cvt_pk_bf16_f32 v55, v133, v55
	ds_read_b128 v[132:135], v98 offset:352
	global_store_dwordx2 v[2:3], v[54:55], off offset:160
	v_mul_f32_e32 v54, v129, v90
	s_waitcnt vmcnt(31)
	v_lshlrev_b32_e32 v55, 16, v52
	v_and_b32_e32 v52, 0xffff0000, v52
	s_waitcnt lgkmcnt(0)
	v_mul_f32_e32 v54, v132, v54
	v_mul_f32_e32 v54, v54, v55
	v_mul_f32_e32 v55, v127, v90
	v_mul_f32_e32 v55, v133, v55
	v_mul_f32_e32 v52, v55, v52
	v_cvt_pk_bf16_f32 v132, v54, v52
	v_mul_f32_e32 v52, v125, v90
	v_mul_f32_e32 v52, v134, v52
	v_lshlrev_b32_e32 v54, 16, v53
	v_mul_f32_e32 v52, v52, v54
	v_mul_f32_e32 v54, v124, v90
	v_mul_f32_e32 v54, v135, v54
	v_and_b32_e32 v53, 0xffff0000, v53
	v_mul_f32_e32 v53, v54, v53
	v_cvt_pk_bf16_f32 v133, v52, v53
	ds_read_b128 v[52:55], v98 offset:384
	v_mul_f32_e32 v124, v131, v90
	global_store_dwordx2 v[2:3], v[132:133], off offset:176
	s_waitcnt lgkmcnt(0)
	v_mul_f32_e32 v52, v52, v124
	s_waitcnt vmcnt(31)
	v_lshlrev_b32_e32 v124, 16, v50
	v_mul_f32_e32 v52, v52, v124
	v_mul_f32_e32 v124, v130, v90
	v_mul_f32_e32 v53, v53, v124
	v_and_b32_e32 v50, 0xffff0000, v50
	v_mul_f32_e32 v50, v53, v50
	v_cvt_pk_bf16_f32 v124, v52, v50
	v_mul_f32_e32 v50, v128, v90
	v_mul_f32_e32 v50, v54, v50
	v_lshlrev_b32_e32 v52, 16, v51
	v_mul_f32_e32 v50, v50, v52
	v_mul_f32_e32 v52, v126, v90
	v_mul_f32_e32 v52, v55, v52
	v_and_b32_e32 v51, 0xffff0000, v51
	v_mul_f32_e32 v51, v52, v51
	v_cvt_pk_bf16_f32 v125, v50, v51
	ds_read_b128 v[50:53], v98 offset:416
	v_mul_f32_e32 v54, v123, v90
	global_store_dwordx2 v[2:3], v[124:125], off offset:192
	s_waitcnt lgkmcnt(0)
	v_mul_f32_e32 v50, v50, v54
	s_waitcnt vmcnt(31)
	v_lshlrev_b32_e32 v54, 16, v48
	v_mul_f32_e32 v50, v50, v54
	v_mul_f32_e32 v54, v122, v90
	v_mul_f32_e32 v51, v51, v54
	v_and_b32_e32 v48, 0xffff0000, v48
	v_mul_f32_e32 v48, v51, v48
	v_cvt_pk_bf16_f32 v54, v50, v48
	v_mul_f32_e32 v48, v121, v90
	v_mul_f32_e32 v48, v52, v48
	v_lshlrev_b32_e32 v50, 16, v49
	v_mul_f32_e32 v48, v48, v50
	v_mul_f32_e32 v50, v120, v90
	v_mul_f32_e32 v50, v53, v50
	v_and_b32_e32 v49, 0xffff0000, v49
	v_mul_f32_e32 v49, v50, v49
	v_cvt_pk_bf16_f32 v55, v48, v49
	ds_read_b128 v[48:51], v98 offset:448
	v_mul_f32_e32 v52, v119, v90
	global_store_dwordx2 v[2:3], v[54:55], off offset:208
	s_waitcnt lgkmcnt(0)
	v_mul_f32_e32 v48, v48, v52
	s_waitcnt vmcnt(31)
	v_lshlrev_b32_e32 v52, 16, v46
	v_mul_f32_e32 v48, v48, v52
	v_mul_f32_e32 v52, v118, v90
	v_mul_f32_e32 v49, v49, v52
	v_and_b32_e32 v46, 0xffff0000, v46
	v_mul_f32_e32 v46, v49, v46
	v_cvt_pk_bf16_f32 v52, v48, v46
	v_mul_f32_e32 v46, v117, v90
	v_mul_f32_e32 v46, v50, v46
	v_lshlrev_b32_e32 v48, 16, v47
	v_mul_f32_e32 v46, v46, v48
	v_mul_f32_e32 v48, v116, v90
	v_mul_f32_e32 v48, v51, v48
	v_and_b32_e32 v47, 0xffff0000, v47
	v_mul_f32_e32 v47, v48, v47
	v_cvt_pk_bf16_f32 v53, v46, v47
	ds_read_b128 v[46:49], v98 offset:480
	v_mul_f32_e32 v50, v114, v90
	global_store_dwordx2 v[2:3], v[52:53], off offset:224
	s_waitcnt lgkmcnt(0)
	v_mul_f32_e32 v46, v46, v50
	s_waitcnt vmcnt(31)
	v_lshlrev_b32_e32 v50, 16, v44
	v_mul_f32_e32 v46, v46, v50
	v_mul_f32_e32 v50, v112, v90
	v_mul_f32_e32 v47, v47, v50
	v_and_b32_e32 v44, 0xffff0000, v44
	v_mul_f32_e32 v44, v47, v44
	v_cvt_pk_bf16_f32 v50, v46, v44
	v_mul_f32_e32 v44, v110, v90
	v_mul_f32_e32 v44, v48, v44
	v_lshlrev_b32_e32 v46, 16, v45
	v_mul_f32_e32 v44, v44, v46
	v_mul_f32_e32 v46, v108, v90
	v_mul_f32_e32 v46, v49, v46
	v_and_b32_e32 v45, 0xffff0000, v45
	v_mul_f32_e32 v45, v46, v45
	v_cvt_pk_bf16_f32 v51, v44, v45
	ds_read_b128 v[44:47], v98 offset:512
	v_mul_f32_e32 v48, v115, v90
	global_store_dwordx2 v[2:3], v[50:51], off offset:240
	s_waitcnt lgkmcnt(0)
	v_mul_f32_e32 v44, v44, v48
	s_waitcnt vmcnt(31)
	v_lshlrev_b32_e32 v48, 16, v42
	v_mul_f32_e32 v44, v44, v48
	v_mul_f32_e32 v48, v113, v90
	v_mul_f32_e32 v45, v45, v48
	v_and_b32_e32 v42, 0xffff0000, v42
	v_mul_f32_e32 v42, v45, v42
	v_cvt_pk_bf16_f32 v48, v44, v42
	v_mul_f32_e32 v42, v111, v90
	v_mul_f32_e32 v42, v46, v42
	v_lshlrev_b32_e32 v44, 16, v43
	v_mul_f32_e32 v42, v42, v44
	v_mul_f32_e32 v44, v109, v90
	v_mul_f32_e32 v44, v47, v44
	v_and_b32_e32 v43, 0xffff0000, v43
	v_mul_f32_e32 v43, v44, v43
	v_cvt_pk_bf16_f32 v49, v42, v43
	ds_read_b128 v[42:45], v98 offset:544
	v_mul_f32_e32 v46, v107, v90
	global_store_dwordx2 v[2:3], v[48:49], off offset:256
	s_waitcnt lgkmcnt(0)
	v_mul_f32_e32 v42, v42, v46
	s_waitcnt vmcnt(31)
	v_lshlrev_b32_e32 v46, 16, v40
	v_mul_f32_e32 v42, v42, v46
	v_mul_f32_e32 v46, v106, v90
	v_mul_f32_e32 v43, v43, v46
	v_and_b32_e32 v40, 0xffff0000, v40
	v_mul_f32_e32 v40, v43, v40
	v_cvt_pk_bf16_f32 v46, v42, v40
	v_mul_f32_e32 v40, v105, v90
	v_mul_f32_e32 v40, v44, v40
	v_lshlrev_b32_e32 v42, 16, v41
	v_mul_f32_e32 v40, v40, v42
	v_mul_f32_e32 v42, v104, v90
	v_mul_f32_e32 v42, v45, v42
	v_and_b32_e32 v41, 0xffff0000, v41
	v_mul_f32_e32 v41, v42, v41
	v_cvt_pk_bf16_f32 v47, v40, v41
	ds_read_b128 v[40:43], v98 offset:576
	v_mul_f32_e32 v44, v103, v90
	global_store_dwordx2 v[2:3], v[46:47], off offset:272
	s_waitcnt lgkmcnt(0)
	v_mul_f32_e32 v40, v40, v44
	s_waitcnt vmcnt(31)
	v_lshlrev_b32_e32 v44, 16, v38
	v_mul_f32_e32 v40, v40, v44
	v_mul_f32_e32 v44, v102, v90
	v_mul_f32_e32 v41, v41, v44
	v_and_b32_e32 v38, 0xffff0000, v38
	v_mul_f32_e32 v38, v41, v38
	v_cvt_pk_bf16_f32 v44, v40, v38
	v_mul_f32_e32 v38, v101, v90
	v_mul_f32_e32 v38, v42, v38
	v_lshlrev_b32_e32 v40, 16, v39
	v_mul_f32_e32 v38, v38, v40
	v_mul_f32_e32 v40, v100, v90
	v_mul_f32_e32 v40, v43, v40
	v_and_b32_e32 v39, 0xffff0000, v39
	v_mul_f32_e32 v39, v40, v39
	v_cvt_pk_bf16_f32 v45, v38, v39
	ds_read_b128 v[38:41], v98 offset:608
	v_mul_f32_e32 v42, v96, v90
	global_store_dwordx2 v[2:3], v[44:45], off offset:288
	s_waitcnt lgkmcnt(0)
	v_mul_f32_e32 v38, v38, v42
	s_waitcnt vmcnt(31)
	v_lshlrev_b32_e32 v42, 16, v36
	v_mul_f32_e32 v38, v38, v42
	v_mul_f32_e32 v42, v95, v90
	v_mul_f32_e32 v39, v39, v42
	v_and_b32_e32 v36, 0xffff0000, v36
	v_mul_f32_e32 v36, v39, v36
	v_cvt_pk_bf16_f32 v42, v38, v36
	v_mul_f32_e32 v36, v92, v90
	v_mul_f32_e32 v36, v40, v36
	v_lshlrev_b32_e32 v38, 16, v37
	v_mul_f32_e32 v36, v36, v38
	v_mul_f32_e32 v38, v91, v90
	v_mul_f32_e32 v38, v41, v38
	v_and_b32_e32 v37, 0xffff0000, v37
	v_mul_f32_e32 v37, v38, v37
	v_cvt_pk_bf16_f32 v43, v36, v37
	ds_read_b128 v[36:39], v98 offset:640
	v_mul_f32_e32 v40, v99, v90
	global_store_dwordx2 v[2:3], v[42:43], off offset:304
	s_waitcnt lgkmcnt(0)
	v_mul_f32_e32 v36, v36, v40
	s_waitcnt vmcnt(31)
	v_lshlrev_b32_e32 v40, 16, v34
	v_mul_f32_e32 v36, v36, v40
	v_mul_f32_e32 v40, v97, v90
	v_mul_f32_e32 v37, v37, v40
	v_and_b32_e32 v34, 0xffff0000, v34
	v_mul_f32_e32 v34, v37, v34
	v_cvt_pk_bf16_f32 v40, v36, v34
	v_mul_f32_e32 v34, v94, v90
	v_mul_f32_e32 v34, v38, v34
	v_lshlrev_b32_e32 v36, 16, v35
	v_mul_f32_e32 v34, v34, v36
	v_mul_f32_e32 v36, v93, v90
	v_mul_f32_e32 v36, v39, v36
	v_and_b32_e32 v35, 0xffff0000, v35
	v_mul_f32_e32 v35, v36, v35
	v_cvt_pk_bf16_f32 v41, v34, v35
	ds_read_b128 v[34:37], v98 offset:672
	v_mul_f32_e32 v38, v89, v90
	global_store_dwordx2 v[2:3], v[40:41], off offset:320
	s_waitcnt lgkmcnt(0)
	v_mul_f32_e32 v34, v34, v38
	s_waitcnt vmcnt(31)
	v_lshlrev_b32_e32 v38, 16, v32
	v_mul_f32_e32 v34, v34, v38
	v_mul_f32_e32 v38, v88, v90
	v_mul_f32_e32 v35, v35, v38
	v_and_b32_e32 v32, 0xffff0000, v32
	v_mul_f32_e32 v32, v35, v32
	v_cvt_pk_bf16_f32 v38, v34, v32
	v_mul_f32_e32 v32, v87, v90
	v_mul_f32_e32 v32, v36, v32
	v_lshlrev_b32_e32 v34, 16, v33
	v_mul_f32_e32 v32, v32, v34
	v_mul_f32_e32 v34, v86, v90
	v_mul_f32_e32 v34, v37, v34
	v_and_b32_e32 v33, 0xffff0000, v33
	v_mul_f32_e32 v33, v34, v33
	v_cvt_pk_bf16_f32 v39, v32, v33
	ds_read_b128 v[32:35], v98 offset:704
	v_mul_f32_e32 v36, v85, v90
	global_store_dwordx2 v[2:3], v[38:39], off offset:336
	s_waitcnt lgkmcnt(0)
	v_mul_f32_e32 v32, v32, v36
	s_waitcnt vmcnt(31)
	v_lshlrev_b32_e32 v36, 16, v30
	v_mul_f32_e32 v32, v32, v36
	v_mul_f32_e32 v36, v84, v90
	v_mul_f32_e32 v33, v33, v36
	v_and_b32_e32 v30, 0xffff0000, v30
	v_mul_f32_e32 v30, v33, v30
	v_cvt_pk_bf16_f32 v36, v32, v30
	v_mul_f32_e32 v30, v83, v90
	v_mul_f32_e32 v30, v34, v30
	v_lshlrev_b32_e32 v32, 16, v31
	v_mul_f32_e32 v30, v30, v32
	v_mul_f32_e32 v32, v82, v90
	v_mul_f32_e32 v32, v35, v32
	v_and_b32_e32 v31, 0xffff0000, v31
	v_mul_f32_e32 v31, v32, v31
	v_cvt_pk_bf16_f32 v37, v30, v31
	ds_read_b128 v[30:33], v98 offset:736
	v_mul_f32_e32 v34, v80, v90
	global_store_dwordx2 v[2:3], v[36:37], off offset:352
	s_waitcnt lgkmcnt(0)
	v_mul_f32_e32 v30, v30, v34
	s_waitcnt vmcnt(31)
	v_lshlrev_b32_e32 v34, 16, v28
	v_mul_f32_e32 v30, v30, v34
	v_mul_f32_e32 v34, v78, v90
	v_mul_f32_e32 v31, v31, v34
	v_and_b32_e32 v28, 0xffff0000, v28
	v_mul_f32_e32 v28, v31, v28
	v_cvt_pk_bf16_f32 v34, v30, v28
	v_mul_f32_e32 v28, v76, v90
	v_mul_f32_e32 v28, v32, v28
	v_lshlrev_b32_e32 v30, 16, v29
	v_mul_f32_e32 v28, v28, v30
	v_mul_f32_e32 v30, v74, v90
	v_mul_f32_e32 v30, v33, v30
	v_and_b32_e32 v29, 0xffff0000, v29
	v_mul_f32_e32 v29, v30, v29
	v_cvt_pk_bf16_f32 v35, v28, v29
	ds_read_b128 v[28:31], v98 offset:768
	v_mul_f32_e32 v32, v81, v90
	global_store_dwordx2 v[2:3], v[34:35], off offset:368
	s_waitcnt lgkmcnt(0)
	v_mul_f32_e32 v28, v32, v28
	s_waitcnt vmcnt(31)
	v_lshlrev_b32_e32 v32, 16, v26
	v_mul_f32_e32 v28, v28, v32
	v_mul_f32_e32 v32, v79, v90
	v_mul_f32_e32 v29, v32, v29
	v_and_b32_e32 v26, 0xffff0000, v26
	v_mul_f32_e32 v26, v29, v26
	v_cvt_pk_bf16_f32 v32, v28, v26
	v_mul_f32_e32 v26, v77, v90
	v_mul_f32_e32 v26, v26, v30
	v_lshlrev_b32_e32 v28, 16, v27
	v_mul_f32_e32 v26, v26, v28
	v_mul_f32_e32 v28, v75, v90
	v_mul_f32_e32 v28, v28, v31
	v_and_b32_e32 v27, 0xffff0000, v27
	v_mul_f32_e32 v27, v28, v27
	v_cvt_pk_bf16_f32 v33, v26, v27
	ds_read_b128 v[26:29], v98 offset:800
	v_mul_f32_e32 v30, v73, v90
	global_store_dwordx2 v[2:3], v[32:33], off offset:384
	s_waitcnt lgkmcnt(0)
	v_mul_f32_e32 v26, v30, v26
	s_waitcnt vmcnt(31)
	v_lshlrev_b32_e32 v30, 16, v24
	v_mul_f32_e32 v26, v26, v30
	v_mul_f32_e32 v30, v72, v90
	v_mul_f32_e32 v27, v30, v27
	v_and_b32_e32 v24, 0xffff0000, v24
	v_mul_f32_e32 v24, v27, v24
	v_cvt_pk_bf16_f32 v30, v26, v24
	v_mul_f32_e32 v24, v71, v90
	v_mul_f32_e32 v24, v24, v28
	v_lshlrev_b32_e32 v26, 16, v25
	v_mul_f32_e32 v24, v24, v26
	v_mul_f32_e32 v26, v70, v90
	v_mul_f32_e32 v26, v26, v29
	v_and_b32_e32 v25, 0xffff0000, v25
	v_mul_f32_e32 v25, v26, v25
	v_cvt_pk_bf16_f32 v31, v24, v25
	ds_read_b128 v[24:27], v98 offset:832
	v_mul_f32_e32 v28, v69, v90
	global_store_dwordx2 v[2:3], v[30:31], off offset:400
	s_waitcnt lgkmcnt(0)
	v_mul_f32_e32 v24, v28, v24
	s_waitcnt vmcnt(31)
	v_lshlrev_b32_e32 v28, 16, v22
	v_mul_f32_e32 v24, v24, v28
	v_mul_f32_e32 v28, v68, v90
	v_mul_f32_e32 v25, v28, v25
	v_and_b32_e32 v22, 0xffff0000, v22
	v_mul_f32_e32 v22, v25, v22
	v_cvt_pk_bf16_f32 v28, v24, v22
	v_mul_f32_e32 v22, v67, v90
	v_mul_f32_e32 v22, v22, v26
	v_lshlrev_b32_e32 v24, 16, v23
	v_mul_f32_e32 v22, v22, v24
	v_mul_f32_e32 v24, v66, v90
	v_mul_f32_e32 v24, v24, v27
	v_and_b32_e32 v23, 0xffff0000, v23
	v_mul_f32_e32 v23, v24, v23
	v_cvt_pk_bf16_f32 v29, v22, v23
	ds_read_b128 v[22:25], v98 offset:864
	v_mul_f32_e32 v26, v65, v90
	global_store_dwordx2 v[2:3], v[28:29], off offset:416
	s_waitcnt lgkmcnt(0)
	v_mul_f32_e32 v22, v26, v22
	s_waitcnt vmcnt(31)
	v_lshlrev_b32_e32 v26, 16, v20
	v_mul_f32_e32 v22, v22, v26
	v_mul_f32_e32 v26, v64, v90
	v_mul_f32_e32 v23, v26, v23
	v_and_b32_e32 v20, 0xffff0000, v20
	v_mul_f32_e32 v20, v23, v20
	v_cvt_pk_bf16_f32 v26, v22, v20
	v_mul_f32_e32 v20, v63, v90
	v_mul_f32_e32 v20, v20, v24
	v_lshlrev_b32_e32 v22, 16, v21
	v_mul_f32_e32 v20, v20, v22
	v_mul_f32_e32 v22, v62, v90
	v_mul_f32_e32 v22, v22, v25
	v_and_b32_e32 v21, 0xffff0000, v21
	v_mul_f32_e32 v21, v22, v21
	v_cvt_pk_bf16_f32 v27, v20, v21
	ds_read_b128 v[20:23], v98 offset:896
	v_mul_f32_e32 v24, v61, v90
	global_store_dwordx2 v[2:3], v[26:27], off offset:432
	s_waitcnt lgkmcnt(0)
	v_mul_f32_e32 v20, v24, v20
	s_waitcnt vmcnt(31)
	v_lshlrev_b32_e32 v24, 16, v18
	v_mul_f32_e32 v20, v20, v24
	v_mul_f32_e32 v24, v60, v90
	v_mul_f32_e32 v21, v24, v21
	v_and_b32_e32 v18, 0xffff0000, v18
	v_mul_f32_e32 v18, v21, v18
	v_cvt_pk_bf16_f32 v24, v20, v18
	v_mul_f32_e32 v18, v59, v90
	v_mul_f32_e32 v18, v18, v22
	v_lshlrev_b32_e32 v20, 16, v19
	v_mul_f32_e32 v18, v18, v20
	v_mul_f32_e32 v20, v58, v90
	v_mul_f32_e32 v20, v20, v23
	v_and_b32_e32 v19, 0xffff0000, v19
	v_mul_f32_e32 v19, v20, v19
	v_cvt_pk_bf16_f32 v25, v18, v19
	ds_read_b128 v[18:21], v98 offset:928
	v_mul_f32_e32 v22, v57, v90
	global_store_dwordx2 v[2:3], v[24:25], off offset:448
	s_waitcnt lgkmcnt(0)
	v_mul_f32_e32 v18, v22, v18
	s_waitcnt vmcnt(31)
	v_lshlrev_b32_e32 v22, 16, v14
	v_mul_f32_e32 v18, v18, v22
	v_mul_f32_e32 v22, v56, v90
	v_mul_f32_e32 v19, v22, v19
	v_and_b32_e32 v14, 0xffff0000, v14
	v_mul_f32_e32 v14, v19, v14
	v_cvt_pk_bf16_f32 v14, v18, v14
	v_mul_f32_e32 v0, v0, v20
	v_lshlrev_b32_e32 v18, 16, v15
	v_mul_f32_e32 v1, v1, v21
	v_and_b32_e32 v15, 0xffff0000, v15
	v_mul_f32_e32 v0, v0, v18
	v_mul_f32_e32 v1, v1, v15
	v_cvt_pk_bf16_f32 v15, v0, v1
	ds_read_b128 v[18:21], v98 offset:960
	v_mul_f32_e32 v0, v16, v90
	s_waitcnt vmcnt(30)
	v_lshlrev_b32_e32 v1, 16, v12
	v_and_b32_e32 v12, 0xffff0000, v12
	global_store_dwordx2 v[2:3], v[14:15], off offset:464
	s_waitcnt lgkmcnt(0)
	v_mul_f32_e32 v0, v0, v18
	v_mul_f32_e32 v0, v0, v1
	v_mul_f32_e32 v1, v17, v90
	v_mul_f32_e32 v1, v1, v19
	v_mul_f32_e32 v1, v1, v12
	v_cvt_pk_bf16_f32 v0, v0, v1
	v_mul_f32_e32 v1, v8, v90
	v_mul_f32_e32 v1, v1, v20
	v_lshlrev_b32_e32 v8, 16, v13
	v_mul_f32_e32 v1, v1, v8
	v_mul_f32_e32 v8, v9, v90
	v_mul_f32_e32 v8, v8, v21
	v_and_b32_e32 v9, 0xffff0000, v13
	v_mul_f32_e32 v8, v8, v9
	v_cvt_pk_bf16_f32 v1, v1, v8
	ds_read_b128 v[12:15], v98 offset:992
	global_store_dwordx2 v[2:3], v[0:1], off offset:480
	v_mul_f32_e32 v0, v6, v90
	s_waitcnt vmcnt(31)
	v_lshlrev_b32_e32 v1, 16, v10
	v_and_b32_e32 v6, 0xffff0000, v10
	s_waitcnt lgkmcnt(0)
	v_mul_f32_e32 v0, v0, v12
	v_mul_f32_e32 v0, v0, v1
	v_mul_f32_e32 v1, v7, v90
	v_mul_f32_e32 v1, v1, v13
	v_mul_f32_e32 v1, v1, v6
	v_cvt_pk_bf16_f32 v0, v0, v1
	v_mul_f32_e32 v1, v4, v90
	v_mul_f32_e32 v1, v1, v14
	v_lshlrev_b32_e32 v4, 16, v11
	v_mul_f32_e32 v1, v1, v4
	v_mul_f32_e32 v4, v5, v90
	v_mul_f32_e32 v4, v4, v15
	v_and_b32_e32 v5, 0xffff0000, v11
	v_mul_f32_e32 v4, v4, v5
	v_cvt_pk_bf16_f32 v1, v1, v4
	global_store_dwordx2 v[2:3], v[0:1], off offset:496
	v_mov_b32_e32 v4, v176
	v_mov_b32_e32 v181, v179
	v_bfe_u32 v0, v4, 4, 2
	v_or_b32_e32 v1, s83, v0
	v_bitop3_b32 v0, v0, v4, s83 bitop3:0x36
	v_lshlrev_b32_e32 v2, 14, v1
	v_lshlrev_b32_e32 v0, 4, v0
	v_and_or_b32 v178, v0, s67, v2
	v_or_b32_e32 v0, 4, v1
	v_bitop3_b32 v1, v1, v4, 4 bitop3:0x36
	v_lshlrev_b32_e32 v0, 14, v0
	v_lshlrev_b32_e32 v1, 4, v1
	v_and_or_b32 v180, v1, s67, v0
	v_bfe_u32 v0, v4, 5, 1
	v_or_b32_e32 v1, s83, v0
	v_and_b32_e32 v2, 31, v4
	v_lshlrev_b32_e32 v3, 14, v1
	v_lshlrev_b32_e32 v0, 6, v0
	v_lshlrev_b32_e32 v5, 4, v2
	v_bitop3_b32 v182, v0, v3, v5 bitop3:0xde
	v_or_b32_e32 v0, 2, v1
	v_lshlrev_b32_e32 v3, 2, v0
	v_bitop3_b32 v3, v3, v2, 12 bitop3:0x6c
	v_lshlrev_b32_e32 v0, 14, v0
	v_lshl_or_b32 v184, v3, 4, v0
	v_or_b32_e32 v0, 6, v1
	v_lshlrev_b32_e32 v1, 2, v0
	v_bitop3_b32 v1, v1, v2, 12 bitop3:0x6c
	v_lshlrev_b32_e32 v0, 14, v0
	v_lshl_or_b32 v188, v1, 4, v0
	v_lshl_add_u64 v[0:1], s[38:39], 0, v[178:179]
	s_mov_b32 s13, m0
	s_mov_b32 m0, s40
	s_nop 0
	global_load_lds_dwordx4 v[0:1], off
	s_mov_b32 m0, s13
	v_lshl_add_u64 v[0:1], s[38:39], 0, v[180:181]
	v_mov_b32_e32 v183, v179
	s_add_i32 s13, s40, 0x400
	s_mov_b32 s14, m0
	s_mov_b32 m0, s13
	s_nop 0
	global_load_lds_dwordx4 v[0:1], off
	s_mov_b32 m0, s14
	v_lshl_add_u64 v[0:1], s[16:17], 0, v[182:183]
	v_mov_b32_e32 v185, v179
	v_or_b32_e32 v186, 0x10000, v182
	s_mov_b32 s13, m0
	s_mov_b32 m0, s41
	s_nop 0
	global_load_lds_dwordx4 v[0:1], off
	s_mov_b32 m0, s13
	v_lshl_add_u64 v[0:1], s[16:17], 0, v[184:185]
	s_add_i32 s12, s12, s33
	v_mov_b32_e32 v187, v179
	s_add_i32 s13, s12, 0xc400
	s_mov_b32 s14, m0
	s_mov_b32 m0, s13
	s_nop 0
	global_load_lds_dwordx4 v[0:1], off
	s_mov_b32 m0, s14
	v_lshl_add_u64 v[0:1], s[16:17], 0, v[186:187]
	v_mov_b32_e32 v189, v179
	s_add_i32 s13, s12, 0xc800
	s_mov_b32 s14, m0
	s_mov_b32 m0, s13
	s_nop 0
	global_load_lds_dwordx4 v[0:1], off
	s_mov_b32 m0, s14
	v_lshl_add_u64 v[0:1], s[16:17], 0, v[188:189]
	s_add_i32 s13, s12, 0xcc00
	s_mov_b32 s14, m0
	s_mov_b32 m0, s13
	s_nop 0
	global_load_lds_dwordx4 v[0:1], off
	s_mov_b32 m0, s14
	v_lshl_add_u64 v[0:1], s[52:53], 0, v[178:179]
	s_add_i32 s13, s40, 0x4000
	s_mov_b32 s14, m0
	s_mov_b32 m0, s13
	s_nop 0
	global_load_lds_dwordx4 v[0:1], off
	s_mov_b32 m0, s14
	v_lshl_add_u64 v[0:1], s[52:53], 0, v[180:181]
	s_add_i32 s13, s40, 0x4400
	s_mov_b32 s14, m0
	s_mov_b32 m0, s13
	s_nop 0
	global_load_lds_dwordx4 v[0:1], off
	s_mov_b32 m0, s14
	v_lshl_add_u64 v[0:1], s[10:11], 0, v[182:183]
	s_add_i32 s13, s12, 0x14000
	s_mov_b32 s14, m0
	s_mov_b32 m0, s13
	s_nop 0
	global_load_lds_dwordx4 v[0:1], off
	s_mov_b32 m0, s14
	v_lshl_add_u64 v[0:1], s[10:11], 0, v[184:185]
	s_add_i32 s13, s12, 0x14400
	s_mov_b32 s14, m0
	s_mov_b32 m0, s13
	s_nop 0
	global_load_lds_dwordx4 v[0:1], off
	s_mov_b32 m0, s14
	v_lshl_add_u64 v[0:1], s[10:11], 0, v[186:187]
	s_add_i32 s13, s12, 0x14800
	s_mov_b32 s14, m0
	s_mov_b32 m0, s13
	s_nop 0
	global_load_lds_dwordx4 v[0:1], off
	s_mov_b32 m0, s14
	v_lshl_add_u64 v[0:1], s[10:11], 0, v[188:189]
	s_add_i32 s12, s12, 0x14c00
	s_mov_b32 s13, m0
	s_mov_b32 m0, s12
	s_nop 0
	global_load_lds_dwordx4 v[0:1], off
	s_mov_b32 m0, s13
	v_or_b32_e32 v0, s18, v2
	v_mov_b32_e32 v1, s19
	v_lshlrev_b64 v[0:1], 14, v[0:1]
	v_lshrrev_b32_e32 v2, 1, v4
	v_lshl_add_u64 v[0:1], s[8:9], 0, v[0:1]
	v_and_b32_e32 v2, 16, v2
	v_mov_b32_e32 v3, v179
	v_lshl_add_u64 v[0:1], v[0:1], 0, v[2:3]
	global_load_dwordx4 v[144:147], v[0:1], off
	global_load_dwordx4 v[148:151], v[0:1], off offset:32
	global_load_dwordx4 v[152:155], v[0:1], off offset:64
	global_load_dwordx4 v[156:159], v[0:1], off offset:96
	global_load_dwordx4 v[160:163], v[0:1], off offset:128
	global_load_dwordx4 v[164:167], v[0:1], off offset:160
	global_load_dwordx4 v[168:171], v[0:1], off offset:192
	global_load_dwordx4 v[172:175], v[0:1], off offset:224
	v_lshrrev_b32_e32 v0, 5, v4
	v_and_b32_e32 v1, 15, v4
	v_bitop3_b32 v0, v0, v1, 1 bitop3:0x6c
	v_lshlrev_b32_e32 v1, 8, v4
	v_lshlrev_b32_e32 v0, 4, v0
	v_and_b32_e32 v1, 0x1f00, v1
	v_mov_b32_e32 v14, v179
	v_mov_b32_e32 v15, v179
	v_or_b32_e32 v195, v0, v1
	v_bitop3_b32 v196, v0, 32, v1 bitop3:0x36
	v_bitop3_b32 v197, v0, 64, v1 bitop3:0x36
	v_bitop3_b32 v198, v0, s68, v1 bitop3:0x36
	v_bitop3_b32 v199, v0, s69, v1 bitop3:0x36
	v_bitop3_b32 v200, v0, s70, v1 bitop3:0x36
	v_bitop3_b32 v201, v0, s71, v1 bitop3:0x36
	v_bitop3_b32 v202, v0, s72, v1 bitop3:0x36
	v_mov_b32_e32 v0, v179
	v_mov_b32_e32 v1, v179
	v_mov_b32_e32 v2, v179
	v_mov_b32_e32 v4, v179
	v_mov_b32_e32 v5, v179
	v_mov_b32_e32 v6, v179
	v_mov_b32_e32 v7, v179
	v_mov_b32_e32 v8, v179
	s_waitcnt vmcnt(7)
	s_waitcnt vmcnt(6)
	s_waitcnt vmcnt(5)
	s_waitcnt vmcnt(4)
	s_waitcnt vmcnt(3)
	s_waitcnt vmcnt(2)
	s_waitcnt vmcnt(1)
	s_waitcnt vmcnt(0)
	s_waitcnt vmcnt(0)
	v_mov_b32_e32 v9, v179
	v_mov_b32_e32 v10, v179
	v_mov_b32_e32 v11, v179
	v_mov_b32_e32 v12, v179
	v_mov_b32_e32 v13, v179
	v_mov_b64_e32 v[30:31], v[14:15]
	v_mov_b64_e32 v[46:47], v[14:15]
	v_mov_b64_e32 v[62:63], v[14:15]
	v_mov_b64_e32 v[78:79], v[14:15]
	v_mov_b64_e32 v[94:95], v[14:15]
	v_mov_b64_e32 v[110:111], v[14:15]
	v_mov_b64_e32 v[126:127], v[14:15]
	v_mov_b32_e32 v190, 0xf149f2ca
	v_mov_b32_e32 v203, 0
	v_mov_b64_e32 v[28:29], v[12:13]
	v_mov_b64_e32 v[26:27], v[10:11]
	v_mov_b64_e32 v[24:25], v[8:9]
	v_mov_b64_e32 v[22:23], v[6:7]
	v_mov_b64_e32 v[20:21], v[4:5]
	v_mov_b64_e32 v[18:19], v[2:3]
	v_mov_b64_e32 v[16:17], v[0:1]
	v_mov_b64_e32 v[44:45], v[12:13]
	v_mov_b64_e32 v[42:43], v[10:11]
	v_mov_b64_e32 v[40:41], v[8:9]
	v_mov_b64_e32 v[38:39], v[6:7]
	v_mov_b64_e32 v[36:37], v[4:5]
	v_mov_b64_e32 v[34:35], v[2:3]
	v_mov_b64_e32 v[32:33], v[0:1]
	v_mov_b64_e32 v[60:61], v[12:13]
	v_mov_b64_e32 v[58:59], v[10:11]
	v_mov_b64_e32 v[56:57], v[8:9]
	v_mov_b64_e32 v[54:55], v[6:7]
	v_mov_b64_e32 v[52:53], v[4:5]
	v_mov_b64_e32 v[50:51], v[2:3]
	v_mov_b64_e32 v[48:49], v[0:1]
	v_mov_b64_e32 v[76:77], v[12:13]
	v_mov_b64_e32 v[74:75], v[10:11]
	v_mov_b64_e32 v[72:73], v[8:9]
	v_mov_b64_e32 v[70:71], v[6:7]
	v_mov_b64_e32 v[68:69], v[4:5]
	v_mov_b64_e32 v[66:67], v[2:3]
	v_mov_b64_e32 v[64:65], v[0:1]
	v_mov_b64_e32 v[92:93], v[12:13]
	v_mov_b64_e32 v[90:91], v[10:11]
	v_mov_b64_e32 v[88:89], v[8:9]
	v_mov_b64_e32 v[86:87], v[6:7]
	v_mov_b64_e32 v[84:85], v[4:5]
	v_mov_b64_e32 v[82:83], v[2:3]
	v_mov_b64_e32 v[80:81], v[0:1]
	v_mov_b64_e32 v[108:109], v[12:13]
	v_mov_b64_e32 v[106:107], v[10:11]
	v_mov_b64_e32 v[104:105], v[8:9]
	v_mov_b64_e32 v[102:103], v[6:7]
	v_mov_b64_e32 v[100:101], v[4:5]
	v_mov_b64_e32 v[98:99], v[2:3]
	v_mov_b64_e32 v[96:97], v[0:1]
	v_mov_b64_e32 v[124:125], v[12:13]
	v_mov_b64_e32 v[122:123], v[10:11]
	v_mov_b64_e32 v[120:121], v[8:9]
	v_mov_b64_e32 v[118:119], v[6:7]
	v_mov_b64_e32 v[116:117], v[4:5]
	v_mov_b64_e32 v[114:115], v[2:3]
	v_mov_b64_e32 v[112:113], v[0:1]
	s_mov_b32 s38, 0
	s_sub_u32 s22, s22, 0x100000
	s_subb_u32 s23, s23, 0
	s_sub_i32 s85, s85, 1
	s_barrier
	s_branch .LBB0_883

.LBB0_883:
	s_cmp_ge_u32 s85, s78
	s_cselect_b64 s[12:13], -1, 0
	v_mov_b32_e32 v204, v176
	s_and_b64 vcc, exec, s[12:13]
	s_cbranch_vccnz .LBB0_885
	s_add_i32 s100, s84, 63
	s_cmp_le_i32 s100, s80
	s_cbranch_scc1 .LBB0_885
	s_add_i32 s14, s38, 1
	s_cmp_eq_u32 s14, 3
	s_cselect_b32 s14, 0, s14
	v_mov_b32_e32 v130, s14
	v_lshlrev_b32_e32 v128, 14, v130
	v_add_u32_e32 v131, s40, v128
	v_lshl_add_u64 v[128:129], s[22:23], 0, v[178:179]
	s_add_u32 s14, s22, 0x1000
	v_readfirstlane_b32 s39, v131
	s_mov_b32 s52, m0
	s_mov_b32 m0, s39
	s_nop 0
	global_load_lds_dwordx4 v[128:129], off
	s_mov_b32 m0, s52
	v_lshl_add_u64 v[128:129], s[22:23], 0, v[180:181]
	s_addc_u32 s15, s23, 0
	s_addk_i32 s39, 0x400
	s_mov_b32 s52, m0
	s_mov_b32 m0, s39
	s_nop 0
	global_load_lds_dwordx4 v[128:129], off
	s_mov_b32 m0, s52
	v_lshlrev_b32_e32 v128, 15, v130
	v_add_u32_e32 v130, s41, v128
	v_lshl_add_u64 v[128:129], s[14:15], 0, v[182:183]
	v_readfirstlane_b32 s39, v130
	s_mov_b32 s52, m0
	s_mov_b32 m0, s39
	s_nop 0
	global_load_lds_dwordx4 v[128:129], off
	s_mov_b32 m0, s52
	v_lshl_add_u64 v[128:129], s[14:15], 0, v[184:185]
	s_add_i32 s52, s39, 0x400
	s_mov_b32 s53, m0
	s_mov_b32 m0, s52
	s_nop 0
	global_load_lds_dwordx4 v[128:129], off
	s_mov_b32 m0, s53
	v_lshl_add_u64 v[128:129], s[14:15], 0, v[186:187]
	s_add_i32 s52, s39, 0x800
	s_mov_b32 s53, m0
	s_mov_b32 m0, s52
	s_nop 0
	global_load_lds_dwordx4 v[128:129], off
	s_mov_b32 m0, s53
	v_lshl_add_u64 v[128:129], s[14:15], 0, v[188:189]
	s_add_i32 s14, s39, 0xc00
	s_mov_b32 s15, m0
	s_mov_b32 m0, s14
	s_nop 0
	global_load_lds_dwordx4 v[128:129], off
	s_mov_b32 m0, s15
.LBB0_885:
	s_cmp_gt_i32 s84, s81
	s_cbranch_scc1 .LBB0_896
	s_add_i32 s100, s84, 63
	s_cmp_le_i32 s100, s80
	s_cbranch_scc0 .Latt_slow_2
	v_lshrrev_b32_e32 v246, 8, v220
	s_nop 0
	v_readfirstlane_b32 s100, v246
	s_nop 0
	s_cmp_eq_u32 s100, 0
	s_cbranch_scc1 .Latt_A_2
	s_cmp_eq_u32 s84, 0
	s_cbranch_scc1 .Latt_B0_2
	s_add_i32 s99, s38, 2
	s_sub_i32 s101, s99, 3
	s_cmp_lt_u32 s99, 3
	s_cselect_b32 s99, s99, s101
	s_lshl_b32 s99, s99, 15
	s_add_i32 s99, s99, 0xc000
	v_bfe_u32 v246, v204, 2, 2
	v_bfe_u32 v247, v204, 5, 1
	v_lshl_or_b32 v247, v247, 2, v246
	v_and_b32_e32 v249, 3, v204
	v_and_b32_e32 v254, 16, v204
	v_lshl_or_b32 v249, v249, 2, v254
	v_lshlrev_b32_e32 v249, 1, v249
	v_lshl_add_u32 v247, v247, 9, v249
	v_add_u32_e32 v247, s99, v247
	v_lshlrev_b32_e32 v246, 6, v246
	v_add_u32_e32 v205, v247, v246
	v_xor_b32_e32 v249, 64, v246
	v_add_u32_e32 v218, v247, v249
	v_xor_b32_e32 v249, 0x80, v246
	v_add_u32_e32 v219, v247, v249
	v_xor_b32_e32 v249, 0xc0, v246
	v_add_u32_e32 v221, v247, v249
	s_lshl_b32 s98, s38, 14
	s_lshl_b32 s99, s38, 15
	s_add_i32 s99, s99, 0xc000
	ds_read_b64_tr_b16 v[206:207], v205 offset:16384
	ds_read_b64_tr_b16 v[208:209], v205 offset:20480
	ds_read_b64_tr_b16 v[210:211], v218 offset:16384
	ds_read_b64_tr_b16 v[212:213], v218 offset:20480
	ds_read_b64_tr_b16 v[214:215], v219 offset:16384
	ds_read_b64_tr_b16 v[216:217], v219 offset:20480
	ds_read_b64_tr_b16 v[238:239], v221 offset:16384
	ds_read_b64_tr_b16 v[240:241], v221 offset:20480
	ds_read_b64_tr_b16 v[222:223], v205 offset:16640
	ds_read_b64_tr_b16 v[224:225], v205 offset:20736
	s_waitcnt lgkmcnt(8)
	v_mfma_f32_32x32x16_bf16 v[112:127], v[206:209], v[242:245], v[112:127]
	ds_read_b64_tr_b16 v[206:207], v218 offset:16640
	ds_read_b64_tr_b16 v[208:209], v218 offset:20736
	s_cmp_lg_u64 s[12:13], 0
	s_cbranch_scc1 .Latt_nd0_2B1
	s_add_i32 s100, s38, 1
	s_cmp_eq_u32 s38, 2
	s_cselect_b32 s100, 0, s100
	s_lshl_b32 s101, s100, 14
	s_add_i32 m0, s40, s101
	s_nop 0
	global_load_lds_dwordx4 v178, s[22:23]
.Latt_nd0_2B1:
	s_waitcnt lgkmcnt(8)
	v_mfma_f32_32x32x16_bf16 v[96:111], v[210:213], v[242:245], v[96:111]
	ds_read_b64_tr_b16 v[210:211], v219 offset:16640
	ds_read_b64_tr_b16 v[212:213], v219 offset:20736
	s_cmp_lg_u64 s[12:13], 0
	s_cbranch_scc1 .Latt_nd1_2B1
	s_add_i32 m0, m0, 0x400
	s_nop 0
	global_load_lds_dwordx4 v180, s[22:23]
.Latt_nd1_2B1:
	s_waitcnt lgkmcnt(8)
	v_mfma_f32_32x32x16_bf16 v[80:95], v[214:217], v[242:245], v[80:95]
	ds_read_b64_tr_b16 v[214:215], v221 offset:16640
	ds_read_b64_tr_b16 v[216:217], v221 offset:20736
	s_cmp_lg_u64 s[12:13], 0
	s_cbranch_scc1 .Latt_nd2_2B1
	s_lshl_b32 s101, s100, 15
	s_add_i32 m0, s41, s101
	s_add_u32 s100, s22, 0x1000
	s_addc_u32 s101, s23, 0
	global_load_lds_dwordx4 v182, s[100:101]
.Latt_nd2_2B1:
	s_waitcnt lgkmcnt(8)
	v_mfma_f32_32x32x16_bf16 v[64:79], v[238:241], v[242:245], v[64:79]
	ds_read_b64_tr_b16 v[238:239], v205 offset:24576
	ds_read_b64_tr_b16 v[240:241], v205 offset:28672
	s_cmp_lg_u64 s[12:13], 0
	s_cbranch_scc1 .Latt_nd3_2B1
	s_add_i32 m0, m0, 0x400
	s_nop 0
	global_load_lds_dwordx4 v184, s[100:101]
.Latt_nd3_2B1:
	s_waitcnt lgkmcnt(8)
	v_mfma_f32_32x32x16_bf16 v[48:63], v[222:225], v[242:245], v[48:63]
	ds_read_b64_tr_b16 v[222:223], v218 offset:24576
	ds_read_b64_tr_b16 v[224:225], v218 offset:28672
	s_cmp_lg_u64 s[12:13], 0
	s_cbranch_scc1 .Latt_nd4_2B1
	s_add_i32 m0, m0, 0x400
	s_nop 0
	global_load_lds_dwordx4 v186, s[100:101]
.Latt_nd4_2B1:
	s_waitcnt lgkmcnt(8)
	v_mfma_f32_32x32x16_bf16 v[32:47], v[206:209], v[242:245], v[32:47]
	ds_read_b64_tr_b16 v[206:207], v219 offset:24576
	ds_read_b64_tr_b16 v[208:209], v219 offset:28672
	s_cmp_lg_u64 s[12:13], 0
	s_cbranch_scc1 .Latt_nd5_2B1
	s_add_i32 m0, m0, 0x400
	s_nop 0
	global_load_lds_dwordx4 v188, s[100:101]
.Latt_nd5_2B1:
	s_waitcnt lgkmcnt(8)
	v_mfma_f32_32x32x16_bf16 v[16:31], v[210:213], v[242:245], v[16:31]
	ds_read_b64_tr_b16 v[210:211], v221 offset:24576
	ds_read_b64_tr_b16 v[212:213], v221 offset:28672
	s_waitcnt lgkmcnt(8)
	v_mfma_f32_32x32x16_bf16 v[0:15], v[214:217], v[242:245], v[0:15]
	ds_read_b64_tr_b16 v[214:215], v205 offset:24832
	ds_read_b64_tr_b16 v[216:217], v205 offset:28928
	s_waitcnt lgkmcnt(8)
	v_mfma_f32_32x32x16_bf16 v[112:127], v[238:241], v[250:253], v[112:127]
	ds_read_b64_tr_b16 v[238:239], v218 offset:24832
	ds_read_b64_tr_b16 v[240:241], v218 offset:28928
	s_waitcnt lgkmcnt(8)
	v_mfma_f32_32x32x16_bf16 v[96:111], v[222:225], v[250:253], v[96:111]
	ds_read_b64_tr_b16 v[222:223], v219 offset:24832
	ds_read_b64_tr_b16 v[224:225], v219 offset:28928
	s_waitcnt lgkmcnt(8)
	v_mfma_f32_32x32x16_bf16 v[80:95], v[206:209], v[250:253], v[80:95]
	ds_read_b64_tr_b16 v[206:207], v221 offset:24832
	ds_read_b64_tr_b16 v[208:209], v221 offset:28928
	v_bfe_u32 v246, v204, 2, 2
	v_bfe_u32 v247, v204, 5, 1
	v_lshl_or_b32 v247, v247, 2, v246
	v_and_b32_e32 v249, 3, v204
	v_and_b32_e32 v254, 16, v204
	v_lshl_or_b32 v249, v249, 2, v254
	v_lshlrev_b32_e32 v249, 1, v249
	v_lshl_add_u32 v247, v247, 9, v249
	v_add_u32_e32 v247, s99, v247
	v_lshlrev_b32_e32 v246, 6, v246
	v_add_u32_e32 v205, v247, v246
	v_xor_b32_e32 v249, 64, v246
	v_add_u32_e32 v218, v247, v249
	v_xor_b32_e32 v249, 0x80, v246
	v_add_u32_e32 v219, v247, v249
	v_xor_b32_e32 v249, 0xc0, v246
	v_add_u32_e32 v221, v247, v249
	s_waitcnt lgkmcnt(8)
	v_mfma_f32_32x32x16_bf16 v[64:79], v[210:213], v[250:253], v[64:79]
	v_add_u32_e32 v210, s98, v195
	ds_read_b128 v[210:213], v210
	v_add_u32_e32 v226, s98, v196
	ds_read_b128 v[226:229], v226
	s_waitcnt lgkmcnt(8)
	v_mfma_f32_32x32x16_bf16 v[48:63], v[214:217], v[250:253], v[48:63]
	v_add_u32_e32 v214, s98, v197
	ds_read_b128 v[214:217], v214
	v_add_u32_e32 v230, s98, v198
	ds_read_b128 v[230:233], v230
	s_waitcnt lgkmcnt(8)
	v_mfma_f32_32x32x16_bf16 v[32:47], v[238:241], v[250:253], v[32:47]
	v_add_u32_e32 v238, s98, v199
	ds_read_b128 v[238:241], v238
	v_add_u32_e32 v234, s98, v200
	ds_read_b128 v[234:237], v234
	s_waitcnt lgkmcnt(8)
	v_mfma_f32_32x32x16_bf16 v[16:31], v[222:225], v[250:253], v[16:31]
	v_add_u32_e32 v222, s98, v201
	ds_read_b128 v[222:225], v222
	s_waitcnt lgkmcnt(7)
	v_mfma_f32_32x32x16_bf16 v[0:15], v[206:209], v[250:253], v[0:15]
	v_add_u32_e32 v206, s98, v202
	ds_read_b128 v[206:209], v206
	v_add_u32_e32 v242, s98, v195
	ds_read_b128 v[242:245], v242 offset:8192
	s_waitcnt lgkmcnt(8)
	v_mfma_f32_32x32x16_bf16 v[128:143], v[210:213], v[144:147], 0
	v_add_u32_e32 v210, s98, v196
	ds_read_b128 v[210:213], v210 offset:8192
	v_add_u32_e32 v250, s98, v197
	ds_read_b128 v[250:253], v250 offset:8192
	s_waitcnt lgkmcnt(9)
	v_mfma_f32_32x32x16_bf16 v[128:143], v[226:229], v[148:151], v[128:143]
	s_waitcnt lgkmcnt(8)
	v_mfma_f32_32x32x16_bf16 v[128:143], v[214:217], v[152:155], v[128:143]
	v_add_u32_e32 v214, s98, v198
	ds_read_b128 v[214:217], v214 offset:8192
	s_waitcnt lgkmcnt(8)
	v_mfma_f32_32x32x16_bf16 v[128:143], v[230:233], v[156:159], v[128:143]
	s_waitcnt lgkmcnt(7)
	v_mfma_f32_32x32x16_bf16 v[128:143], v[238:241], v[160:163], v[128:143]
	v_add_u32_e32 v238, s98, v199
	ds_read_b128 v[238:241], v238 offset:8192
	s_waitcnt lgkmcnt(7)
	v_mfma_f32_32x32x16_bf16 v[128:143], v[234:237], v[164:167], v[128:143]
	s_waitcnt lgkmcnt(6)
	v_mfma_f32_32x32x16_bf16 v[128:143], v[222:225], v[168:171], v[128:143]
	s_waitcnt lgkmcnt(5)
	v_mfma_f32_32x32x16_bf16 v[128:143], v[206:209], v[172:175], v[128:143]
	v_add_u32_e32 v206, s98, v200
	ds_read_b128 v[206:209], v206 offset:8192
	s_waitcnt lgkmcnt(5)
	v_mfma_f32_32x32x16_bf16 v[222:237], v[242:245], v[144:147], 0
	v_add_u32_e32 v242, s98, v201
	ds_read_b128 v[242:245], v242 offset:8192
	s_nop 5
	v_max3_f32 v246, v128, v129, v130
	v_max3_f32 v247, v131, v132, v133
	v_max3_f32 v246, v246, v134, v135
	v_max3_f32 v247, v247, v136, v137
	v_max3_f32 v246, v246, v138, v139
	v_max3_f32 v247, v247, v140, v141
	v_max3_f32 v246, v246, v142, v143
	s_waitcnt lgkmcnt(5)
	v_mfma_f32_32x32x16_bf16 v[222:237], v[210:213], v[148:151], v[222:237]
	v_add_u32_e32 v210, s98, v202
	ds_read_b128 v[210:213], v210 offset:8192
	v_max_f32_e32 v246, v246, v247
	v_mov_b32_e32 v247, v246
	v_add_f32_e32 v249, 0x41000000, v190
	s_nop 1
	v_permlane32_swap_b32_e32 v246, v247
	v_max_f32_e32 v246, v246, v247
	v_cmp_gt_f32_e32 vcc, v246, v249
	s_cbranch_vccz .Latt_nr0_2B1
	v_max_f32_e32 v246, v190, v246
	v_sub_f32_e32 v190, v190, v246
	v_exp_f32_e32 v190, v190
	s_nop 0
	v_pk_mul_f32 v[126:127], v[126:127], v[190:191] op_sel_hi:[1,0]
	v_pk_mul_f32 v[124:125], v[124:125], v[190:191] op_sel_hi:[1,0]
	v_pk_mul_f32 v[122:123], v[122:123], v[190:191] op_sel_hi:[1,0]
	v_pk_mul_f32 v[120:121], v[120:121], v[190:191] op_sel_hi:[1,0]
	v_pk_mul_f32 v[118:119], v[118:119], v[190:191] op_sel_hi:[1,0]
	v_pk_mul_f32 v[116:117], v[116:117], v[190:191] op_sel_hi:[1,0]
	v_pk_mul_f32 v[114:115], v[114:115], v[190:191] op_sel_hi:[1,0]
	v_pk_mul_f32 v[112:113], v[112:113], v[190:191] op_sel_hi:[1,0]
	v_pk_mul_f32 v[110:111], v[110:111], v[190:191] op_sel_hi:[1,0]
	v_pk_mul_f32 v[108:109], v[108:109], v[190:191] op_sel_hi:[1,0]
	v_pk_mul_f32 v[106:107], v[106:107], v[190:191] op_sel_hi:[1,0]
	v_pk_mul_f32 v[104:105], v[104:105], v[190:191] op_sel_hi:[1,0]
	v_pk_mul_f32 v[102:103], v[102:103], v[190:191] op_sel_hi:[1,0]
	v_pk_mul_f32 v[100:101], v[100:101], v[190:191] op_sel_hi:[1,0]
	v_pk_mul_f32 v[98:99], v[98:99], v[190:191] op_sel_hi:[1,0]
	v_pk_mul_f32 v[96:97], v[96:97], v[190:191] op_sel_hi:[1,0]
	v_pk_mul_f32 v[94:95], v[94:95], v[190:191] op_sel_hi:[1,0]
	v_pk_mul_f32 v[92:93], v[92:93], v[190:191] op_sel_hi:[1,0]
	v_pk_mul_f32 v[90:91], v[90:91], v[190:191] op_sel_hi:[1,0]
	v_pk_mul_f32 v[88:89], v[88:89], v[190:191] op_sel_hi:[1,0]
	v_pk_mul_f32 v[86:87], v[86:87], v[190:191] op_sel_hi:[1,0]
	v_pk_mul_f32 v[84:85], v[84:85], v[190:191] op_sel_hi:[1,0]
	v_pk_mul_f32 v[82:83], v[82:83], v[190:191] op_sel_hi:[1,0]
	v_pk_mul_f32 v[80:81], v[80:81], v[190:191] op_sel_hi:[1,0]
	v_pk_mul_f32 v[78:79], v[78:79], v[190:191] op_sel_hi:[1,0]
	v_pk_mul_f32 v[76:77], v[76:77], v[190:191] op_sel_hi:[1,0]
	v_pk_mul_f32 v[74:75], v[74:75], v[190:191] op_sel_hi:[1,0]
	v_pk_mul_f32 v[72:73], v[72:73], v[190:191] op_sel_hi:[1,0]
	v_pk_mul_f32 v[70:71], v[70:71], v[190:191] op_sel_hi:[1,0]
	v_pk_mul_f32 v[68:69], v[68:69], v[190:191] op_sel_hi:[1,0]
	v_pk_mul_f32 v[66:67], v[66:67], v[190:191] op_sel_hi:[1,0]
	v_pk_mul_f32 v[64:65], v[64:65], v[190:191] op_sel_hi:[1,0]
	v_pk_mul_f32 v[62:63], v[62:63], v[190:191] op_sel_hi:[1,0]
	v_pk_mul_f32 v[60:61], v[60:61], v[190:191] op_sel_hi:[1,0]
	v_pk_mul_f32 v[58:59], v[58:59], v[190:191] op_sel_hi:[1,0]
	v_pk_mul_f32 v[56:57], v[56:57], v[190:191] op_sel_hi:[1,0]
	v_pk_mul_f32 v[54:55], v[54:55], v[190:191] op_sel_hi:[1,0]
	v_pk_mul_f32 v[52:53], v[52:53], v[190:191] op_sel_hi:[1,0]
	v_pk_mul_f32 v[50:51], v[50:51], v[190:191] op_sel_hi:[1,0]
	v_pk_mul_f32 v[48:49], v[48:49], v[190:191] op_sel_hi:[1,0]
	v_pk_mul_f32 v[46:47], v[46:47], v[190:191] op_sel_hi:[1,0]
	v_pk_mul_f32 v[44:45], v[44:45], v[190:191] op_sel_hi:[1,0]
	v_pk_mul_f32 v[42:43], v[42:43], v[190:191] op_sel_hi:[1,0]
	v_pk_mul_f32 v[40:41], v[40:41], v[190:191] op_sel_hi:[1,0]
	v_pk_mul_f32 v[38:39], v[38:39], v[190:191] op_sel_hi:[1,0]
	v_pk_mul_f32 v[36:37], v[36:37], v[190:191] op_sel_hi:[1,0]
	v_pk_mul_f32 v[34:35], v[34:35], v[190:191] op_sel_hi:[1,0]
	v_pk_mul_f32 v[32:33], v[32:33], v[190:191] op_sel_hi:[1,0]
	v_pk_mul_f32 v[30:31], v[30:31], v[190:191] op_sel_hi:[1,0]
	v_pk_mul_f32 v[28:29], v[28:29], v[190:191] op_sel_hi:[1,0]
	v_pk_mul_f32 v[26:27], v[26:27], v[190:191] op_sel_hi:[1,0]
	v_pk_mul_f32 v[24:25], v[24:25], v[190:191] op_sel_hi:[1,0]
	v_pk_mul_f32 v[22:23], v[22:23], v[190:191] op_sel_hi:[1,0]
	v_pk_mul_f32 v[20:21], v[20:21], v[190:191] op_sel_hi:[1,0]
	v_pk_mul_f32 v[18:19], v[18:19], v[190:191] op_sel_hi:[1,0]
	v_pk_mul_f32 v[16:17], v[16:17], v[190:191] op_sel_hi:[1,0]
	v_pk_mul_f32 v[14:15], v[14:15], v[190:191] op_sel_hi:[1,0]
	v_pk_mul_f32 v[12:13], v[12:13], v[190:191] op_sel_hi:[1,0]
	v_pk_mul_f32 v[10:11], v[10:11], v[190:191] op_sel_hi:[1,0]
	v_pk_mul_f32 v[8:9], v[8:9], v[190:191] op_sel_hi:[1,0]
	v_pk_mul_f32 v[6:7], v[6:7], v[190:191] op_sel_hi:[1,0]
	v_pk_mul_f32 v[4:5], v[4:5], v[190:191] op_sel_hi:[1,0]
	v_pk_mul_f32 v[2:3], v[2:3], v[190:191] op_sel_hi:[1,0]
	v_pk_mul_f32 v[0:1], v[0:1], v[190:191] op_sel_hi:[1,0]
	v_mul_f32_e32 v203, v203, v190
	v_mov_b32_e32 v190, v246
.Latt_nr0_2B1:
	s_waitcnt lgkmcnt(5)
	v_mfma_f32_32x32x16_bf16 v[222:237], v[250:253], v[152:155], v[222:237]
	v_sub_f32_e32 v128, v128, v190
	v_exp_f32_e32 v128, v128
	v_sub_f32_e32 v129, v129, v190
	v_exp_f32_e32 v129, v129
	v_sub_f32_e32 v130, v130, v190
	v_add_f32_e32 v254, 0, v128
	v_exp_f32_e32 v130, v130
	v_sub_f32_e32 v131, v131, v190
	s_waitcnt lgkmcnt(4)
	v_mfma_f32_32x32x16_bf16 v[222:237], v[214:217], v[156:159], v[222:237]
	ds_read_b64_tr_b16 v[214:215], v205
	ds_read_b64_tr_b16 v[216:217], v205 offset:4096
	v_add_f32_e32 v254, v129, v254
	v_exp_f32_e32 v131, v131
	v_sub_f32_e32 v132, v132, v190
	v_add_f32_e32 v254, v130, v254
	v_exp_f32_e32 v132, v132
	v_sub_f32_e32 v133, v133, v190
	v_add_f32_e32 v254, v131, v254
	v_exp_f32_e32 v133, v133
	s_waitcnt lgkmcnt(5)
	v_mfma_f32_32x32x16_bf16 v[222:237], v[238:241], v[160:163], v[222:237]
	ds_read_b64_tr_b16 v[238:239], v218
	ds_read_b64_tr_b16 v[240:241], v218 offset:4096
	v_sub_f32_e32 v134, v134, v190
	v_add_f32_e32 v254, v132, v254
	v_exp_f32_e32 v134, v134
	v_sub_f32_e32 v135, v135, v190
	v_add_f32_e32 v254, v133, v254
	v_exp_f32_e32 v135, v135
	v_sub_f32_e32 v136, v136, v190
	v_add_f32_e32 v254, v134, v254
	s_waitcnt lgkmcnt(6)
	v_mfma_f32_32x32x16_bf16 v[222:237], v[206:209], v[164:167], v[222:237]
	ds_read_b64_tr_b16 v[206:207], v219
	ds_read_b64_tr_b16 v[208:209], v219 offset:4096
	v_exp_f32_e32 v136, v136
	v_sub_f32_e32 v137, v137, v190
	v_add_f32_e32 v254, v135, v254
	v_exp_f32_e32 v137, v137
	v_sub_f32_e32 v138, v138, v190
	v_add_f32_e32 v254, v136, v254
	v_exp_f32_e32 v138, v138
	v_sub_f32_e32 v139, v139, v190
	s_waitcnt lgkmcnt(7)
	v_mfma_f32_32x32x16_bf16 v[222:237], v[242:245], v[168:171], v[222:237]
	v_add_f32_e32 v254, v137, v254
	v_exp_f32_e32 v139, v139
	v_sub_f32_e32 v140, v140, v190
	v_add_f32_e32 v254, v138, v254
	v_exp_f32_e32 v140, v140
	v_sub_f32_e32 v141, v141, v190
	v_add_f32_e32 v254, v139, v254
	v_exp_f32_e32 v141, v141
	s_waitcnt lgkmcnt(6)
	v_mfma_f32_32x32x16_bf16 v[222:237], v[210:213], v[172:175], v[222:237]
	ds_read_b64_tr_b16 v[210:211], v221
	ds_read_b64_tr_b16 v[212:213], v221 offset:4096
	v_sub_f32_e32 v142, v142, v190
	v_add_f32_e32 v254, v140, v254
	v_exp_f32_e32 v142, v142
	v_sub_f32_e32 v143, v143, v190
	v_add_f32_e32 v254, v141, v254
	v_exp_f32_e32 v143, v143
	v_add_f32_e32 v254, v142, v254
	v_add_f32_e32 v254, v143, v254
	v_cvt_pk_bf16_f32 v242, v128, v129
	v_cvt_pk_bf16_f32 v243, v130, v131
	v_cvt_pk_bf16_f32 v244, v132, v133
	v_cvt_pk_bf16_f32 v245, v134, v135
	v_cvt_pk_bf16_f32 v250, v136, v137
	v_cvt_pk_bf16_f32 v251, v138, v139
	v_cvt_pk_bf16_f32 v252, v140, v141
	v_cvt_pk_bf16_f32 v253, v142, v143
	v_add_f32_e32 v203, v203, v254
	s_nop 1
	ds_read_b64_tr_b16 v[128:129], v205 offset:256
	ds_read_b64_tr_b16 v[130:131], v205 offset:4352
	s_waitcnt lgkmcnt(8)
	v_mfma_f32_32x32x16_bf16 v[112:127], v[214:217], v[242:245], v[112:127]
	ds_read_b64_tr_b16 v[214:215], v218 offset:256
	ds_read_b64_tr_b16 v[216:217], v218 offset:4352
	s_waitcnt lgkmcnt(8)
	v_mfma_f32_32x32x16_bf16 v[96:111], v[238:241], v[242:245], v[96:111]
	ds_read_b64_tr_b16 v[238:239], v219 offset:256
	ds_read_b64_tr_b16 v[240:241], v219 offset:4352
	s_waitcnt lgkmcnt(8)
	v_mfma_f32_32x32x16_bf16 v[80:95], v[206:209], v[242:245], v[80:95]
	ds_read_b64_tr_b16 v[206:207], v221 offset:256
	ds_read_b64_tr_b16 v[208:209], v221 offset:4352
	v_max3_f32 v246, v222, v223, v224
	v_max3_f32 v247, v225, v226, v227
	v_max3_f32 v246, v246, v228, v229
	v_max3_f32 v247, v247, v230, v231
	v_max3_f32 v246, v246, v232, v233
	v_max3_f32 v247, v247, v234, v235
	s_waitcnt lgkmcnt(8)
	v_mfma_f32_32x32x16_bf16 v[64:79], v[210:213], v[242:245], v[64:79]
	ds_read_b64_tr_b16 v[210:211], v205 offset:8192
	ds_read_b64_tr_b16 v[212:213], v205 offset:12288
	v_max3_f32 v246, v246, v236, v237
	v_max_f32_e32 v246, v246, v247
	v_mov_b32_e32 v247, v246
	v_add_f32_e32 v249, 0x41000000, v190
	s_nop 1
	s_waitcnt lgkmcnt(8)
	v_mfma_f32_32x32x16_bf16 v[48:63], v[128:131], v[242:245], v[48:63]
	ds_read_b64_tr_b16 v[128:129], v218 offset:8192
	ds_read_b64_tr_b16 v[130:131], v218 offset:12288
	v_permlane32_swap_b32_e32 v246, v247
	v_max_f32_e32 v246, v246, v247
	v_cmp_gt_f32_e32 vcc, v246, v249
	s_cbranch_vccnz .Latt_rs1_2B1
	s_waitcnt lgkmcnt(8)
	v_mfma_f32_32x32x16_bf16 v[32:47], v[214:217], v[242:245], v[32:47]
	ds_read_b64_tr_b16 v[214:215], v219 offset:8192
	ds_read_b64_tr_b16 v[216:217], v219 offset:12288
	v_sub_f32_e32 v222, v222, v190
	v_exp_f32_e32 v222, v222
	v_sub_f32_e32 v223, v223, v190
	v_exp_f32_e32 v223, v223
	v_sub_f32_e32 v224, v224, v190
	s_waitcnt lgkmcnt(8)
	v_mfma_f32_32x32x16_bf16 v[16:31], v[238:241], v[242:245], v[16:31]
	ds_read_b64_tr_b16 v[238:239], v221 offset:8192
	ds_read_b64_tr_b16 v[240:241], v221 offset:12288
	v_add_f32_e32 v254, 0, v222
	v_exp_f32_e32 v224, v224
	v_sub_f32_e32 v225, v225, v190
	v_add_f32_e32 v254, v223, v254
	v_exp_f32_e32 v225, v225
	s_waitcnt lgkmcnt(8)
	v_mfma_f32_32x32x16_bf16 v[0:15], v[206:209], v[242:245], v[0:15]
	ds_read_b64_tr_b16 v[206:207], v205 offset:8448
	ds_read_b64_tr_b16 v[208:209], v205 offset:12544
	v_sub_f32_e32 v226, v226, v190
	v_add_f32_e32 v254, v224, v254
	v_exp_f32_e32 v226, v226
	v_sub_f32_e32 v227, v227, v190
	v_add_f32_e32 v254, v225, v254
	s_waitcnt lgkmcnt(8)
	v_mfma_f32_32x32x16_bf16 v[112:127], v[210:213], v[250:253], v[112:127]
	ds_read_b64_tr_b16 v[210:211], v218 offset:8448
	ds_read_b64_tr_b16 v[212:213], v218 offset:12544
	v_exp_f32_e32 v227, v227
	v_sub_f32_e32 v228, v228, v190
	v_add_f32_e32 v254, v226, v254
	v_exp_f32_e32 v228, v228
	v_sub_f32_e32 v229, v229, v190
	s_waitcnt lgkmcnt(8)
	v_mfma_f32_32x32x16_bf16 v[96:111], v[128:131], v[250:253], v[96:111]
	ds_read_b64_tr_b16 v[128:129], v219 offset:8448
	ds_read_b64_tr_b16 v[130:131], v219 offset:12544
	v_add_f32_e32 v254, v227, v254
	v_exp_f32_e32 v229, v229
	v_sub_f32_e32 v230, v230, v190
	v_add_f32_e32 v254, v228, v254
	s_waitcnt lgkmcnt(8)
	v_mfma_f32_32x32x16_bf16 v[80:95], v[214:217], v[250:253], v[80:95]
	ds_read_b64_tr_b16 v[214:215], v221 offset:8448
	ds_read_b64_tr_b16 v[216:217], v221 offset:12544
	v_exp_f32_e32 v230, v230
	v_sub_f32_e32 v231, v231, v190
	v_add_f32_e32 v254, v229, v254
	v_exp_f32_e32 v231, v231
	s_waitcnt lgkmcnt(8)
	v_mfma_f32_32x32x16_bf16 v[64:79], v[238:241], v[250:253], v[64:79]
	v_sub_f32_e32 v232, v232, v190
	v_add_f32_e32 v254, v230, v254
	v_exp_f32_e32 v232, v232
	v_sub_f32_e32 v233, v233, v190
	s_waitcnt lgkmcnt(6)
	v_mfma_f32_32x32x16_bf16 v[48:63], v[206:209], v[250:253], v[48:63]
	v_add_f32_e32 v254, v231, v254
	v_exp_f32_e32 v233, v233
	v_sub_f32_e32 v234, v234, v190
	v_add_f32_e32 v254, v232, v254
	s_waitcnt lgkmcnt(4)
	v_mfma_f32_32x32x16_bf16 v[32:47], v[210:213], v[250:253], v[32:47]
	v_exp_f32_e32 v234, v234
	v_sub_f32_e32 v235, v235, v190
	v_add_f32_e32 v254, v233, v254
	v_exp_f32_e32 v235, v235
	s_waitcnt lgkmcnt(2)
	v_mfma_f32_32x32x16_bf16 v[16:31], v[128:131], v[250:253], v[16:31]
	v_sub_f32_e32 v236, v236, v190
	v_add_f32_e32 v254, v234, v254
	v_exp_f32_e32 v236, v236
	v_sub_f32_e32 v237, v237, v190
	s_waitcnt lgkmcnt(0)
	v_mfma_f32_32x32x16_bf16 v[0:15], v[214:217], v[250:253], v[0:15]
	v_add_f32_e32 v254, v235, v254
	v_exp_f32_e32 v237, v237
	v_add_f32_e32 v254, v236, v254
	v_add_f32_e32 v254, v237, v254
	v_cvt_pk_bf16_f32 v242, v222, v223
	v_cvt_pk_bf16_f32 v243, v224, v225
	v_cvt_pk_bf16_f32 v244, v226, v227
	v_cvt_pk_bf16_f32 v245, v228, v229
	v_cvt_pk_bf16_f32 v250, v230, v231
	v_cvt_pk_bf16_f32 v251, v232, v233
	v_cvt_pk_bf16_f32 v252, v234, v235
	v_cvt_pk_bf16_f32 v253, v236, v237
	v_add_f32_e32 v203, v203, v254
	s_nop 1

.Latt_rs1_2B1:
	s_waitcnt lgkmcnt(8)
	v_mfma_f32_32x32x16_bf16 v[32:47], v[214:217], v[242:245], v[32:47]
	ds_read_b64_tr_b16 v[214:215], v219 offset:8192
	ds_read_b64_tr_b16 v[216:217], v219 offset:12288
	s_waitcnt lgkmcnt(8)
	v_mfma_f32_32x32x16_bf16 v[16:31], v[238:241], v[242:245], v[16:31]
	ds_read_b64_tr_b16 v[238:239], v221 offset:8192
	ds_read_b64_tr_b16 v[240:241], v221 offset:12288
	s_waitcnt lgkmcnt(8)
	v_mfma_f32_32x32x16_bf16 v[0:15], v[206:209], v[242:245], v[0:15]
	ds_read_b64_tr_b16 v[206:207], v205 offset:8448
	ds_read_b64_tr_b16 v[208:209], v205 offset:12544
	s_waitcnt lgkmcnt(8)
	v_mfma_f32_32x32x16_bf16 v[112:127], v[210:213], v[250:253], v[112:127]
	ds_read_b64_tr_b16 v[210:211], v218 offset:8448
	ds_read_b64_tr_b16 v[212:213], v218 offset:12544
	s_waitcnt lgkmcnt(8)
	v_mfma_f32_32x32x16_bf16 v[96:111], v[128:131], v[250:253], v[96:111]
	ds_read_b64_tr_b16 v[128:129], v219 offset:8448
	ds_read_b64_tr_b16 v[130:131], v219 offset:12544
	s_waitcnt lgkmcnt(8)
	v_mfma_f32_32x32x16_bf16 v[80:95], v[214:217], v[250:253], v[80:95]
	ds_read_b64_tr_b16 v[214:215], v221 offset:8448
	ds_read_b64_tr_b16 v[216:217], v221 offset:12544
	s_waitcnt lgkmcnt(8)
	v_mfma_f32_32x32x16_bf16 v[64:79], v[238:241], v[250:253], v[64:79]
	s_waitcnt lgkmcnt(6)
	v_mfma_f32_32x32x16_bf16 v[48:63], v[206:209], v[250:253], v[48:63]
	s_waitcnt lgkmcnt(4)
	v_mfma_f32_32x32x16_bf16 v[32:47], v[210:213], v[250:253], v[32:47]
	s_waitcnt lgkmcnt(2)
	v_mfma_f32_32x32x16_bf16 v[16:31], v[128:131], v[250:253], v[16:31]
	s_waitcnt lgkmcnt(0)
	v_mfma_f32_32x32x16_bf16 v[0:15], v[214:217], v[250:253], v[0:15]
	s_nop 11
	v_max_f32_e32 v246, v190, v246
	v_sub_f32_e32 v190, v190, v246
	v_exp_f32_e32 v190, v190
	s_nop 0
	v_pk_mul_f32 v[126:127], v[126:127], v[190:191] op_sel_hi:[1,0]
	v_pk_mul_f32 v[124:125], v[124:125], v[190:191] op_sel_hi:[1,0]
	v_pk_mul_f32 v[122:123], v[122:123], v[190:191] op_sel_hi:[1,0]
	v_pk_mul_f32 v[120:121], v[120:121], v[190:191] op_sel_hi:[1,0]
	v_pk_mul_f32 v[118:119], v[118:119], v[190:191] op_sel_hi:[1,0]
	v_pk_mul_f32 v[116:117], v[116:117], v[190:191] op_sel_hi:[1,0]
	v_pk_mul_f32 v[114:115], v[114:115], v[190:191] op_sel_hi:[1,0]
	v_pk_mul_f32 v[112:113], v[112:113], v[190:191] op_sel_hi:[1,0]
	v_pk_mul_f32 v[110:111], v[110:111], v[190:191] op_sel_hi:[1,0]
	v_pk_mul_f32 v[108:109], v[108:109], v[190:191] op_sel_hi:[1,0]
	v_pk_mul_f32 v[106:107], v[106:107], v[190:191] op_sel_hi:[1,0]
	v_pk_mul_f32 v[104:105], v[104:105], v[190:191] op_sel_hi:[1,0]
	v_pk_mul_f32 v[102:103], v[102:103], v[190:191] op_sel_hi:[1,0]
	v_pk_mul_f32 v[100:101], v[100:101], v[190:191] op_sel_hi:[1,0]
	v_pk_mul_f32 v[98:99], v[98:99], v[190:191] op_sel_hi:[1,0]
	v_pk_mul_f32 v[96:97], v[96:97], v[190:191] op_sel_hi:[1,0]
	v_pk_mul_f32 v[94:95], v[94:95], v[190:191] op_sel_hi:[1,0]
	v_pk_mul_f32 v[92:93], v[92:93], v[190:191] op_sel_hi:[1,0]
	v_pk_mul_f32 v[90:91], v[90:91], v[190:191] op_sel_hi:[1,0]
	v_pk_mul_f32 v[88:89], v[88:89], v[190:191] op_sel_hi:[1,0]
	v_pk_mul_f32 v[86:87], v[86:87], v[190:191] op_sel_hi:[1,0]
	v_pk_mul_f32 v[84:85], v[84:85], v[190:191] op_sel_hi:[1,0]
	v_pk_mul_f32 v[82:83], v[82:83], v[190:191] op_sel_hi:[1,0]
	v_pk_mul_f32 v[80:81], v[80:81], v[190:191] op_sel_hi:[1,0]
	v_pk_mul_f32 v[78:79], v[78:79], v[190:191] op_sel_hi:[1,0]
	v_pk_mul_f32 v[76:77], v[76:77], v[190:191] op_sel_hi:[1,0]
	v_pk_mul_f32 v[74:75], v[74:75], v[190:191] op_sel_hi:[1,0]
	v_pk_mul_f32 v[72:73], v[72:73], v[190:191] op_sel_hi:[1,0]
	v_pk_mul_f32 v[70:71], v[70:71], v[190:191] op_sel_hi:[1,0]
	v_pk_mul_f32 v[68:69], v[68:69], v[190:191] op_sel_hi:[1,0]
	v_pk_mul_f32 v[66:67], v[66:67], v[190:191] op_sel_hi:[1,0]
	v_pk_mul_f32 v[64:65], v[64:65], v[190:191] op_sel_hi:[1,0]
	v_pk_mul_f32 v[62:63], v[62:63], v[190:191] op_sel_hi:[1,0]
	v_pk_mul_f32 v[60:61], v[60:61], v[190:191] op_sel_hi:[1,0]
	v_pk_mul_f32 v[58:59], v[58:59], v[190:191] op_sel_hi:[1,0]
	v_pk_mul_f32 v[56:57], v[56:57], v[190:191] op_sel_hi:[1,0]
	v_pk_mul_f32 v[54:55], v[54:55], v[190:191] op_sel_hi:[1,0]
	v_pk_mul_f32 v[52:53], v[52:53], v[190:191] op_sel_hi:[1,0]
	v_pk_mul_f32 v[50:51], v[50:51], v[190:191] op_sel_hi:[1,0]
	v_pk_mul_f32 v[48:49], v[48:49], v[190:191] op_sel_hi:[1,0]
	v_pk_mul_f32 v[46:47], v[46:47], v[190:191] op_sel_hi:[1,0]
	v_pk_mul_f32 v[44:45], v[44:45], v[190:191] op_sel_hi:[1,0]
	v_pk_mul_f32 v[42:43], v[42:43], v[190:191] op_sel_hi:[1,0]
	v_pk_mul_f32 v[40:41], v[40:41], v[190:191] op_sel_hi:[1,0]
	v_pk_mul_f32 v[38:39], v[38:39], v[190:191] op_sel_hi:[1,0]
	v_pk_mul_f32 v[36:37], v[36:37], v[190:191] op_sel_hi:[1,0]
	v_pk_mul_f32 v[34:35], v[34:35], v[190:191] op_sel_hi:[1,0]
	v_pk_mul_f32 v[32:33], v[32:33], v[190:191] op_sel_hi:[1,0]
	v_pk_mul_f32 v[30:31], v[30:31], v[190:191] op_sel_hi:[1,0]
	v_pk_mul_f32 v[28:29], v[28:29], v[190:191] op_sel_hi:[1,0]
	v_pk_mul_f32 v[26:27], v[26:27], v[190:191] op_sel_hi:[1,0]
	v_pk_mul_f32 v[24:25], v[24:25], v[190:191] op_sel_hi:[1,0]
	v_pk_mul_f32 v[22:23], v[22:23], v[190:191] op_sel_hi:[1,0]
	v_pk_mul_f32 v[20:21], v[20:21], v[190:191] op_sel_hi:[1,0]
	v_pk_mul_f32 v[18:19], v[18:19], v[190:191] op_sel_hi:[1,0]
	v_pk_mul_f32 v[16:17], v[16:17], v[190:191] op_sel_hi:[1,0]
	v_pk_mul_f32 v[14:15], v[14:15], v[190:191] op_sel_hi:[1,0]
	v_pk_mul_f32 v[12:13], v[12:13], v[190:191] op_sel_hi:[1,0]
	v_pk_mul_f32 v[10:11], v[10:11], v[190:191] op_sel_hi:[1,0]
	v_pk_mul_f32 v[8:9], v[8:9], v[190:191] op_sel_hi:[1,0]
	v_pk_mul_f32 v[6:7], v[6:7], v[190:191] op_sel_hi:[1,0]
	v_pk_mul_f32 v[4:5], v[4:5], v[190:191] op_sel_hi:[1,0]
	v_pk_mul_f32 v[2:3], v[2:3], v[190:191] op_sel_hi:[1,0]
	v_pk_mul_f32 v[0:1], v[0:1], v[190:191] op_sel_hi:[1,0]
	v_mul_f32_e32 v203, v203, v190
	v_mov_b32_e32 v190, v246
	v_sub_f32_e32 v222, v222, v190
	v_exp_f32_e32 v222, v222
	v_sub_f32_e32 v223, v223, v190
	v_exp_f32_e32 v223, v223
	v_sub_f32_e32 v224, v224, v190
	v_add_f32_e32 v254, 0, v222
	v_exp_f32_e32 v224, v224
	v_sub_f32_e32 v225, v225, v190
	v_add_f32_e32 v254, v223, v254
	v_exp_f32_e32 v225, v225
	v_sub_f32_e32 v226, v226, v190
	v_add_f32_e32 v254, v224, v254
	v_exp_f32_e32 v226, v226
	v_sub_f32_e32 v227, v227, v190
	v_add_f32_e32 v254, v225, v254
	v_exp_f32_e32 v227, v227
	v_sub_f32_e32 v228, v228, v190
	v_add_f32_e32 v254, v226, v254
	v_exp_f32_e32 v228, v228
	v_sub_f32_e32 v229, v229, v190
	v_add_f32_e32 v254, v227, v254
	v_exp_f32_e32 v229, v229
	v_sub_f32_e32 v230, v230, v190
	v_add_f32_e32 v254, v228, v254
	v_exp_f32_e32 v230, v230
	v_sub_f32_e32 v231, v231, v190
	v_add_f32_e32 v254, v229, v254
	v_exp_f32_e32 v231, v231
	v_sub_f32_e32 v232, v232, v190
	v_add_f32_e32 v254, v230, v254
	v_exp_f32_e32 v232, v232
	v_sub_f32_e32 v233, v233, v190
	v_add_f32_e32 v254, v231, v254
	v_exp_f32_e32 v233, v233
	v_sub_f32_e32 v234, v234, v190
	v_add_f32_e32 v254, v232, v254
	v_exp_f32_e32 v234, v234
	v_sub_f32_e32 v235, v235, v190
	v_add_f32_e32 v254, v233, v254
	v_exp_f32_e32 v235, v235
	v_sub_f32_e32 v236, v236, v190
	v_add_f32_e32 v254, v234, v254
	v_exp_f32_e32 v236, v236
	v_sub_f32_e32 v237, v237, v190
	v_add_f32_e32 v254, v235, v254
	v_exp_f32_e32 v237, v237
	v_add_f32_e32 v254, v236, v254
	v_add_f32_e32 v254, v237, v254
	v_cvt_pk_bf16_f32 v242, v222, v223
	v_cvt_pk_bf16_f32 v243, v224, v225
	v_cvt_pk_bf16_f32 v244, v226, v227
	v_cvt_pk_bf16_f32 v245, v228, v229
	v_cvt_pk_bf16_f32 v250, v230, v231
	v_cvt_pk_bf16_f32 v251, v232, v233
	v_cvt_pk_bf16_f32 v252, v234, v235
	v_cvt_pk_bf16_f32 v253, v236, v237
	v_add_f32_e32 v203, v203, v254
	s_nop 1
	s_branch .Latt_pv1_2B1
.Latt_B0_2:
	s_lshl_b32 s98, s38, 14
	s_lshl_b32 s99, s38, 15
	s_add_i32 s99, s99, 0xc000
	v_add_u32_e32 v206, s98, v195
	ds_read_b128 v[206:209], v206
	v_add_u32_e32 v210, s98, v196
	ds_read_b128 v[210:213], v210
	v_add_u32_e32 v214, s98, v197
	ds_read_b128 v[214:217], v214
	v_add_u32_e32 v238, s98, v198
	ds_read_b128 v[238:241], v238
	v_add_u32_e32 v242, s98, v199
	ds_read_b128 v[242:245], v242
	v_add_u32_e32 v250, s98, v200
	ds_read_b128 v[250:253], v250
	v_add_u32_e32 v222, s98, v201
	ds_read_b128 v[222:225], v222
	v_add_u32_e32 v226, s98, v202
	ds_read_b128 v[226:229], v226
	v_bfe_u32 v246, v204, 2, 2
	v_bfe_u32 v247, v204, 5, 1
	v_lshl_or_b32 v247, v247, 2, v246
	v_and_b32_e32 v249, 3, v204
	v_and_b32_e32 v254, 16, v204
	v_lshl_or_b32 v249, v249, 2, v254
	v_lshlrev_b32_e32 v249, 1, v249
	v_lshl_add_u32 v247, v247, 9, v249
	v_add_u32_e32 v247, s99, v247
	v_lshlrev_b32_e32 v246, 6, v246
	v_add_u32_e32 v205, v247, v246
	v_xor_b32_e32 v249, 64, v246
	v_add_u32_e32 v218, v247, v249
	v_xor_b32_e32 v249, 0x80, v246
	v_add_u32_e32 v219, v247, v249
	v_xor_b32_e32 v249, 0xc0, v246
	v_add_u32_e32 v221, v247, v249
	s_waitcnt lgkmcnt(7)
	v_mfma_f32_32x32x16_bf16 v[128:143], v[206:209], v[144:147], 0
	v_add_u32_e32 v206, s98, v195
	ds_read_b128 v[206:209], v206 offset:8192
	s_cmp_lg_u64 s[12:13], 0
	s_cbranch_scc1 .Latt_nd0_2B0
	s_add_i32 s100, s38, 1
	s_cmp_eq_u32 s38, 2
	s_cselect_b32 s100, 0, s100
	s_lshl_b32 s101, s100, 14
	s_add_i32 m0, s40, s101
	s_nop 0
	global_load_lds_dwordx4 v178, s[22:23]
.Latt_nd0_2B0:
	s_waitcnt lgkmcnt(7)
	v_mfma_f32_32x32x16_bf16 v[128:143], v[210:213], v[148:151], v[128:143]
	v_add_u32_e32 v210, s98, v196
	ds_read_b128 v[210:213], v210 offset:8192
	s_cmp_lg_u64 s[12:13], 0
	s_cbranch_scc1 .Latt_nd1_2B0
	s_add_i32 m0, m0, 0x400
	s_nop 0
	global_load_lds_dwordx4 v180, s[22:23]
.Latt_nd1_2B0:
	s_waitcnt lgkmcnt(7)
	v_mfma_f32_32x32x16_bf16 v[128:143], v[214:217], v[152:155], v[128:143]
	v_add_u32_e32 v214, s98, v197
	ds_read_b128 v[214:217], v214 offset:8192
	s_cmp_lg_u64 s[12:13], 0
	s_cbranch_scc1 .Latt_nd2_2B0
	s_lshl_b32 s101, s100, 15
	s_add_i32 m0, s41, s101
	s_add_u32 s100, s22, 0x1000
	s_addc_u32 s101, s23, 0
	global_load_lds_dwordx4 v182, s[100:101]
.Latt_nd2_2B0:
	s_waitcnt lgkmcnt(7)
	v_mfma_f32_32x32x16_bf16 v[128:143], v[238:241], v[156:159], v[128:143]
	v_add_u32_e32 v238, s98, v198
	ds_read_b128 v[238:241], v238 offset:8192
	s_cmp_lg_u64 s[12:13], 0
	s_cbranch_scc1 .Latt_nd3_2B0
	s_add_i32 m0, m0, 0x400
	s_nop 0
	global_load_lds_dwordx4 v184, s[100:101]
.Latt_nd3_2B0:
	s_waitcnt lgkmcnt(7)
	v_mfma_f32_32x32x16_bf16 v[128:143], v[242:245], v[160:163], v[128:143]
	v_add_u32_e32 v242, s98, v199
	ds_read_b128 v[242:245], v242 offset:8192
	s_cmp_lg_u64 s[12:13], 0
	s_cbranch_scc1 .Latt_nd4_2B0
	s_add_i32 m0, m0, 0x400
	s_nop 0
	global_load_lds_dwordx4 v186, s[100:101]
.Latt_nd4_2B0:
	s_waitcnt lgkmcnt(7)
	v_mfma_f32_32x32x16_bf16 v[128:143], v[250:253], v[164:167], v[128:143]
	v_add_u32_e32 v250, s98, v200
	ds_read_b128 v[250:253], v250 offset:8192
	s_cmp_lg_u64 s[12:13], 0
	s_cbranch_scc1 .Latt_nd5_2B0
	s_add_i32 m0, m0, 0x400
	s_nop 0
	global_load_lds_dwordx4 v188, s[100:101]
.Latt_nd5_2B0:
	s_waitcnt lgkmcnt(7)
	v_mfma_f32_32x32x16_bf16 v[128:143], v[222:225], v[168:171], v[128:143]
	s_waitcnt lgkmcnt(6)
	v_mfma_f32_32x32x16_bf16 v[128:143], v[226:229], v[172:175], v[128:143]
	s_waitcnt lgkmcnt(5)
	v_mfma_f32_32x32x16_bf16 v[222:237], v[206:209], v[144:147], 0
	v_add_u32_e32 v206, s98, v201
	ds_read_b128 v[206:209], v206 offset:8192
	s_nop 7
	v_max3_f32 v246, v128, v129, v130
	v_max3_f32 v247, v131, v132, v133
	v_max3_f32 v246, v246, v134, v135
	v_max3_f32 v247, v247, v136, v137
	v_max3_f32 v246, v246, v138, v139
	v_max3_f32 v247, v247, v140, v141
	v_max3_f32 v246, v246, v142, v143
	s_waitcnt lgkmcnt(5)
	v_mfma_f32_32x32x16_bf16 v[222:237], v[210:213], v[148:151], v[222:237]
	v_add_u32_e32 v210, s98, v202
	ds_read_b128 v[210:213], v210 offset:8192
	v_max_f32_e32 v246, v246, v247
	v_mov_b32_e32 v247, v246
	v_add_f32_e32 v249, 0x41000000, v190
	s_nop 1
	v_permlane32_swap_b32_e32 v246, v247
	v_max_f32_e32 v246, v246, v247
	v_cmp_gt_f32_e32 vcc, v246, v249
	s_cbranch_vccz .Latt_nr0_2B0
	v_max_f32_e32 v246, v190, v246
	v_sub_f32_e32 v190, v190, v246
	v_exp_f32_e32 v190, v190
	s_nop 0
	v_pk_mul_f32 v[126:127], v[126:127], v[190:191] op_sel_hi:[1,0]
	v_pk_mul_f32 v[124:125], v[124:125], v[190:191] op_sel_hi:[1,0]
	v_pk_mul_f32 v[122:123], v[122:123], v[190:191] op_sel_hi:[1,0]
	v_pk_mul_f32 v[120:121], v[120:121], v[190:191] op_sel_hi:[1,0]
	v_pk_mul_f32 v[118:119], v[118:119], v[190:191] op_sel_hi:[1,0]
	v_pk_mul_f32 v[116:117], v[116:117], v[190:191] op_sel_hi:[1,0]
	v_pk_mul_f32 v[114:115], v[114:115], v[190:191] op_sel_hi:[1,0]
	v_pk_mul_f32 v[112:113], v[112:113], v[190:191] op_sel_hi:[1,0]
	v_pk_mul_f32 v[110:111], v[110:111], v[190:191] op_sel_hi:[1,0]
	v_pk_mul_f32 v[108:109], v[108:109], v[190:191] op_sel_hi:[1,0]
	v_pk_mul_f32 v[106:107], v[106:107], v[190:191] op_sel_hi:[1,0]
	v_pk_mul_f32 v[104:105], v[104:105], v[190:191] op_sel_hi:[1,0]
	v_pk_mul_f32 v[102:103], v[102:103], v[190:191] op_sel_hi:[1,0]
	v_pk_mul_f32 v[100:101], v[100:101], v[190:191] op_sel_hi:[1,0]
	v_pk_mul_f32 v[98:99], v[98:99], v[190:191] op_sel_hi:[1,0]
	v_pk_mul_f32 v[96:97], v[96:97], v[190:191] op_sel_hi:[1,0]
	v_pk_mul_f32 v[94:95], v[94:95], v[190:191] op_sel_hi:[1,0]
	v_pk_mul_f32 v[92:93], v[92:93], v[190:191] op_sel_hi:[1,0]
	v_pk_mul_f32 v[90:91], v[90:91], v[190:191] op_sel_hi:[1,0]
	v_pk_mul_f32 v[88:89], v[88:89], v[190:191] op_sel_hi:[1,0]
	v_pk_mul_f32 v[86:87], v[86:87], v[190:191] op_sel_hi:[1,0]
	v_pk_mul_f32 v[84:85], v[84:85], v[190:191] op_sel_hi:[1,0]
	v_pk_mul_f32 v[82:83], v[82:83], v[190:191] op_sel_hi:[1,0]
	v_pk_mul_f32 v[80:81], v[80:81], v[190:191] op_sel_hi:[1,0]
	v_pk_mul_f32 v[78:79], v[78:79], v[190:191] op_sel_hi:[1,0]
	v_pk_mul_f32 v[76:77], v[76:77], v[190:191] op_sel_hi:[1,0]
	v_pk_mul_f32 v[74:75], v[74:75], v[190:191] op_sel_hi:[1,0]
	v_pk_mul_f32 v[72:73], v[72:73], v[190:191] op_sel_hi:[1,0]
	v_pk_mul_f32 v[70:71], v[70:71], v[190:191] op_sel_hi:[1,0]
	v_pk_mul_f32 v[68:69], v[68:69], v[190:191] op_sel_hi:[1,0]
	v_pk_mul_f32 v[66:67], v[66:67], v[190:191] op_sel_hi:[1,0]
	v_pk_mul_f32 v[64:65], v[64:65], v[190:191] op_sel_hi:[1,0]
	v_pk_mul_f32 v[62:63], v[62:63], v[190:191] op_sel_hi:[1,0]
	v_pk_mul_f32 v[60:61], v[60:61], v[190:191] op_sel_hi:[1,0]
	v_pk_mul_f32 v[58:59], v[58:59], v[190:191] op_sel_hi:[1,0]
	v_pk_mul_f32 v[56:57], v[56:57], v[190:191] op_sel_hi:[1,0]
	v_pk_mul_f32 v[54:55], v[54:55], v[190:191] op_sel_hi:[1,0]
	v_pk_mul_f32 v[52:53], v[52:53], v[190:191] op_sel_hi:[1,0]
	v_pk_mul_f32 v[50:51], v[50:51], v[190:191] op_sel_hi:[1,0]
	v_pk_mul_f32 v[48:49], v[48:49], v[190:191] op_sel_hi:[1,0]
	v_pk_mul_f32 v[46:47], v[46:47], v[190:191] op_sel_hi:[1,0]
	v_pk_mul_f32 v[44:45], v[44:45], v[190:191] op_sel_hi:[1,0]
	v_pk_mul_f32 v[42:43], v[42:43], v[190:191] op_sel_hi:[1,0]
	v_pk_mul_f32 v[40:41], v[40:41], v[190:191] op_sel_hi:[1,0]
	v_pk_mul_f32 v[38:39], v[38:39], v[190:191] op_sel_hi:[1,0]
	v_pk_mul_f32 v[36:37], v[36:37], v[190:191] op_sel_hi:[1,0]
	v_pk_mul_f32 v[34:35], v[34:35], v[190:191] op_sel_hi:[1,0]
	v_pk_mul_f32 v[32:33], v[32:33], v[190:191] op_sel_hi:[1,0]
	v_pk_mul_f32 v[30:31], v[30:31], v[190:191] op_sel_hi:[1,0]
	v_pk_mul_f32 v[28:29], v[28:29], v[190:191] op_sel_hi:[1,0]
	v_pk_mul_f32 v[26:27], v[26:27], v[190:191] op_sel_hi:[1,0]
	v_pk_mul_f32 v[24:25], v[24:25], v[190:191] op_sel_hi:[1,0]
	v_pk_mul_f32 v[22:23], v[22:23], v[190:191] op_sel_hi:[1,0]
	v_pk_mul_f32 v[20:21], v[20:21], v[190:191] op_sel_hi:[1,0]
	v_pk_mul_f32 v[18:19], v[18:19], v[190:191] op_sel_hi:[1,0]
	v_pk_mul_f32 v[16:17], v[16:17], v[190:191] op_sel_hi:[1,0]
	v_pk_mul_f32 v[14:15], v[14:15], v[190:191] op_sel_hi:[1,0]
	v_pk_mul_f32 v[12:13], v[12:13], v[190:191] op_sel_hi:[1,0]
	v_pk_mul_f32 v[10:11], v[10:11], v[190:191] op_sel_hi:[1,0]
	v_pk_mul_f32 v[8:9], v[8:9], v[190:191] op_sel_hi:[1,0]
	v_pk_mul_f32 v[6:7], v[6:7], v[190:191] op_sel_hi:[1,0]
	v_pk_mul_f32 v[4:5], v[4:5], v[190:191] op_sel_hi:[1,0]
	v_pk_mul_f32 v[2:3], v[2:3], v[190:191] op_sel_hi:[1,0]
	v_pk_mul_f32 v[0:1], v[0:1], v[190:191] op_sel_hi:[1,0]
	v_mul_f32_e32 v203, v203, v190
	v_mov_b32_e32 v190, v246
.Latt_nr0_2B0:
	s_waitcnt lgkmcnt(5)
	v_mfma_f32_32x32x16_bf16 v[222:237], v[214:217], v[152:155], v[222:237]
	ds_read_b64_tr_b16 v[214:215], v205
	ds_read_b64_tr_b16 v[216:217], v205 offset:4096
	v_sub_f32_e32 v128, v128, v190
	v_exp_f32_e32 v128, v128
	v_sub_f32_e32 v129, v129, v190
	v_exp_f32_e32 v129, v129
	v_sub_f32_e32 v130, v130, v190
	v_add_f32_e32 v254, 0, v128
	v_exp_f32_e32 v130, v130
	v_sub_f32_e32 v131, v131, v190
	s_waitcnt lgkmcnt(6)
	v_mfma_f32_32x32x16_bf16 v[222:237], v[238:241], v[156:159], v[222:237]
	ds_read_b64_tr_b16 v[238:239], v218
	ds_read_b64_tr_b16 v[240:241], v218 offset:4096
	v_add_f32_e32 v254, v129, v254
	v_exp_f32_e32 v131, v131
	v_sub_f32_e32 v132, v132, v190
	v_add_f32_e32 v254, v130, v254
	v_exp_f32_e32 v132, v132
	v_sub_f32_e32 v133, v133, v190
	v_add_f32_e32 v254, v131, v254
	v_exp_f32_e32 v133, v133
	s_waitcnt lgkmcnt(7)
	v_mfma_f32_32x32x16_bf16 v[222:237], v[242:245], v[160:163], v[222:237]
	v_sub_f32_e32 v134, v134, v190
	v_add_f32_e32 v254, v132, v254
	v_exp_f32_e32 v134, v134
	v_sub_f32_e32 v135, v135, v190
	v_add_f32_e32 v254, v133, v254
	v_exp_f32_e32 v135, v135
	v_sub_f32_e32 v136, v136, v190
	v_add_f32_e32 v254, v134, v254
	s_waitcnt lgkmcnt(6)
	v_mfma_f32_32x32x16_bf16 v[222:237], v[250:253], v[164:167], v[222:237]
	v_exp_f32_e32 v136, v136
	v_sub_f32_e32 v137, v137, v190
	v_add_f32_e32 v254, v135, v254
	v_exp_f32_e32 v137, v137
	v_sub_f32_e32 v138, v138, v190
	v_add_f32_e32 v254, v136, v254
	v_exp_f32_e32 v138, v138
	v_sub_f32_e32 v139, v139, v190
	s_waitcnt lgkmcnt(5)
	v_mfma_f32_32x32x16_bf16 v[222:237], v[206:209], v[168:171], v[222:237]
	ds_read_b64_tr_b16 v[206:207], v219
	ds_read_b64_tr_b16 v[208:209], v219 offset:4096
	v_add_f32_e32 v254, v137, v254
	v_exp_f32_e32 v139, v139
	v_sub_f32_e32 v140, v140, v190
	v_add_f32_e32 v254, v138, v254
	v_exp_f32_e32 v140, v140
	v_sub_f32_e32 v141, v141, v190
	v_add_f32_e32 v254, v139, v254
	v_exp_f32_e32 v141, v141
	s_waitcnt lgkmcnt(6)
	v_mfma_f32_32x32x16_bf16 v[222:237], v[210:213], v[172:175], v[222:237]
	ds_read_b64_tr_b16 v[210:211], v221
	ds_read_b64_tr_b16 v[212:213], v221 offset:4096
	v_sub_f32_e32 v142, v142, v190
	v_add_f32_e32 v254, v140, v254
	v_exp_f32_e32 v142, v142
	v_sub_f32_e32 v143, v143, v190
	v_add_f32_e32 v254, v141, v254
	v_exp_f32_e32 v143, v143
	v_add_f32_e32 v254, v142, v254
	v_add_f32_e32 v254, v143, v254
	v_cvt_pk_bf16_f32 v242, v128, v129
	v_cvt_pk_bf16_f32 v243, v130, v131
	v_cvt_pk_bf16_f32 v244, v132, v133
	v_cvt_pk_bf16_f32 v245, v134, v135
	v_cvt_pk_bf16_f32 v250, v136, v137
	v_cvt_pk_bf16_f32 v251, v138, v139
	v_cvt_pk_bf16_f32 v252, v140, v141
	v_cvt_pk_bf16_f32 v253, v142, v143
	v_add_f32_e32 v203, v203, v254
	s_nop 1
	ds_read_b64_tr_b16 v[128:129], v205 offset:256
	ds_read_b64_tr_b16 v[130:131], v205 offset:4352
	s_waitcnt lgkmcnt(8)
	v_mfma_f32_32x32x16_bf16 v[112:127], v[214:217], v[242:245], v[112:127]
	ds_read_b64_tr_b16 v[214:215], v218 offset:256
	ds_read_b64_tr_b16 v[216:217], v218 offset:4352
	s_waitcnt lgkmcnt(8)
	v_mfma_f32_32x32x16_bf16 v[96:111], v[238:241], v[242:245], v[96:111]
	ds_read_b64_tr_b16 v[238:239], v219 offset:256
	ds_read_b64_tr_b16 v[240:241], v219 offset:4352
	s_waitcnt lgkmcnt(8)
	v_mfma_f32_32x32x16_bf16 v[80:95], v[206:209], v[242:245], v[80:95]
	ds_read_b64_tr_b16 v[206:207], v221 offset:256
	ds_read_b64_tr_b16 v[208:209], v221 offset:4352
	v_max3_f32 v246, v222, v223, v224
	v_max3_f32 v247, v225, v226, v227
	v_max3_f32 v246, v246, v228, v229
	v_max3_f32 v247, v247, v230, v231
	v_max3_f32 v246, v246, v232, v233
	v_max3_f32 v247, v247, v234, v235
	s_waitcnt lgkmcnt(8)
	v_mfma_f32_32x32x16_bf16 v[64:79], v[210:213], v[242:245], v[64:79]
	ds_read_b64_tr_b16 v[210:211], v205 offset:8192
	ds_read_b64_tr_b16 v[212:213], v205 offset:12288
	v_max3_f32 v246, v246, v236, v237
	v_max_f32_e32 v246, v246, v247
	v_mov_b32_e32 v247, v246
	v_add_f32_e32 v249, 0x41000000, v190
	s_nop 1
	s_waitcnt lgkmcnt(8)
	v_mfma_f32_32x32x16_bf16 v[48:63], v[128:131], v[242:245], v[48:63]
	ds_read_b64_tr_b16 v[128:129], v218 offset:8192
	ds_read_b64_tr_b16 v[130:131], v218 offset:12288
	v_permlane32_swap_b32_e32 v246, v247
	v_max_f32_e32 v246, v246, v247
	v_cmp_gt_f32_e32 vcc, v246, v249
	s_cbranch_vccnz .Latt_rs1_2B0
	s_waitcnt lgkmcnt(8)
	v_mfma_f32_32x32x16_bf16 v[32:47], v[214:217], v[242:245], v[32:47]
	ds_read_b64_tr_b16 v[214:215], v219 offset:8192
	ds_read_b64_tr_b16 v[216:217], v219 offset:12288
	v_sub_f32_e32 v222, v222, v190
	v_exp_f32_e32 v222, v222
	v_sub_f32_e32 v223, v223, v190
	v_exp_f32_e32 v223, v223
	v_sub_f32_e32 v224, v224, v190
	s_waitcnt lgkmcnt(8)
	v_mfma_f32_32x32x16_bf16 v[16:31], v[238:241], v[242:245], v[16:31]
	ds_read_b64_tr_b16 v[238:239], v221 offset:8192
	ds_read_b64_tr_b16 v[240:241], v221 offset:12288
	v_add_f32_e32 v254, 0, v222
	v_exp_f32_e32 v224, v224
	v_sub_f32_e32 v225, v225, v190
	v_add_f32_e32 v254, v223, v254
	v_exp_f32_e32 v225, v225
	s_waitcnt lgkmcnt(8)
	v_mfma_f32_32x32x16_bf16 v[0:15], v[206:209], v[242:245], v[0:15]
	ds_read_b64_tr_b16 v[206:207], v205 offset:8448
	ds_read_b64_tr_b16 v[208:209], v205 offset:12544
	v_sub_f32_e32 v226, v226, v190
	v_add_f32_e32 v254, v224, v254
	v_exp_f32_e32 v226, v226
	v_sub_f32_e32 v227, v227, v190
	v_add_f32_e32 v254, v225, v254
	s_waitcnt lgkmcnt(8)
	v_mfma_f32_32x32x16_bf16 v[112:127], v[210:213], v[250:253], v[112:127]
	ds_read_b64_tr_b16 v[210:211], v218 offset:8448
	ds_read_b64_tr_b16 v[212:213], v218 offset:12544
	v_exp_f32_e32 v227, v227
	v_sub_f32_e32 v228, v228, v190
	v_add_f32_e32 v254, v226, v254
	v_exp_f32_e32 v228, v228
	v_sub_f32_e32 v229, v229, v190
	s_waitcnt lgkmcnt(8)
	v_mfma_f32_32x32x16_bf16 v[96:111], v[128:131], v[250:253], v[96:111]
	ds_read_b64_tr_b16 v[128:129], v219 offset:8448
	ds_read_b64_tr_b16 v[130:131], v219 offset:12544
	v_add_f32_e32 v254, v227, v254
	v_exp_f32_e32 v229, v229
	v_sub_f32_e32 v230, v230, v190
	v_add_f32_e32 v254, v228, v254
	s_waitcnt lgkmcnt(8)
	v_mfma_f32_32x32x16_bf16 v[80:95], v[214:217], v[250:253], v[80:95]
	ds_read_b64_tr_b16 v[214:215], v221 offset:8448
	ds_read_b64_tr_b16 v[216:217], v221 offset:12544
	v_exp_f32_e32 v230, v230
	v_sub_f32_e32 v231, v231, v190
	v_add_f32_e32 v254, v229, v254
	v_exp_f32_e32 v231, v231
	s_waitcnt lgkmcnt(8)
	v_mfma_f32_32x32x16_bf16 v[64:79], v[238:241], v[250:253], v[64:79]
	v_sub_f32_e32 v232, v232, v190
	v_add_f32_e32 v254, v230, v254
	v_exp_f32_e32 v232, v232
	v_sub_f32_e32 v233, v233, v190
	s_waitcnt lgkmcnt(6)
	v_mfma_f32_32x32x16_bf16 v[48:63], v[206:209], v[250:253], v[48:63]
	v_add_f32_e32 v254, v231, v254
	v_exp_f32_e32 v233, v233
	v_sub_f32_e32 v234, v234, v190
	v_add_f32_e32 v254, v232, v254
	s_waitcnt lgkmcnt(4)
	v_mfma_f32_32x32x16_bf16 v[32:47], v[210:213], v[250:253], v[32:47]
	v_exp_f32_e32 v234, v234
	v_sub_f32_e32 v235, v235, v190
	v_add_f32_e32 v254, v233, v254
	v_exp_f32_e32 v235, v235
	s_waitcnt lgkmcnt(2)
	v_mfma_f32_32x32x16_bf16 v[16:31], v[128:131], v[250:253], v[16:31]
	v_sub_f32_e32 v236, v236, v190
	v_add_f32_e32 v254, v234, v254
	v_exp_f32_e32 v236, v236
	v_sub_f32_e32 v237, v237, v190
	s_waitcnt lgkmcnt(0)
	v_mfma_f32_32x32x16_bf16 v[0:15], v[214:217], v[250:253], v[0:15]
	v_add_f32_e32 v254, v235, v254
	v_exp_f32_e32 v237, v237
	v_add_f32_e32 v254, v236, v254
	v_add_f32_e32 v254, v237, v254
	v_cvt_pk_bf16_f32 v242, v222, v223
	v_cvt_pk_bf16_f32 v243, v224, v225
	v_cvt_pk_bf16_f32 v244, v226, v227
	v_cvt_pk_bf16_f32 v245, v228, v229
	v_cvt_pk_bf16_f32 v250, v230, v231
	v_cvt_pk_bf16_f32 v251, v232, v233
	v_cvt_pk_bf16_f32 v252, v234, v235
	v_cvt_pk_bf16_f32 v253, v236, v237
	v_add_f32_e32 v203, v203, v254
	s_nop 1

.Latt_slow_2:
	v_lshrrev_b32_e32 v246, 8, v220
	s_nop 0
	v_readfirstlane_b32 s100, v246
	s_nop 0
	s_cmp_eq_u32 s100, 0
	s_cbranch_scc1 .Latt_slow2_2
	s_cmp_eq_u32 s84, 0
	s_cbranch_scc1 .Latt_slow2_2
	s_add_i32 s99, s38, 2
	s_sub_i32 s101, s99, 3
	s_cmp_lt_u32 s99, 3
	s_cselect_b32 s99, s99, s101
	s_lshl_b32 s99, s99, 15
	s_add_i32 s99, s99, 0xc000
	v_bfe_u32 v246, v204, 2, 2
	v_bfe_u32 v247, v204, 5, 1
	v_lshl_or_b32 v247, v247, 2, v246
	v_and_b32_e32 v249, 3, v204
	v_and_b32_e32 v254, 16, v204
	v_lshl_or_b32 v249, v249, 2, v254
	v_lshlrev_b32_e32 v249, 1, v249
	v_lshl_add_u32 v247, v247, 9, v249
	v_add_u32_e32 v247, s99, v247
	v_lshlrev_b32_e32 v246, 6, v246
	v_add_u32_e32 v205, v247, v246
	v_xor_b32_e32 v249, 64, v246
	v_add_u32_e32 v218, v247, v249
	v_xor_b32_e32 v249, 0x80, v246
	v_add_u32_e32 v219, v247, v249
	v_xor_b32_e32 v249, 0xc0, v246
	v_add_u32_e32 v221, v247, v249
	ds_read_b64_tr_b16 v[206:207], v205 offset:16384
	ds_read_b64_tr_b16 v[208:209], v205 offset:20480
	ds_read_b64_tr_b16 v[210:211], v218 offset:16384
	ds_read_b64_tr_b16 v[212:213], v218 offset:20480
	ds_read_b64_tr_b16 v[214:215], v219 offset:16384
	ds_read_b64_tr_b16 v[216:217], v219 offset:20480
	ds_read_b64_tr_b16 v[238:239], v221 offset:16384
	ds_read_b64_tr_b16 v[240:241], v221 offset:20480
	ds_read_b64_tr_b16 v[222:223], v205 offset:16640
	ds_read_b64_tr_b16 v[224:225], v205 offset:20736
	s_waitcnt lgkmcnt(8)
	v_mfma_f32_32x32x16_bf16 v[112:127], v[206:209], v[242:245], v[112:127]
	ds_read_b64_tr_b16 v[206:207], v218 offset:16640
	ds_read_b64_tr_b16 v[208:209], v218 offset:20736
	s_waitcnt lgkmcnt(8)
	v_mfma_f32_32x32x16_bf16 v[96:111], v[210:213], v[242:245], v[96:111]
	ds_read_b64_tr_b16 v[210:211], v219 offset:16640
	ds_read_b64_tr_b16 v[212:213], v219 offset:20736
	s_waitcnt lgkmcnt(8)
	v_mfma_f32_32x32x16_bf16 v[80:95], v[214:217], v[242:245], v[80:95]
	ds_read_b64_tr_b16 v[214:215], v221 offset:16640
	ds_read_b64_tr_b16 v[216:217], v221 offset:20736
	s_waitcnt lgkmcnt(8)
	v_mfma_f32_32x32x16_bf16 v[64:79], v[238:241], v[242:245], v[64:79]
	ds_read_b64_tr_b16 v[238:239], v205 offset:24576
	ds_read_b64_tr_b16 v[240:241], v205 offset:28672
	s_waitcnt lgkmcnt(8)
	v_mfma_f32_32x32x16_bf16 v[48:63], v[222:225], v[242:245], v[48:63]
	ds_read_b64_tr_b16 v[222:223], v218 offset:24576
	ds_read_b64_tr_b16 v[224:225], v218 offset:28672
	s_waitcnt lgkmcnt(8)
	v_mfma_f32_32x32x16_bf16 v[32:47], v[206:209], v[242:245], v[32:47]
	ds_read_b64_tr_b16 v[206:207], v219 offset:24576
	ds_read_b64_tr_b16 v[208:209], v219 offset:28672
	s_waitcnt lgkmcnt(8)
	v_mfma_f32_32x32x16_bf16 v[16:31], v[210:213], v[242:245], v[16:31]
	ds_read_b64_tr_b16 v[210:211], v221 offset:24576
	ds_read_b64_tr_b16 v[212:213], v221 offset:28672
	s_waitcnt lgkmcnt(8)
	v_mfma_f32_32x32x16_bf16 v[0:15], v[214:217], v[242:245], v[0:15]
	ds_read_b64_tr_b16 v[214:215], v205 offset:24832
	ds_read_b64_tr_b16 v[216:217], v205 offset:28928
	s_waitcnt lgkmcnt(8)
	v_mfma_f32_32x32x16_bf16 v[112:127], v[238:241], v[250:253], v[112:127]
	ds_read_b64_tr_b16 v[238:239], v218 offset:24832
	ds_read_b64_tr_b16 v[240:241], v218 offset:28928
	s_waitcnt lgkmcnt(8)
	v_mfma_f32_32x32x16_bf16 v[96:111], v[222:225], v[250:253], v[96:111]
	ds_read_b64_tr_b16 v[222:223], v219 offset:24832
	ds_read_b64_tr_b16 v[224:225], v219 offset:28928
	s_waitcnt lgkmcnt(8)
	v_mfma_f32_32x32x16_bf16 v[80:95], v[206:209], v[250:253], v[80:95]
	ds_read_b64_tr_b16 v[206:207], v221 offset:24832
	ds_read_b64_tr_b16 v[208:209], v221 offset:28928
	s_waitcnt lgkmcnt(8)
	v_mfma_f32_32x32x16_bf16 v[64:79], v[210:213], v[250:253], v[64:79]
	s_waitcnt lgkmcnt(6)
	v_mfma_f32_32x32x16_bf16 v[48:63], v[214:217], v[250:253], v[48:63]
	s_waitcnt lgkmcnt(4)
	v_mfma_f32_32x32x16_bf16 v[32:47], v[238:241], v[250:253], v[32:47]
	s_waitcnt lgkmcnt(2)
	v_mfma_f32_32x32x16_bf16 v[16:31], v[222:225], v[250:253], v[16:31]
	s_waitcnt lgkmcnt(0)
	v_mfma_f32_32x32x16_bf16 v[0:15], v[206:209], v[250:253], v[0:15]

.LBB0_898:
	s_andn2_b64 vcc, exec, s[14:15]
	s_cbranch_vccnz .LBB0_882
	s_waitcnt vmcnt(0)
	s_branch .LBB0_882
.LBB0_900:
	ds_bpermute_b32 v128, v194, v203
	s_add_i32 s12, s86, s60
	s_mov_b32 s13, s5
	s_lshl_b64 s[12:13], s[12:13], 14
	s_add_u32 s12, s58, s12
	s_waitcnt lgkmcnt(0)
	v_add_f32_e32 v128, v203, v128
	v_rcp_f32_e32 v130, v128
	v_mov_b32_e32 v128, v176
	s_addc_u32 s13, s59, s13
	v_lshlrev_b32_e32 v128, 4, v128
	v_mul_f32_e32 v112, v112, v130
	v_mul_f32_e32 v113, v113, v130
	v_mul_f32_e32 v114, v114, v130
	v_mul_f32_e32 v115, v115, v130
	v_and_b32_e32 v178, 0x3f0, v128
	v_mul_f32_e32 v116, v116, v130
	v_mul_f32_e32 v117, v117, v130
	v_mul_f32_e32 v118, v118, v130
	v_mul_f32_e32 v119, v119, v130
	v_cvt_pk_bf16_f32 v112, v112, v113
	v_cvt_pk_bf16_f32 v113, v114, v115
	v_cvt_pk_bf16_f32 v114, v116, v117
	v_cvt_pk_bf16_f32 v115, v118, v119
	v_mul_f32_e32 v96, v96, v130
	v_mul_f32_e32 v97, v97, v130
	v_mul_f32_e32 v98, v98, v130
	v_mul_f32_e32 v99, v99, v130
	v_lshl_add_u64 v[128:129], s[12:13], 0, v[178:179]
	v_mul_f32_e32 v120, v120, v130
	v_mul_f32_e32 v121, v121, v130
	v_mul_f32_e32 v122, v122, v130
	v_mul_f32_e32 v123, v123, v130
	v_mul_f32_e32 v124, v124, v130
	v_mul_f32_e32 v125, v125, v130
	v_mul_f32_e32 v126, v126, v130
	v_mul_f32_e32 v127, v127, v130
	v_cvt_pk_bf16_f32 v116, v120, v121
	v_cvt_pk_bf16_f32 v117, v122, v123
	v_cvt_pk_bf16_f32 v118, v124, v125
	v_cvt_pk_bf16_f32 v119, v126, v127
	global_store_dwordx4 v178, v[112:115], s[12:13]
	global_store_dwordx4 v178, v[116:119], s[12:13] offset:1024
	v_mul_f32_e32 v100, v100, v130
	v_mul_f32_e32 v101, v101, v130
	v_mul_f32_e32 v102, v102, v130
	v_mul_f32_e32 v103, v103, v130
	v_cvt_pk_bf16_f32 v96, v96, v97
	v_cvt_pk_bf16_f32 v97, v98, v99
	v_cvt_pk_bf16_f32 v98, v100, v101
	v_cvt_pk_bf16_f32 v99, v102, v103
	v_mul_f32_e32 v80, v80, v130
	v_mul_f32_e32 v81, v81, v130
	v_mul_f32_e32 v82, v82, v130
	v_mul_f32_e32 v83, v83, v130
	v_mul_f32_e32 v84, v84, v130
	v_mul_f32_e32 v88, v88, v130
	v_mul_f32_e32 v104, v104, v130
	v_mul_f32_e32 v105, v105, v130
	v_mul_f32_e32 v106, v106, v130
	v_mul_f32_e32 v107, v107, v130
	v_mul_f32_e32 v108, v108, v130
	v_mul_f32_e32 v109, v109, v130
	v_mul_f32_e32 v110, v110, v130
	v_mul_f32_e32 v111, v111, v130
	v_cvt_pk_bf16_f32 v100, v104, v105
	v_cvt_pk_bf16_f32 v101, v106, v107
	v_cvt_pk_bf16_f32 v102, v108, v109
	v_cvt_pk_bf16_f32 v103, v110, v111
	global_store_dwordx4 v178, v[96:99], s[12:13] offset:2048
	global_store_dwordx4 v178, v[100:103], s[12:13] offset:3072
	v_mul_f32_e32 v85, v85, v130
	v_mul_f32_e32 v86, v86, v130
	v_mul_f32_e32 v87, v87, v130
	v_mul_f32_e32 v89, v89, v130
	v_cvt_pk_bf16_f32 v80, v80, v81
	v_cvt_pk_bf16_f32 v81, v82, v83
	v_cvt_pk_bf16_f32 v82, v84, v85
	v_cvt_pk_bf16_f32 v83, v86, v87
	v_cvt_pk_bf16_f32 v84, v88, v89
	v_add_co_u32_e32 v88, vcc, s73, v128
	v_mul_f32_e32 v90, v90, v130
	s_nop 0
	v_addc_co_u32_e32 v89, vcc, 0, v129, vcc
	v_mul_f32_e32 v91, v91, v130
	v_cvt_pk_bf16_f32 v85, v90, v91
	v_add_co_u32_e32 v90, vcc, s74, v128
	v_mul_f32_e32 v64, v64, v130
	s_nop 0
	v_addc_co_u32_e32 v91, vcc, 0, v129, vcc
	v_mul_f32_e32 v65, v65, v130
	v_mul_f32_e32 v66, v66, v130
	v_mul_f32_e32 v67, v67, v130
	v_mul_f32_e32 v92, v92, v130
	v_mul_f32_e32 v93, v93, v130
	v_mul_f32_e32 v94, v94, v130
	v_mul_f32_e32 v95, v95, v130
	v_cvt_pk_bf16_f32 v86, v92, v93
	v_cvt_pk_bf16_f32 v87, v94, v95
	global_store_dwordx4 v[90:91], v[80:83], off offset:-4096
	global_store_dwordx4 v[88:89], v[84:87], off offset:1024
	v_mul_f32_e32 v68, v68, v130
	v_mul_f32_e32 v69, v69, v130
	v_mul_f32_e32 v70, v70, v130
	v_mul_f32_e32 v71, v71, v130
	v_cvt_pk_bf16_f32 v64, v64, v65
	v_cvt_pk_bf16_f32 v65, v66, v67
	v_cvt_pk_bf16_f32 v66, v68, v69
	v_cvt_pk_bf16_f32 v67, v70, v71
	v_mul_f32_e32 v48, v48, v130
	v_mul_f32_e32 v49, v49, v130
	v_mul_f32_e32 v50, v50, v130
	v_mul_f32_e32 v51, v51, v130
	v_mul_f32_e32 v72, v72, v130
	v_mul_f32_e32 v73, v73, v130
	v_mul_f32_e32 v74, v74, v130
	v_mul_f32_e32 v75, v75, v130
	v_mul_f32_e32 v76, v76, v130
	v_mul_f32_e32 v77, v77, v130
	v_mul_f32_e32 v78, v78, v130
	v_mul_f32_e32 v79, v79, v130
	v_cvt_pk_bf16_f32 v68, v72, v73
	v_cvt_pk_bf16_f32 v69, v74, v75
	v_cvt_pk_bf16_f32 v70, v76, v77
	v_cvt_pk_bf16_f32 v71, v78, v79
	global_store_dwordx4 v[88:89], v[64:67], off offset:2048
	global_store_dwordx4 v[88:89], v[68:71], off offset:3072
	v_mul_f32_e32 v52, v52, v130
	v_mul_f32_e32 v53, v53, v130
	v_mul_f32_e32 v54, v54, v130
	v_mul_f32_e32 v55, v55, v130
	v_cvt_pk_bf16_f32 v48, v48, v49
	v_cvt_pk_bf16_f32 v49, v50, v51
	v_cvt_pk_bf16_f32 v50, v52, v53
	v_cvt_pk_bf16_f32 v51, v54, v55
	v_mul_f32_e32 v32, v32, v130
	v_mul_f32_e32 v33, v33, v130
	v_mul_f32_e32 v34, v34, v130
	v_mul_f32_e32 v35, v35, v130
	v_mul_f32_e32 v56, v56, v130
	v_mul_f32_e32 v57, v57, v130
	v_mul_f32_e32 v58, v58, v130
	v_mul_f32_e32 v59, v59, v130
	v_mul_f32_e32 v60, v60, v130
	v_mul_f32_e32 v61, v61, v130
	v_mul_f32_e32 v62, v62, v130
	v_mul_f32_e32 v63, v63, v130
	v_cvt_pk_bf16_f32 v52, v56, v57
	v_cvt_pk_bf16_f32 v53, v58, v59
	v_cvt_pk_bf16_f32 v54, v60, v61
	v_cvt_pk_bf16_f32 v55, v62, v63
	global_store_dwordx4 v[90:91], v[48:51], off
	global_store_dwordx4 v[90:91], v[52:55], off offset:1024
	v_mul_f32_e32 v36, v36, v130
	v_mul_f32_e32 v37, v37, v130
	v_mul_f32_e32 v38, v38, v130
	v_mul_f32_e32 v39, v39, v130
	v_cvt_pk_bf16_f32 v32, v32, v33
	v_cvt_pk_bf16_f32 v33, v34, v35
	v_cvt_pk_bf16_f32 v34, v36, v37
	v_cvt_pk_bf16_f32 v35, v38, v39
	v_mul_f32_e32 v16, v16, v130
	v_mul_f32_e32 v17, v17, v130
	v_mul_f32_e32 v18, v18, v130
	v_mul_f32_e32 v19, v19, v130
	v_mul_f32_e32 v20, v20, v130
	v_mul_f32_e32 v24, v24, v130
	v_mul_f32_e32 v40, v40, v130
	v_mul_f32_e32 v41, v41, v130
	v_mul_f32_e32 v42, v42, v130
	v_mul_f32_e32 v43, v43, v130
	v_mul_f32_e32 v44, v44, v130
	v_mul_f32_e32 v45, v45, v130
	v_mul_f32_e32 v46, v46, v130
	v_mul_f32_e32 v47, v47, v130
	v_cvt_pk_bf16_f32 v36, v40, v41
	v_cvt_pk_bf16_f32 v37, v42, v43
	v_cvt_pk_bf16_f32 v38, v44, v45
	v_cvt_pk_bf16_f32 v39, v46, v47
	global_store_dwordx4 v[90:91], v[32:35], off offset:2048
	global_store_dwordx4 v[90:91], v[36:39], off offset:3072
	v_mul_f32_e32 v21, v21, v130
	v_mul_f32_e32 v22, v22, v130
	v_mul_f32_e32 v23, v23, v130
	v_mul_f32_e32 v25, v25, v130
	v_cvt_pk_bf16_f32 v16, v16, v17
	v_cvt_pk_bf16_f32 v17, v18, v19
	v_cvt_pk_bf16_f32 v18, v20, v21
	v_cvt_pk_bf16_f32 v19, v22, v23
	v_cvt_pk_bf16_f32 v20, v24, v25
	v_add_co_u32_e32 v24, vcc, s75, v128
	v_mul_f32_e32 v0, v0, v130
	s_nop 0
	v_addc_co_u32_e32 v25, vcc, 0, v129, vcc
	v_mul_f32_e32 v1, v1, v130
	v_mul_f32_e32 v2, v2, v130
	v_mul_f32_e32 v3, v3, v130
	s_mov_b32 s14, 0
	v_mul_f32_e32 v26, v26, v130
	v_mul_f32_e32 v27, v27, v130
	v_mul_f32_e32 v28, v28, v130
	v_mul_f32_e32 v29, v29, v130
	v_mul_f32_e32 v30, v30, v130
	v_mul_f32_e32 v31, v31, v130
	v_cvt_pk_bf16_f32 v21, v26, v27
	v_cvt_pk_bf16_f32 v22, v28, v29
	v_cvt_pk_bf16_f32 v23, v30, v31
	global_store_dwordx4 v[24:25], v[16:19], off
	global_store_dwordx4 v[24:25], v[20:23], off offset:1024
	v_mul_f32_e32 v4, v4, v130
	v_mul_f32_e32 v5, v5, v130
	v_mul_f32_e32 v6, v6, v130
	v_mul_f32_e32 v7, v7, v130
	v_mul_f32_e32 v8, v8, v130
	v_mul_f32_e32 v9, v9, v130
	v_mul_f32_e32 v10, v10, v130
	v_mul_f32_e32 v11, v11, v130
	v_mul_f32_e32 v12, v12, v130
	v_mul_f32_e32 v13, v13, v130
	v_mul_f32_e32 v14, v14, v130
	v_mul_f32_e32 v15, v15, v130
	v_cvt_pk_bf16_f32 v0, v0, v1
	v_cvt_pk_bf16_f32 v1, v2, v3
	v_cvt_pk_bf16_f32 v2, v4, v5
	v_cvt_pk_bf16_f32 v3, v6, v7
	v_cvt_pk_bf16_f32 v4, v8, v9
	v_cvt_pk_bf16_f32 v5, v10, v11
	v_cvt_pk_bf16_f32 v6, v12, v13
	v_cvt_pk_bf16_f32 v7, v14, v15
	global_store_dwordx4 v[24:25], v[0:3], off offset:2048
	global_store_dwordx4 v[24:25], v[4:7], off offset:3072
	s_nop 1
	v_mov_b32_e32 v4, v176
	s_cmp_lg_u32 0, -1
	v_bfe_u32 v0, v4, 4, 2
	v_or_b32_e32 v1, s83, v0
	v_bitop3_b32 v0, v0, v4, s83 bitop3:0x36
	v_lshlrev_b32_e32 v2, 14, v1
	v_lshlrev_b32_e32 v0, 4, v0
	v_and_or_b32 v178, v0, s67, v2
	v_or_b32_e32 v0, 4, v1
	v_bitop3_b32 v1, v1, v4, 4 bitop3:0x36
	v_lshlrev_b32_e32 v0, 14, v0
	v_lshlrev_b32_e32 v1, 4, v1
	v_and_or_b32 v180, v1, s67, v0
	v_bfe_u32 v0, v4, 5, 1
	v_or_b32_e32 v1, s83, v0
	v_and_b32_e32 v2, 31, v4
	v_lshlrev_b32_e32 v3, 14, v1
	v_lshlrev_b32_e32 v0, 6, v0
	v_lshlrev_b32_e32 v5, 4, v2
	v_bitop3_b32 v182, v0, v3, v5 bitop3:0xde
	v_or_b32_e32 v0, 2, v1
	v_lshlrev_b32_e32 v3, 2, v0
	v_bitop3_b32 v3, v3, v2, 12 bitop3:0x6c
	v_lshlrev_b32_e32 v0, 14, v0
	v_lshl_or_b32 v184, v3, 4, v0
	v_or_b32_e32 v0, 6, v1
	v_lshlrev_b32_e32 v1, 2, v0
	v_bitop3_b32 v1, v1, v2, 12 bitop3:0x6c
	v_lshlrev_b32_e32 v0, 14, v0
	v_lshl_or_b32 v188, v1, 4, v0
	v_lshl_add_u64 v[0:1], s[42:43], 0, v[178:179]
	s_cselect_b32 s15, 0, 0
	v_mov_b32_e32 v181, v179
	s_add_i32 s22, s82, s15
	s_mov_b32 s23, m0
	s_mov_b32 m0, s22
	s_nop 0
	global_load_lds_dwordx4 v[0:1], off
	s_mov_b32 m0, s23
	v_lshl_add_u64 v[0:1], s[42:43], 0, v[180:181]
	v_mov_b32_e32 v183, v179
	s_add_i32 s23, s22, 0x400
	s_mov_b32 s38, m0
	s_mov_b32 m0, s23
	s_nop 0
	global_load_lds_dwordx4 v[0:1], off
	s_mov_b32 m0, s38
	v_lshl_add_u64 v[0:1], s[16:17], 0, v[182:183]
	s_add_i32 s15, s15, s33
	v_mov_b32_e32 v185, v179
	v_or_b32_e32 v186, 0x10000, v182
	s_add_i32 s23, s15, 0xc000
	s_mov_b32 s33, m0
	s_mov_b32 m0, s23
	s_nop 0
	global_load_lds_dwordx4 v[0:1], off
	s_mov_b32 m0, s33
	v_lshl_add_u64 v[0:1], s[16:17], 0, v[184:185]
	v_mov_b32_e32 v187, v179
	s_add_i32 s23, s15, 0xc400
	s_mov_b32 s33, m0
	s_mov_b32 m0, s23
	s_nop 0
	global_load_lds_dwordx4 v[0:1], off
	s_mov_b32 m0, s33
	v_lshl_add_u64 v[0:1], s[16:17], 0, v[186:187]
	v_mov_b32_e32 v189, v179
	s_add_i32 s23, s15, 0xc800
	s_mov_b32 s33, m0
	s_mov_b32 m0, s23
	s_nop 0
	global_load_lds_dwordx4 v[0:1], off
	s_mov_b32 m0, s33
	v_lshl_add_u64 v[0:1], s[16:17], 0, v[188:189]
	s_add_i32 s16, s15, 0xcc00
	s_mov_b32 s17, m0
	s_mov_b32 m0, s16
	s_nop 0
	global_load_lds_dwordx4 v[0:1], off
	s_mov_b32 m0, s17
	v_lshl_add_u64 v[0:1], s[54:55], 0, v[178:179]
	s_add_i32 s16, s22, 0x4000
	s_mov_b32 s17, m0
	s_mov_b32 m0, s16
	s_nop 0
	global_load_lds_dwordx4 v[0:1], off
	s_mov_b32 m0, s17
	v_lshl_add_u64 v[0:1], s[54:55], 0, v[180:181]
	s_addk_i32 s22, 0x4400
	s_mov_b32 s16, m0
	s_mov_b32 m0, s22
	s_nop 0
	global_load_lds_dwordx4 v[0:1], off
	s_mov_b32 m0, s16
	v_lshl_add_u64 v[0:1], s[10:11], 0, v[182:183]
	s_add_i32 s16, s15, 0x14000
	s_mov_b32 s17, m0
	s_mov_b32 m0, s16
	s_nop 0
	global_load_lds_dwordx4 v[0:1], off
	s_mov_b32 m0, s17
	v_lshl_add_u64 v[0:1], s[10:11], 0, v[184:185]
	s_add_i32 s16, s15, 0x14400
	s_mov_b32 s17, m0
	s_mov_b32 m0, s16
	s_nop 0
	global_load_lds_dwordx4 v[0:1], off
	s_mov_b32 m0, s17
	v_lshl_add_u64 v[0:1], s[10:11], 0, v[186:187]
	s_add_i32 s16, s15, 0x14800
	s_mov_b32 s17, m0
	s_mov_b32 m0, s16
	s_nop 0
	global_load_lds_dwordx4 v[0:1], off
	s_mov_b32 m0, s17
	v_lshl_add_u64 v[0:1], s[10:11], 0, v[188:189]
	s_add_i32 s15, s15, 0x14c00
	s_mov_b32 s10, m0
	s_mov_b32 m0, s15
	s_nop 0
	global_load_lds_dwordx4 v[0:1], off
	s_mov_b32 m0, s10
	v_or_b32_e32 v0, s18, v2
	v_mov_b32_e32 v1, s19
	v_lshlrev_b64 v[0:1], 14, v[0:1]
	v_lshrrev_b32_e32 v2, 1, v4
	v_lshl_add_u64 v[0:1], s[8:9], 0, v[0:1]
	v_and_b32_e32 v2, 16, v2
	v_mov_b32_e32 v3, v179
	v_lshl_add_u64 v[0:1], v[0:1], 0, v[2:3]
	global_load_dwordx4 v[144:147], v[0:1], off offset:256
	global_load_dwordx4 v[148:151], v[0:1], off offset:288
	global_load_dwordx4 v[152:155], v[0:1], off offset:320
	global_load_dwordx4 v[156:159], v[0:1], off offset:352
	global_load_dwordx4 v[160:163], v[0:1], off offset:384
	global_load_dwordx4 v[164:167], v[0:1], off offset:416
	global_load_dwordx4 v[168:171], v[0:1], off offset:448
	global_load_dwordx4 v[172:175], v[0:1], off offset:480
	v_lshrrev_b32_e32 v0, 5, v4
	v_and_b32_e32 v1, 15, v4
	v_bitop3_b32 v0, v0, v1, 1 bitop3:0x6c
	v_lshlrev_b32_e32 v1, 8, v4
	v_lshlrev_b32_e32 v0, 4, v0
	v_and_b32_e32 v1, 0x1f00, v1
	v_mov_b32_e32 v14, v179
	v_mov_b32_e32 v15, v179
	v_or_b32_e32 v196, v0, v1
	v_bitop3_b32 v197, v0, 32, v1 bitop3:0x36
	v_bitop3_b32 v198, v0, 64, v1 bitop3:0x36
	v_bitop3_b32 v199, v0, s68, v1 bitop3:0x36
	v_bitop3_b32 v200, v0, s69, v1 bitop3:0x36
	v_bitop3_b32 v201, v0, s70, v1 bitop3:0x36
	v_bitop3_b32 v202, v0, s71, v1 bitop3:0x36
	v_bitop3_b32 v203, v0, s72, v1 bitop3:0x36
	v_mov_b32_e32 v0, v179
	v_mov_b32_e32 v1, v179
	v_mov_b32_e32 v2, v179
	v_mov_b32_e32 v4, v179
	s_waitcnt vmcnt(7)
	s_waitcnt vmcnt(6)
	s_waitcnt vmcnt(5)
	s_waitcnt vmcnt(4)
	s_waitcnt vmcnt(3)
	s_waitcnt vmcnt(2)
	s_waitcnt vmcnt(1)
	s_waitcnt vmcnt(0)
	s_waitcnt vmcnt(0)
	v_mov_b32_e32 v5, v179
	v_mov_b32_e32 v6, v179
	v_mov_b32_e32 v7, v179
	v_mov_b32_e32 v8, v179
	v_mov_b32_e32 v9, v179
	v_mov_b32_e32 v10, v179
	v_mov_b32_e32 v11, v179
	v_mov_b32_e32 v12, v179
	v_mov_b32_e32 v13, v179
	v_mov_b64_e32 v[30:31], v[14:15]
	v_mov_b64_e32 v[46:47], v[14:15]
	v_mov_b64_e32 v[62:63], v[14:15]
	v_mov_b64_e32 v[78:79], v[14:15]
	v_mov_b64_e32 v[94:95], v[14:15]
	v_mov_b64_e32 v[110:111], v[14:15]
	v_mov_b64_e32 v[126:127], v[14:15]
	s_mov_b32 s10, 2
	v_mov_b32_e32 v190, 0xf149f2ca
	v_mov_b32_e32 v195, 0
	v_mov_b64_e32 v[28:29], v[12:13]
	v_mov_b64_e32 v[26:27], v[10:11]
	v_mov_b64_e32 v[24:25], v[8:9]
	v_mov_b64_e32 v[22:23], v[6:7]
	v_mov_b64_e32 v[20:21], v[4:5]
	v_mov_b64_e32 v[18:19], v[2:3]
	v_mov_b64_e32 v[16:17], v[0:1]
	v_mov_b64_e32 v[44:45], v[12:13]
	v_mov_b64_e32 v[42:43], v[10:11]
	v_mov_b64_e32 v[40:41], v[8:9]
	v_mov_b64_e32 v[38:39], v[6:7]
	v_mov_b64_e32 v[36:37], v[4:5]
	v_mov_b64_e32 v[34:35], v[2:3]
	v_mov_b64_e32 v[32:33], v[0:1]
	v_mov_b64_e32 v[60:61], v[12:13]
	v_mov_b64_e32 v[58:59], v[10:11]
	v_mov_b64_e32 v[56:57], v[8:9]
	v_mov_b64_e32 v[54:55], v[6:7]
	v_mov_b64_e32 v[52:53], v[4:5]
	v_mov_b64_e32 v[50:51], v[2:3]
	v_mov_b64_e32 v[48:49], v[0:1]
	v_mov_b64_e32 v[76:77], v[12:13]
	v_mov_b64_e32 v[74:75], v[10:11]
	v_mov_b64_e32 v[72:73], v[8:9]
	v_mov_b64_e32 v[70:71], v[6:7]
	v_mov_b64_e32 v[68:69], v[4:5]
	v_mov_b64_e32 v[66:67], v[2:3]
	v_mov_b64_e32 v[64:65], v[0:1]
	v_mov_b64_e32 v[92:93], v[12:13]
	v_mov_b64_e32 v[90:91], v[10:11]
	v_mov_b64_e32 v[88:89], v[8:9]
	v_mov_b64_e32 v[86:87], v[6:7]
	v_mov_b64_e32 v[84:85], v[4:5]
	v_mov_b64_e32 v[82:83], v[2:3]
	v_mov_b64_e32 v[80:81], v[0:1]
	v_mov_b64_e32 v[108:109], v[12:13]
	v_mov_b64_e32 v[106:107], v[10:11]
	v_mov_b64_e32 v[104:105], v[8:9]
	v_mov_b64_e32 v[102:103], v[6:7]
	v_mov_b64_e32 v[100:101], v[4:5]
	v_mov_b64_e32 v[98:99], v[2:3]
	v_mov_b64_e32 v[96:97], v[0:1]
	v_mov_b64_e32 v[124:125], v[12:13]
	v_mov_b64_e32 v[122:123], v[10:11]
	v_mov_b64_e32 v[120:121], v[8:9]
	v_mov_b64_e32 v[118:119], v[6:7]
	v_mov_b64_e32 v[116:117], v[4:5]
	v_mov_b64_e32 v[114:115], v[2:3]
	v_mov_b64_e32 v[112:113], v[0:1]
	s_mov_b32 s11, 0
	s_sub_u32 s34, s34, 0x100000
	s_subb_u32 s35, s35, 0
	s_sub_i32 s10, s10, 1
	s_barrier
	s_branch .LBB0_902

.LBB0_902:
	s_cmp_ge_u32 s10, s78
	s_cselect_b64 s[8:9], -1, 0
	v_mov_b32_e32 v204, v176
	s_and_b64 vcc, exec, s[8:9]
	s_cbranch_vccnz .LBB0_904
	s_add_i32 s100, s14, 63
	s_cmp_le_i32 s100, s80
	s_cbranch_scc1 .LBB0_904
	s_add_i32 s16, s11, 1
	s_cmp_eq_u32 s16, 3
	s_cselect_b32 s16, 0, s16
	v_mov_b32_e32 v130, s16
	v_lshlrev_b32_e32 v128, 14, v130
	v_add_u32_e32 v131, s40, v128
	v_lshl_add_u64 v[128:129], s[34:35], 0, v[178:179]
	s_add_u32 s16, s34, 0xf00
	v_readfirstlane_b32 s15, v131
	s_mov_b32 s22, m0
	s_mov_b32 m0, s15
	s_nop 0
	global_load_lds_dwordx4 v[128:129], off
	s_mov_b32 m0, s22
	v_lshl_add_u64 v[128:129], s[34:35], 0, v[180:181]
	s_addc_u32 s17, s35, 0
	s_addk_i32 s15, 0x400
	s_mov_b32 s22, m0
	s_mov_b32 m0, s15
	s_nop 0
	global_load_lds_dwordx4 v[128:129], off
	s_mov_b32 m0, s22
	v_lshlrev_b32_e32 v128, 15, v130
	v_add_u32_e32 v130, s41, v128
	v_lshl_add_u64 v[128:129], s[16:17], 0, v[182:183]
	v_readfirstlane_b32 s15, v130
	s_mov_b32 s22, m0
	s_mov_b32 m0, s15
	s_nop 0
	global_load_lds_dwordx4 v[128:129], off
	s_mov_b32 m0, s22
	v_lshl_add_u64 v[128:129], s[16:17], 0, v[184:185]
	s_add_i32 s22, s15, 0x400
	s_mov_b32 s23, m0
	s_mov_b32 m0, s22
	s_nop 0
	global_load_lds_dwordx4 v[128:129], off
	s_mov_b32 m0, s23
	v_lshl_add_u64 v[128:129], s[16:17], 0, v[186:187]
	s_add_i32 s22, s15, 0x800
	s_mov_b32 s23, m0
	s_mov_b32 m0, s22
	s_nop 0
	global_load_lds_dwordx4 v[128:129], off
	s_mov_b32 m0, s23
	v_lshl_add_u64 v[128:129], s[16:17], 0, v[188:189]
	s_addk_i32 s15, 0xc00
	s_mov_b32 s16, m0
	s_mov_b32 m0, s15
	s_nop 0
	global_load_lds_dwordx4 v[128:129], off
	s_mov_b32 m0, s16
.LBB0_904:
	s_cmp_gt_i32 s14, s81
	s_cbranch_scc1 .LBB0_915
	s_add_i32 s100, s14, 63
	s_cmp_le_i32 s100, s80
	s_cbranch_scc0 .Latt_slow_3
	v_lshrrev_b32_e32 v246, 8, v220
	s_nop 0
	v_readfirstlane_b32 s100, v246
	s_nop 0
	s_cmp_eq_u32 s100, 0
	s_cbranch_scc1 .Latt_A_3
	s_cmp_eq_u32 s14, 0
	s_cbranch_scc1 .Latt_B0_3
	s_add_i32 s99, s11, 2
	s_sub_i32 s101, s99, 3
	s_cmp_lt_u32 s99, 3
	s_cselect_b32 s99, s99, s101
	s_lshl_b32 s99, s99, 15
	s_add_i32 s99, s99, 0xc000
	v_bfe_u32 v246, v204, 2, 2
	v_bfe_u32 v247, v204, 5, 1
	v_lshl_or_b32 v247, v247, 2, v246
	v_and_b32_e32 v249, 3, v204
	v_and_b32_e32 v254, 16, v204
	v_lshl_or_b32 v249, v249, 2, v254
	v_lshlrev_b32_e32 v249, 1, v249
	v_lshl_add_u32 v247, v247, 9, v249
	v_add_u32_e32 v247, s99, v247
	v_lshlrev_b32_e32 v246, 6, v246
	v_add_u32_e32 v205, v247, v246
	v_xor_b32_e32 v249, 64, v246
	v_add_u32_e32 v218, v247, v249
	v_xor_b32_e32 v249, 0x80, v246
	v_add_u32_e32 v219, v247, v249
	v_xor_b32_e32 v249, 0xc0, v246
	v_add_u32_e32 v221, v247, v249
	s_lshl_b32 s98, s11, 14
	s_lshl_b32 s99, s11, 15
	s_add_i32 s99, s99, 0xc000
	ds_read_b64_tr_b16 v[206:207], v205 offset:16384
	ds_read_b64_tr_b16 v[208:209], v205 offset:20480
	ds_read_b64_tr_b16 v[210:211], v218 offset:16384
	ds_read_b64_tr_b16 v[212:213], v218 offset:20480
	ds_read_b64_tr_b16 v[214:215], v219 offset:16384
	ds_read_b64_tr_b16 v[216:217], v219 offset:20480
	ds_read_b64_tr_b16 v[238:239], v221 offset:16384
	ds_read_b64_tr_b16 v[240:241], v221 offset:20480
	ds_read_b64_tr_b16 v[222:223], v205 offset:16640
	ds_read_b64_tr_b16 v[224:225], v205 offset:20736
	s_waitcnt lgkmcnt(8)
	v_mfma_f32_32x32x16_bf16 v[112:127], v[206:209], v[242:245], v[112:127]
	ds_read_b64_tr_b16 v[206:207], v218 offset:16640
	ds_read_b64_tr_b16 v[208:209], v218 offset:20736
	s_cmp_lg_u64 s[8:9], 0
	s_cbranch_scc1 .Latt_nd0_3B1
	s_add_i32 s100, s11, 1
	s_cmp_eq_u32 s11, 2
	s_cselect_b32 s100, 0, s100
	s_lshl_b32 s101, s100, 14
	s_add_i32 m0, s40, s101
	s_nop 0
	global_load_lds_dwordx4 v178, s[34:35]
.Latt_nd0_3B1:
	s_waitcnt lgkmcnt(8)
	v_mfma_f32_32x32x16_bf16 v[96:111], v[210:213], v[242:245], v[96:111]
	ds_read_b64_tr_b16 v[210:211], v219 offset:16640
	ds_read_b64_tr_b16 v[212:213], v219 offset:20736
	s_cmp_lg_u64 s[8:9], 0
	s_cbranch_scc1 .Latt_nd1_3B1
	s_add_i32 m0, m0, 0x400
	s_nop 0
	global_load_lds_dwordx4 v180, s[34:35]
.Latt_nd1_3B1:
	s_waitcnt lgkmcnt(8)
	v_mfma_f32_32x32x16_bf16 v[80:95], v[214:217], v[242:245], v[80:95]
	ds_read_b64_tr_b16 v[214:215], v221 offset:16640
	ds_read_b64_tr_b16 v[216:217], v221 offset:20736
	s_cmp_lg_u64 s[8:9], 0
	s_cbranch_scc1 .Latt_nd2_3B1
	s_lshl_b32 s101, s100, 15
	s_add_i32 m0, s41, s101
	s_add_u32 s100, s34, 0xf00
	s_addc_u32 s101, s35, 0
	global_load_lds_dwordx4 v182, s[100:101]
.Latt_nd2_3B1:
	s_waitcnt lgkmcnt(8)
	v_mfma_f32_32x32x16_bf16 v[64:79], v[238:241], v[242:245], v[64:79]
	ds_read_b64_tr_b16 v[238:239], v205 offset:24576
	ds_read_b64_tr_b16 v[240:241], v205 offset:28672
	s_cmp_lg_u64 s[8:9], 0
	s_cbranch_scc1 .Latt_nd3_3B1
	s_add_i32 m0, m0, 0x400
	s_nop 0
	global_load_lds_dwordx4 v184, s[100:101]
.Latt_nd3_3B1:
	s_waitcnt lgkmcnt(8)
	v_mfma_f32_32x32x16_bf16 v[48:63], v[222:225], v[242:245], v[48:63]
	ds_read_b64_tr_b16 v[222:223], v218 offset:24576
	ds_read_b64_tr_b16 v[224:225], v218 offset:28672
	s_cmp_lg_u64 s[8:9], 0
	s_cbranch_scc1 .Latt_nd4_3B1
	s_add_i32 m0, m0, 0x400
	s_nop 0
	global_load_lds_dwordx4 v186, s[100:101]
.Latt_nd4_3B1:
	s_waitcnt lgkmcnt(8)
	v_mfma_f32_32x32x16_bf16 v[32:47], v[206:209], v[242:245], v[32:47]
	ds_read_b64_tr_b16 v[206:207], v219 offset:24576
	ds_read_b64_tr_b16 v[208:209], v219 offset:28672
	s_cmp_lg_u64 s[8:9], 0
	s_cbranch_scc1 .Latt_nd5_3B1
	s_add_i32 m0, m0, 0x400
	s_nop 0
	global_load_lds_dwordx4 v188, s[100:101]

.Latt_B0_3:
	s_lshl_b32 s98, s11, 14
	s_lshl_b32 s99, s11, 15
	s_add_i32 s99, s99, 0xc000
	v_add_u32_e32 v206, s98, v196
	ds_read_b128 v[206:209], v206
	v_add_u32_e32 v210, s98, v197
	ds_read_b128 v[210:213], v210
	v_add_u32_e32 v214, s98, v198
	ds_read_b128 v[214:217], v214
	v_add_u32_e32 v238, s98, v199
	ds_read_b128 v[238:241], v238
	v_add_u32_e32 v242, s98, v200
	ds_read_b128 v[242:245], v242
	v_add_u32_e32 v250, s98, v201
	ds_read_b128 v[250:253], v250
	v_add_u32_e32 v222, s98, v202
	ds_read_b128 v[222:225], v222
	v_add_u32_e32 v226, s98, v203
	ds_read_b128 v[226:229], v226
	v_bfe_u32 v246, v204, 2, 2
	v_bfe_u32 v247, v204, 5, 1
	v_lshl_or_b32 v247, v247, 2, v246
	v_and_b32_e32 v249, 3, v204
	v_and_b32_e32 v254, 16, v204
	v_lshl_or_b32 v249, v249, 2, v254
	v_lshlrev_b32_e32 v249, 1, v249
	v_lshl_add_u32 v247, v247, 9, v249
	v_add_u32_e32 v247, s99, v247
	v_lshlrev_b32_e32 v246, 6, v246
	v_add_u32_e32 v205, v247, v246
	v_xor_b32_e32 v249, 64, v246
	v_add_u32_e32 v218, v247, v249
	v_xor_b32_e32 v249, 0x80, v246
	v_add_u32_e32 v219, v247, v249
	v_xor_b32_e32 v249, 0xc0, v246
	v_add_u32_e32 v221, v247, v249
	s_waitcnt lgkmcnt(7)
	v_mfma_f32_32x32x16_bf16 v[128:143], v[206:209], v[144:147], 0
	v_add_u32_e32 v206, s98, v196
	ds_read_b128 v[206:209], v206 offset:8192
	s_cmp_lg_u64 s[8:9], 0
	s_cbranch_scc1 .Latt_nd0_3B0
	s_add_i32 s100, s11, 1
	s_cmp_eq_u32 s11, 2
	s_cselect_b32 s100, 0, s100
	s_lshl_b32 s101, s100, 14
	s_add_i32 m0, s40, s101
	s_nop 0
	global_load_lds_dwordx4 v178, s[34:35]
.Latt_nd0_3B0:
	s_waitcnt lgkmcnt(7)
	v_mfma_f32_32x32x16_bf16 v[128:143], v[210:213], v[148:151], v[128:143]
	v_add_u32_e32 v210, s98, v197
	ds_read_b128 v[210:213], v210 offset:8192
	s_cmp_lg_u64 s[8:9], 0
	s_cbranch_scc1 .Latt_nd1_3B0
	s_add_i32 m0, m0, 0x400
	s_nop 0
	global_load_lds_dwordx4 v180, s[34:35]
.Latt_nd1_3B0:
	s_waitcnt lgkmcnt(7)
	v_mfma_f32_32x32x16_bf16 v[128:143], v[214:217], v[152:155], v[128:143]
	v_add_u32_e32 v214, s98, v198
	ds_read_b128 v[214:217], v214 offset:8192
	s_cmp_lg_u64 s[8:9], 0
	s_cbranch_scc1 .Latt_nd2_3B0
	s_lshl_b32 s101, s100, 15
	s_add_i32 m0, s41, s101
	s_add_u32 s100, s34, 0xf00
	s_addc_u32 s101, s35, 0
	global_load_lds_dwordx4 v182, s[100:101]
.Latt_nd2_3B0:
	s_waitcnt lgkmcnt(7)
	v_mfma_f32_32x32x16_bf16 v[128:143], v[238:241], v[156:159], v[128:143]
	v_add_u32_e32 v238, s98, v199
	ds_read_b128 v[238:241], v238 offset:8192
	s_cmp_lg_u64 s[8:9], 0
	s_cbranch_scc1 .Latt_nd3_3B0
	s_add_i32 m0, m0, 0x400
	s_nop 0
	global_load_lds_dwordx4 v184, s[100:101]
.Latt_nd3_3B0:
	s_waitcnt lgkmcnt(7)
	v_mfma_f32_32x32x16_bf16 v[128:143], v[242:245], v[160:163], v[128:143]
	v_add_u32_e32 v242, s98, v200
	ds_read_b128 v[242:245], v242 offset:8192
	s_cmp_lg_u64 s[8:9], 0
	s_cbranch_scc1 .Latt_nd4_3B0
	s_add_i32 m0, m0, 0x400
	s_nop 0
	global_load_lds_dwordx4 v186, s[100:101]
.Latt_nd4_3B0:
	s_waitcnt lgkmcnt(7)
	v_mfma_f32_32x32x16_bf16 v[128:143], v[250:253], v[164:167], v[128:143]
	v_add_u32_e32 v250, s98, v201
	ds_read_b128 v[250:253], v250 offset:8192
	s_cmp_lg_u64 s[8:9], 0
	s_cbranch_scc1 .Latt_nd5_3B0
	s_add_i32 m0, m0, 0x400
	s_nop 0
	global_load_lds_dwordx4 v188, s[100:101]

.Latt_slow_3:
	v_lshrrev_b32_e32 v246, 8, v220
	s_nop 0
	v_readfirstlane_b32 s100, v246
	s_nop 0
	s_cmp_eq_u32 s100, 0
	s_cbranch_scc1 .Latt_slow2_3
	s_cmp_eq_u32 s14, 0
	s_cbranch_scc1 .Latt_slow2_3
	s_add_i32 s99, s11, 2
	s_sub_i32 s101, s99, 3
	s_cmp_lt_u32 s99, 3
	s_cselect_b32 s99, s99, s101
	s_lshl_b32 s99, s99, 15
	s_add_i32 s99, s99, 0xc000
	v_bfe_u32 v246, v204, 2, 2
	v_bfe_u32 v247, v204, 5, 1
	v_lshl_or_b32 v247, v247, 2, v246
	v_and_b32_e32 v249, 3, v204
	v_and_b32_e32 v254, 16, v204
	v_lshl_or_b32 v249, v249, 2, v254
	v_lshlrev_b32_e32 v249, 1, v249
	v_lshl_add_u32 v247, v247, 9, v249
	v_add_u32_e32 v247, s99, v247
	v_lshlrev_b32_e32 v246, 6, v246
	v_add_u32_e32 v205, v247, v246
	v_xor_b32_e32 v249, 64, v246
	v_add_u32_e32 v218, v247, v249
	v_xor_b32_e32 v249, 0x80, v246
	v_add_u32_e32 v219, v247, v249
	v_xor_b32_e32 v249, 0xc0, v246
	v_add_u32_e32 v221, v247, v249
	ds_read_b64_tr_b16 v[206:207], v205 offset:16384
	ds_read_b64_tr_b16 v[208:209], v205 offset:20480
	ds_read_b64_tr_b16 v[210:211], v218 offset:16384
	ds_read_b64_tr_b16 v[212:213], v218 offset:20480
	ds_read_b64_tr_b16 v[214:215], v219 offset:16384
	ds_read_b64_tr_b16 v[216:217], v219 offset:20480
	ds_read_b64_tr_b16 v[238:239], v221 offset:16384
	ds_read_b64_tr_b16 v[240:241], v221 offset:20480
	ds_read_b64_tr_b16 v[222:223], v205 offset:16640
	ds_read_b64_tr_b16 v[224:225], v205 offset:20736
	s_waitcnt lgkmcnt(8)
	v_mfma_f32_32x32x16_bf16 v[112:127], v[206:209], v[242:245], v[112:127]
	ds_read_b64_tr_b16 v[206:207], v218 offset:16640
	ds_read_b64_tr_b16 v[208:209], v218 offset:20736
	s_waitcnt lgkmcnt(8)
	v_mfma_f32_32x32x16_bf16 v[96:111], v[210:213], v[242:245], v[96:111]
	ds_read_b64_tr_b16 v[210:211], v219 offset:16640
	ds_read_b64_tr_b16 v[212:213], v219 offset:20736
	s_waitcnt lgkmcnt(8)
	v_mfma_f32_32x32x16_bf16 v[80:95], v[214:217], v[242:245], v[80:95]
	ds_read_b64_tr_b16 v[214:215], v221 offset:16640
	ds_read_b64_tr_b16 v[216:217], v221 offset:20736
	s_waitcnt lgkmcnt(8)
	v_mfma_f32_32x32x16_bf16 v[64:79], v[238:241], v[242:245], v[64:79]
	ds_read_b64_tr_b16 v[238:239], v205 offset:24576
	ds_read_b64_tr_b16 v[240:241], v205 offset:28672
	s_waitcnt lgkmcnt(8)
	v_mfma_f32_32x32x16_bf16 v[48:63], v[222:225], v[242:245], v[48:63]
	ds_read_b64_tr_b16 v[222:223], v218 offset:24576
	ds_read_b64_tr_b16 v[224:225], v218 offset:28672
	s_waitcnt lgkmcnt(8)
	v_mfma_f32_32x32x16_bf16 v[32:47], v[206:209], v[242:245], v[32:47]
	ds_read_b64_tr_b16 v[206:207], v219 offset:24576
	ds_read_b64_tr_b16 v[208:209], v219 offset:28672
	s_waitcnt lgkmcnt(8)
	v_mfma_f32_32x32x16_bf16 v[16:31], v[210:213], v[242:245], v[16:31]
	ds_read_b64_tr_b16 v[210:211], v221 offset:24576
	ds_read_b64_tr_b16 v[212:213], v221 offset:28672
	s_waitcnt lgkmcnt(8)
	v_mfma_f32_32x32x16_bf16 v[0:15], v[214:217], v[242:245], v[0:15]
	ds_read_b64_tr_b16 v[214:215], v205 offset:24832
	ds_read_b64_tr_b16 v[216:217], v205 offset:28928
	s_waitcnt lgkmcnt(8)
	v_mfma_f32_32x32x16_bf16 v[112:127], v[238:241], v[250:253], v[112:127]
	ds_read_b64_tr_b16 v[238:239], v218 offset:24832
	ds_read_b64_tr_b16 v[240:241], v218 offset:28928
	s_waitcnt lgkmcnt(8)
	v_mfma_f32_32x32x16_bf16 v[96:111], v[222:225], v[250:253], v[96:111]
	ds_read_b64_tr_b16 v[222:223], v219 offset:24832
	ds_read_b64_tr_b16 v[224:225], v219 offset:28928
	s_waitcnt lgkmcnt(8)
	v_mfma_f32_32x32x16_bf16 v[80:95], v[206:209], v[250:253], v[80:95]
	ds_read_b64_tr_b16 v[206:207], v221 offset:24832
	ds_read_b64_tr_b16 v[208:209], v221 offset:28928
	s_waitcnt lgkmcnt(8)
	v_mfma_f32_32x32x16_bf16 v[64:79], v[210:213], v[250:253], v[64:79]
	s_waitcnt lgkmcnt(6)
	v_mfma_f32_32x32x16_bf16 v[48:63], v[214:217], v[250:253], v[48:63]
	s_waitcnt lgkmcnt(4)
	v_mfma_f32_32x32x16_bf16 v[32:47], v[238:241], v[250:253], v[32:47]
	s_waitcnt lgkmcnt(2)
	v_mfma_f32_32x32x16_bf16 v[16:31], v[222:225], v[250:253], v[16:31]
	s_waitcnt lgkmcnt(0)
	v_mfma_f32_32x32x16_bf16 v[0:15], v[206:209], v[250:253], v[0:15]

.LBB0_917:
	s_andn2_b64 vcc, exec, s[8:9]
	s_cbranch_vccnz .LBB0_901
	s_waitcnt vmcnt(0)
	s_branch .LBB0_901

.LBB0_1797:
	s_lshl_b32 s4, s49, 1
	s_and_b32 s14, s4, 0xe00
	s_and_b32 s66, s53, 7
	v_readfirstlane_b32 s4, v176
	s_xor_b32 s9, s66, 15
	s_ashr_i32 s4, s4, 6
	s_ashr_i32 s8, s53, 6
	s_lshl_b32 s75, s9, 8
	s_lshl_b32 s15, s4, 5
	s_lshl_b32 s70, s9, 2
	s_add_i32 s71, s15, s75
	s_ashr_i32 s9, s8, 31
	s_add_i32 s70, s70, 4
	s_or_b32 s72, s71, 31
	s_lshl_b64 s[36:37], s[8:9], 12
	s_lshl_b64 s[12:13], s[8:9], 26
	s_add_u32 s8, s2, s12
	s_addc_u32 s9, s3, s13
	s_lshl_b32 s10, s53, 5
	s_and_b32 s67, s10, 0x700
	s_lshl_b32 s10, s67, 1
	s_add_u32 s18, s8, s10
	s_addc_u32 s19, s9, 0
	s_add_u32 s34, s18, 0x1000
	s_addc_u32 s35, s19, 0
	s_add_u32 s16, s18, 0x2000
	s_addc_u32 s17, s19, 0
	s_add_u32 s8, s2, s10
	s_addc_u32 s9, s3, 0
	s_lshl_b32 s43, s4, 3
	s_lshl_b32 s42, s4, 11
	s_lshl_b32 s33, s4, 12
	s_add_u32 s10, s18, 0x102000
	s_addc_u32 s11, s19, 0
	s_or_b32 s20, s36, s75
	s_ashr_i32 s21, s15, 31
	s_add_u32 s68, s20, s15
	s_addc_u32 s69, s37, s21
	s_cmp_lg_u32 0, -1
	s_cselect_b32 s15, 0, 0
	s_add_i32 s20, s15, 0xc000
	s_add_i32 s73, s42, s15
	s_add_i32 s74, s33, s20
	v_mov_b32_e32 v4, v176
	v_mov_b32_e32 v181, v179
	v_bfe_u32 v0, v4, 4, 2
	v_or_b32_e32 v1, s43, v0
	v_bitop3_b32 v0, v0, v4, s43 bitop3:0x36
	v_lshlrev_b32_e32 v2, 14, v1
	v_lshlrev_b32_e32 v0, 4, v0
	v_and_or_b32 v178, v0, s55, v2
	v_or_b32_e32 v0, 4, v1
	v_bitop3_b32 v1, v1, v4, 4 bitop3:0x36
	v_lshlrev_b32_e32 v0, 14, v0
	v_lshlrev_b32_e32 v1, 4, v1
	v_and_or_b32 v180, v1, s55, v0
	v_bfe_u32 v0, v4, 5, 1
	v_or_b32_e32 v1, s43, v0
	v_and_b32_e32 v2, 31, v4
	v_lshlrev_b32_e32 v3, 14, v1
	v_lshlrev_b32_e32 v0, 6, v0
	v_lshlrev_b32_e32 v5, 4, v2
	v_bitop3_b32 v182, v0, v3, v5 bitop3:0xde
	v_or_b32_e32 v0, 2, v1
	v_lshlrev_b32_e32 v3, 2, v0
	v_bitop3_b32 v3, v3, v2, 12 bitop3:0x6c
	v_lshlrev_b32_e32 v0, 14, v0
	v_lshl_or_b32 v184, v3, 4, v0
	v_or_b32_e32 v0, 6, v1
	v_lshlrev_b32_e32 v1, 2, v0
	v_bitop3_b32 v1, v1, v2, 12 bitop3:0x6c
	v_lshlrev_b32_e32 v0, 14, v0
	v_lshl_or_b32 v188, v1, 4, v0
	v_lshl_add_u64 v[0:1], s[34:35], 0, v[178:179]
	s_mov_b32 s20, m0
	s_mov_b32 m0, s73
	s_nop 0
	global_load_lds_dwordx4 v[0:1], off
	s_mov_b32 m0, s20
	v_lshl_add_u64 v[0:1], s[34:35], 0, v[180:181]
	s_add_i32 s20, s73, 0x400
	s_mov_b32 s21, m0
	s_mov_b32 m0, s20
	s_nop 0
	global_load_lds_dwordx4 v[0:1], off
	s_mov_b32 m0, s21
	v_mov_b32_e32 v183, v179
	v_lshl_add_u64 v[0:1], s[16:17], 0, v[182:183]
	s_mov_b32 s20, m0
	s_mov_b32 m0, s74
	s_nop 0
	global_load_lds_dwordx4 v[0:1], off
	s_mov_b32 m0, s20
	s_add_i32 s15, s15, s33
	v_mov_b32_e32 v185, v179
	s_add_i32 s20, s15, 0xc400
	v_or_b32_e32 v186, 0x10000, v182
	v_lshl_add_u64 v[0:1], s[16:17], 0, v[184:185]
	s_mov_b32 s21, m0
	s_mov_b32 m0, s20
	s_nop 0
	global_load_lds_dwordx4 v[0:1], off
	s_mov_b32 m0, s21
	v_mov_b32_e32 v187, v179
	s_add_i32 s20, s15, 0xc800
	v_lshl_add_u64 v[0:1], s[16:17], 0, v[186:187]
	s_mov_b32 s21, m0
	s_mov_b32 m0, s20
	s_nop 0
	global_load_lds_dwordx4 v[0:1], off
	s_mov_b32 m0, s21
	s_add_i32 s20, s15, 0xcc00
	v_mov_b32_e32 v189, v179
	s_add_u32 s40, s18, 0x101000
	v_lshl_add_u64 v[0:1], s[16:17], 0, v[188:189]
	s_addc_u32 s41, s19, 0
	s_mov_b32 s21, m0
	s_mov_b32 m0, s20
	s_nop 0
	global_load_lds_dwordx4 v[0:1], off
	s_mov_b32 m0, s21
	v_lshl_add_u64 v[0:1], s[40:41], 0, v[178:179]
	s_add_i32 s18, s73, 0x4000
	s_mov_b32 s19, m0
	s_mov_b32 m0, s18
	s_nop 0
	global_load_lds_dwordx4 v[0:1], off
	s_mov_b32 m0, s19
	v_lshl_add_u64 v[0:1], s[40:41], 0, v[180:181]
	s_add_i32 s18, s73, 0x4400
	s_mov_b32 s19, m0
	s_mov_b32 m0, s18
	s_nop 0
	global_load_lds_dwordx4 v[0:1], off
	s_mov_b32 m0, s19
	v_lshl_add_u64 v[0:1], s[10:11], 0, v[182:183]
	s_add_i32 s18, s15, 0x14000
	s_mov_b32 s19, m0
	s_mov_b32 m0, s18
	s_nop 0
	global_load_lds_dwordx4 v[0:1], off
	s_mov_b32 m0, s19
	v_lshl_add_u64 v[0:1], s[10:11], 0, v[184:185]
	s_add_i32 s18, s15, 0x14400
	s_mov_b32 s19, m0
	s_mov_b32 m0, s18
	s_nop 0
	global_load_lds_dwordx4 v[0:1], off
	s_mov_b32 m0, s19
	v_lshl_add_u64 v[0:1], s[10:11], 0, v[186:187]
	s_add_i32 s18, s15, 0x14800
	s_mov_b32 s19, m0
	s_mov_b32 m0, s18
	s_nop 0
	global_load_lds_dwordx4 v[0:1], off
	s_mov_b32 m0, s19
	v_lshl_add_u64 v[0:1], s[10:11], 0, v[188:189]
	s_add_i32 s15, s15, 0x14c00
	s_mov_b32 s18, m0
	s_mov_b32 m0, s15
	s_nop 0
	global_load_lds_dwordx4 v[0:1], off
	s_mov_b32 m0, s18
	v_or_b32_e32 v0, s68, v2
	v_mov_b32_e32 v1, s69
	v_lshlrev_b64 v[0:1], 14, v[0:1]
	v_lshrrev_b32_e32 v2, 1, v4
	v_lshl_add_u64 v[0:1], s[8:9], 0, v[0:1]
	v_and_b32_e32 v2, 16, v2
	v_mov_b32_e32 v3, v179
	v_lshl_add_u64 v[0:1], v[0:1], 0, v[2:3]
	global_load_dwordx4 v[144:147], v[0:1], off
	global_load_dwordx4 v[148:151], v[0:1], off offset:32
	global_load_dwordx4 v[152:155], v[0:1], off offset:64
	global_load_dwordx4 v[156:159], v[0:1], off offset:96
	global_load_dwordx4 v[160:163], v[0:1], off offset:128
	global_load_dwordx4 v[164:167], v[0:1], off offset:160
	global_load_dwordx4 v[168:171], v[0:1], off offset:192
	global_load_dwordx4 v[172:175], v[0:1], off offset:224
	v_lshrrev_b32_e32 v0, 5, v4
	v_and_b32_e32 v1, 15, v4
	v_bitop3_b32 v0, v0, v1, 1 bitop3:0x6c
	v_lshlrev_b32_e32 v1, 8, v4
	s_addk_i32 s75, 0x100
	s_or_b32 s12, s12, s14
	v_lshlrev_b32_e32 v0, 4, v0
	v_and_b32_e32 v1, 0x1f00, v1
	s_add_u32 s20, s47, s12
	v_mov_b32_e32 v14, v179
	v_mov_b32_e32 v15, v179
	v_or_b32_e32 v194, v0, v1
	v_bitop3_b32 v195, v0, 32, v1 bitop3:0x36
	v_bitop3_b32 v196, v0, 64, v1 bitop3:0x36
	v_bitop3_b32 v197, v0, s56, v1 bitop3:0x36
	v_bitop3_b32 v198, v0, s57, v1 bitop3:0x36
	v_bitop3_b32 v199, v0, s58, v1 bitop3:0x36
	v_bitop3_b32 v200, v0, s59, v1 bitop3:0x36
	v_bitop3_b32 v201, v0, s60, v1 bitop3:0x36
	s_addc_u32 s21, s48, s13
	v_mov_b32_e32 v0, v179
	v_mov_b32_e32 v1, v179
	v_mov_b32_e32 v2, v179
	v_mov_b32_e32 v4, v179
	s_waitcnt vmcnt(7)
	s_waitcnt vmcnt(6)
	s_waitcnt vmcnt(5)
	s_waitcnt vmcnt(4)
	s_waitcnt vmcnt(3)
	s_waitcnt vmcnt(2)
	s_waitcnt vmcnt(1)
	s_waitcnt vmcnt(0)
	s_waitcnt vmcnt(0)
	v_mov_b32_e32 v5, v179
	v_mov_b32_e32 v6, v179
	v_mov_b32_e32 v7, v179
	v_mov_b32_e32 v8, v179
	v_mov_b32_e32 v9, v179
	v_mov_b32_e32 v10, v179
	v_mov_b32_e32 v11, v179
	v_mov_b32_e32 v12, v179
	v_mov_b32_e32 v13, v179
	v_mov_b64_e32 v[30:31], v[14:15]
	v_mov_b64_e32 v[46:47], v[14:15]
	v_mov_b64_e32 v[62:63], v[14:15]
	v_mov_b64_e32 v[78:79], v[14:15]
	v_mov_b64_e32 v[94:95], v[14:15]
	v_mov_b64_e32 v[110:111], v[14:15]
	v_mov_b64_e32 v[126:127], v[14:15]
	v_mov_b32_e32 v190, 0xf149f2ca
	s_mov_b32 s38, 2
	s_mov_b64 s[14:15], s[20:21]
	s_mov_b32 s39, 0
	v_mov_b64_e32 v[28:29], v[12:13]
	v_mov_b64_e32 v[26:27], v[10:11]
	v_mov_b64_e32 v[24:25], v[8:9]
	v_mov_b64_e32 v[22:23], v[6:7]
	v_mov_b64_e32 v[20:21], v[4:5]
	v_mov_b64_e32 v[18:19], v[2:3]
	v_mov_b64_e32 v[16:17], v[0:1]
	v_mov_b64_e32 v[44:45], v[12:13]
	v_mov_b64_e32 v[42:43], v[10:11]
	v_mov_b64_e32 v[40:41], v[8:9]
	v_mov_b64_e32 v[38:39], v[6:7]
	v_mov_b64_e32 v[36:37], v[4:5]
	v_mov_b64_e32 v[34:35], v[2:3]
	v_mov_b64_e32 v[32:33], v[0:1]
	v_mov_b64_e32 v[60:61], v[12:13]
	v_mov_b64_e32 v[58:59], v[10:11]
	v_mov_b64_e32 v[56:57], v[8:9]
	v_mov_b64_e32 v[54:55], v[6:7]
	v_mov_b64_e32 v[52:53], v[4:5]
	v_mov_b64_e32 v[50:51], v[2:3]
	v_mov_b64_e32 v[48:49], v[0:1]
	v_mov_b64_e32 v[76:77], v[12:13]
	v_mov_b64_e32 v[74:75], v[10:11]
	v_mov_b64_e32 v[72:73], v[8:9]
	v_mov_b64_e32 v[70:71], v[6:7]
	v_mov_b64_e32 v[68:69], v[4:5]
	v_mov_b64_e32 v[66:67], v[2:3]
	v_mov_b64_e32 v[64:65], v[0:1]
	v_mov_b64_e32 v[92:93], v[12:13]
	v_mov_b64_e32 v[90:91], v[10:11]
	v_mov_b64_e32 v[88:89], v[8:9]
	v_mov_b64_e32 v[86:87], v[6:7]
	v_mov_b64_e32 v[84:85], v[4:5]
	v_mov_b64_e32 v[82:83], v[2:3]
	v_mov_b64_e32 v[80:81], v[0:1]
	v_mov_b64_e32 v[108:109], v[12:13]
	v_mov_b64_e32 v[106:107], v[10:11]
	v_mov_b64_e32 v[104:105], v[8:9]
	v_mov_b64_e32 v[102:103], v[6:7]
	v_mov_b64_e32 v[100:101], v[4:5]
	v_mov_b64_e32 v[98:99], v[2:3]
	v_mov_b64_e32 v[96:97], v[0:1]
	v_mov_b64_e32 v[124:125], v[12:13]
	v_mov_b64_e32 v[122:123], v[10:11]
	v_mov_b64_e32 v[120:121], v[8:9]
	v_mov_b64_e32 v[118:119], v[6:7]
	v_mov_b64_e32 v[116:117], v[4:5]
	v_mov_b64_e32 v[114:115], v[2:3]
	v_mov_b64_e32 v[112:113], v[0:1]
	v_mov_b32_e32 v202, v179
	s_mov_b32 s76, 0
	s_sub_u32 s14, s14, 0x100000
	s_subb_u32 s15, s15, 0
	s_sub_i32 s38, s38, 1
	s_barrier
	s_branch .LBB0_1799

.LBB0_1799:
	s_cmp_ge_u32 s38, s70
	s_cselect_b64 s[18:19], -1, 0
	v_mov_b32_e32 v203, v176
	s_and_b64 vcc, exec, s[18:19]
	s_cbranch_vccnz .LBB0_1801
	s_add_i32 s100, s39, 63
	s_cmp_le_i32 s100, s71
	s_cbranch_scc1 .LBB0_1801
	s_add_i32 s22, s76, 1
	s_cmp_eq_u32 s22, 3
	s_cselect_b32 s22, 0, s22
	v_mov_b32_e32 v130, s22
	v_lshlrev_b32_e32 v128, 14, v130
	v_add_u32_e32 v131, s73, v128
	v_lshl_add_u64 v[128:129], s[14:15], 0, v[178:179]
	s_add_u32 s22, s14, 0x1000
	v_readfirstlane_b32 s77, v131
	s_mov_b32 s78, m0
	s_mov_b32 m0, s77
	s_nop 0
	global_load_lds_dwordx4 v[128:129], off
	s_mov_b32 m0, s78
	v_lshl_add_u64 v[128:129], s[14:15], 0, v[180:181]
	s_addc_u32 s23, s15, 0
	s_addk_i32 s77, 0x400
	s_mov_b32 s78, m0
	s_mov_b32 m0, s77
	s_nop 0
	global_load_lds_dwordx4 v[128:129], off
	s_mov_b32 m0, s78
	v_lshlrev_b32_e32 v128, 15, v130
	v_add_u32_e32 v130, s74, v128
	v_lshl_add_u64 v[128:129], s[22:23], 0, v[182:183]
	v_readfirstlane_b32 s77, v130
	s_mov_b32 s78, m0
	s_mov_b32 m0, s77
	s_nop 0
	global_load_lds_dwordx4 v[128:129], off
	s_mov_b32 m0, s78
	v_lshl_add_u64 v[128:129], s[22:23], 0, v[184:185]
	s_add_i32 s78, s77, 0x400
	s_mov_b32 s79, m0
	s_mov_b32 m0, s78
	s_nop 0
	global_load_lds_dwordx4 v[128:129], off
	s_mov_b32 m0, s79
	v_lshl_add_u64 v[128:129], s[22:23], 0, v[186:187]
	s_add_i32 s78, s77, 0x800
	s_mov_b32 s79, m0
	s_mov_b32 m0, s78
	s_nop 0
	global_load_lds_dwordx4 v[128:129], off
	s_mov_b32 m0, s79
	v_lshl_add_u64 v[128:129], s[22:23], 0, v[188:189]
	s_add_i32 s22, s77, 0xc00
	s_mov_b32 s23, m0
	s_mov_b32 m0, s22
	s_nop 0
	global_load_lds_dwordx4 v[128:129], off
	s_mov_b32 m0, s23
.LBB0_1801:
	s_cmp_gt_i32 s39, s72
	s_cbranch_scc1 .LBB0_1812
	s_add_i32 s100, s39, 63
	s_cmp_le_i32 s100, s71
	s_cbranch_scc0 .Latt_slow_4
	v_lshrrev_b32_e32 v246, 8, v220
	s_nop 0
	v_readfirstlane_b32 s100, v246
	s_nop 0
	s_cmp_eq_u32 s100, 0
	s_cbranch_scc1 .Latt_A_4
	s_cmp_eq_u32 s39, 0
	s_cbranch_scc1 .Latt_B0_4
	s_add_i32 s99, s76, 2
	s_sub_i32 s101, s99, 3
	s_cmp_lt_u32 s99, 3
	s_cselect_b32 s99, s99, s101
	s_lshl_b32 s99, s99, 15
	s_add_i32 s99, s99, 0xc000
	v_bfe_u32 v246, v203, 2, 2
	v_bfe_u32 v247, v203, 5, 1
	v_lshl_or_b32 v247, v247, 2, v246
	v_and_b32_e32 v249, 3, v203
	v_and_b32_e32 v254, 16, v203
	v_lshl_or_b32 v249, v249, 2, v254
	v_lshlrev_b32_e32 v249, 1, v249
	v_lshl_add_u32 v247, v247, 9, v249
	v_add_u32_e32 v247, s99, v247
	v_lshlrev_b32_e32 v246, 6, v246
	v_add_u32_e32 v205, v247, v246
	v_xor_b32_e32 v249, 64, v246
	v_add_u32_e32 v218, v247, v249
	v_xor_b32_e32 v249, 0x80, v246
	v_add_u32_e32 v219, v247, v249
	v_xor_b32_e32 v249, 0xc0, v246
	v_add_u32_e32 v221, v247, v249
	s_lshl_b32 s98, s76, 14
	s_lshl_b32 s99, s76, 15
	s_add_i32 s99, s99, 0xc000
	ds_read_b64_tr_b16 v[206:207], v205 offset:16384
	ds_read_b64_tr_b16 v[208:209], v205 offset:20480
	ds_read_b64_tr_b16 v[210:211], v218 offset:16384
	ds_read_b64_tr_b16 v[212:213], v218 offset:20480
	ds_read_b64_tr_b16 v[214:215], v219 offset:16384
	ds_read_b64_tr_b16 v[216:217], v219 offset:20480
	ds_read_b64_tr_b16 v[238:239], v221 offset:16384
	ds_read_b64_tr_b16 v[240:241], v221 offset:20480
	ds_read_b64_tr_b16 v[222:223], v205 offset:16640
	ds_read_b64_tr_b16 v[224:225], v205 offset:20736
	s_waitcnt lgkmcnt(8)
	v_mfma_f32_32x32x16_bf16 v[112:127], v[206:209], v[242:245], v[112:127]
	ds_read_b64_tr_b16 v[206:207], v218 offset:16640
	ds_read_b64_tr_b16 v[208:209], v218 offset:20736
	s_cmp_lg_u64 s[18:19], 0
	s_cbranch_scc1 .Latt_nd0_4B1
	s_add_i32 s100, s76, 1
	s_cmp_eq_u32 s76, 2
	s_cselect_b32 s100, 0, s100
	s_lshl_b32 s101, s100, 14
	s_add_i32 m0, s73, s101
	s_nop 0
	global_load_lds_dwordx4 v178, s[14:15]

.Latt_nd1_4B1:
	s_waitcnt lgkmcnt(8)
	v_mfma_f32_32x32x16_bf16 v[80:95], v[214:217], v[242:245], v[80:95]
	ds_read_b64_tr_b16 v[214:215], v221 offset:16640
	ds_read_b64_tr_b16 v[216:217], v221 offset:20736
	s_cmp_lg_u64 s[18:19], 0
	s_cbranch_scc1 .Latt_nd2_4B1
	s_lshl_b32 s101, s100, 15
	s_add_i32 m0, s74, s101
	s_add_u32 s100, s14, 0x1000
	s_addc_u32 s101, s15, 0
	global_load_lds_dwordx4 v182, s[100:101]

.Latt_B0_4:
	s_lshl_b32 s98, s76, 14
	s_lshl_b32 s99, s76, 15
	s_add_i32 s99, s99, 0xc000
	v_add_u32_e32 v206, s98, v194
	ds_read_b128 v[206:209], v206
	v_add_u32_e32 v210, s98, v195
	ds_read_b128 v[210:213], v210
	v_add_u32_e32 v214, s98, v196
	ds_read_b128 v[214:217], v214
	v_add_u32_e32 v238, s98, v197
	ds_read_b128 v[238:241], v238
	v_add_u32_e32 v242, s98, v198
	ds_read_b128 v[242:245], v242
	v_add_u32_e32 v250, s98, v199
	ds_read_b128 v[250:253], v250
	v_add_u32_e32 v222, s98, v200
	ds_read_b128 v[222:225], v222
	v_add_u32_e32 v226, s98, v201
	ds_read_b128 v[226:229], v226
	v_bfe_u32 v246, v203, 2, 2
	v_bfe_u32 v247, v203, 5, 1
	v_lshl_or_b32 v247, v247, 2, v246
	v_and_b32_e32 v249, 3, v203
	v_and_b32_e32 v254, 16, v203
	v_lshl_or_b32 v249, v249, 2, v254
	v_lshlrev_b32_e32 v249, 1, v249
	v_lshl_add_u32 v247, v247, 9, v249
	v_add_u32_e32 v247, s99, v247
	v_lshlrev_b32_e32 v246, 6, v246
	v_add_u32_e32 v205, v247, v246
	v_xor_b32_e32 v249, 64, v246
	v_add_u32_e32 v218, v247, v249
	v_xor_b32_e32 v249, 0x80, v246
	v_add_u32_e32 v219, v247, v249
	v_xor_b32_e32 v249, 0xc0, v246
	v_add_u32_e32 v221, v247, v249
	s_waitcnt lgkmcnt(7)
	v_mfma_f32_32x32x16_bf16 v[128:143], v[206:209], v[144:147], 0
	v_add_u32_e32 v206, s98, v194
	ds_read_b128 v[206:209], v206 offset:8192
	s_cmp_lg_u64 s[18:19], 0
	s_cbranch_scc1 .Latt_nd0_4B0
	s_add_i32 s100, s76, 1
	s_cmp_eq_u32 s76, 2
	s_cselect_b32 s100, 0, s100
	s_lshl_b32 s101, s100, 14
	s_add_i32 m0, s73, s101
	s_nop 0
	global_load_lds_dwordx4 v178, s[14:15]

.Latt_nd1_4B0:
	s_waitcnt lgkmcnt(7)
	v_mfma_f32_32x32x16_bf16 v[128:143], v[214:217], v[152:155], v[128:143]
	v_add_u32_e32 v214, s98, v196
	ds_read_b128 v[214:217], v214 offset:8192
	s_cmp_lg_u64 s[18:19], 0
	s_cbranch_scc1 .Latt_nd2_4B0
	s_lshl_b32 s101, s100, 15
	s_add_i32 m0, s74, s101
	s_add_u32 s100, s14, 0x1000
	s_addc_u32 s101, s15, 0
	global_load_lds_dwordx4 v182, s[100:101]

.Latt_slow_4:
	v_lshrrev_b32_e32 v246, 8, v220
	s_nop 0
	v_readfirstlane_b32 s100, v246
	s_nop 0
	s_cmp_eq_u32 s100, 0
	s_cbranch_scc1 .Latt_slow2_4
	s_cmp_eq_u32 s39, 0
	s_cbranch_scc1 .Latt_slow2_4
	s_add_i32 s99, s76, 2
	s_sub_i32 s101, s99, 3
	s_cmp_lt_u32 s99, 3
	s_cselect_b32 s99, s99, s101
	s_lshl_b32 s99, s99, 15
	s_add_i32 s99, s99, 0xc000
	v_bfe_u32 v246, v203, 2, 2
	v_bfe_u32 v247, v203, 5, 1
	v_lshl_or_b32 v247, v247, 2, v246
	v_and_b32_e32 v249, 3, v203
	v_and_b32_e32 v254, 16, v203
	v_lshl_or_b32 v249, v249, 2, v254
	v_lshlrev_b32_e32 v249, 1, v249
	v_lshl_add_u32 v247, v247, 9, v249
	v_add_u32_e32 v247, s99, v247
	v_lshlrev_b32_e32 v246, 6, v246
	v_add_u32_e32 v205, v247, v246
	v_xor_b32_e32 v249, 64, v246
	v_add_u32_e32 v218, v247, v249
	v_xor_b32_e32 v249, 0x80, v246
	v_add_u32_e32 v219, v247, v249
	v_xor_b32_e32 v249, 0xc0, v246
	v_add_u32_e32 v221, v247, v249
	ds_read_b64_tr_b16 v[206:207], v205 offset:16384
	ds_read_b64_tr_b16 v[208:209], v205 offset:20480
	ds_read_b64_tr_b16 v[210:211], v218 offset:16384
	ds_read_b64_tr_b16 v[212:213], v218 offset:20480
	ds_read_b64_tr_b16 v[214:215], v219 offset:16384
	ds_read_b64_tr_b16 v[216:217], v219 offset:20480
	ds_read_b64_tr_b16 v[238:239], v221 offset:16384
	ds_read_b64_tr_b16 v[240:241], v221 offset:20480
	ds_read_b64_tr_b16 v[222:223], v205 offset:16640
	ds_read_b64_tr_b16 v[224:225], v205 offset:20736
	s_waitcnt lgkmcnt(8)
	v_mfma_f32_32x32x16_bf16 v[112:127], v[206:209], v[242:245], v[112:127]
	ds_read_b64_tr_b16 v[206:207], v218 offset:16640
	ds_read_b64_tr_b16 v[208:209], v218 offset:20736
	s_waitcnt lgkmcnt(8)
	v_mfma_f32_32x32x16_bf16 v[96:111], v[210:213], v[242:245], v[96:111]
	ds_read_b64_tr_b16 v[210:211], v219 offset:16640
	ds_read_b64_tr_b16 v[212:213], v219 offset:20736
	s_waitcnt lgkmcnt(8)
	v_mfma_f32_32x32x16_bf16 v[80:95], v[214:217], v[242:245], v[80:95]
	ds_read_b64_tr_b16 v[214:215], v221 offset:16640
	ds_read_b64_tr_b16 v[216:217], v221 offset:20736
	s_waitcnt lgkmcnt(8)
	v_mfma_f32_32x32x16_bf16 v[64:79], v[238:241], v[242:245], v[64:79]
	ds_read_b64_tr_b16 v[238:239], v205 offset:24576
	ds_read_b64_tr_b16 v[240:241], v205 offset:28672
	s_waitcnt lgkmcnt(8)
	v_mfma_f32_32x32x16_bf16 v[48:63], v[222:225], v[242:245], v[48:63]
	ds_read_b64_tr_b16 v[222:223], v218 offset:24576
	ds_read_b64_tr_b16 v[224:225], v218 offset:28672
	s_waitcnt lgkmcnt(8)
	v_mfma_f32_32x32x16_bf16 v[32:47], v[206:209], v[242:245], v[32:47]
	ds_read_b64_tr_b16 v[206:207], v219 offset:24576
	ds_read_b64_tr_b16 v[208:209], v219 offset:28672
	s_waitcnt lgkmcnt(8)
	v_mfma_f32_32x32x16_bf16 v[16:31], v[210:213], v[242:245], v[16:31]
	ds_read_b64_tr_b16 v[210:211], v221 offset:24576
	ds_read_b64_tr_b16 v[212:213], v221 offset:28672
	s_waitcnt lgkmcnt(8)
	v_mfma_f32_32x32x16_bf16 v[0:15], v[214:217], v[242:245], v[0:15]
	ds_read_b64_tr_b16 v[214:215], v205 offset:24832
	ds_read_b64_tr_b16 v[216:217], v205 offset:28928
	s_waitcnt lgkmcnt(8)
	v_mfma_f32_32x32x16_bf16 v[112:127], v[238:241], v[250:253], v[112:127]
	ds_read_b64_tr_b16 v[238:239], v218 offset:24832
	ds_read_b64_tr_b16 v[240:241], v218 offset:28928
	s_waitcnt lgkmcnt(8)
	v_mfma_f32_32x32x16_bf16 v[96:111], v[222:225], v[250:253], v[96:111]
	ds_read_b64_tr_b16 v[222:223], v219 offset:24832
	ds_read_b64_tr_b16 v[224:225], v219 offset:28928
	s_waitcnt lgkmcnt(8)
	v_mfma_f32_32x32x16_bf16 v[80:95], v[206:209], v[250:253], v[80:95]
	ds_read_b64_tr_b16 v[206:207], v221 offset:24832
	ds_read_b64_tr_b16 v[208:209], v221 offset:28928
	s_waitcnt lgkmcnt(8)
	v_mfma_f32_32x32x16_bf16 v[64:79], v[210:213], v[250:253], v[64:79]
	s_waitcnt lgkmcnt(6)
	v_mfma_f32_32x32x16_bf16 v[48:63], v[214:217], v[250:253], v[48:63]
	s_waitcnt lgkmcnt(4)
	v_mfma_f32_32x32x16_bf16 v[32:47], v[238:241], v[250:253], v[32:47]
	s_waitcnt lgkmcnt(2)
	v_mfma_f32_32x32x16_bf16 v[16:31], v[222:225], v[250:253], v[16:31]
	s_waitcnt lgkmcnt(0)
	v_mfma_f32_32x32x16_bf16 v[0:15], v[206:209], v[250:253], v[0:15]

.LBB0_1814:
	s_andn2_b64 vcc, exec, s[22:23]
	s_cbranch_vccnz .LBB0_1798
	s_waitcnt vmcnt(0)
	s_branch .LBB0_1798
.LBB0_1816:
	v_and_b32_e32 v129, 64, v193
	v_xor_b32_e32 v128, 32, v193
	v_add_u32_e32 v129, 64, v129
	v_cmp_lt_i32_e32 vcc, v128, v129
	s_add_i32 s4, s4, s46
	s_lshl_b64 s[14:15], s[4:5], 14
	v_cndmask_b32_e32 v128, v193, v128, vcc
	v_lshlrev_b32_e32 v194, 2, v128
	ds_bpermute_b32 v128, v194, v202
	s_add_u32 s14, s44, s14
	s_addc_u32 s15, s45, s15
	s_mov_b32 s4, 0
	s_mov_b32 s76, 2
	s_waitcnt lgkmcnt(0)
	v_add_f32_e32 v128, v202, v128
	v_rcp_f32_e32 v130, v128
	v_mov_b32_e32 v128, v176
	v_mul_f32_e32 v112, v112, v130
	v_lshlrev_b32_e32 v128, 4, v128
	v_mul_f32_e32 v113, v113, v130
	v_mul_f32_e32 v114, v114, v130
	v_mul_f32_e32 v115, v115, v130
	v_and_b32_e32 v178, 0x3f0, v128
	v_mul_f32_e32 v116, v116, v130
	v_mul_f32_e32 v117, v117, v130
	v_mul_f32_e32 v118, v118, v130
	v_mul_f32_e32 v119, v119, v130
	v_cvt_pk_bf16_f32 v112, v112, v113
	v_cvt_pk_bf16_f32 v113, v114, v115
	v_cvt_pk_bf16_f32 v114, v116, v117
	v_cvt_pk_bf16_f32 v115, v118, v119
	v_mul_f32_e32 v96, v96, v130
	v_mul_f32_e32 v97, v97, v130
	v_mul_f32_e32 v98, v98, v130
	v_mul_f32_e32 v99, v99, v130
	v_lshl_add_u64 v[128:129], s[14:15], 0, v[178:179]
	v_mul_f32_e32 v120, v120, v130
	v_mul_f32_e32 v121, v121, v130
	v_mul_f32_e32 v122, v122, v130
	v_mul_f32_e32 v123, v123, v130
	v_mul_f32_e32 v124, v124, v130
	v_mul_f32_e32 v125, v125, v130
	v_mul_f32_e32 v126, v126, v130
	v_mul_f32_e32 v127, v127, v130
	v_cvt_pk_bf16_f32 v116, v120, v121
	v_cvt_pk_bf16_f32 v117, v122, v123
	v_cvt_pk_bf16_f32 v118, v124, v125
	v_cvt_pk_bf16_f32 v119, v126, v127
	global_store_dwordx4 v178, v[112:115], s[14:15]
	global_store_dwordx4 v178, v[116:119], s[14:15] offset:1024
	v_mul_f32_e32 v100, v100, v130
	v_mul_f32_e32 v101, v101, v130
	v_mul_f32_e32 v102, v102, v130
	v_mul_f32_e32 v103, v103, v130
	v_cvt_pk_bf16_f32 v96, v96, v97
	v_cvt_pk_bf16_f32 v97, v98, v99
	v_cvt_pk_bf16_f32 v98, v100, v101
	v_cvt_pk_bf16_f32 v99, v102, v103
	v_mul_f32_e32 v80, v80, v130
	v_mul_f32_e32 v81, v81, v130
	v_mul_f32_e32 v82, v82, v130
	v_mul_f32_e32 v83, v83, v130
	v_mul_f32_e32 v84, v84, v130
	v_mul_f32_e32 v88, v88, v130
	v_mul_f32_e32 v104, v104, v130
	v_mul_f32_e32 v105, v105, v130
	v_mul_f32_e32 v106, v106, v130
	v_mul_f32_e32 v107, v107, v130
	v_mul_f32_e32 v108, v108, v130
	v_mul_f32_e32 v109, v109, v130
	v_mul_f32_e32 v110, v110, v130
	v_mul_f32_e32 v111, v111, v130
	v_cvt_pk_bf16_f32 v100, v104, v105
	v_cvt_pk_bf16_f32 v101, v106, v107
	v_cvt_pk_bf16_f32 v102, v108, v109
	v_cvt_pk_bf16_f32 v103, v110, v111
	global_store_dwordx4 v178, v[96:99], s[14:15] offset:2048
	global_store_dwordx4 v178, v[100:103], s[14:15] offset:3072
	v_mul_f32_e32 v85, v85, v130
	v_mul_f32_e32 v86, v86, v130
	v_mul_f32_e32 v87, v87, v130
	v_mul_f32_e32 v89, v89, v130
	v_cvt_pk_bf16_f32 v80, v80, v81
	v_cvt_pk_bf16_f32 v81, v82, v83
	v_cvt_pk_bf16_f32 v82, v84, v85
	v_cvt_pk_bf16_f32 v83, v86, v87
	v_cvt_pk_bf16_f32 v84, v88, v89
	v_add_co_u32_e32 v88, vcc, s61, v128
	v_mul_f32_e32 v90, v90, v130
	s_nop 0
	v_addc_co_u32_e32 v89, vcc, 0, v129, vcc
	v_mul_f32_e32 v91, v91, v130
	v_cvt_pk_bf16_f32 v85, v90, v91
	v_add_co_u32_e32 v90, vcc, s62, v128
	v_mul_f32_e32 v64, v64, v130
	s_nop 0
	v_addc_co_u32_e32 v91, vcc, 0, v129, vcc
	v_mul_f32_e32 v65, v65, v130
	v_mul_f32_e32 v66, v66, v130
	v_mul_f32_e32 v67, v67, v130
	v_mul_f32_e32 v92, v92, v130
	v_mul_f32_e32 v93, v93, v130
	v_mul_f32_e32 v94, v94, v130
	v_mul_f32_e32 v95, v95, v130
	v_cvt_pk_bf16_f32 v86, v92, v93
	v_cvt_pk_bf16_f32 v87, v94, v95
	global_store_dwordx4 v[90:91], v[80:83], off offset:-4096
	global_store_dwordx4 v[88:89], v[84:87], off offset:1024
	v_mul_f32_e32 v68, v68, v130
	v_mul_f32_e32 v69, v69, v130
	v_mul_f32_e32 v70, v70, v130
	v_mul_f32_e32 v71, v71, v130
	v_cvt_pk_bf16_f32 v64, v64, v65
	v_cvt_pk_bf16_f32 v65, v66, v67
	v_cvt_pk_bf16_f32 v66, v68, v69
	v_cvt_pk_bf16_f32 v67, v70, v71
	v_mul_f32_e32 v48, v48, v130
	v_mul_f32_e32 v49, v49, v130
	v_mul_f32_e32 v50, v50, v130
	v_mul_f32_e32 v51, v51, v130
	v_mul_f32_e32 v72, v72, v130
	v_mul_f32_e32 v73, v73, v130
	v_mul_f32_e32 v74, v74, v130
	v_mul_f32_e32 v75, v75, v130
	v_mul_f32_e32 v76, v76, v130
	v_mul_f32_e32 v77, v77, v130
	v_mul_f32_e32 v78, v78, v130
	v_mul_f32_e32 v79, v79, v130
	v_cvt_pk_bf16_f32 v68, v72, v73
	v_cvt_pk_bf16_f32 v69, v74, v75
	v_cvt_pk_bf16_f32 v70, v76, v77
	v_cvt_pk_bf16_f32 v71, v78, v79
	global_store_dwordx4 v[88:89], v[64:67], off offset:2048
	global_store_dwordx4 v[88:89], v[68:71], off offset:3072
	v_mul_f32_e32 v52, v52, v130
	v_mul_f32_e32 v53, v53, v130
	v_mul_f32_e32 v54, v54, v130
	v_mul_f32_e32 v55, v55, v130
	v_cvt_pk_bf16_f32 v48, v48, v49
	v_cvt_pk_bf16_f32 v49, v50, v51
	v_cvt_pk_bf16_f32 v50, v52, v53
	v_cvt_pk_bf16_f32 v51, v54, v55
	v_mul_f32_e32 v32, v32, v130
	v_mul_f32_e32 v33, v33, v130
	v_mul_f32_e32 v34, v34, v130
	v_mul_f32_e32 v35, v35, v130
	v_mul_f32_e32 v56, v56, v130
	v_mul_f32_e32 v57, v57, v130
	v_mul_f32_e32 v58, v58, v130
	v_mul_f32_e32 v59, v59, v130
	v_mul_f32_e32 v60, v60, v130
	v_mul_f32_e32 v61, v61, v130
	v_mul_f32_e32 v62, v62, v130
	v_mul_f32_e32 v63, v63, v130
	v_cvt_pk_bf16_f32 v52, v56, v57
	v_cvt_pk_bf16_f32 v53, v58, v59
	v_cvt_pk_bf16_f32 v54, v60, v61
	v_cvt_pk_bf16_f32 v55, v62, v63
	global_store_dwordx4 v[90:91], v[48:51], off
	global_store_dwordx4 v[90:91], v[52:55], off offset:1024
	v_mul_f32_e32 v36, v36, v130
	v_mul_f32_e32 v37, v37, v130
	v_mul_f32_e32 v38, v38, v130
	v_mul_f32_e32 v39, v39, v130
	v_cvt_pk_bf16_f32 v32, v32, v33
	v_cvt_pk_bf16_f32 v33, v34, v35
	v_cvt_pk_bf16_f32 v34, v36, v37
	v_cvt_pk_bf16_f32 v35, v38, v39
	v_mul_f32_e32 v16, v16, v130
	v_mul_f32_e32 v17, v17, v130
	v_mul_f32_e32 v18, v18, v130
	v_mul_f32_e32 v19, v19, v130
	v_mul_f32_e32 v20, v20, v130
	v_mul_f32_e32 v24, v24, v130
	v_mul_f32_e32 v40, v40, v130
	v_mul_f32_e32 v41, v41, v130
	v_mul_f32_e32 v42, v42, v130
	v_mul_f32_e32 v43, v43, v130
	v_mul_f32_e32 v44, v44, v130
	v_mul_f32_e32 v45, v45, v130
	v_mul_f32_e32 v46, v46, v130
	v_mul_f32_e32 v47, v47, v130
	v_cvt_pk_bf16_f32 v36, v40, v41
	v_cvt_pk_bf16_f32 v37, v42, v43
	v_cvt_pk_bf16_f32 v38, v44, v45
	v_cvt_pk_bf16_f32 v39, v46, v47
	global_store_dwordx4 v[90:91], v[32:35], off offset:2048
	global_store_dwordx4 v[90:91], v[36:39], off offset:3072
	v_mul_f32_e32 v21, v21, v130
	v_mul_f32_e32 v22, v22, v130
	v_mul_f32_e32 v23, v23, v130
	v_mul_f32_e32 v25, v25, v130
	v_cvt_pk_bf16_f32 v16, v16, v17
	v_cvt_pk_bf16_f32 v17, v18, v19
	v_cvt_pk_bf16_f32 v18, v20, v21
	v_cvt_pk_bf16_f32 v19, v22, v23
	v_cvt_pk_bf16_f32 v20, v24, v25
	v_add_co_u32_e32 v24, vcc, s63, v128
	v_mul_f32_e32 v0, v0, v130
	s_nop 0
	v_addc_co_u32_e32 v25, vcc, 0, v129, vcc
	v_mul_f32_e32 v1, v1, v130
	v_mul_f32_e32 v2, v2, v130
	v_mul_f32_e32 v3, v3, v130
	v_mul_f32_e32 v26, v26, v130
	v_mul_f32_e32 v27, v27, v130
	v_mul_f32_e32 v28, v28, v130
	v_mul_f32_e32 v29, v29, v130
	v_mul_f32_e32 v30, v30, v130
	v_mul_f32_e32 v31, v31, v130
	v_cvt_pk_bf16_f32 v21, v26, v27
	v_cvt_pk_bf16_f32 v22, v28, v29
	v_cvt_pk_bf16_f32 v23, v30, v31
	global_store_dwordx4 v[24:25], v[16:19], off
	global_store_dwordx4 v[24:25], v[20:23], off offset:1024
	v_mul_f32_e32 v4, v4, v130
	v_mul_f32_e32 v5, v5, v130
	v_mul_f32_e32 v6, v6, v130
	v_mul_f32_e32 v7, v7, v130
	v_mul_f32_e32 v8, v8, v130
	v_mul_f32_e32 v9, v9, v130
	v_mul_f32_e32 v10, v10, v130
	v_mul_f32_e32 v11, v11, v130
	v_mul_f32_e32 v12, v12, v130
	v_mul_f32_e32 v13, v13, v130
	v_mul_f32_e32 v14, v14, v130
	v_mul_f32_e32 v15, v15, v130
	v_cvt_pk_bf16_f32 v0, v0, v1
	v_cvt_pk_bf16_f32 v1, v2, v3
	v_cvt_pk_bf16_f32 v2, v4, v5
	v_cvt_pk_bf16_f32 v3, v6, v7
	v_cvt_pk_bf16_f32 v4, v8, v9
	v_cvt_pk_bf16_f32 v5, v10, v11
	v_cvt_pk_bf16_f32 v6, v12, v13
	v_cvt_pk_bf16_f32 v7, v14, v15
	global_store_dwordx4 v[24:25], v[0:3], off offset:2048
	global_store_dwordx4 v[24:25], v[4:7], off offset:3072
	s_nop 1
	v_mov_b32_e32 v4, v176
	s_add_u32 s38, s34, 0x100
	v_bfe_u32 v0, v4, 4, 2
	v_or_b32_e32 v1, s43, v0
	v_bitop3_b32 v0, v0, v4, s43 bitop3:0x36
	v_lshlrev_b32_e32 v2, 14, v1
	v_lshlrev_b32_e32 v0, 4, v0
	v_and_or_b32 v178, v0, s55, v2
	v_or_b32_e32 v0, 4, v1
	v_bitop3_b32 v1, v1, v4, 4 bitop3:0x36
	v_lshlrev_b32_e32 v0, 14, v0
	v_lshlrev_b32_e32 v1, 4, v1
	v_and_or_b32 v180, v1, s55, v0
	v_bfe_u32 v0, v4, 5, 1
	v_or_b32_e32 v1, s43, v0
	v_and_b32_e32 v2, 31, v4
	v_lshlrev_b32_e32 v3, 14, v1
	v_lshlrev_b32_e32 v0, 6, v0
	v_lshlrev_b32_e32 v5, 4, v2
	v_bitop3_b32 v182, v0, v3, v5 bitop3:0xde
	v_or_b32_e32 v0, 2, v1
	v_lshlrev_b32_e32 v3, 2, v0
	v_bitop3_b32 v3, v3, v2, 12 bitop3:0x6c
	v_lshlrev_b32_e32 v0, 14, v0
	s_addc_u32 s39, s35, 0
	v_lshl_or_b32 v184, v3, 4, v0
	v_or_b32_e32 v0, 6, v1
	v_lshlrev_b32_e32 v1, 2, v0
	s_cmp_lg_u32 0, -1
	v_bitop3_b32 v1, v1, v2, 12 bitop3:0x6c
	v_lshlrev_b32_e32 v0, 14, v0
	s_cselect_b32 s18, 0, 0
	v_lshl_or_b32 v188, v1, 4, v0
	v_lshl_add_u64 v[0:1], s[38:39], 0, v[178:179]
	s_add_i32 s19, s42, s18
	s_mov_b32 s22, m0
	s_mov_b32 m0, s19
	s_nop 0
	global_load_lds_dwordx4 v[0:1], off
	s_mov_b32 m0, s22
	v_mov_b32_e32 v181, v179
	s_add_i32 s22, s19, 0x400
	s_add_i32 s18, s18, s33
	v_lshl_add_u64 v[0:1], s[38:39], 0, v[180:181]
	s_mov_b32 s23, m0
	s_mov_b32 m0, s22
	s_nop 0
	global_load_lds_dwordx4 v[0:1], off
	s_mov_b32 m0, s23
	v_mov_b32_e32 v183, v179
	s_add_i32 s22, s18, 0xc000
	v_lshl_add_u64 v[0:1], s[16:17], 0, v[182:183]
	s_mov_b32 s23, m0
	s_mov_b32 m0, s22
	s_nop 0
	global_load_lds_dwordx4 v[0:1], off
	s_mov_b32 m0, s23
	v_mov_b32_e32 v185, v179
	s_add_i32 s22, s18, 0xc400
	v_or_b32_e32 v186, 0x10000, v182
	v_lshl_add_u64 v[0:1], s[16:17], 0, v[184:185]
	s_mov_b32 s23, m0
	s_mov_b32 m0, s22
	s_nop 0
	global_load_lds_dwordx4 v[0:1], off
	s_mov_b32 m0, s23
	v_mov_b32_e32 v187, v179
	s_add_i32 s22, s18, 0xc800
	v_lshl_add_u64 v[0:1], s[16:17], 0, v[186:187]
	s_mov_b32 s23, m0
	s_mov_b32 m0, s22
	s_nop 0
	global_load_lds_dwordx4 v[0:1], off
	s_mov_b32 m0, s23
	s_add_i32 s22, s18, 0xcc00
	v_mov_b32_e32 v189, v179
	s_add_u32 s42, s34, 0x100100
	v_lshl_add_u64 v[0:1], s[16:17], 0, v[188:189]
	s_addc_u32 s43, s35, 0
	s_mov_b32 s23, m0
	s_mov_b32 m0, s22
	s_nop 0
	global_load_lds_dwordx4 v[0:1], off
	s_mov_b32 m0, s23
	v_lshl_add_u64 v[0:1], s[42:43], 0, v[178:179]
	s_add_i32 s22, s19, 0x4000
	s_mov_b32 s23, m0
	s_mov_b32 m0, s22
	s_nop 0
	global_load_lds_dwordx4 v[0:1], off
	s_mov_b32 m0, s23
	v_lshl_add_u64 v[0:1], s[42:43], 0, v[180:181]
	s_addk_i32 s19, 0x4400
	s_mov_b32 s22, m0
	s_mov_b32 m0, s19
	s_nop 0
	global_load_lds_dwordx4 v[0:1], off
	s_mov_b32 m0, s22
	v_lshl_add_u64 v[0:1], s[10:11], 0, v[182:183]
	s_add_i32 s19, s18, 0x14000
	s_mov_b32 s22, m0
	s_mov_b32 m0, s19
	s_nop 0
	global_load_lds_dwordx4 v[0:1], off
	s_mov_b32 m0, s22
	v_lshl_add_u64 v[0:1], s[10:11], 0, v[184:185]
	s_add_i32 s19, s18, 0x14400
	s_mov_b32 s22, m0
	s_mov_b32 m0, s19
	s_nop 0
	global_load_lds_dwordx4 v[0:1], off
	s_mov_b32 m0, s22
	v_lshl_add_u64 v[0:1], s[10:11], 0, v[186:187]
	s_add_i32 s19, s18, 0x14800
	s_mov_b32 s22, m0
	s_mov_b32 m0, s19
	s_nop 0
	global_load_lds_dwordx4 v[0:1], off
	s_mov_b32 m0, s22
	v_lshl_add_u64 v[0:1], s[10:11], 0, v[188:189]
	s_add_i32 s18, s18, 0x14c00
	s_mov_b32 s19, m0
	s_mov_b32 m0, s18
	s_nop 0
	global_load_lds_dwordx4 v[0:1], off
	s_mov_b32 m0, s19
	v_or_b32_e32 v0, s68, v2
	v_mov_b32_e32 v1, s69
	v_lshlrev_b64 v[0:1], 14, v[0:1]
	v_lshrrev_b32_e32 v2, 1, v4
	v_lshl_add_u64 v[0:1], s[8:9], 0, v[0:1]
	v_and_b32_e32 v2, 16, v2
	v_mov_b32_e32 v3, v179
	v_lshl_add_u64 v[0:1], v[0:1], 0, v[2:3]
	global_load_dwordx4 v[144:147], v[0:1], off offset:256
	global_load_dwordx4 v[148:151], v[0:1], off offset:288
	global_load_dwordx4 v[152:155], v[0:1], off offset:320
	global_load_dwordx4 v[156:159], v[0:1], off offset:352
	global_load_dwordx4 v[160:163], v[0:1], off offset:384
	global_load_dwordx4 v[164:167], v[0:1], off offset:416
	global_load_dwordx4 v[168:171], v[0:1], off offset:448
	global_load_dwordx4 v[172:175], v[0:1], off offset:480
	v_lshrrev_b32_e32 v0, 5, v4
	v_and_b32_e32 v1, 15, v4
	v_bitop3_b32 v0, v0, v1, 1 bitop3:0x6c
	v_lshlrev_b32_e32 v1, 8, v4
	v_lshlrev_b32_e32 v0, 4, v0
	v_and_b32_e32 v1, 0x1f00, v1
	s_add_u32 s22, s51, s12
	v_mov_b32_e32 v14, v179
	v_mov_b32_e32 v15, v179
	v_or_b32_e32 v196, v0, v1
	v_bitop3_b32 v197, v0, 32, v1 bitop3:0x36
	v_bitop3_b32 v198, v0, 64, v1 bitop3:0x36
	v_bitop3_b32 v199, v0, s56, v1 bitop3:0x36
	v_bitop3_b32 v200, v0, s57, v1 bitop3:0x36
	v_bitop3_b32 v201, v0, s58, v1 bitop3:0x36
	v_bitop3_b32 v202, v0, s59, v1 bitop3:0x36
	v_bitop3_b32 v203, v0, s60, v1 bitop3:0x36
	s_addc_u32 s23, s54, s13
	s_waitcnt vmcnt(7)
	s_waitcnt vmcnt(6)
	s_waitcnt vmcnt(5)
	s_waitcnt vmcnt(4)
	s_waitcnt vmcnt(3)
	s_waitcnt vmcnt(2)
	s_waitcnt vmcnt(1)
	s_waitcnt vmcnt(0)
	s_waitcnt vmcnt(0)
	v_mov_b32_e32 v0, v179
	v_mov_b32_e32 v1, v179
	v_mov_b32_e32 v2, v179
	v_mov_b32_e32 v4, v179
	v_mov_b32_e32 v5, v179
	v_mov_b32_e32 v6, v179
	v_mov_b32_e32 v7, v179
	v_mov_b32_e32 v8, v179
	v_mov_b32_e32 v9, v179
	v_mov_b32_e32 v10, v179
	v_mov_b32_e32 v11, v179
	v_mov_b32_e32 v12, v179
	v_mov_b32_e32 v13, v179
	v_mov_b64_e32 v[30:31], v[14:15]
	v_mov_b64_e32 v[46:47], v[14:15]
	v_mov_b64_e32 v[62:63], v[14:15]
	v_mov_b64_e32 v[78:79], v[14:15]
	v_mov_b64_e32 v[94:95], v[14:15]
	v_mov_b64_e32 v[110:111], v[14:15]
	v_mov_b64_e32 v[126:127], v[14:15]
	v_mov_b32_e32 v190, 0xf149f2ca
	v_mov_b32_e32 v195, 0
	s_mov_b64 s[12:13], s[22:23]
	v_mov_b64_e32 v[28:29], v[12:13]
	v_mov_b64_e32 v[26:27], v[10:11]
	v_mov_b64_e32 v[24:25], v[8:9]
	v_mov_b64_e32 v[22:23], v[6:7]
	v_mov_b64_e32 v[20:21], v[4:5]
	v_mov_b64_e32 v[18:19], v[2:3]
	v_mov_b64_e32 v[16:17], v[0:1]
	v_mov_b64_e32 v[44:45], v[12:13]
	v_mov_b64_e32 v[42:43], v[10:11]
	v_mov_b64_e32 v[40:41], v[8:9]
	v_mov_b64_e32 v[38:39], v[6:7]
	v_mov_b64_e32 v[36:37], v[4:5]
	v_mov_b64_e32 v[34:35], v[2:3]
	v_mov_b64_e32 v[32:33], v[0:1]
	v_mov_b64_e32 v[60:61], v[12:13]
	v_mov_b64_e32 v[58:59], v[10:11]
	v_mov_b64_e32 v[56:57], v[8:9]
	v_mov_b64_e32 v[54:55], v[6:7]
	v_mov_b64_e32 v[52:53], v[4:5]
	v_mov_b64_e32 v[50:51], v[2:3]
	v_mov_b64_e32 v[48:49], v[0:1]
	v_mov_b64_e32 v[76:77], v[12:13]
	v_mov_b64_e32 v[74:75], v[10:11]
	v_mov_b64_e32 v[72:73], v[8:9]
	v_mov_b64_e32 v[70:71], v[6:7]
	v_mov_b64_e32 v[68:69], v[4:5]
	v_mov_b64_e32 v[66:67], v[2:3]
	v_mov_b64_e32 v[64:65], v[0:1]
	v_mov_b64_e32 v[92:93], v[12:13]
	v_mov_b64_e32 v[90:91], v[10:11]
	v_mov_b64_e32 v[88:89], v[8:9]
	v_mov_b64_e32 v[86:87], v[6:7]
	v_mov_b64_e32 v[84:85], v[4:5]
	v_mov_b64_e32 v[82:83], v[2:3]
	v_mov_b64_e32 v[80:81], v[0:1]
	v_mov_b64_e32 v[108:109], v[12:13]
	v_mov_b64_e32 v[106:107], v[10:11]
	v_mov_b64_e32 v[104:105], v[8:9]
	v_mov_b64_e32 v[102:103], v[6:7]
	v_mov_b64_e32 v[100:101], v[4:5]
	v_mov_b64_e32 v[98:99], v[2:3]
	v_mov_b64_e32 v[96:97], v[0:1]
	v_mov_b64_e32 v[124:125], v[12:13]
	v_mov_b64_e32 v[122:123], v[10:11]
	v_mov_b64_e32 v[120:121], v[8:9]
	v_mov_b64_e32 v[118:119], v[6:7]
	v_mov_b64_e32 v[116:117], v[4:5]
	v_mov_b64_e32 v[114:115], v[2:3]
	v_mov_b64_e32 v[112:113], v[0:1]
	s_mov_b32 s33, 0
	s_sub_u32 s12, s12, 0x100000
	s_subb_u32 s13, s13, 0
	s_sub_i32 s76, s76, 1
	s_barrier
	s_branch .LBB0_1818

.LBB0_1818:
	s_cmp_ge_u32 s76, s70
	s_cselect_b64 s[18:19], -1, 0
	v_mov_b32_e32 v204, v176
	s_and_b64 vcc, exec, s[18:19]
	s_cbranch_vccnz .LBB0_1820
	s_add_i32 s100, s4, 63
	s_cmp_le_i32 s100, s71
	s_cbranch_scc1 .LBB0_1820
	s_add_i32 s78, s33, 1
	s_cmp_eq_u32 s78, 3
	s_cselect_b32 s78, 0, s78
	v_mov_b32_e32 v130, s78
	v_lshlrev_b32_e32 v128, 14, v130
	v_add_u32_e32 v131, s73, v128
	v_lshl_add_u64 v[128:129], s[12:13], 0, v[178:179]
	s_add_u32 s78, s12, 0xf00
	v_readfirstlane_b32 s77, v131
	s_mov_b32 s80, m0
	s_mov_b32 m0, s77
	s_nop 0
	global_load_lds_dwordx4 v[128:129], off
	s_mov_b32 m0, s80
	v_lshl_add_u64 v[128:129], s[12:13], 0, v[180:181]
	s_addc_u32 s79, s13, 0
	s_addk_i32 s77, 0x400
	s_mov_b32 s80, m0
	s_mov_b32 m0, s77
	s_nop 0
	global_load_lds_dwordx4 v[128:129], off
	s_mov_b32 m0, s80
	v_lshlrev_b32_e32 v128, 15, v130
	v_add_u32_e32 v130, s74, v128
	v_lshl_add_u64 v[128:129], s[78:79], 0, v[182:183]
	v_readfirstlane_b32 s77, v130
	s_mov_b32 s80, m0
	s_mov_b32 m0, s77
	s_nop 0
	global_load_lds_dwordx4 v[128:129], off
	s_mov_b32 m0, s80
	v_lshl_add_u64 v[128:129], s[78:79], 0, v[184:185]
	s_add_i32 s80, s77, 0x400
	s_mov_b32 s81, m0
	s_mov_b32 m0, s80
	s_nop 0
	global_load_lds_dwordx4 v[128:129], off
	s_mov_b32 m0, s81
	v_lshl_add_u64 v[128:129], s[78:79], 0, v[186:187]
	s_add_i32 s80, s77, 0x800
	s_mov_b32 s81, m0
	s_mov_b32 m0, s80
	s_nop 0
	global_load_lds_dwordx4 v[128:129], off
	s_mov_b32 m0, s81
	v_lshl_add_u64 v[128:129], s[78:79], 0, v[188:189]
	s_addk_i32 s77, 0xc00
	s_mov_b32 s78, m0
	s_mov_b32 m0, s77
	s_nop 0
	global_load_lds_dwordx4 v[128:129], off
	s_mov_b32 m0, s78
.LBB0_1820:
	s_cmp_gt_i32 s4, s72
	s_cbranch_scc1 .LBB0_1831
	s_add_i32 s100, s4, 63
	s_cmp_le_i32 s100, s71
	s_cbranch_scc0 .Latt_slow_5
	v_lshrrev_b32_e32 v246, 8, v220
	s_nop 0
	v_readfirstlane_b32 s100, v246
	s_nop 0
	s_cmp_eq_u32 s100, 0
	s_cbranch_scc1 .Latt_A_5
	s_cmp_eq_u32 s4, 0
	s_cbranch_scc1 .Latt_B0_5
	s_add_i32 s99, s33, 2
	s_sub_i32 s101, s99, 3
	s_cmp_lt_u32 s99, 3
	s_cselect_b32 s99, s99, s101
	s_lshl_b32 s99, s99, 15
	s_add_i32 s99, s99, 0xc000
	v_bfe_u32 v246, v204, 2, 2
	v_bfe_u32 v247, v204, 5, 1
	v_lshl_or_b32 v247, v247, 2, v246
	v_and_b32_e32 v249, 3, v204
	v_and_b32_e32 v254, 16, v204
	v_lshl_or_b32 v249, v249, 2, v254
	v_lshlrev_b32_e32 v249, 1, v249
	v_lshl_add_u32 v247, v247, 9, v249
	v_add_u32_e32 v247, s99, v247
	v_lshlrev_b32_e32 v246, 6, v246
	v_add_u32_e32 v205, v247, v246
	v_xor_b32_e32 v249, 64, v246
	v_add_u32_e32 v218, v247, v249
	v_xor_b32_e32 v249, 0x80, v246
	v_add_u32_e32 v219, v247, v249
	v_xor_b32_e32 v249, 0xc0, v246
	v_add_u32_e32 v221, v247, v249
	s_lshl_b32 s98, s33, 14
	s_lshl_b32 s99, s33, 15
	s_add_i32 s99, s99, 0xc000
	ds_read_b64_tr_b16 v[206:207], v205 offset:16384
	ds_read_b64_tr_b16 v[208:209], v205 offset:20480
	ds_read_b64_tr_b16 v[210:211], v218 offset:16384
	ds_read_b64_tr_b16 v[212:213], v218 offset:20480
	ds_read_b64_tr_b16 v[214:215], v219 offset:16384
	ds_read_b64_tr_b16 v[216:217], v219 offset:20480
	ds_read_b64_tr_b16 v[238:239], v221 offset:16384
	ds_read_b64_tr_b16 v[240:241], v221 offset:20480
	ds_read_b64_tr_b16 v[222:223], v205 offset:16640
	ds_read_b64_tr_b16 v[224:225], v205 offset:20736
	s_waitcnt lgkmcnt(8)
	v_mfma_f32_32x32x16_bf16 v[112:127], v[206:209], v[242:245], v[112:127]
	ds_read_b64_tr_b16 v[206:207], v218 offset:16640
	ds_read_b64_tr_b16 v[208:209], v218 offset:20736
	s_cmp_lg_u64 s[18:19], 0
	s_cbranch_scc1 .Latt_nd0_5B1
	s_add_i32 s100, s33, 1
	s_cmp_eq_u32 s33, 2
	s_cselect_b32 s100, 0, s100
	s_lshl_b32 s101, s100, 14
	s_add_i32 m0, s73, s101
	s_nop 0
	global_load_lds_dwordx4 v178, s[12:13]

.Latt_nd1_5B1:
	s_waitcnt lgkmcnt(8)
	v_mfma_f32_32x32x16_bf16 v[80:95], v[214:217], v[242:245], v[80:95]
	ds_read_b64_tr_b16 v[214:215], v221 offset:16640
	ds_read_b64_tr_b16 v[216:217], v221 offset:20736
	s_cmp_lg_u64 s[18:19], 0
	s_cbranch_scc1 .Latt_nd2_5B1
	s_lshl_b32 s101, s100, 15
	s_add_i32 m0, s74, s101
	s_add_u32 s100, s12, 0xf00
	s_addc_u32 s101, s13, 0
	global_load_lds_dwordx4 v182, s[100:101]

.Latt_B0_5:
	s_lshl_b32 s98, s33, 14
	s_lshl_b32 s99, s33, 15
	s_add_i32 s99, s99, 0xc000
	v_add_u32_e32 v206, s98, v196
	ds_read_b128 v[206:209], v206
	v_add_u32_e32 v210, s98, v197
	ds_read_b128 v[210:213], v210
	v_add_u32_e32 v214, s98, v198
	ds_read_b128 v[214:217], v214
	v_add_u32_e32 v238, s98, v199
	ds_read_b128 v[238:241], v238
	v_add_u32_e32 v242, s98, v200
	ds_read_b128 v[242:245], v242
	v_add_u32_e32 v250, s98, v201
	ds_read_b128 v[250:253], v250
	v_add_u32_e32 v222, s98, v202
	ds_read_b128 v[222:225], v222
	v_add_u32_e32 v226, s98, v203
	ds_read_b128 v[226:229], v226
	v_bfe_u32 v246, v204, 2, 2
	v_bfe_u32 v247, v204, 5, 1
	v_lshl_or_b32 v247, v247, 2, v246
	v_and_b32_e32 v249, 3, v204
	v_and_b32_e32 v254, 16, v204
	v_lshl_or_b32 v249, v249, 2, v254
	v_lshlrev_b32_e32 v249, 1, v249
	v_lshl_add_u32 v247, v247, 9, v249
	v_add_u32_e32 v247, s99, v247
	v_lshlrev_b32_e32 v246, 6, v246
	v_add_u32_e32 v205, v247, v246
	v_xor_b32_e32 v249, 64, v246
	v_add_u32_e32 v218, v247, v249
	v_xor_b32_e32 v249, 0x80, v246
	v_add_u32_e32 v219, v247, v249
	v_xor_b32_e32 v249, 0xc0, v246
	v_add_u32_e32 v221, v247, v249
	s_waitcnt lgkmcnt(7)
	v_mfma_f32_32x32x16_bf16 v[128:143], v[206:209], v[144:147], 0
	v_add_u32_e32 v206, s98, v196
	ds_read_b128 v[206:209], v206 offset:8192
	s_cmp_lg_u64 s[18:19], 0
	s_cbranch_scc1 .Latt_nd0_5B0
	s_add_i32 s100, s33, 1
	s_cmp_eq_u32 s33, 2
	s_cselect_b32 s100, 0, s100
	s_lshl_b32 s101, s100, 14
	s_add_i32 m0, s73, s101
	s_nop 0
	global_load_lds_dwordx4 v178, s[12:13]

.Latt_nd1_5B0:
	s_waitcnt lgkmcnt(7)
	v_mfma_f32_32x32x16_bf16 v[128:143], v[214:217], v[152:155], v[128:143]
	v_add_u32_e32 v214, s98, v198
	ds_read_b128 v[214:217], v214 offset:8192
	s_cmp_lg_u64 s[18:19], 0
	s_cbranch_scc1 .Latt_nd2_5B0
	s_lshl_b32 s101, s100, 15
	s_add_i32 m0, s74, s101
	s_add_u32 s100, s12, 0xf00
	s_addc_u32 s101, s13, 0
	global_load_lds_dwordx4 v182, s[100:101]

.LBB0_1835:
	ds_bpermute_b32 v138, v194, v195
	v_mov_b32_e32 v153, v176
	v_mov_b32_e32 v149, s69
	v_lshlrev_b32_e32 v128, 4, v153
	v_and_b32_e32 v178, 0x3f0, v128
	v_lshl_add_u64 v[136:137], s[14:15], 0, v[178:179]
	s_waitcnt lgkmcnt(0)
	v_add_f32_e32 v152, v195, v138
	v_add_co_u32_e32 v138, vcc, s61, v136
	global_load_dwordx4 v[132:135], v178, s[14:15]
	global_load_dwordx4 v[128:131], v178, s[14:15] offset:1024
	global_load_dwordx4 v[144:147], v178, s[14:15] offset:2048
	global_load_dwordx4 v[140:143], v178, s[14:15] offset:3072
	v_addc_co_u32_e32 v139, vcc, 0, v137, vcc
	v_add_co_u32_e32 v150, vcc, s62, v136
	v_rcp_f32_e32 v152, v152
	s_nop 0
	v_addc_co_u32_e32 v151, vcc, 0, v137, vcc
	v_add_co_u32_e32 v154, vcc, s63, v136
	v_mul_f32_e32 v152, v177, v152
	s_nop 0
	v_addc_co_u32_e32 v155, vcc, 0, v137, vcc
	global_load_dwordx4 v[196:199], v[150:151], off offset:-4096
	global_load_dwordx4 v[200:203], v[138:139], off offset:1024
	global_load_dwordx4 v[204:207], v[138:139], off offset:2048
	global_load_dwordx4 v[208:211], v[138:139], off offset:3072
	s_nop 0
	global_load_dwordx4 v[136:139], v[154:155], off offset:3072
	v_and_or_b32 v148, v153, 31, s68
	s_lshl_b32 s4, s67, 1
	s_and_b32 s12, s65, 7
	s_lshl_b32 s67, s12, 8
	v_readfirstlane_b32 s12, v176
	s_ashr_i32 s74, s12, 6
	s_lshl_b32 s12, s66, 8
	s_lshl_b32 s13, s74, 5
	s_lshl_b32 s66, s66, 2
	s_add_i32 s68, s13, s12
	s_addk_i32 s67, 0x100
	s_add_i32 s66, s66, 4
	s_or_b32 s69, s68, 31
	s_lshl_b32 s71, s74, 3
	s_lshl_b32 s70, s74, 11
	s_lshl_b32 s33, s74, 12
	s_or_b32 s12, s36, s12
	s_ashr_i32 s14, s13, 31
	s_add_u32 s18, s12, s13
	s_addc_u32 s19, s37, s14
	s_cmp_lg_u32 0, -1
	s_cselect_b32 s12, 0, 0
	s_add_i32 s13, s12, 0xc000
	s_mov_b32 s72, 0
	s_mov_b32 s73, 2
	s_add_i32 s36, s70, s12
	s_add_i32 s37, s33, s13
	s_waitcnt vmcnt(8)
	v_lshlrev_b32_e32 v157, 16, v133
	v_lshlrev_b32_e32 v159, 16, v135
	s_waitcnt vmcnt(6)
	v_lshlrev_b32_e32 v164, 16, v144
	v_and_b32_e32 v144, 0xffff0000, v144
	v_lshlrev_b32_e32 v165, 16, v145
	v_lshlrev_b32_e32 v162, 16, v130
	v_and_b32_e32 v145, 0xffff0000, v145
	v_lshlrev_b32_e32 v168, 16, v146
	v_lshlrev_b32_e32 v169, 16, v147
	v_and_b32_e32 v147, 0xffff0000, v147
	v_fma_f32 v171, -v96, v152, v164
	v_fma_f32 v170, -v97, v152, v144
	v_fma_f32 v167, -v98, v152, v165
	s_waitcnt vmcnt(4)
	v_lshlrev_b32_e32 v96, 16, v196
	v_and_b32_e32 v97, 0xffff0000, v196
	v_lshlrev_b32_e32 v98, 16, v197
	v_fma_f32 v212, -v114, v152, v157
	v_fma_f32 v185, -v118, v152, v159
	v_fma_f32 v175, -v124, v152, v162
	v_fma_f32 v166, -v99, v152, v145
	v_fma_f32 v162, -v100, v152, v168
	v_fma_f32 v168, -v103, v152, v147
	v_fma_f32 v159, -v80, v152, v96
	v_fma_f32 v157, -v81, v152, v97
	v_fma_f32 v147, -v82, v152, v98
	global_load_dwordx4 v[96:99], v[150:151], off
	v_lshlrev_b32_e32 v160, 16, v128
	v_and_b32_e32 v146, 0xffff0000, v146
	v_lshlrev_b32_e32 v156, 16, v132
	v_lshlrev_b32_e32 v178, 16, v140
	v_lshlrev_b32_e32 v188, 16, v142
	v_and_b32_e32 v142, 0xffff0000, v142
	v_lshlrev_b32_e32 v189, 16, v143
	v_and_b32_e32 v143, 0xffff0000, v143
	v_fma_f32 v183, -v120, v152, v160
	v_fma_f32 v160, -v101, v152, v146
	v_fma_f32 v169, -v102, v152, v169
	v_lshlrev_b32_e32 v101, 16, v198
	v_and_b32_e32 v102, 0xffff0000, v198
	v_lshlrev_b32_e32 v161, 16, v129
	v_and_b32_e32 v130, 0xffff0000, v130
	v_lshlrev_b32_e32 v163, 16, v131
	v_and_b32_e32 v131, 0xffff0000, v131
	v_and_b32_e32 v140, 0xffff0000, v140
	v_lshlrev_b32_e32 v187, 16, v141
	v_and_b32_e32 v141, 0xffff0000, v141
	v_fma_f32 v190, -v112, v152, v156
	v_fma_f32 v165, -v104, v152, v178
	v_fma_f32 v156, -v109, v152, v142
	v_fma_f32 v144, -v111, v152, v143
	v_lshlrev_b32_e32 v103, 16, v199
	v_and_b32_e32 v104, 0xffff0000, v199
	v_fma_f32 v143, -v84, v152, v101
	v_fma_f32 v142, -v85, v152, v102
	s_waitcnt vmcnt(3)
	v_lshlrev_b32_e32 v84, 16, v204
	v_and_b32_e32 v85, 0xffff0000, v204
	v_fma_f32 v181, -v122, v152, v161
	v_fma_f32 v174, -v125, v152, v130
	v_fma_f32 v172, -v127, v152, v131
	v_fma_f32 v164, -v105, v152, v140
	v_fma_f32 v161, -v107, v152, v141
	v_fma_f32 v141, -v86, v152, v103
	v_fma_f32 v140, -v87, v152, v104
	v_fma_f32 v131, -v64, v152, v84
	v_fma_f32 v130, -v65, v152, v85
	global_load_dwordx4 v[84:87], v[150:151], off offset:2048
	v_and_b32_e32 v100, 0xffff0000, v197
	v_fma_f32 v146, -v83, v152, v100
	global_load_dwordx4 v[80:83], v[150:151], off offset:1024
	v_and_b32_e32 v132, 0xffff0000, v132
	v_fma_f32 v195, -v113, v152, v132
	v_mul_f32_e32 v215, v195, v195
	v_and_b32_e32 v133, 0xffff0000, v133
	v_fmac_f32_e32 v215, v190, v190
	v_lshlrev_b32_e32 v158, 16, v134
	v_fma_f32 v213, -v115, v152, v133
	v_fmac_f32_e32 v215, v212, v212
	v_and_b32_e32 v134, 0xffff0000, v134
	v_fma_f32 v214, -v116, v152, v158
	v_fmac_f32_e32 v215, v213, v213
	v_and_b32_e32 v135, 0xffff0000, v135
	v_fma_f32 v186, -v117, v152, v134
	v_fma_f32 v173, -v126, v152, v163
	v_fmac_f32_e32 v215, v214, v214
	v_fma_f32 v163, -v106, v152, v187
	v_lshlrev_b32_e32 v105, 16, v200
	v_and_b32_e32 v106, 0xffff0000, v200
	v_and_b32_e32 v128, 0xffff0000, v128
	v_fma_f32 v184, -v119, v152, v135
	v_fmac_f32_e32 v215, v186, v186
	v_fma_f32 v135, -v88, v152, v105
	v_fma_f32 v134, -v89, v152, v106
	v_lshlrev_b32_e32 v88, 16, v205
	v_and_b32_e32 v89, 0xffff0000, v205
	v_fma_f32 v182, -v121, v152, v128
	v_fmac_f32_e32 v215, v185, v185
	v_fma_f32 v128, -v66, v152, v88
	v_fma_f32 v126, -v67, v152, v89
	global_load_dwordx4 v[64:67], v[150:151], off offset:3072
	v_fmac_f32_e32 v215, v184, v184
	v_fmac_f32_e32 v215, v183, v183
	v_and_b32_e32 v129, 0xffff0000, v129
	v_fmac_f32_e32 v215, v182, v182
	v_fma_f32 v180, -v123, v152, v129
	v_fmac_f32_e32 v215, v181, v181
	v_fmac_f32_e32 v215, v180, v180
	v_fmac_f32_e32 v215, v175, v175
	v_fmac_f32_e32 v215, v174, v174
	v_fmac_f32_e32 v215, v173, v173
	global_load_dwordx4 v[196:199], v[154:155], off
	v_fmac_f32_e32 v215, v172, v172
	v_fmac_f32_e32 v215, v171, v171
	v_fmac_f32_e32 v215, v170, v170
	v_fmac_f32_e32 v215, v167, v167
	v_fmac_f32_e32 v215, v166, v166
	v_fma_f32 v158, -v108, v152, v188
	v_fma_f32 v145, -v110, v152, v189
	v_lshlrev_b32_e32 v107, 16, v201
	v_and_b32_e32 v108, 0xffff0000, v201
	v_lshlrev_b32_e32 v109, 16, v202
	v_and_b32_e32 v110, 0xffff0000, v202
	v_fmac_f32_e32 v215, v162, v162
	v_fma_f32 v133, -v90, v152, v107
	v_fma_f32 v132, -v91, v152, v108
	v_fma_f32 v129, -v92, v152, v109
	v_fma_f32 v127, -v93, v152, v110
	v_lshlrev_b32_e32 v90, 16, v206
	v_and_b32_e32 v91, 0xffff0000, v206
	v_lshlrev_b32_e32 v92, 16, v207
	v_and_b32_e32 v93, 0xffff0000, v207
	v_fmac_f32_e32 v215, v160, v160
	v_lshlrev_b32_e32 v111, 16, v203
	v_fma_f32 v123, -v68, v152, v90
	v_fma_f32 v122, -v69, v152, v91
	v_fma_f32 v121, -v70, v152, v92
	v_fma_f32 v120, -v71, v152, v93
	s_waitcnt vmcnt(4)
	v_lshlrev_b32_e32 v68, 16, v96
	v_and_b32_e32 v69, 0xffff0000, v96
	v_lshlrev_b32_e32 v70, 16, v97
	v_and_b32_e32 v71, 0xffff0000, v97
	v_fmac_f32_e32 v215, v169, v169
	v_fma_f32 v125, -v94, v152, v111
	v_fma_f32 v115, -v48, v152, v68
	v_fma_f32 v113, -v49, v152, v69
	v_fma_f32 v111, -v50, v152, v70
	v_fma_f32 v109, -v51, v152, v71
	global_load_dwordx4 v[48:51], v[154:155], off offset:1024
	v_fmac_f32_e32 v215, v168, v168
	v_fmac_f32_e32 v215, v165, v165
	v_fmac_f32_e32 v215, v164, v164
	v_fmac_f32_e32 v215, v163, v163
	v_fmac_f32_e32 v215, v161, v161
	v_and_b32_e32 v112, 0xffff0000, v203
	v_lshlrev_b32_e32 v94, 16, v208
	v_fmac_f32_e32 v215, v158, v158
	v_fma_f32 v124, -v95, v152, v112
	v_and_b32_e32 v95, 0xffff0000, v208
	v_lshlrev_b32_e32 v100, 16, v209
	v_and_b32_e32 v101, 0xffff0000, v209
	v_fma_f32 v119, -v72, v152, v94
	v_lshlrev_b32_e32 v72, 16, v98
	v_fmac_f32_e32 v215, v156, v156
	v_lshlrev_b32_e32 v104, 16, v211
	v_and_b32_e32 v105, 0xffff0000, v211
	v_fma_f32 v118, -v73, v152, v95
	v_fma_f32 v117, -v74, v152, v100
	v_fma_f32 v116, -v75, v152, v101
	v_and_b32_e32 v73, 0xffff0000, v98
	v_lshlrev_b32_e32 v74, 16, v99
	v_and_b32_e32 v75, 0xffff0000, v99
	v_fma_f32 v107, -v52, v152, v72
	s_waitcnt vmcnt(4)
	v_lshlrev_b32_e32 v52, 16, v84
	v_fmac_f32_e32 v215, v145, v145
	v_fma_f32 v110, -v78, v152, v104
	v_fma_f32 v108, -v79, v152, v105
	v_fma_f32 v106, -v53, v152, v73
	v_fma_f32 v105, -v54, v152, v74
	v_fma_f32 v104, -v55, v152, v75
	v_fma_f32 v99, -v32, v152, v52
	global_load_dwordx4 v[52:55], v[154:155], off offset:2048
	v_fmac_f32_e32 v215, v144, v144
	v_fmac_f32_e32 v215, v159, v159
	v_fmac_f32_e32 v215, v157, v157
	v_fmac_f32_e32 v215, v147, v147
	v_fmac_f32_e32 v215, v146, v146
	v_fmac_f32_e32 v215, v143, v143
	v_fmac_f32_e32 v215, v142, v142
	v_fmac_f32_e32 v215, v141, v141
	v_fmac_f32_e32 v215, v140, v140
	v_fmac_f32_e32 v215, v135, v135
	v_fmac_f32_e32 v215, v134, v134
	v_fmac_f32_e32 v215, v133, v133
	v_fmac_f32_e32 v215, v132, v132
	v_fmac_f32_e32 v215, v129, v129
	v_fmac_f32_e32 v215, v127, v127
	v_fmac_f32_e32 v215, v125, v125
	v_fmac_f32_e32 v215, v124, v124
	v_fmac_f32_e32 v215, v131, v131
	v_fmac_f32_e32 v215, v130, v130
	v_fmac_f32_e32 v215, v128, v128
	v_fmac_f32_e32 v215, v126, v126
	v_fmac_f32_e32 v215, v123, v123
	v_fmac_f32_e32 v215, v122, v122
	v_fmac_f32_e32 v215, v121, v121
	v_fmac_f32_e32 v215, v120, v120
	v_fmac_f32_e32 v215, v119, v119
	v_fmac_f32_e32 v215, v118, v118
	v_lshlrev_b32_e32 v102, 16, v210
	v_fmac_f32_e32 v215, v117, v117
	v_and_b32_e32 v103, 0xffff0000, v210
	v_fmac_f32_e32 v215, v116, v116
	v_fma_f32 v114, -v76, v152, v102
	v_fmac_f32_e32 v215, v114, v114
	v_fma_f32 v112, -v77, v152, v103
	v_fmac_f32_e32 v215, v112, v112
	v_fmac_f32_e32 v215, v110, v110
	v_fmac_f32_e32 v215, v108, v108
	v_fmac_f32_e32 v215, v115, v115
	v_fmac_f32_e32 v215, v113, v113
	v_fmac_f32_e32 v215, v111, v111
	v_fmac_f32_e32 v215, v109, v109
	v_fmac_f32_e32 v215, v107, v107
	v_fmac_f32_e32 v215, v106, v106
	s_waitcnt vmcnt(4)
	v_lshlrev_b32_e32 v76, 16, v80
	v_fmac_f32_e32 v215, v105, v105
	v_and_b32_e32 v77, 0xffff0000, v80
	v_fmac_f32_e32 v215, v104, v104
	v_fma_f32 v103, -v56, v152, v76
	v_lshlrev_b32_e32 v78, 16, v81
	v_fmac_f32_e32 v215, v103, v103
	v_fma_f32 v102, -v57, v152, v77
	v_and_b32_e32 v79, 0xffff0000, v81
	v_fmac_f32_e32 v215, v102, v102
	v_fma_f32 v101, -v58, v152, v78
	v_lshlrev_b32_e32 v80, 16, v82
	v_fmac_f32_e32 v215, v101, v101
	v_fma_f32 v100, -v59, v152, v79
	v_and_b32_e32 v81, 0xffff0000, v82
	v_fmac_f32_e32 v215, v100, v100
	v_fma_f32 v96, -v60, v152, v80
	v_lshlrev_b32_e32 v82, 16, v83
	v_fmac_f32_e32 v215, v96, v96
	v_fma_f32 v95, -v61, v152, v81
	v_and_b32_e32 v83, 0xffff0000, v83
	v_fmac_f32_e32 v215, v95, v95
	v_fma_f32 v92, -v62, v152, v82
	v_fmac_f32_e32 v215, v92, v92
	v_fma_f32 v91, -v63, v152, v83
	v_fmac_f32_e32 v215, v91, v91
	v_and_b32_e32 v56, 0xffff0000, v84
	v_lshlrev_b32_e32 v57, 16, v85
	v_fmac_f32_e32 v215, v99, v99
	v_fma_f32 v97, -v33, v152, v56
	v_and_b32_e32 v58, 0xffff0000, v85
	v_fmac_f32_e32 v215, v97, v97
	v_fma_f32 v94, -v34, v152, v57
	v_lshlrev_b32_e32 v59, 16, v86
	v_fmac_f32_e32 v215, v94, v94
	v_fma_f32 v93, -v35, v152, v58
	v_and_b32_e32 v60, 0xffff0000, v86
	v_fmac_f32_e32 v215, v93, v93
	v_fma_f32 v89, -v36, v152, v59
	v_lshlrev_b32_e32 v61, 16, v87
	v_fmac_f32_e32 v215, v89, v89
	v_fma_f32 v88, -v37, v152, v60
	v_and_b32_e32 v62, 0xffff0000, v87
	v_fmac_f32_e32 v215, v88, v88
	v_fma_f32 v87, -v38, v152, v61
	s_waitcnt vmcnt(3)
	v_lshlrev_b32_e32 v63, 16, v64
	v_fmac_f32_e32 v215, v87, v87
	v_fma_f32 v86, -v39, v152, v62
	v_and_b32_e32 v64, 0xffff0000, v64
	v_fmac_f32_e32 v215, v86, v86
	v_fma_f32 v85, -v40, v152, v63
	v_lshlrev_b32_e32 v68, 16, v65
	v_fmac_f32_e32 v215, v85, v85
	v_fma_f32 v84, -v41, v152, v64
	v_and_b32_e32 v65, 0xffff0000, v65
	v_fmac_f32_e32 v215, v84, v84
	v_fma_f32 v83, -v42, v152, v68
	v_lshlrev_b32_e32 v69, 16, v66
	v_fmac_f32_e32 v215, v83, v83
	v_fma_f32 v82, -v43, v152, v65
	v_and_b32_e32 v66, 0xffff0000, v66
	v_fmac_f32_e32 v215, v82, v82
	v_fma_f32 v80, -v44, v152, v69
	v_lshlrev_b32_e32 v70, 16, v67
	v_fmac_f32_e32 v215, v80, v80
	v_fma_f32 v78, -v45, v152, v66
	v_and_b32_e32 v67, 0xffff0000, v67
	v_fmac_f32_e32 v215, v78, v78
	v_fma_f32 v76, -v46, v152, v70
	v_fmac_f32_e32 v215, v76, v76
	v_fma_f32 v74, -v47, v152, v67
	s_waitcnt vmcnt(2)
	v_lshlrev_b32_e32 v32, 16, v196
	v_fmac_f32_e32 v215, v74, v74
	v_and_b32_e32 v33, 0xffff0000, v196
	v_fma_f32 v81, -v16, v152, v32
	v_lshlrev_b32_e32 v34, 16, v197
	v_fmac_f32_e32 v215, v81, v81
	v_fma_f32 v79, -v17, v152, v33
	v_and_b32_e32 v35, 0xffff0000, v197
	v_fmac_f32_e32 v215, v79, v79
	v_fma_f32 v77, -v18, v152, v34
	v_lshlrev_b32_e32 v36, 16, v198
	v_fmac_f32_e32 v215, v77, v77
	v_fma_f32 v75, -v19, v152, v35
	v_and_b32_e32 v37, 0xffff0000, v198
	v_fmac_f32_e32 v215, v75, v75
	v_fma_f32 v73, -v20, v152, v36
	v_lshlrev_b32_e32 v38, 16, v199
	v_fmac_f32_e32 v215, v73, v73
	v_fma_f32 v72, -v21, v152, v37
	v_and_b32_e32 v39, 0xffff0000, v199
	v_fmac_f32_e32 v215, v72, v72
	v_fma_f32 v71, -v22, v152, v38
	s_waitcnt vmcnt(1)
	v_lshlrev_b32_e32 v40, 16, v48
	v_fmac_f32_e32 v215, v71, v71
	v_fma_f32 v70, -v23, v152, v39
	v_and_b32_e32 v41, 0xffff0000, v48
	v_fmac_f32_e32 v215, v70, v70
	v_fma_f32 v69, -v24, v152, v40
	v_lshlrev_b32_e32 v42, 16, v49
	v_fmac_f32_e32 v215, v69, v69
	v_fma_f32 v68, -v25, v152, v41
	v_and_b32_e32 v43, 0xffff0000, v49
	v_fmac_f32_e32 v215, v68, v68
	v_fma_f32 v67, -v26, v152, v42
	v_lshlrev_b32_e32 v44, 16, v50
	v_fmac_f32_e32 v215, v67, v67
	v_fma_f32 v66, -v27, v152, v43
	v_and_b32_e32 v45, 0xffff0000, v50
	v_fmac_f32_e32 v215, v66, v66
	v_fma_f32 v65, -v28, v152, v44
	v_lshlrev_b32_e32 v46, 16, v51
	v_fmac_f32_e32 v215, v65, v65
	v_fma_f32 v64, -v29, v152, v45
	v_and_b32_e32 v47, 0xffff0000, v51
	v_fmac_f32_e32 v215, v64, v64
	v_fma_f32 v63, -v30, v152, v46
	v_fmac_f32_e32 v215, v63, v63
	v_fma_f32 v62, -v31, v152, v47
	s_waitcnt vmcnt(0)
	v_lshlrev_b32_e32 v16, 16, v52
	v_fmac_f32_e32 v215, v62, v62
	v_and_b32_e32 v17, 0xffff0000, v52
	v_fma_f32 v61, -v0, v152, v16
	v_lshlrev_b32_e32 v18, 16, v53
	v_lshlrev_b32_e32 v20, 16, v54
	v_and_b32_e32 v21, 0xffff0000, v54
	v_fmac_f32_e32 v215, v61, v61
	v_fma_f32 v60, -v1, v152, v17
	v_and_b32_e32 v1, 0xffff0000, v55
	v_lshlrev_b32_e32 v0, 16, v55
	v_and_b32_e32 v19, 0xffff0000, v53
	v_fmac_f32_e32 v215, v60, v60
	v_fma_f32 v59, -v2, v152, v18
	v_fma_f32 v57, -v4, v152, v20
	v_fma_f32 v56, -v5, v152, v21
	v_pk_fma_f32 v[0:1], v[6:7], v[152:153], v[0:1] op_sel_hi:[1,0,1] neg_lo:[1,0,0] neg_hi:[1,0,0]
	v_lshlrev_b64 v[4:5], 14, v[148:149]
	v_lshrrev_b32_e32 v6, 3, v153
	v_fmac_f32_e32 v215, v59, v59
	v_fma_f32 v58, -v3, v152, v19
	v_lshl_add_u64 v[4:5], s[2:3], 0, v[4:5]
	v_and_b32_e32 v90, 4, v6
	v_fmac_f32_e32 v215, v58, v58
	v_lshl_add_u64 v[4:5], v[4:5], 0, s[4:5]
	v_lshlrev_b32_e32 v178, 1, v90
	v_fmac_f32_e32 v215, v57, v57
	v_lshl_add_u64 v[4:5], v[4:5], 0, v[178:179]
	v_fmac_f32_e32 v215, v56, v56
	v_pk_mul_f32 v[2:3], v[0:1], v[0:1]
	v_add_co_u32_e32 v148, vcc, s63, v4
	v_add_f32_e32 v2, v2, v215
	s_waitcnt vmcnt(0)
	s_nop 0
	v_addc_co_u32_e32 v149, vcc, 0, v5, vcc
	global_load_dwordx2 v[150:151], v[148:149], off
	v_add_f32_e32 v6, v3, v2
	v_and_b32_e32 v3, 0xffff0000, v136
	v_lshlrev_b32_e32 v2, 16, v136
	v_pk_fma_f32 v[16:17], v[8:9], v[152:153], v[2:3] op_sel_hi:[1,0,1] neg_lo:[1,0,0] neg_hi:[1,0,0]
	s_nop 0
	v_pk_mul_f32 v[2:3], v[16:17], v[16:17]
	s_nop 0
	v_add_f32_e32 v2, v2, v6
	v_add_f32_e32 v6, v3, v2
	v_and_b32_e32 v3, 0xffff0000, v137
	v_lshlrev_b32_e32 v2, 16, v137
	v_pk_fma_f32 v[8:9], v[10:11], v[152:153], v[2:3] op_sel_hi:[1,0,1] neg_lo:[1,0,0] neg_hi:[1,0,0]
	v_and_b32_e32 v11, 0xffff0000, v139
	v_pk_mul_f32 v[2:3], v[8:9], v[8:9]
	s_nop 0
	v_add_f32_e32 v2, v2, v6
	v_add_f32_e32 v10, v3, v2
	v_and_b32_e32 v3, 0xffff0000, v138
	v_lshlrev_b32_e32 v2, 16, v138
	v_pk_fma_f32 v[6:7], v[12:13], v[152:153], v[2:3] op_sel_hi:[1,0,1] neg_lo:[1,0,0] neg_hi:[1,0,0]
	s_nop 0
	v_pk_mul_f32 v[2:3], v[6:7], v[6:7]
	s_nop 0
	v_add_f32_e32 v2, v2, v10
	v_add_f32_e32 v12, v3, v2
	v_lshl_add_u64 v[2:3], v[4:5], 0, s[6:7]
	global_load_dwordx2 v[154:155], v[2:3], off offset:16
	v_lshlrev_b32_e32 v10, 16, v139
	v_pk_fma_f32 v[4:5], v[14:15], v[152:153], v[10:11] op_sel_hi:[1,0,1] neg_lo:[1,0,0] neg_hi:[1,0,0]
	global_load_dwordx2 v[152:153], v[2:3], off offset:32
	global_load_dwordx2 v[188:189], v[2:3], off offset:48
	global_load_dwordx2 v[196:197], v[2:3], off offset:64
	global_load_dwordx2 v[198:199], v[2:3], off offset:80
	global_load_dwordx2 v[200:201], v[2:3], off offset:96
	global_load_dwordx2 v[202:203], v[2:3], off offset:112
	global_load_dwordx2 v[204:205], v[2:3], off offset:128
	global_load_dwordx2 v[206:207], v[2:3], off offset:144
	global_load_dwordx2 v[54:55], v[2:3], off offset:160
	global_load_dwordx2 v[52:53], v[2:3], off offset:176
	global_load_dwordx2 v[50:51], v[2:3], off offset:192
	global_load_dwordx2 v[48:49], v[2:3], off offset:208
	global_load_dwordx2 v[46:47], v[2:3], off offset:224
	global_load_dwordx2 v[44:45], v[2:3], off offset:240
	global_load_dwordx2 v[42:43], v[2:3], off offset:256
	global_load_dwordx2 v[40:41], v[2:3], off offset:272
	global_load_dwordx2 v[38:39], v[2:3], off offset:288
	global_load_dwordx2 v[36:37], v[2:3], off offset:304
	global_load_dwordx2 v[34:35], v[2:3], off offset:320
	global_load_dwordx2 v[32:33], v[2:3], off offset:336
	global_load_dwordx2 v[30:31], v[2:3], off offset:352
	global_load_dwordx2 v[28:29], v[2:3], off offset:368
	global_load_dwordx2 v[26:27], v[2:3], off offset:384
	global_load_dwordx2 v[24:25], v[2:3], off offset:400
	global_load_dwordx2 v[22:23], v[2:3], off offset:416
	global_load_dwordx2 v[20:21], v[2:3], off offset:432
	global_load_dwordx2 v[18:19], v[2:3], off offset:448
	v_pk_mul_f32 v[10:11], v[4:5], v[4:5]
	s_nop 0
	v_add_f32_e32 v10, v10, v12
	v_add_f32_e32 v10, v11, v10
	ds_bpermute_b32 v11, v194, v10
	s_waitcnt lgkmcnt(0)
	v_add_f32_e32 v10, v10, v11
	v_fmamk_f32 v10, v10, 0x3b800000, v191
	v_mul_f32_e32 v11, 0x4b800000, v10
	v_cmp_gt_f32_e32 vcc, s64, v10
	s_nop 1
	v_cndmask_b32_e32 v10, v10, v11, vcc
	v_rsq_f32_e32 v10, v10
	s_nop 0
	v_mul_f32_e32 v11, 0x45800000, v10
	v_cndmask_b32_e32 v178, v10, v11, vcc
	v_lshl_add_u32 v10, v90, 2, 0
	v_add_u32_e32 v98, 0x24000, v10
	ds_read_b128 v[136:139], v98
	v_mul_f32_e32 v90, 0x3ee34c56, v178
	v_mul_f32_e32 v178, v190, v90
	global_load_dwordx2 v[14:15], v[2:3], off offset:464
	global_load_dwordx2 v[12:13], v[2:3], off offset:480
	global_load_dwordx2 v[10:11], v[2:3], off offset:496
	v_mul_f32_e32 v143, v143, v90
	s_waitcnt lgkmcnt(0)
	v_mul_f32_e32 v136, v136, v178
	v_mul_f32_e32 v142, v142, v90
	v_mul_f32_e32 v135, v135, v90
	v_mul_f32_e32 v134, v134, v90
	v_mul_f32_e32 v133, v133, v90
	v_mul_f32_e32 v132, v132, v90
	v_mul_f32_e32 v0, v0, v90
	v_mul_f32_e32 v1, v1, v90
	s_waitcnt vmcnt(31)
	v_lshlrev_b32_e32 v178, 16, v150
	v_mul_f32_e32 v136, v136, v178
	v_mul_f32_e32 v178, v195, v90
	v_mul_f32_e32 v137, v137, v178
	v_and_b32_e32 v150, 0xffff0000, v150
	v_mul_f32_e32 v137, v137, v150
	v_cvt_pk_bf16_f32 v150, v136, v137
	v_mul_f32_e32 v136, v212, v90
	v_mul_f32_e32 v136, v138, v136
	v_lshlrev_b32_e32 v137, 16, v151
	v_mul_f32_e32 v136, v136, v137
	v_mul_f32_e32 v137, v213, v90
	v_mul_f32_e32 v137, v139, v137
	v_and_b32_e32 v138, 0xffff0000, v151
	v_mul_f32_e32 v137, v137, v138
	v_cvt_pk_bf16_f32 v151, v136, v137
	ds_read_b128 v[136:139], v98 offset:32
	global_store_dwordx2 v[148:149], v[150:151], off
	v_mul_f32_e32 v148, v214, v90
	s_waitcnt lgkmcnt(0)
	v_mul_f32_e32 v136, v136, v148
	s_waitcnt vmcnt(31)
	v_lshlrev_b32_e32 v148, 16, v154
	v_mul_f32_e32 v136, v136, v148
	v_mul_f32_e32 v148, v186, v90
	v_mul_f32_e32 v137, v137, v148
	v_and_b32_e32 v148, 0xffff0000, v154
	v_mul_f32_e32 v137, v137, v148
	v_cvt_pk_bf16_f32 v148, v136, v137
	v_mul_f32_e32 v136, v185, v90
	v_mul_f32_e32 v136, v138, v136
	v_lshlrev_b32_e32 v137, 16, v155
	v_mul_f32_e32 v136, v136, v137
	v_mul_f32_e32 v137, v184, v90
	v_mul_f32_e32 v137, v139, v137
	v_and_b32_e32 v138, 0xffff0000, v155
	v_mul_f32_e32 v137, v137, v138
	v_cvt_pk_bf16_f32 v149, v136, v137
	ds_read_b128 v[136:139], v98 offset:64
	global_store_dwordx2 v[2:3], v[148:149], off offset:16
	v_mul_f32_e32 v148, v183, v90
	s_waitcnt lgkmcnt(0)
	v_mul_f32_e32 v136, v136, v148
	s_waitcnt vmcnt(31)
	v_lshlrev_b32_e32 v148, 16, v152
	v_mul_f32_e32 v136, v136, v148
	v_mul_f32_e32 v148, v182, v90
	v_mul_f32_e32 v137, v137, v148
	v_and_b32_e32 v148, 0xffff0000, v152
	v_mul_f32_e32 v137, v137, v148
	v_cvt_pk_bf16_f32 v148, v136, v137
	v_mul_f32_e32 v136, v181, v90
	v_mul_f32_e32 v136, v138, v136
	v_lshlrev_b32_e32 v137, 16, v153
	v_mul_f32_e32 v136, v136, v137
	v_mul_f32_e32 v137, v180, v90
	v_mul_f32_e32 v137, v139, v137
	v_and_b32_e32 v138, 0xffff0000, v153
	v_mul_f32_e32 v137, v137, v138
	v_cvt_pk_bf16_f32 v149, v136, v137
	ds_read_b128 v[136:139], v98 offset:96
	global_store_dwordx2 v[2:3], v[148:149], off offset:32
	v_mul_f32_e32 v148, v175, v90
	s_waitcnt lgkmcnt(0)
	v_mul_f32_e32 v136, v136, v148
	s_waitcnt vmcnt(31)
	v_lshlrev_b32_e32 v148, 16, v188
	v_mul_f32_e32 v136, v136, v148
	v_mul_f32_e32 v148, v174, v90
	v_mul_f32_e32 v137, v137, v148
	v_and_b32_e32 v148, 0xffff0000, v188
	v_mul_f32_e32 v137, v137, v148
	v_cvt_pk_bf16_f32 v148, v136, v137
	v_mul_f32_e32 v136, v173, v90
	v_mul_f32_e32 v136, v138, v136
	v_lshlrev_b32_e32 v137, 16, v189
	v_mul_f32_e32 v136, v136, v137
	v_mul_f32_e32 v137, v172, v90
	v_mul_f32_e32 v137, v139, v137
	v_and_b32_e32 v138, 0xffff0000, v189
	v_mul_f32_e32 v137, v137, v138
	v_cvt_pk_bf16_f32 v149, v136, v137
	ds_read_b128 v[136:139], v98 offset:128
	global_store_dwordx2 v[2:3], v[148:149], off offset:48
	v_mul_f32_e32 v148, v171, v90
	s_waitcnt lgkmcnt(0)
	v_mul_f32_e32 v136, v136, v148
	s_waitcnt vmcnt(31)
	v_lshlrev_b32_e32 v148, 16, v196
	v_mul_f32_e32 v136, v136, v148
	v_mul_f32_e32 v148, v170, v90
	v_mul_f32_e32 v137, v137, v148
	v_and_b32_e32 v148, 0xffff0000, v196
	v_mul_f32_e32 v137, v137, v148
	v_cvt_pk_bf16_f32 v148, v136, v137
	v_mul_f32_e32 v136, v167, v90
	v_mul_f32_e32 v136, v138, v136
	v_lshlrev_b32_e32 v137, 16, v197
	v_mul_f32_e32 v136, v136, v137
	v_mul_f32_e32 v137, v166, v90
	v_mul_f32_e32 v137, v139, v137
	v_and_b32_e32 v138, 0xffff0000, v197
	v_mul_f32_e32 v137, v137, v138
	v_cvt_pk_bf16_f32 v149, v136, v137
	ds_read_b128 v[136:139], v98 offset:160
	global_store_dwordx2 v[2:3], v[148:149], off offset:64
	v_mul_f32_e32 v148, v162, v90
	s_waitcnt lgkmcnt(0)
	v_mul_f32_e32 v136, v136, v148
	s_waitcnt vmcnt(31)
	v_lshlrev_b32_e32 v148, 16, v198
	v_mul_f32_e32 v136, v136, v148
	v_mul_f32_e32 v148, v160, v90
	v_mul_f32_e32 v137, v137, v148
	v_and_b32_e32 v148, 0xffff0000, v198
	v_mul_f32_e32 v137, v137, v148
	v_cvt_pk_bf16_f32 v148, v136, v137
	v_mul_f32_e32 v136, v169, v90
	v_mul_f32_e32 v136, v138, v136
	v_lshlrev_b32_e32 v137, 16, v199
	v_mul_f32_e32 v136, v136, v137
	v_mul_f32_e32 v137, v168, v90
	v_mul_f32_e32 v137, v139, v137
	v_and_b32_e32 v138, 0xffff0000, v199
	v_mul_f32_e32 v137, v137, v138
	v_cvt_pk_bf16_f32 v149, v136, v137
	ds_read_b128 v[136:139], v98 offset:192
	global_store_dwordx2 v[2:3], v[148:149], off offset:80
	v_mul_f32_e32 v148, v165, v90
	s_waitcnt lgkmcnt(0)
	v_mul_f32_e32 v136, v136, v148
	s_waitcnt vmcnt(31)
	v_lshlrev_b32_e32 v148, 16, v200
	v_mul_f32_e32 v136, v136, v148
	v_mul_f32_e32 v148, v164, v90
	v_mul_f32_e32 v137, v137, v148
	v_and_b32_e32 v148, 0xffff0000, v200
	v_mul_f32_e32 v137, v137, v148
	v_cvt_pk_bf16_f32 v148, v136, v137
	v_mul_f32_e32 v136, v163, v90
	v_mul_f32_e32 v136, v138, v136
	v_lshlrev_b32_e32 v137, 16, v201
	v_mul_f32_e32 v136, v136, v137
	v_mul_f32_e32 v137, v161, v90
	v_mul_f32_e32 v137, v139, v137
	v_and_b32_e32 v138, 0xffff0000, v201
	v_mul_f32_e32 v137, v137, v138
	v_cvt_pk_bf16_f32 v149, v136, v137
	ds_read_b128 v[136:139], v98 offset:224
	global_store_dwordx2 v[2:3], v[148:149], off offset:96
	v_mul_f32_e32 v148, v158, v90
	s_waitcnt lgkmcnt(0)
	v_mul_f32_e32 v136, v136, v148
	s_waitcnt vmcnt(31)
	v_lshlrev_b32_e32 v148, 16, v202
	v_mul_f32_e32 v136, v136, v148
	v_mul_f32_e32 v148, v156, v90
	v_mul_f32_e32 v137, v137, v148
	v_and_b32_e32 v148, 0xffff0000, v202
	v_mul_f32_e32 v137, v137, v148
	v_cvt_pk_bf16_f32 v148, v136, v137
	v_mul_f32_e32 v136, v145, v90
	v_mul_f32_e32 v136, v138, v136
	v_lshlrev_b32_e32 v137, 16, v203
	v_mul_f32_e32 v136, v136, v137
	v_mul_f32_e32 v137, v144, v90
	v_mul_f32_e32 v137, v139, v137
	v_and_b32_e32 v138, 0xffff0000, v203
	v_mul_f32_e32 v137, v137, v138
	v_cvt_pk_bf16_f32 v149, v136, v137
	ds_read_b128 v[136:139], v98 offset:256
	v_mul_f32_e32 v144, v159, v90
	global_store_dwordx2 v[2:3], v[148:149], off offset:112
	s_waitcnt lgkmcnt(0)
	v_mul_f32_e32 v136, v136, v144
	s_waitcnt vmcnt(31)
	v_lshlrev_b32_e32 v144, 16, v204
	v_mul_f32_e32 v136, v136, v144
	v_mul_f32_e32 v144, v157, v90
	v_mul_f32_e32 v137, v137, v144
	v_and_b32_e32 v144, 0xffff0000, v204
	v_mul_f32_e32 v137, v137, v144
	v_cvt_pk_bf16_f32 v144, v136, v137
	v_mul_f32_e32 v136, v147, v90
	v_mul_f32_e32 v136, v138, v136
	v_lshlrev_b32_e32 v137, 16, v205
	v_mul_f32_e32 v136, v136, v137
	v_mul_f32_e32 v137, v146, v90
	v_mul_f32_e32 v137, v139, v137
	v_and_b32_e32 v138, 0xffff0000, v205
	v_mul_f32_e32 v137, v137, v138
	v_cvt_pk_bf16_f32 v145, v136, v137
	ds_read_b128 v[136:139], v98 offset:288
	global_store_dwordx2 v[2:3], v[144:145], off offset:128
	s_waitcnt lgkmcnt(0)
	v_mul_f32_e32 v136, v136, v143
	s_waitcnt vmcnt(31)
	v_lshlrev_b32_e32 v143, 16, v206
	v_mul_f32_e32 v136, v136, v143
	v_mul_f32_e32 v137, v137, v142
	v_and_b32_e32 v142, 0xffff0000, v206
	v_mul_f32_e32 v137, v137, v142
	v_cvt_pk_bf16_f32 v142, v136, v137
	v_mul_f32_e32 v136, v141, v90
	v_mul_f32_e32 v136, v138, v136
	v_lshlrev_b32_e32 v137, 16, v207
	v_mul_f32_e32 v136, v136, v137
	v_mul_f32_e32 v137, v140, v90
	v_mul_f32_e32 v137, v139, v137
	v_and_b32_e32 v138, 0xffff0000, v207
	v_mul_f32_e32 v137, v137, v138
	v_cvt_pk_bf16_f32 v143, v136, v137
	ds_read_b128 v[136:139], v98 offset:320
	global_store_dwordx2 v[2:3], v[142:143], off offset:144
	s_waitcnt lgkmcnt(0)
	v_mul_f32_e32 v135, v136, v135
	s_waitcnt vmcnt(31)
	v_lshlrev_b32_e32 v136, 16, v54
	v_mul_f32_e32 v134, v137, v134
	v_and_b32_e32 v54, 0xffff0000, v54
	v_mul_f32_e32 v54, v134, v54
	v_mul_f32_e32 v133, v138, v133
	v_lshlrev_b32_e32 v134, 16, v55
	v_mul_f32_e32 v132, v139, v132
	v_and_b32_e32 v55, 0xffff0000, v55
	v_mul_f32_e32 v135, v135, v136
	v_mul_f32_e32 v133, v133, v134
	v_mul_f32_e32 v55, v132, v55
	v_cvt_pk_bf16_f32 v54, v135, v54
	v_cvt_pk_bf16_f32 v55, v133, v55
	ds_read_b128 v[132:135], v98 offset:352
	global_store_dwordx2 v[2:3], v[54:55], off offset:160
	v_mul_f32_e32 v54, v129, v90
	s_waitcnt vmcnt(31)
	v_lshlrev_b32_e32 v55, 16, v52
	v_and_b32_e32 v52, 0xffff0000, v52
	s_waitcnt lgkmcnt(0)
	v_mul_f32_e32 v54, v132, v54
	v_mul_f32_e32 v54, v54, v55
	v_mul_f32_e32 v55, v127, v90
	v_mul_f32_e32 v55, v133, v55
	v_mul_f32_e32 v52, v55, v52
	v_cvt_pk_bf16_f32 v132, v54, v52
	v_mul_f32_e32 v52, v125, v90
	v_mul_f32_e32 v52, v134, v52
	v_lshlrev_b32_e32 v54, 16, v53
	v_mul_f32_e32 v52, v52, v54
	v_mul_f32_e32 v54, v124, v90
	v_mul_f32_e32 v54, v135, v54
	v_and_b32_e32 v53, 0xffff0000, v53
	v_mul_f32_e32 v53, v54, v53
	v_cvt_pk_bf16_f32 v133, v52, v53
	ds_read_b128 v[52:55], v98 offset:384
	v_mul_f32_e32 v124, v131, v90
	global_store_dwordx2 v[2:3], v[132:133], off offset:176
	s_waitcnt lgkmcnt(0)
	v_mul_f32_e32 v52, v52, v124
	s_waitcnt vmcnt(31)
	v_lshlrev_b32_e32 v124, 16, v50
	v_mul_f32_e32 v52, v52, v124
	v_mul_f32_e32 v124, v130, v90
	v_mul_f32_e32 v53, v53, v124
	v_and_b32_e32 v50, 0xffff0000, v50
	v_mul_f32_e32 v50, v53, v50
	v_cvt_pk_bf16_f32 v124, v52, v50
	v_mul_f32_e32 v50, v128, v90
	v_mul_f32_e32 v50, v54, v50
	v_lshlrev_b32_e32 v52, 16, v51
	v_mul_f32_e32 v50, v50, v52
	v_mul_f32_e32 v52, v126, v90
	v_mul_f32_e32 v52, v55, v52
	v_and_b32_e32 v51, 0xffff0000, v51
	v_mul_f32_e32 v51, v52, v51
	v_cvt_pk_bf16_f32 v125, v50, v51
	ds_read_b128 v[50:53], v98 offset:416
	v_mul_f32_e32 v54, v123, v90
	global_store_dwordx2 v[2:3], v[124:125], off offset:192
	s_waitcnt lgkmcnt(0)
	v_mul_f32_e32 v50, v50, v54
	s_waitcnt vmcnt(31)
	v_lshlrev_b32_e32 v54, 16, v48
	v_mul_f32_e32 v50, v50, v54
	v_mul_f32_e32 v54, v122, v90
	v_mul_f32_e32 v51, v51, v54
	v_and_b32_e32 v48, 0xffff0000, v48
	v_mul_f32_e32 v48, v51, v48
	v_cvt_pk_bf16_f32 v54, v50, v48
	v_mul_f32_e32 v48, v121, v90
	v_mul_f32_e32 v48, v52, v48
	v_lshlrev_b32_e32 v50, 16, v49
	v_mul_f32_e32 v48, v48, v50
	v_mul_f32_e32 v50, v120, v90
	v_mul_f32_e32 v50, v53, v50
	v_and_b32_e32 v49, 0xffff0000, v49
	v_mul_f32_e32 v49, v50, v49
	v_cvt_pk_bf16_f32 v55, v48, v49
	ds_read_b128 v[48:51], v98 offset:448
	v_mul_f32_e32 v52, v119, v90
	global_store_dwordx2 v[2:3], v[54:55], off offset:208
	s_waitcnt lgkmcnt(0)
	v_mul_f32_e32 v48, v48, v52
	s_waitcnt vmcnt(31)
	v_lshlrev_b32_e32 v52, 16, v46
	v_mul_f32_e32 v48, v48, v52
	v_mul_f32_e32 v52, v118, v90
	v_mul_f32_e32 v49, v49, v52
	v_and_b32_e32 v46, 0xffff0000, v46
	v_mul_f32_e32 v46, v49, v46
	v_cvt_pk_bf16_f32 v52, v48, v46
	v_mul_f32_e32 v46, v117, v90
	v_mul_f32_e32 v46, v50, v46
	v_lshlrev_b32_e32 v48, 16, v47
	v_mul_f32_e32 v46, v46, v48
	v_mul_f32_e32 v48, v116, v90
	v_mul_f32_e32 v48, v51, v48
	v_and_b32_e32 v47, 0xffff0000, v47
	v_mul_f32_e32 v47, v48, v47
	v_cvt_pk_bf16_f32 v53, v46, v47
	ds_read_b128 v[46:49], v98 offset:480
	v_mul_f32_e32 v50, v114, v90
	global_store_dwordx2 v[2:3], v[52:53], off offset:224
	s_waitcnt lgkmcnt(0)
	v_mul_f32_e32 v46, v46, v50
	s_waitcnt vmcnt(31)
	v_lshlrev_b32_e32 v50, 16, v44
	v_mul_f32_e32 v46, v46, v50
	v_mul_f32_e32 v50, v112, v90
	v_mul_f32_e32 v47, v47, v50
	v_and_b32_e32 v44, 0xffff0000, v44
	v_mul_f32_e32 v44, v47, v44
	v_cvt_pk_bf16_f32 v50, v46, v44
	v_mul_f32_e32 v44, v110, v90
	v_mul_f32_e32 v44, v48, v44
	v_lshlrev_b32_e32 v46, 16, v45
	v_mul_f32_e32 v44, v44, v46
	v_mul_f32_e32 v46, v108, v90
	v_mul_f32_e32 v46, v49, v46
	v_and_b32_e32 v45, 0xffff0000, v45
	v_mul_f32_e32 v45, v46, v45
	v_cvt_pk_bf16_f32 v51, v44, v45
	ds_read_b128 v[44:47], v98 offset:512
	v_mul_f32_e32 v48, v115, v90
	global_store_dwordx2 v[2:3], v[50:51], off offset:240
	s_waitcnt lgkmcnt(0)
	v_mul_f32_e32 v44, v44, v48
	s_waitcnt vmcnt(31)
	v_lshlrev_b32_e32 v48, 16, v42
	v_mul_f32_e32 v44, v44, v48
	v_mul_f32_e32 v48, v113, v90
	v_mul_f32_e32 v45, v45, v48
	v_and_b32_e32 v42, 0xffff0000, v42
	v_mul_f32_e32 v42, v45, v42
	v_cvt_pk_bf16_f32 v48, v44, v42
	v_mul_f32_e32 v42, v111, v90
	v_mul_f32_e32 v42, v46, v42
	v_lshlrev_b32_e32 v44, 16, v43
	v_mul_f32_e32 v42, v42, v44
	v_mul_f32_e32 v44, v109, v90
	v_mul_f32_e32 v44, v47, v44
	v_and_b32_e32 v43, 0xffff0000, v43
	v_mul_f32_e32 v43, v44, v43
	v_cvt_pk_bf16_f32 v49, v42, v43
	ds_read_b128 v[42:45], v98 offset:544
	v_mul_f32_e32 v46, v107, v90
	global_store_dwordx2 v[2:3], v[48:49], off offset:256
	s_waitcnt lgkmcnt(0)
	v_mul_f32_e32 v42, v42, v46
	s_waitcnt vmcnt(31)
	v_lshlrev_b32_e32 v46, 16, v40
	v_mul_f32_e32 v42, v42, v46
	v_mul_f32_e32 v46, v106, v90
	v_mul_f32_e32 v43, v43, v46
	v_and_b32_e32 v40, 0xffff0000, v40
	v_mul_f32_e32 v40, v43, v40
	v_cvt_pk_bf16_f32 v46, v42, v40
	v_mul_f32_e32 v40, v105, v90
	v_mul_f32_e32 v40, v44, v40
	v_lshlrev_b32_e32 v42, 16, v41
	v_mul_f32_e32 v40, v40, v42
	v_mul_f32_e32 v42, v104, v90
	v_mul_f32_e32 v42, v45, v42
	v_and_b32_e32 v41, 0xffff0000, v41
	v_mul_f32_e32 v41, v42, v41
	v_cvt_pk_bf16_f32 v47, v40, v41
	ds_read_b128 v[40:43], v98 offset:576
	v_mul_f32_e32 v44, v103, v90
	global_store_dwordx2 v[2:3], v[46:47], off offset:272
	s_waitcnt lgkmcnt(0)
	v_mul_f32_e32 v40, v40, v44
	s_waitcnt vmcnt(31)
	v_lshlrev_b32_e32 v44, 16, v38
	v_mul_f32_e32 v40, v40, v44
	v_mul_f32_e32 v44, v102, v90
	v_mul_f32_e32 v41, v41, v44
	v_and_b32_e32 v38, 0xffff0000, v38
	v_mul_f32_e32 v38, v41, v38
	v_cvt_pk_bf16_f32 v44, v40, v38
	v_mul_f32_e32 v38, v101, v90
	v_mul_f32_e32 v38, v42, v38
	v_lshlrev_b32_e32 v40, 16, v39
	v_mul_f32_e32 v38, v38, v40
	v_mul_f32_e32 v40, v100, v90
	v_mul_f32_e32 v40, v43, v40
	v_and_b32_e32 v39, 0xffff0000, v39
	v_mul_f32_e32 v39, v40, v39
	v_cvt_pk_bf16_f32 v45, v38, v39
	ds_read_b128 v[38:41], v98 offset:608
	v_mul_f32_e32 v42, v96, v90
	global_store_dwordx2 v[2:3], v[44:45], off offset:288
	s_waitcnt lgkmcnt(0)
	v_mul_f32_e32 v38, v38, v42
	s_waitcnt vmcnt(31)
	v_lshlrev_b32_e32 v42, 16, v36
	v_mul_f32_e32 v38, v38, v42
	v_mul_f32_e32 v42, v95, v90
	v_mul_f32_e32 v39, v39, v42
	v_and_b32_e32 v36, 0xffff0000, v36
	v_mul_f32_e32 v36, v39, v36
	v_cvt_pk_bf16_f32 v42, v38, v36
	v_mul_f32_e32 v36, v92, v90
	v_mul_f32_e32 v36, v40, v36
	v_lshlrev_b32_e32 v38, 16, v37
	v_mul_f32_e32 v36, v36, v38
	v_mul_f32_e32 v38, v91, v90
	v_mul_f32_e32 v38, v41, v38
	v_and_b32_e32 v37, 0xffff0000, v37
	v_mul_f32_e32 v37, v38, v37
	v_cvt_pk_bf16_f32 v43, v36, v37
	ds_read_b128 v[36:39], v98 offset:640
	v_mul_f32_e32 v40, v99, v90
	global_store_dwordx2 v[2:3], v[42:43], off offset:304
	s_waitcnt lgkmcnt(0)
	v_mul_f32_e32 v36, v36, v40
	s_waitcnt vmcnt(31)
	v_lshlrev_b32_e32 v40, 16, v34
	v_mul_f32_e32 v36, v36, v40
	v_mul_f32_e32 v40, v97, v90
	v_mul_f32_e32 v37, v37, v40
	v_and_b32_e32 v34, 0xffff0000, v34
	v_mul_f32_e32 v34, v37, v34
	v_cvt_pk_bf16_f32 v40, v36, v34
	v_mul_f32_e32 v34, v94, v90
	v_mul_f32_e32 v34, v38, v34
	v_lshlrev_b32_e32 v36, 16, v35
	v_mul_f32_e32 v34, v34, v36
	v_mul_f32_e32 v36, v93, v90
	v_mul_f32_e32 v36, v39, v36
	v_and_b32_e32 v35, 0xffff0000, v35
	v_mul_f32_e32 v35, v36, v35
	v_cvt_pk_bf16_f32 v41, v34, v35
	ds_read_b128 v[34:37], v98 offset:672
	v_mul_f32_e32 v38, v89, v90
	global_store_dwordx2 v[2:3], v[40:41], off offset:320
	s_waitcnt lgkmcnt(0)
	v_mul_f32_e32 v34, v34, v38
	s_waitcnt vmcnt(31)
	v_lshlrev_b32_e32 v38, 16, v32
	v_mul_f32_e32 v34, v34, v38
	v_mul_f32_e32 v38, v88, v90
	v_mul_f32_e32 v35, v35, v38
	v_and_b32_e32 v32, 0xffff0000, v32
	v_mul_f32_e32 v32, v35, v32
	v_cvt_pk_bf16_f32 v38, v34, v32
	v_mul_f32_e32 v32, v87, v90
	v_mul_f32_e32 v32, v36, v32
	v_lshlrev_b32_e32 v34, 16, v33
	v_mul_f32_e32 v32, v32, v34
	v_mul_f32_e32 v34, v86, v90
	v_mul_f32_e32 v34, v37, v34
	v_and_b32_e32 v33, 0xffff0000, v33
	v_mul_f32_e32 v33, v34, v33
	v_cvt_pk_bf16_f32 v39, v32, v33
	ds_read_b128 v[32:35], v98 offset:704
	v_mul_f32_e32 v36, v85, v90
	global_store_dwordx2 v[2:3], v[38:39], off offset:336
	s_waitcnt lgkmcnt(0)
	v_mul_f32_e32 v32, v32, v36
	s_waitcnt vmcnt(31)
	v_lshlrev_b32_e32 v36, 16, v30
	v_mul_f32_e32 v32, v32, v36
	v_mul_f32_e32 v36, v84, v90
	v_mul_f32_e32 v33, v33, v36
	v_and_b32_e32 v30, 0xffff0000, v30
	v_mul_f32_e32 v30, v33, v30
	v_cvt_pk_bf16_f32 v36, v32, v30
	v_mul_f32_e32 v30, v83, v90
	v_mul_f32_e32 v30, v34, v30
	v_lshlrev_b32_e32 v32, 16, v31
	v_mul_f32_e32 v30, v30, v32
	v_mul_f32_e32 v32, v82, v90
	v_mul_f32_e32 v32, v35, v32
	v_and_b32_e32 v31, 0xffff0000, v31
	v_mul_f32_e32 v31, v32, v31
	v_cvt_pk_bf16_f32 v37, v30, v31
	ds_read_b128 v[30:33], v98 offset:736
	v_mul_f32_e32 v34, v80, v90
	global_store_dwordx2 v[2:3], v[36:37], off offset:352
	s_waitcnt lgkmcnt(0)
	v_mul_f32_e32 v30, v30, v34
	s_waitcnt vmcnt(31)
	v_lshlrev_b32_e32 v34, 16, v28
	v_mul_f32_e32 v30, v30, v34
	v_mul_f32_e32 v34, v78, v90
	v_mul_f32_e32 v31, v31, v34
	v_and_b32_e32 v28, 0xffff0000, v28
	v_mul_f32_e32 v28, v31, v28
	v_cvt_pk_bf16_f32 v34, v30, v28
	v_mul_f32_e32 v28, v76, v90
	v_mul_f32_e32 v28, v32, v28
	v_lshlrev_b32_e32 v30, 16, v29
	v_mul_f32_e32 v28, v28, v30
	v_mul_f32_e32 v30, v74, v90
	v_mul_f32_e32 v30, v33, v30
	v_and_b32_e32 v29, 0xffff0000, v29
	v_mul_f32_e32 v29, v30, v29
	v_cvt_pk_bf16_f32 v35, v28, v29
	ds_read_b128 v[28:31], v98 offset:768
	v_mul_f32_e32 v32, v81, v90
	global_store_dwordx2 v[2:3], v[34:35], off offset:368
	s_waitcnt lgkmcnt(0)
	v_mul_f32_e32 v28, v32, v28
	s_waitcnt vmcnt(31)
	v_lshlrev_b32_e32 v32, 16, v26
	v_mul_f32_e32 v28, v28, v32
	v_mul_f32_e32 v32, v79, v90
	v_mul_f32_e32 v29, v32, v29
	v_and_b32_e32 v26, 0xffff0000, v26
	v_mul_f32_e32 v26, v29, v26
	v_cvt_pk_bf16_f32 v32, v28, v26
	v_mul_f32_e32 v26, v77, v90
	v_mul_f32_e32 v26, v26, v30
	v_lshlrev_b32_e32 v28, 16, v27
	v_mul_f32_e32 v26, v26, v28
	v_mul_f32_e32 v28, v75, v90
	v_mul_f32_e32 v28, v28, v31
	v_and_b32_e32 v27, 0xffff0000, v27
	v_mul_f32_e32 v27, v28, v27
	v_cvt_pk_bf16_f32 v33, v26, v27
	ds_read_b128 v[26:29], v98 offset:800
	v_mul_f32_e32 v30, v73, v90
	global_store_dwordx2 v[2:3], v[32:33], off offset:384
	s_waitcnt lgkmcnt(0)
	v_mul_f32_e32 v26, v30, v26
	s_waitcnt vmcnt(31)
	v_lshlrev_b32_e32 v30, 16, v24
	v_mul_f32_e32 v26, v26, v30
	v_mul_f32_e32 v30, v72, v90
	v_mul_f32_e32 v27, v30, v27
	v_and_b32_e32 v24, 0xffff0000, v24
	v_mul_f32_e32 v24, v27, v24
	v_cvt_pk_bf16_f32 v30, v26, v24
	v_mul_f32_e32 v24, v71, v90
	v_mul_f32_e32 v24, v24, v28
	v_lshlrev_b32_e32 v26, 16, v25
	v_mul_f32_e32 v24, v24, v26
	v_mul_f32_e32 v26, v70, v90
	v_mul_f32_e32 v26, v26, v29
	v_and_b32_e32 v25, 0xffff0000, v25
	v_mul_f32_e32 v25, v26, v25
	v_cvt_pk_bf16_f32 v31, v24, v25
	ds_read_b128 v[24:27], v98 offset:832
	v_mul_f32_e32 v28, v69, v90
	global_store_dwordx2 v[2:3], v[30:31], off offset:400
	s_waitcnt lgkmcnt(0)
	v_mul_f32_e32 v24, v28, v24
	s_waitcnt vmcnt(31)
	v_lshlrev_b32_e32 v28, 16, v22
	v_mul_f32_e32 v24, v24, v28
	v_mul_f32_e32 v28, v68, v90
	v_mul_f32_e32 v25, v28, v25
	v_and_b32_e32 v22, 0xffff0000, v22
	v_mul_f32_e32 v22, v25, v22
	v_cvt_pk_bf16_f32 v28, v24, v22
	v_mul_f32_e32 v22, v67, v90
	v_mul_f32_e32 v22, v22, v26
	v_lshlrev_b32_e32 v24, 16, v23
	v_mul_f32_e32 v22, v22, v24
	v_mul_f32_e32 v24, v66, v90
	v_mul_f32_e32 v24, v24, v27
	v_and_b32_e32 v23, 0xffff0000, v23
	v_mul_f32_e32 v23, v24, v23
	v_cvt_pk_bf16_f32 v29, v22, v23
	ds_read_b128 v[22:25], v98 offset:864
	v_mul_f32_e32 v26, v65, v90
	global_store_dwordx2 v[2:3], v[28:29], off offset:416
	s_waitcnt lgkmcnt(0)
	v_mul_f32_e32 v22, v26, v22
	s_waitcnt vmcnt(31)
	v_lshlrev_b32_e32 v26, 16, v20
	v_mul_f32_e32 v22, v22, v26
	v_mul_f32_e32 v26, v64, v90
	v_mul_f32_e32 v23, v26, v23
	v_and_b32_e32 v20, 0xffff0000, v20
	v_mul_f32_e32 v20, v23, v20
	v_cvt_pk_bf16_f32 v26, v22, v20
	v_mul_f32_e32 v20, v63, v90
	v_mul_f32_e32 v20, v20, v24
	v_lshlrev_b32_e32 v22, 16, v21
	v_mul_f32_e32 v20, v20, v22
	v_mul_f32_e32 v22, v62, v90
	v_mul_f32_e32 v22, v22, v25
	v_and_b32_e32 v21, 0xffff0000, v21
	v_mul_f32_e32 v21, v22, v21
	v_cvt_pk_bf16_f32 v27, v20, v21
	ds_read_b128 v[20:23], v98 offset:896
	v_mul_f32_e32 v24, v61, v90
	global_store_dwordx2 v[2:3], v[26:27], off offset:432
	s_waitcnt lgkmcnt(0)
	v_mul_f32_e32 v20, v24, v20
	s_waitcnt vmcnt(31)
	v_lshlrev_b32_e32 v24, 16, v18
	v_mul_f32_e32 v20, v20, v24
	v_mul_f32_e32 v24, v60, v90
	v_mul_f32_e32 v21, v24, v21
	v_and_b32_e32 v18, 0xffff0000, v18
	v_mul_f32_e32 v18, v21, v18
	v_cvt_pk_bf16_f32 v24, v20, v18
	v_mul_f32_e32 v18, v59, v90
	v_mul_f32_e32 v18, v18, v22
	v_lshlrev_b32_e32 v20, 16, v19
	v_mul_f32_e32 v18, v18, v20
	v_mul_f32_e32 v20, v58, v90
	v_mul_f32_e32 v20, v20, v23
	v_and_b32_e32 v19, 0xffff0000, v19
	v_mul_f32_e32 v19, v20, v19
	v_cvt_pk_bf16_f32 v25, v18, v19
	ds_read_b128 v[18:21], v98 offset:928
	v_mul_f32_e32 v22, v57, v90
	global_store_dwordx2 v[2:3], v[24:25], off offset:448
	s_waitcnt lgkmcnt(0)
	v_mul_f32_e32 v18, v22, v18
	s_waitcnt vmcnt(31)
	v_lshlrev_b32_e32 v22, 16, v14
	v_mul_f32_e32 v18, v18, v22
	v_mul_f32_e32 v22, v56, v90
	v_mul_f32_e32 v19, v22, v19
	v_and_b32_e32 v14, 0xffff0000, v14
	v_mul_f32_e32 v14, v19, v14
	v_cvt_pk_bf16_f32 v14, v18, v14
	v_mul_f32_e32 v0, v0, v20
	v_lshlrev_b32_e32 v18, 16, v15
	v_mul_f32_e32 v1, v1, v21
	v_and_b32_e32 v15, 0xffff0000, v15
	v_mul_f32_e32 v0, v0, v18
	v_mul_f32_e32 v1, v1, v15
	v_cvt_pk_bf16_f32 v15, v0, v1
	ds_read_b128 v[18:21], v98 offset:960
	v_mul_f32_e32 v0, v16, v90
	s_waitcnt vmcnt(30)
	v_lshlrev_b32_e32 v1, 16, v12
	v_and_b32_e32 v12, 0xffff0000, v12
	global_store_dwordx2 v[2:3], v[14:15], off offset:464
	s_waitcnt lgkmcnt(0)
	v_mul_f32_e32 v0, v0, v18
	v_mul_f32_e32 v0, v0, v1
	v_mul_f32_e32 v1, v17, v90
	v_mul_f32_e32 v1, v1, v19
	v_mul_f32_e32 v1, v1, v12
	v_cvt_pk_bf16_f32 v0, v0, v1
	v_mul_f32_e32 v1, v8, v90
	v_mul_f32_e32 v1, v1, v20
	v_lshlrev_b32_e32 v8, 16, v13
	v_mul_f32_e32 v1, v1, v8
	v_mul_f32_e32 v8, v9, v90
	v_mul_f32_e32 v8, v8, v21
	v_and_b32_e32 v9, 0xffff0000, v13
	v_mul_f32_e32 v8, v8, v9
	v_cvt_pk_bf16_f32 v1, v1, v8
	ds_read_b128 v[12:15], v98 offset:992
	global_store_dwordx2 v[2:3], v[0:1], off offset:480
	v_mul_f32_e32 v0, v6, v90
	s_waitcnt vmcnt(31)
	v_lshlrev_b32_e32 v1, 16, v10
	v_and_b32_e32 v6, 0xffff0000, v10
	s_waitcnt lgkmcnt(0)
	v_mul_f32_e32 v0, v0, v12
	v_mul_f32_e32 v0, v0, v1
	v_mul_f32_e32 v1, v7, v90
	v_mul_f32_e32 v1, v1, v13
	v_mul_f32_e32 v1, v1, v6
	v_cvt_pk_bf16_f32 v0, v0, v1
	v_mul_f32_e32 v1, v4, v90
	v_mul_f32_e32 v1, v1, v14
	v_lshlrev_b32_e32 v4, 16, v11
	v_mul_f32_e32 v1, v1, v4
	v_mul_f32_e32 v4, v5, v90
	v_mul_f32_e32 v4, v4, v15
	v_and_b32_e32 v5, 0xffff0000, v11
	v_mul_f32_e32 v4, v4, v5
	v_cvt_pk_bf16_f32 v1, v1, v4
	global_store_dwordx2 v[2:3], v[0:1], off offset:496
	v_mov_b32_e32 v4, v176
	v_mov_b32_e32 v181, v179
	v_bfe_u32 v0, v4, 4, 2
	v_or_b32_e32 v1, s71, v0
	v_bitop3_b32 v0, v0, v4, s71 bitop3:0x36
	v_lshlrev_b32_e32 v2, 14, v1
	v_lshlrev_b32_e32 v0, 4, v0
	v_and_or_b32 v178, v0, s55, v2
	v_or_b32_e32 v0, 4, v1
	v_bitop3_b32 v1, v1, v4, 4 bitop3:0x36
	v_lshlrev_b32_e32 v0, 14, v0
	v_lshlrev_b32_e32 v1, 4, v1
	v_and_or_b32 v180, v1, s55, v0
	v_bfe_u32 v0, v4, 5, 1
	v_or_b32_e32 v1, s71, v0
	v_and_b32_e32 v2, 31, v4
	v_lshlrev_b32_e32 v3, 14, v1
	v_lshlrev_b32_e32 v0, 6, v0
	v_lshlrev_b32_e32 v5, 4, v2
	v_bitop3_b32 v182, v0, v3, v5 bitop3:0xde
	v_or_b32_e32 v0, 2, v1
	v_lshlrev_b32_e32 v3, 2, v0
	v_bitop3_b32 v3, v3, v2, 12 bitop3:0x6c
	v_lshlrev_b32_e32 v0, 14, v0
	v_lshl_or_b32 v184, v3, 4, v0
	v_or_b32_e32 v0, 6, v1
	v_lshlrev_b32_e32 v1, 2, v0
	v_bitop3_b32 v1, v1, v2, 12 bitop3:0x6c
	v_lshlrev_b32_e32 v0, 14, v0
	v_lshl_or_b32 v188, v1, 4, v0
	v_lshl_add_u64 v[0:1], s[34:35], 0, v[178:179]
	s_mov_b32 s13, m0
	s_mov_b32 m0, s36
	s_nop 0
	global_load_lds_dwordx4 v[0:1], off
	s_mov_b32 m0, s13
	v_lshl_add_u64 v[0:1], s[34:35], 0, v[180:181]
	v_mov_b32_e32 v183, v179
	s_add_i32 s13, s36, 0x400
	s_mov_b32 s14, m0
	s_mov_b32 m0, s13
	s_nop 0
	global_load_lds_dwordx4 v[0:1], off
	s_mov_b32 m0, s14
	v_lshl_add_u64 v[0:1], s[16:17], 0, v[182:183]
	v_mov_b32_e32 v185, v179
	v_or_b32_e32 v186, 0x10000, v182
	s_mov_b32 s13, m0
	s_mov_b32 m0, s37
	s_nop 0
	global_load_lds_dwordx4 v[0:1], off
	s_mov_b32 m0, s13
	v_lshl_add_u64 v[0:1], s[16:17], 0, v[184:185]
	s_add_i32 s12, s12, s33
	v_mov_b32_e32 v187, v179
	s_add_i32 s13, s12, 0xc400
	s_mov_b32 s14, m0
	s_mov_b32 m0, s13
	s_nop 0
	global_load_lds_dwordx4 v[0:1], off
	s_mov_b32 m0, s14
	v_lshl_add_u64 v[0:1], s[16:17], 0, v[186:187]
	v_mov_b32_e32 v189, v179
	s_add_i32 s13, s12, 0xc800
	s_mov_b32 s14, m0
	s_mov_b32 m0, s13
	s_nop 0
	global_load_lds_dwordx4 v[0:1], off
	s_mov_b32 m0, s14
	v_lshl_add_u64 v[0:1], s[16:17], 0, v[188:189]
	s_add_i32 s13, s12, 0xcc00
	s_mov_b32 s14, m0
	s_mov_b32 m0, s13
	s_nop 0
	global_load_lds_dwordx4 v[0:1], off
	s_mov_b32 m0, s14
	v_lshl_add_u64 v[0:1], s[40:41], 0, v[178:179]
	s_add_i32 s13, s36, 0x4000
	s_mov_b32 s14, m0
	s_mov_b32 m0, s13
	s_nop 0
	global_load_lds_dwordx4 v[0:1], off
	s_mov_b32 m0, s14
	v_lshl_add_u64 v[0:1], s[40:41], 0, v[180:181]
	s_add_i32 s13, s36, 0x4400
	s_mov_b32 s14, m0
	s_mov_b32 m0, s13
	s_nop 0
	global_load_lds_dwordx4 v[0:1], off
	s_mov_b32 m0, s14
	v_lshl_add_u64 v[0:1], s[10:11], 0, v[182:183]
	s_add_i32 s13, s12, 0x14000
	s_mov_b32 s14, m0
	s_mov_b32 m0, s13
	s_nop 0
	global_load_lds_dwordx4 v[0:1], off
	s_mov_b32 m0, s14
	v_lshl_add_u64 v[0:1], s[10:11], 0, v[184:185]
	s_add_i32 s13, s12, 0x14400
	s_mov_b32 s14, m0
	s_mov_b32 m0, s13
	s_nop 0
	global_load_lds_dwordx4 v[0:1], off
	s_mov_b32 m0, s14
	v_lshl_add_u64 v[0:1], s[10:11], 0, v[186:187]
	s_add_i32 s13, s12, 0x14800
	s_mov_b32 s14, m0
	s_mov_b32 m0, s13
	s_nop 0
	global_load_lds_dwordx4 v[0:1], off
	s_mov_b32 m0, s14
	v_lshl_add_u64 v[0:1], s[10:11], 0, v[188:189]
	s_add_i32 s12, s12, 0x14c00
	s_mov_b32 s13, m0
	s_mov_b32 m0, s12
	s_nop 0
	global_load_lds_dwordx4 v[0:1], off
	s_mov_b32 m0, s13
	v_or_b32_e32 v0, s18, v2
	v_mov_b32_e32 v1, s19
	v_lshlrev_b64 v[0:1], 14, v[0:1]
	v_lshrrev_b32_e32 v2, 1, v4
	v_lshl_add_u64 v[0:1], s[8:9], 0, v[0:1]
	v_and_b32_e32 v2, 16, v2
	v_mov_b32_e32 v3, v179
	v_lshl_add_u64 v[0:1], v[0:1], 0, v[2:3]
	global_load_dwordx4 v[144:147], v[0:1], off
	global_load_dwordx4 v[148:151], v[0:1], off offset:32
	global_load_dwordx4 v[152:155], v[0:1], off offset:64
	global_load_dwordx4 v[156:159], v[0:1], off offset:96
	global_load_dwordx4 v[160:163], v[0:1], off offset:128
	global_load_dwordx4 v[164:167], v[0:1], off offset:160
	global_load_dwordx4 v[168:171], v[0:1], off offset:192
	global_load_dwordx4 v[172:175], v[0:1], off offset:224
	v_lshrrev_b32_e32 v0, 5, v4
	v_and_b32_e32 v1, 15, v4
	v_bitop3_b32 v0, v0, v1, 1 bitop3:0x6c
	v_lshlrev_b32_e32 v1, 8, v4
	v_lshlrev_b32_e32 v0, 4, v0
	v_and_b32_e32 v1, 0x1f00, v1
	v_mov_b32_e32 v14, v179
	v_mov_b32_e32 v15, v179
	v_or_b32_e32 v195, v0, v1
	v_bitop3_b32 v196, v0, 32, v1 bitop3:0x36
	v_bitop3_b32 v197, v0, 64, v1 bitop3:0x36
	v_bitop3_b32 v198, v0, s56, v1 bitop3:0x36
	v_bitop3_b32 v199, v0, s57, v1 bitop3:0x36
	v_bitop3_b32 v200, v0, s58, v1 bitop3:0x36
	v_bitop3_b32 v201, v0, s59, v1 bitop3:0x36
	v_bitop3_b32 v202, v0, s60, v1 bitop3:0x36
	v_mov_b32_e32 v0, v179
	v_mov_b32_e32 v1, v179
	v_mov_b32_e32 v2, v179
	v_mov_b32_e32 v4, v179
	v_mov_b32_e32 v5, v179
	v_mov_b32_e32 v6, v179
	v_mov_b32_e32 v7, v179
	v_mov_b32_e32 v8, v179
	s_waitcnt vmcnt(7)
	s_waitcnt vmcnt(6)
	s_waitcnt vmcnt(5)
	s_waitcnt vmcnt(4)
	s_waitcnt vmcnt(3)
	s_waitcnt vmcnt(2)
	s_waitcnt vmcnt(1)
	s_waitcnt vmcnt(0)
	s_waitcnt vmcnt(0)
	v_mov_b32_e32 v9, v179
	v_mov_b32_e32 v10, v179
	v_mov_b32_e32 v11, v179
	v_mov_b32_e32 v12, v179
	v_mov_b32_e32 v13, v179
	v_mov_b64_e32 v[30:31], v[14:15]
	v_mov_b64_e32 v[46:47], v[14:15]
	v_mov_b64_e32 v[62:63], v[14:15]
	v_mov_b64_e32 v[78:79], v[14:15]
	v_mov_b64_e32 v[94:95], v[14:15]
	v_mov_b64_e32 v[110:111], v[14:15]
	v_mov_b64_e32 v[126:127], v[14:15]
	v_mov_b32_e32 v190, 0xf149f2ca
	v_mov_b32_e32 v203, 0
	v_mov_b64_e32 v[28:29], v[12:13]
	v_mov_b64_e32 v[26:27], v[10:11]
	v_mov_b64_e32 v[24:25], v[8:9]
	v_mov_b64_e32 v[22:23], v[6:7]
	v_mov_b64_e32 v[20:21], v[4:5]
	v_mov_b64_e32 v[18:19], v[2:3]
	v_mov_b64_e32 v[16:17], v[0:1]
	v_mov_b64_e32 v[44:45], v[12:13]
	v_mov_b64_e32 v[42:43], v[10:11]
	v_mov_b64_e32 v[40:41], v[8:9]
	v_mov_b64_e32 v[38:39], v[6:7]
	v_mov_b64_e32 v[36:37], v[4:5]
	v_mov_b64_e32 v[34:35], v[2:3]
	v_mov_b64_e32 v[32:33], v[0:1]
	v_mov_b64_e32 v[60:61], v[12:13]
	v_mov_b64_e32 v[58:59], v[10:11]
	v_mov_b64_e32 v[56:57], v[8:9]
	v_mov_b64_e32 v[54:55], v[6:7]
	v_mov_b64_e32 v[52:53], v[4:5]
	v_mov_b64_e32 v[50:51], v[2:3]
	v_mov_b64_e32 v[48:49], v[0:1]
	v_mov_b64_e32 v[76:77], v[12:13]
	v_mov_b64_e32 v[74:75], v[10:11]
	v_mov_b64_e32 v[72:73], v[8:9]
	v_mov_b64_e32 v[70:71], v[6:7]
	v_mov_b64_e32 v[68:69], v[4:5]
	v_mov_b64_e32 v[66:67], v[2:3]
	v_mov_b64_e32 v[64:65], v[0:1]
	v_mov_b64_e32 v[92:93], v[12:13]
	v_mov_b64_e32 v[90:91], v[10:11]
	v_mov_b64_e32 v[88:89], v[8:9]
	v_mov_b64_e32 v[86:87], v[6:7]
	v_mov_b64_e32 v[84:85], v[4:5]
	v_mov_b64_e32 v[82:83], v[2:3]
	v_mov_b64_e32 v[80:81], v[0:1]
	v_mov_b64_e32 v[108:109], v[12:13]
	v_mov_b64_e32 v[106:107], v[10:11]
	v_mov_b64_e32 v[104:105], v[8:9]
	v_mov_b64_e32 v[102:103], v[6:7]
	v_mov_b64_e32 v[100:101], v[4:5]
	v_mov_b64_e32 v[98:99], v[2:3]
	v_mov_b64_e32 v[96:97], v[0:1]
	v_mov_b64_e32 v[124:125], v[12:13]
	v_mov_b64_e32 v[122:123], v[10:11]
	v_mov_b64_e32 v[120:121], v[8:9]
	v_mov_b64_e32 v[118:119], v[6:7]
	v_mov_b64_e32 v[116:117], v[4:5]
	v_mov_b64_e32 v[114:115], v[2:3]
	v_mov_b64_e32 v[112:113], v[0:1]
	s_mov_b32 s34, 0
	s_sub_u32 s20, s20, 0x100000
	s_subb_u32 s21, s21, 0
	s_sub_i32 s73, s73, 1
	s_barrier
	s_branch .LBB0_1837

.LBB0_1837:
	s_cmp_ge_u32 s73, s66
	s_cselect_b64 s[12:13], -1, 0
	v_mov_b32_e32 v204, v176
	s_and_b64 vcc, exec, s[12:13]
	s_cbranch_vccnz .LBB0_1839
	s_add_i32 s100, s72, 63
	s_cmp_le_i32 s100, s68
	s_cbranch_scc1 .LBB0_1839
	s_add_i32 s14, s34, 1
	s_cmp_eq_u32 s14, 3
	s_cselect_b32 s14, 0, s14
	v_mov_b32_e32 v130, s14
	v_lshlrev_b32_e32 v128, 14, v130
	v_add_u32_e32 v131, s36, v128
	v_lshl_add_u64 v[128:129], s[20:21], 0, v[178:179]
	s_add_u32 s14, s20, 0x1000
	v_readfirstlane_b32 s35, v131
	s_mov_b32 s40, m0
	s_mov_b32 m0, s35
	s_nop 0
	global_load_lds_dwordx4 v[128:129], off
	s_mov_b32 m0, s40
	v_lshl_add_u64 v[128:129], s[20:21], 0, v[180:181]
	s_addc_u32 s15, s21, 0
	s_addk_i32 s35, 0x400
	s_mov_b32 s40, m0
	s_mov_b32 m0, s35
	s_nop 0
	global_load_lds_dwordx4 v[128:129], off
	s_mov_b32 m0, s40
	v_lshlrev_b32_e32 v128, 15, v130
	v_add_u32_e32 v130, s37, v128
	v_lshl_add_u64 v[128:129], s[14:15], 0, v[182:183]
	v_readfirstlane_b32 s35, v130
	s_mov_b32 s40, m0
	s_mov_b32 m0, s35
	s_nop 0
	global_load_lds_dwordx4 v[128:129], off
	s_mov_b32 m0, s40
	v_lshl_add_u64 v[128:129], s[14:15], 0, v[184:185]
	s_add_i32 s40, s35, 0x400
	s_mov_b32 s41, m0
	s_mov_b32 m0, s40
	s_nop 0
	global_load_lds_dwordx4 v[128:129], off
	s_mov_b32 m0, s41
	v_lshl_add_u64 v[128:129], s[14:15], 0, v[186:187]
	s_add_i32 s40, s35, 0x800
	s_mov_b32 s41, m0
	s_mov_b32 m0, s40
	s_nop 0
	global_load_lds_dwordx4 v[128:129], off
	s_mov_b32 m0, s41
	v_lshl_add_u64 v[128:129], s[14:15], 0, v[188:189]
	s_add_i32 s14, s35, 0xc00
	s_mov_b32 s15, m0
	s_mov_b32 m0, s14
	s_nop 0
	global_load_lds_dwordx4 v[128:129], off
	s_mov_b32 m0, s15
.LBB0_1839:
	s_cmp_gt_i32 s72, s69
	s_cbranch_scc1 .LBB0_1850
	s_add_i32 s100, s72, 63
	s_cmp_le_i32 s100, s68
	s_cbranch_scc0 .Latt_slow_6
	v_lshrrev_b32_e32 v246, 8, v220
	s_nop 0
	v_readfirstlane_b32 s100, v246
	s_nop 0
	s_cmp_eq_u32 s100, 0
	s_cbranch_scc1 .Latt_A_6
	s_cmp_eq_u32 s72, 0
	s_cbranch_scc1 .Latt_B0_6
	s_add_i32 s99, s34, 2
	s_sub_i32 s101, s99, 3
	s_cmp_lt_u32 s99, 3
	s_cselect_b32 s99, s99, s101
	s_lshl_b32 s99, s99, 15
	s_add_i32 s99, s99, 0xc000
	v_bfe_u32 v246, v204, 2, 2
	v_bfe_u32 v247, v204, 5, 1
	v_lshl_or_b32 v247, v247, 2, v246
	v_and_b32_e32 v249, 3, v204
	v_and_b32_e32 v254, 16, v204
	v_lshl_or_b32 v249, v249, 2, v254
	v_lshlrev_b32_e32 v249, 1, v249
	v_lshl_add_u32 v247, v247, 9, v249
	v_add_u32_e32 v247, s99, v247
	v_lshlrev_b32_e32 v246, 6, v246
	v_add_u32_e32 v205, v247, v246
	v_xor_b32_e32 v249, 64, v246
	v_add_u32_e32 v218, v247, v249
	v_xor_b32_e32 v249, 0x80, v246
	v_add_u32_e32 v219, v247, v249
	v_xor_b32_e32 v249, 0xc0, v246
	v_add_u32_e32 v221, v247, v249
	s_lshl_b32 s98, s34, 14
	s_lshl_b32 s99, s34, 15
	s_add_i32 s99, s99, 0xc000
	ds_read_b64_tr_b16 v[206:207], v205 offset:16384
	ds_read_b64_tr_b16 v[208:209], v205 offset:20480
	ds_read_b64_tr_b16 v[210:211], v218 offset:16384
	ds_read_b64_tr_b16 v[212:213], v218 offset:20480
	ds_read_b64_tr_b16 v[214:215], v219 offset:16384
	ds_read_b64_tr_b16 v[216:217], v219 offset:20480
	ds_read_b64_tr_b16 v[238:239], v221 offset:16384
	ds_read_b64_tr_b16 v[240:241], v221 offset:20480
	ds_read_b64_tr_b16 v[222:223], v205 offset:16640
	ds_read_b64_tr_b16 v[224:225], v205 offset:20736
	s_waitcnt lgkmcnt(8)
	v_mfma_f32_32x32x16_bf16 v[112:127], v[206:209], v[242:245], v[112:127]
	ds_read_b64_tr_b16 v[206:207], v218 offset:16640
	ds_read_b64_tr_b16 v[208:209], v218 offset:20736
	s_cmp_lg_u64 s[12:13], 0
	s_cbranch_scc1 .Latt_nd0_6B1
	s_add_i32 s100, s34, 1
	s_cmp_eq_u32 s34, 2
	s_cselect_b32 s100, 0, s100
	s_lshl_b32 s101, s100, 14
	s_add_i32 m0, s36, s101
	s_nop 0
	global_load_lds_dwordx4 v178, s[20:21]
.Latt_nd0_6B1:
	s_waitcnt lgkmcnt(8)
	v_mfma_f32_32x32x16_bf16 v[96:111], v[210:213], v[242:245], v[96:111]
	ds_read_b64_tr_b16 v[210:211], v219 offset:16640
	ds_read_b64_tr_b16 v[212:213], v219 offset:20736
	s_cmp_lg_u64 s[12:13], 0
	s_cbranch_scc1 .Latt_nd1_6B1
	s_add_i32 m0, m0, 0x400
	s_nop 0
	global_load_lds_dwordx4 v180, s[20:21]
.Latt_nd1_6B1:
	s_waitcnt lgkmcnt(8)
	v_mfma_f32_32x32x16_bf16 v[80:95], v[214:217], v[242:245], v[80:95]
	ds_read_b64_tr_b16 v[214:215], v221 offset:16640
	ds_read_b64_tr_b16 v[216:217], v221 offset:20736
	s_cmp_lg_u64 s[12:13], 0
	s_cbranch_scc1 .Latt_nd2_6B1
	s_lshl_b32 s101, s100, 15
	s_add_i32 m0, s37, s101
	s_add_u32 s100, s20, 0x1000
	s_addc_u32 s101, s21, 0
	global_load_lds_dwordx4 v182, s[100:101]

.Latt_B0_6:
	s_lshl_b32 s98, s34, 14
	s_lshl_b32 s99, s34, 15
	s_add_i32 s99, s99, 0xc000
	v_add_u32_e32 v206, s98, v195
	ds_read_b128 v[206:209], v206
	v_add_u32_e32 v210, s98, v196
	ds_read_b128 v[210:213], v210
	v_add_u32_e32 v214, s98, v197
	ds_read_b128 v[214:217], v214
	v_add_u32_e32 v238, s98, v198
	ds_read_b128 v[238:241], v238
	v_add_u32_e32 v242, s98, v199
	ds_read_b128 v[242:245], v242
	v_add_u32_e32 v250, s98, v200
	ds_read_b128 v[250:253], v250
	v_add_u32_e32 v222, s98, v201
	ds_read_b128 v[222:225], v222
	v_add_u32_e32 v226, s98, v202
	ds_read_b128 v[226:229], v226
	v_bfe_u32 v246, v204, 2, 2
	v_bfe_u32 v247, v204, 5, 1
	v_lshl_or_b32 v247, v247, 2, v246
	v_and_b32_e32 v249, 3, v204
	v_and_b32_e32 v254, 16, v204
	v_lshl_or_b32 v249, v249, 2, v254
	v_lshlrev_b32_e32 v249, 1, v249
	v_lshl_add_u32 v247, v247, 9, v249
	v_add_u32_e32 v247, s99, v247
	v_lshlrev_b32_e32 v246, 6, v246
	v_add_u32_e32 v205, v247, v246
	v_xor_b32_e32 v249, 64, v246
	v_add_u32_e32 v218, v247, v249
	v_xor_b32_e32 v249, 0x80, v246
	v_add_u32_e32 v219, v247, v249
	v_xor_b32_e32 v249, 0xc0, v246
	v_add_u32_e32 v221, v247, v249
	s_waitcnt lgkmcnt(7)
	v_mfma_f32_32x32x16_bf16 v[128:143], v[206:209], v[144:147], 0
	v_add_u32_e32 v206, s98, v195
	ds_read_b128 v[206:209], v206 offset:8192
	s_cmp_lg_u64 s[12:13], 0
	s_cbranch_scc1 .Latt_nd0_6B0
	s_add_i32 s100, s34, 1
	s_cmp_eq_u32 s34, 2
	s_cselect_b32 s100, 0, s100
	s_lshl_b32 s101, s100, 14
	s_add_i32 m0, s36, s101
	s_nop 0
	global_load_lds_dwordx4 v178, s[20:21]
.Latt_nd0_6B0:
	s_waitcnt lgkmcnt(7)
	v_mfma_f32_32x32x16_bf16 v[128:143], v[210:213], v[148:151], v[128:143]
	v_add_u32_e32 v210, s98, v196
	ds_read_b128 v[210:213], v210 offset:8192
	s_cmp_lg_u64 s[12:13], 0
	s_cbranch_scc1 .Latt_nd1_6B0
	s_add_i32 m0, m0, 0x400
	s_nop 0
	global_load_lds_dwordx4 v180, s[20:21]
.Latt_nd1_6B0:
	s_waitcnt lgkmcnt(7)
	v_mfma_f32_32x32x16_bf16 v[128:143], v[214:217], v[152:155], v[128:143]
	v_add_u32_e32 v214, s98, v197
	ds_read_b128 v[214:217], v214 offset:8192
	s_cmp_lg_u64 s[12:13], 0
	s_cbranch_scc1 .Latt_nd2_6B0
	s_lshl_b32 s101, s100, 15
	s_add_i32 m0, s37, s101
	s_add_u32 s100, s20, 0x1000
	s_addc_u32 s101, s21, 0
	global_load_lds_dwordx4 v182, s[100:101]

.Latt_slow_6:
	v_lshrrev_b32_e32 v246, 8, v220
	s_nop 0
	v_readfirstlane_b32 s100, v246
	s_nop 0
	s_cmp_eq_u32 s100, 0
	s_cbranch_scc1 .Latt_slow2_6
	s_cmp_eq_u32 s72, 0
	s_cbranch_scc1 .Latt_slow2_6
	s_add_i32 s99, s34, 2
	s_sub_i32 s101, s99, 3
	s_cmp_lt_u32 s99, 3
	s_cselect_b32 s99, s99, s101
	s_lshl_b32 s99, s99, 15
	s_add_i32 s99, s99, 0xc000
	v_bfe_u32 v246, v204, 2, 2
	v_bfe_u32 v247, v204, 5, 1
	v_lshl_or_b32 v247, v247, 2, v246
	v_and_b32_e32 v249, 3, v204
	v_and_b32_e32 v254, 16, v204
	v_lshl_or_b32 v249, v249, 2, v254
	v_lshlrev_b32_e32 v249, 1, v249
	v_lshl_add_u32 v247, v247, 9, v249
	v_add_u32_e32 v247, s99, v247
	v_lshlrev_b32_e32 v246, 6, v246
	v_add_u32_e32 v205, v247, v246
	v_xor_b32_e32 v249, 64, v246
	v_add_u32_e32 v218, v247, v249
	v_xor_b32_e32 v249, 0x80, v246
	v_add_u32_e32 v219, v247, v249
	v_xor_b32_e32 v249, 0xc0, v246
	v_add_u32_e32 v221, v247, v249
	ds_read_b64_tr_b16 v[206:207], v205 offset:16384
	ds_read_b64_tr_b16 v[208:209], v205 offset:20480
	ds_read_b64_tr_b16 v[210:211], v218 offset:16384
	ds_read_b64_tr_b16 v[212:213], v218 offset:20480
	ds_read_b64_tr_b16 v[214:215], v219 offset:16384
	ds_read_b64_tr_b16 v[216:217], v219 offset:20480
	ds_read_b64_tr_b16 v[238:239], v221 offset:16384
	ds_read_b64_tr_b16 v[240:241], v221 offset:20480
	ds_read_b64_tr_b16 v[222:223], v205 offset:16640
	ds_read_b64_tr_b16 v[224:225], v205 offset:20736
	s_waitcnt lgkmcnt(8)
	v_mfma_f32_32x32x16_bf16 v[112:127], v[206:209], v[242:245], v[112:127]
	ds_read_b64_tr_b16 v[206:207], v218 offset:16640
	ds_read_b64_tr_b16 v[208:209], v218 offset:20736
	s_waitcnt lgkmcnt(8)
	v_mfma_f32_32x32x16_bf16 v[96:111], v[210:213], v[242:245], v[96:111]
	ds_read_b64_tr_b16 v[210:211], v219 offset:16640
	ds_read_b64_tr_b16 v[212:213], v219 offset:20736
	s_waitcnt lgkmcnt(8)
	v_mfma_f32_32x32x16_bf16 v[80:95], v[214:217], v[242:245], v[80:95]
	ds_read_b64_tr_b16 v[214:215], v221 offset:16640
	ds_read_b64_tr_b16 v[216:217], v221 offset:20736
	s_waitcnt lgkmcnt(8)
	v_mfma_f32_32x32x16_bf16 v[64:79], v[238:241], v[242:245], v[64:79]
	ds_read_b64_tr_b16 v[238:239], v205 offset:24576
	ds_read_b64_tr_b16 v[240:241], v205 offset:28672
	s_waitcnt lgkmcnt(8)
	v_mfma_f32_32x32x16_bf16 v[48:63], v[222:225], v[242:245], v[48:63]
	ds_read_b64_tr_b16 v[222:223], v218 offset:24576
	ds_read_b64_tr_b16 v[224:225], v218 offset:28672
	s_waitcnt lgkmcnt(8)
	v_mfma_f32_32x32x16_bf16 v[32:47], v[206:209], v[242:245], v[32:47]
	ds_read_b64_tr_b16 v[206:207], v219 offset:24576
	ds_read_b64_tr_b16 v[208:209], v219 offset:28672
	s_waitcnt lgkmcnt(8)
	v_mfma_f32_32x32x16_bf16 v[16:31], v[210:213], v[242:245], v[16:31]
	ds_read_b64_tr_b16 v[210:211], v221 offset:24576
	ds_read_b64_tr_b16 v[212:213], v221 offset:28672
	s_waitcnt lgkmcnt(8)
	v_mfma_f32_32x32x16_bf16 v[0:15], v[214:217], v[242:245], v[0:15]
	ds_read_b64_tr_b16 v[214:215], v205 offset:24832
	ds_read_b64_tr_b16 v[216:217], v205 offset:28928
	s_waitcnt lgkmcnt(8)
	v_mfma_f32_32x32x16_bf16 v[112:127], v[238:241], v[250:253], v[112:127]
	ds_read_b64_tr_b16 v[238:239], v218 offset:24832
	ds_read_b64_tr_b16 v[240:241], v218 offset:28928
	s_waitcnt lgkmcnt(8)
	v_mfma_f32_32x32x16_bf16 v[96:111], v[222:225], v[250:253], v[96:111]
	ds_read_b64_tr_b16 v[222:223], v219 offset:24832
	ds_read_b64_tr_b16 v[224:225], v219 offset:28928
	s_waitcnt lgkmcnt(8)
	v_mfma_f32_32x32x16_bf16 v[80:95], v[206:209], v[250:253], v[80:95]
	ds_read_b64_tr_b16 v[206:207], v221 offset:24832
	ds_read_b64_tr_b16 v[208:209], v221 offset:28928
	s_waitcnt lgkmcnt(8)
	v_mfma_f32_32x32x16_bf16 v[64:79], v[210:213], v[250:253], v[64:79]
	s_waitcnt lgkmcnt(6)
	v_mfma_f32_32x32x16_bf16 v[48:63], v[214:217], v[250:253], v[48:63]
	s_waitcnt lgkmcnt(4)
	v_mfma_f32_32x32x16_bf16 v[32:47], v[238:241], v[250:253], v[32:47]
	s_waitcnt lgkmcnt(2)
	v_mfma_f32_32x32x16_bf16 v[16:31], v[222:225], v[250:253], v[16:31]
	s_waitcnt lgkmcnt(0)
	v_mfma_f32_32x32x16_bf16 v[0:15], v[206:209], v[250:253], v[0:15]

.LBB0_1854:
	ds_bpermute_b32 v128, v194, v203
	s_add_i32 s12, s74, s46
	s_mov_b32 s13, s5
	s_lshl_b64 s[12:13], s[12:13], 14
	s_add_u32 s12, s44, s12
	s_waitcnt lgkmcnt(0)
	v_add_f32_e32 v128, v203, v128
	v_rcp_f32_e32 v130, v128
	v_mov_b32_e32 v128, v176
	s_addc_u32 s13, s45, s13
	v_lshlrev_b32_e32 v128, 4, v128
	v_mul_f32_e32 v112, v112, v130
	v_mul_f32_e32 v113, v113, v130
	v_mul_f32_e32 v114, v114, v130
	v_mul_f32_e32 v115, v115, v130
	v_and_b32_e32 v178, 0x3f0, v128
	v_mul_f32_e32 v116, v116, v130
	v_mul_f32_e32 v117, v117, v130
	v_mul_f32_e32 v118, v118, v130
	v_mul_f32_e32 v119, v119, v130
	v_cvt_pk_bf16_f32 v112, v112, v113
	v_cvt_pk_bf16_f32 v113, v114, v115
	v_cvt_pk_bf16_f32 v114, v116, v117
	v_cvt_pk_bf16_f32 v115, v118, v119
	v_mul_f32_e32 v96, v96, v130
	v_mul_f32_e32 v97, v97, v130
	v_mul_f32_e32 v98, v98, v130
	v_mul_f32_e32 v99, v99, v130
	v_lshl_add_u64 v[128:129], s[12:13], 0, v[178:179]
	v_mul_f32_e32 v120, v120, v130
	v_mul_f32_e32 v121, v121, v130
	v_mul_f32_e32 v122, v122, v130
	v_mul_f32_e32 v123, v123, v130
	v_mul_f32_e32 v124, v124, v130
	v_mul_f32_e32 v125, v125, v130
	v_mul_f32_e32 v126, v126, v130
	v_mul_f32_e32 v127, v127, v130
	v_cvt_pk_bf16_f32 v116, v120, v121
	v_cvt_pk_bf16_f32 v117, v122, v123
	v_cvt_pk_bf16_f32 v118, v124, v125
	v_cvt_pk_bf16_f32 v119, v126, v127
	global_store_dwordx4 v178, v[112:115], s[12:13]
	global_store_dwordx4 v178, v[116:119], s[12:13] offset:1024
	v_mul_f32_e32 v100, v100, v130
	v_mul_f32_e32 v101, v101, v130
	v_mul_f32_e32 v102, v102, v130
	v_mul_f32_e32 v103, v103, v130
	v_cvt_pk_bf16_f32 v96, v96, v97
	v_cvt_pk_bf16_f32 v97, v98, v99
	v_cvt_pk_bf16_f32 v98, v100, v101
	v_cvt_pk_bf16_f32 v99, v102, v103
	v_mul_f32_e32 v80, v80, v130
	v_mul_f32_e32 v81, v81, v130
	v_mul_f32_e32 v82, v82, v130
	v_mul_f32_e32 v83, v83, v130
	v_mul_f32_e32 v84, v84, v130
	v_mul_f32_e32 v88, v88, v130
	v_mul_f32_e32 v104, v104, v130
	v_mul_f32_e32 v105, v105, v130
	v_mul_f32_e32 v106, v106, v130
	v_mul_f32_e32 v107, v107, v130
	v_mul_f32_e32 v108, v108, v130
	v_mul_f32_e32 v109, v109, v130
	v_mul_f32_e32 v110, v110, v130
	v_mul_f32_e32 v111, v111, v130
	v_cvt_pk_bf16_f32 v100, v104, v105
	v_cvt_pk_bf16_f32 v101, v106, v107
	v_cvt_pk_bf16_f32 v102, v108, v109
	v_cvt_pk_bf16_f32 v103, v110, v111
	global_store_dwordx4 v178, v[96:99], s[12:13] offset:2048
	global_store_dwordx4 v178, v[100:103], s[12:13] offset:3072
	v_mul_f32_e32 v85, v85, v130
	v_mul_f32_e32 v86, v86, v130
	v_mul_f32_e32 v87, v87, v130
	v_mul_f32_e32 v89, v89, v130
	v_cvt_pk_bf16_f32 v80, v80, v81
	v_cvt_pk_bf16_f32 v81, v82, v83
	v_cvt_pk_bf16_f32 v82, v84, v85
	v_cvt_pk_bf16_f32 v83, v86, v87
	v_cvt_pk_bf16_f32 v84, v88, v89
	v_add_co_u32_e32 v88, vcc, s61, v128
	v_mul_f32_e32 v90, v90, v130
	s_nop 0
	v_addc_co_u32_e32 v89, vcc, 0, v129, vcc
	v_mul_f32_e32 v91, v91, v130
	v_cvt_pk_bf16_f32 v85, v90, v91
	v_add_co_u32_e32 v90, vcc, s62, v128
	v_mul_f32_e32 v64, v64, v130
	s_nop 0
	v_addc_co_u32_e32 v91, vcc, 0, v129, vcc
	v_mul_f32_e32 v65, v65, v130
	v_mul_f32_e32 v66, v66, v130
	v_mul_f32_e32 v67, v67, v130
	v_mul_f32_e32 v92, v92, v130
	v_mul_f32_e32 v93, v93, v130
	v_mul_f32_e32 v94, v94, v130
	v_mul_f32_e32 v95, v95, v130
	v_cvt_pk_bf16_f32 v86, v92, v93
	v_cvt_pk_bf16_f32 v87, v94, v95
	global_store_dwordx4 v[90:91], v[80:83], off offset:-4096
	global_store_dwordx4 v[88:89], v[84:87], off offset:1024
	v_mul_f32_e32 v68, v68, v130
	v_mul_f32_e32 v69, v69, v130
	v_mul_f32_e32 v70, v70, v130
	v_mul_f32_e32 v71, v71, v130
	v_cvt_pk_bf16_f32 v64, v64, v65
	v_cvt_pk_bf16_f32 v65, v66, v67
	v_cvt_pk_bf16_f32 v66, v68, v69
	v_cvt_pk_bf16_f32 v67, v70, v71
	v_mul_f32_e32 v48, v48, v130
	v_mul_f32_e32 v49, v49, v130
	v_mul_f32_e32 v50, v50, v130
	v_mul_f32_e32 v51, v51, v130
	v_mul_f32_e32 v72, v72, v130
	v_mul_f32_e32 v73, v73, v130
	v_mul_f32_e32 v74, v74, v130
	v_mul_f32_e32 v75, v75, v130
	v_mul_f32_e32 v76, v76, v130
	v_mul_f32_e32 v77, v77, v130
	v_mul_f32_e32 v78, v78, v130
	v_mul_f32_e32 v79, v79, v130
	v_cvt_pk_bf16_f32 v68, v72, v73
	v_cvt_pk_bf16_f32 v69, v74, v75
	v_cvt_pk_bf16_f32 v70, v76, v77
	v_cvt_pk_bf16_f32 v71, v78, v79
	global_store_dwordx4 v[88:89], v[64:67], off offset:2048
	global_store_dwordx4 v[88:89], v[68:71], off offset:3072
	v_mul_f32_e32 v52, v52, v130
	v_mul_f32_e32 v53, v53, v130
	v_mul_f32_e32 v54, v54, v130
	v_mul_f32_e32 v55, v55, v130
	v_cvt_pk_bf16_f32 v48, v48, v49
	v_cvt_pk_bf16_f32 v49, v50, v51
	v_cvt_pk_bf16_f32 v50, v52, v53
	v_cvt_pk_bf16_f32 v51, v54, v55
	v_mul_f32_e32 v32, v32, v130
	v_mul_f32_e32 v33, v33, v130
	v_mul_f32_e32 v34, v34, v130
	v_mul_f32_e32 v35, v35, v130
	v_mul_f32_e32 v56, v56, v130
	v_mul_f32_e32 v57, v57, v130
	v_mul_f32_e32 v58, v58, v130
	v_mul_f32_e32 v59, v59, v130
	v_mul_f32_e32 v60, v60, v130
	v_mul_f32_e32 v61, v61, v130
	v_mul_f32_e32 v62, v62, v130
	v_mul_f32_e32 v63, v63, v130
	v_cvt_pk_bf16_f32 v52, v56, v57
	v_cvt_pk_bf16_f32 v53, v58, v59
	v_cvt_pk_bf16_f32 v54, v60, v61
	v_cvt_pk_bf16_f32 v55, v62, v63
	global_store_dwordx4 v[90:91], v[48:51], off
	global_store_dwordx4 v[90:91], v[52:55], off offset:1024
	v_mul_f32_e32 v36, v36, v130
	v_mul_f32_e32 v37, v37, v130
	v_mul_f32_e32 v38, v38, v130
	v_mul_f32_e32 v39, v39, v130
	v_cvt_pk_bf16_f32 v32, v32, v33
	v_cvt_pk_bf16_f32 v33, v34, v35
	v_cvt_pk_bf16_f32 v34, v36, v37
	v_cvt_pk_bf16_f32 v35, v38, v39
	v_mul_f32_e32 v16, v16, v130
	v_mul_f32_e32 v17, v17, v130
	v_mul_f32_e32 v18, v18, v130
	v_mul_f32_e32 v19, v19, v130
	v_mul_f32_e32 v20, v20, v130
	v_mul_f32_e32 v24, v24, v130
	v_mul_f32_e32 v40, v40, v130
	v_mul_f32_e32 v41, v41, v130
	v_mul_f32_e32 v42, v42, v130
	v_mul_f32_e32 v43, v43, v130
	v_mul_f32_e32 v44, v44, v130
	v_mul_f32_e32 v45, v45, v130
	v_mul_f32_e32 v46, v46, v130
	v_mul_f32_e32 v47, v47, v130
	v_cvt_pk_bf16_f32 v36, v40, v41
	v_cvt_pk_bf16_f32 v37, v42, v43
	v_cvt_pk_bf16_f32 v38, v44, v45
	v_cvt_pk_bf16_f32 v39, v46, v47
	global_store_dwordx4 v[90:91], v[32:35], off offset:2048
	global_store_dwordx4 v[90:91], v[36:39], off offset:3072
	v_mul_f32_e32 v21, v21, v130
	v_mul_f32_e32 v22, v22, v130
	v_mul_f32_e32 v23, v23, v130
	v_mul_f32_e32 v25, v25, v130
	v_cvt_pk_bf16_f32 v16, v16, v17
	v_cvt_pk_bf16_f32 v17, v18, v19
	v_cvt_pk_bf16_f32 v18, v20, v21
	v_cvt_pk_bf16_f32 v19, v22, v23
	v_cvt_pk_bf16_f32 v20, v24, v25
	v_add_co_u32_e32 v24, vcc, s63, v128
	v_mul_f32_e32 v0, v0, v130
	s_nop 0
	v_addc_co_u32_e32 v25, vcc, 0, v129, vcc
	v_mul_f32_e32 v1, v1, v130
	v_mul_f32_e32 v2, v2, v130
	v_mul_f32_e32 v3, v3, v130
	s_mov_b32 s14, 0
	v_mul_f32_e32 v26, v26, v130
	v_mul_f32_e32 v27, v27, v130
	v_mul_f32_e32 v28, v28, v130
	v_mul_f32_e32 v29, v29, v130
	v_mul_f32_e32 v30, v30, v130
	v_mul_f32_e32 v31, v31, v130
	v_cvt_pk_bf16_f32 v21, v26, v27
	v_cvt_pk_bf16_f32 v22, v28, v29
	v_cvt_pk_bf16_f32 v23, v30, v31
	global_store_dwordx4 v[24:25], v[16:19], off
	global_store_dwordx4 v[24:25], v[20:23], off offset:1024
	v_mul_f32_e32 v4, v4, v130
	v_mul_f32_e32 v5, v5, v130
	v_mul_f32_e32 v6, v6, v130
	v_mul_f32_e32 v7, v7, v130
	v_mul_f32_e32 v8, v8, v130
	v_mul_f32_e32 v9, v9, v130
	v_mul_f32_e32 v10, v10, v130
	v_mul_f32_e32 v11, v11, v130
	v_mul_f32_e32 v12, v12, v130
	v_mul_f32_e32 v13, v13, v130
	v_mul_f32_e32 v14, v14, v130
	v_mul_f32_e32 v15, v15, v130
	v_cvt_pk_bf16_f32 v0, v0, v1
	v_cvt_pk_bf16_f32 v1, v2, v3
	v_cvt_pk_bf16_f32 v2, v4, v5
	v_cvt_pk_bf16_f32 v3, v6, v7
	v_cvt_pk_bf16_f32 v4, v8, v9
	v_cvt_pk_bf16_f32 v5, v10, v11
	v_cvt_pk_bf16_f32 v6, v12, v13
	v_cvt_pk_bf16_f32 v7, v14, v15
	global_store_dwordx4 v[24:25], v[0:3], off offset:2048
	global_store_dwordx4 v[24:25], v[4:7], off offset:3072
	s_nop 1
	v_mov_b32_e32 v4, v176
	s_cmp_lg_u32 0, -1
	v_bfe_u32 v0, v4, 4, 2
	v_or_b32_e32 v1, s71, v0
	v_bitop3_b32 v0, v0, v4, s71 bitop3:0x36
	v_lshlrev_b32_e32 v2, 14, v1
	v_lshlrev_b32_e32 v0, 4, v0
	v_and_or_b32 v178, v0, s55, v2
	v_or_b32_e32 v0, 4, v1
	v_bitop3_b32 v1, v1, v4, 4 bitop3:0x36
	v_lshlrev_b32_e32 v0, 14, v0
	v_lshlrev_b32_e32 v1, 4, v1
	v_and_or_b32 v180, v1, s55, v0
	v_bfe_u32 v0, v4, 5, 1
	v_or_b32_e32 v1, s71, v0
	v_and_b32_e32 v2, 31, v4
	v_lshlrev_b32_e32 v3, 14, v1
	v_lshlrev_b32_e32 v0, 6, v0
	v_lshlrev_b32_e32 v5, 4, v2
	v_bitop3_b32 v182, v0, v3, v5 bitop3:0xde
	v_or_b32_e32 v0, 2, v1
	v_lshlrev_b32_e32 v3, 2, v0
	v_bitop3_b32 v3, v3, v2, 12 bitop3:0x6c
	v_lshlrev_b32_e32 v0, 14, v0
	v_lshl_or_b32 v184, v3, 4, v0
	v_or_b32_e32 v0, 6, v1
	v_lshlrev_b32_e32 v1, 2, v0
	v_bitop3_b32 v1, v1, v2, 12 bitop3:0x6c
	v_lshlrev_b32_e32 v0, 14, v0
	v_lshl_or_b32 v188, v1, 4, v0
	v_lshl_add_u64 v[0:1], s[38:39], 0, v[178:179]
	s_cselect_b32 s15, 0, 0
	v_mov_b32_e32 v181, v179
	s_add_i32 s20, s70, s15
	s_mov_b32 s21, m0
	s_mov_b32 m0, s20
	s_nop 0
	global_load_lds_dwordx4 v[0:1], off
	s_mov_b32 m0, s21
	v_lshl_add_u64 v[0:1], s[38:39], 0, v[180:181]
	v_mov_b32_e32 v183, v179
	s_add_i32 s21, s20, 0x400
	s_mov_b32 s34, m0
	s_mov_b32 m0, s21
	s_nop 0
	global_load_lds_dwordx4 v[0:1], off
	s_mov_b32 m0, s34
	v_lshl_add_u64 v[0:1], s[16:17], 0, v[182:183]
	s_add_i32 s15, s15, s33
	v_mov_b32_e32 v185, v179
	v_or_b32_e32 v186, 0x10000, v182
	s_add_i32 s21, s15, 0xc000
	s_mov_b32 s33, m0
	s_mov_b32 m0, s21
	s_nop 0
	global_load_lds_dwordx4 v[0:1], off
	s_mov_b32 m0, s33
	v_lshl_add_u64 v[0:1], s[16:17], 0, v[184:185]
	v_mov_b32_e32 v187, v179
	s_add_i32 s21, s15, 0xc400
	s_mov_b32 s33, m0
	s_mov_b32 m0, s21
	s_nop 0
	global_load_lds_dwordx4 v[0:1], off
	s_mov_b32 m0, s33
	v_lshl_add_u64 v[0:1], s[16:17], 0, v[186:187]
	v_mov_b32_e32 v189, v179
	s_add_i32 s21, s15, 0xc800
	s_mov_b32 s33, m0
	s_mov_b32 m0, s21
	s_nop 0
	global_load_lds_dwordx4 v[0:1], off
	s_mov_b32 m0, s33
	v_lshl_add_u64 v[0:1], s[16:17], 0, v[188:189]
	s_add_i32 s16, s15, 0xcc00
	s_mov_b32 s17, m0
	s_mov_b32 m0, s16
	s_nop 0
	global_load_lds_dwordx4 v[0:1], off
	s_mov_b32 m0, s17
	v_lshl_add_u64 v[0:1], s[42:43], 0, v[178:179]
	s_add_i32 s16, s20, 0x4000
	s_mov_b32 s17, m0
	s_mov_b32 m0, s16
	s_nop 0
	global_load_lds_dwordx4 v[0:1], off
	s_mov_b32 m0, s17
	v_lshl_add_u64 v[0:1], s[42:43], 0, v[180:181]
	s_addk_i32 s20, 0x4400
	s_mov_b32 s16, m0
	s_mov_b32 m0, s20
	s_nop 0
	global_load_lds_dwordx4 v[0:1], off
	s_mov_b32 m0, s16
	v_lshl_add_u64 v[0:1], s[10:11], 0, v[182:183]
	s_add_i32 s16, s15, 0x14000
	s_mov_b32 s17, m0
	s_mov_b32 m0, s16
	s_nop 0
	global_load_lds_dwordx4 v[0:1], off
	s_mov_b32 m0, s17
	v_lshl_add_u64 v[0:1], s[10:11], 0, v[184:185]
	s_add_i32 s16, s15, 0x14400
	s_mov_b32 s17, m0
	s_mov_b32 m0, s16
	s_nop 0
	global_load_lds_dwordx4 v[0:1], off
	s_mov_b32 m0, s17
	v_lshl_add_u64 v[0:1], s[10:11], 0, v[186:187]
	s_add_i32 s16, s15, 0x14800
	s_mov_b32 s17, m0
	s_mov_b32 m0, s16
	s_nop 0
	global_load_lds_dwordx4 v[0:1], off
	s_mov_b32 m0, s17
	v_lshl_add_u64 v[0:1], s[10:11], 0, v[188:189]
	s_add_i32 s15, s15, 0x14c00
	s_mov_b32 s10, m0
	s_mov_b32 m0, s15
	s_nop 0
	global_load_lds_dwordx4 v[0:1], off
	s_mov_b32 m0, s10
	v_or_b32_e32 v0, s18, v2
	v_mov_b32_e32 v1, s19
	v_lshlrev_b64 v[0:1], 14, v[0:1]
	v_lshrrev_b32_e32 v2, 1, v4
	v_lshl_add_u64 v[0:1], s[8:9], 0, v[0:1]
	v_and_b32_e32 v2, 16, v2
	v_mov_b32_e32 v3, v179
	v_lshl_add_u64 v[0:1], v[0:1], 0, v[2:3]
	global_load_dwordx4 v[144:147], v[0:1], off offset:256
	global_load_dwordx4 v[148:151], v[0:1], off offset:288
	global_load_dwordx4 v[152:155], v[0:1], off offset:320
	global_load_dwordx4 v[156:159], v[0:1], off offset:352
	global_load_dwordx4 v[160:163], v[0:1], off offset:384
	global_load_dwordx4 v[164:167], v[0:1], off offset:416
	global_load_dwordx4 v[168:171], v[0:1], off offset:448
	global_load_dwordx4 v[172:175], v[0:1], off offset:480
	v_lshrrev_b32_e32 v0, 5, v4
	v_and_b32_e32 v1, 15, v4
	v_bitop3_b32 v0, v0, v1, 1 bitop3:0x6c
	v_lshlrev_b32_e32 v1, 8, v4
	v_lshlrev_b32_e32 v0, 4, v0
	v_and_b32_e32 v1, 0x1f00, v1
	v_mov_b32_e32 v14, v179
	v_mov_b32_e32 v15, v179
	v_or_b32_e32 v196, v0, v1
	v_bitop3_b32 v197, v0, 32, v1 bitop3:0x36
	v_bitop3_b32 v198, v0, 64, v1 bitop3:0x36
	v_bitop3_b32 v199, v0, s56, v1 bitop3:0x36
	v_bitop3_b32 v200, v0, s57, v1 bitop3:0x36
	v_bitop3_b32 v201, v0, s58, v1 bitop3:0x36
	v_bitop3_b32 v202, v0, s59, v1 bitop3:0x36
	v_bitop3_b32 v203, v0, s60, v1 bitop3:0x36
	v_mov_b32_e32 v0, v179
	v_mov_b32_e32 v1, v179
	v_mov_b32_e32 v2, v179
	v_mov_b32_e32 v4, v179
	s_waitcnt vmcnt(7)
	s_waitcnt vmcnt(6)
	s_waitcnt vmcnt(5)
	s_waitcnt vmcnt(4)
	s_waitcnt vmcnt(3)
	s_waitcnt vmcnt(2)
	s_waitcnt vmcnt(1)
	s_waitcnt vmcnt(0)
	s_waitcnt vmcnt(0)
	v_mov_b32_e32 v5, v179
	v_mov_b32_e32 v6, v179
	v_mov_b32_e32 v7, v179
	v_mov_b32_e32 v8, v179
	v_mov_b32_e32 v9, v179
	v_mov_b32_e32 v10, v179
	v_mov_b32_e32 v11, v179
	v_mov_b32_e32 v12, v179
	v_mov_b32_e32 v13, v179
	v_mov_b64_e32 v[30:31], v[14:15]
	v_mov_b64_e32 v[46:47], v[14:15]
	v_mov_b64_e32 v[62:63], v[14:15]
	v_mov_b64_e32 v[78:79], v[14:15]
	v_mov_b64_e32 v[94:95], v[14:15]
	v_mov_b64_e32 v[110:111], v[14:15]
	v_mov_b64_e32 v[126:127], v[14:15]
	s_mov_b32 s10, 2
	v_mov_b32_e32 v190, 0xf149f2ca
	v_mov_b32_e32 v195, 0
	v_mov_b64_e32 v[28:29], v[12:13]
	v_mov_b64_e32 v[26:27], v[10:11]
	v_mov_b64_e32 v[24:25], v[8:9]
	v_mov_b64_e32 v[22:23], v[6:7]
	v_mov_b64_e32 v[20:21], v[4:5]
	v_mov_b64_e32 v[18:19], v[2:3]
	v_mov_b64_e32 v[16:17], v[0:1]
	v_mov_b64_e32 v[44:45], v[12:13]
	v_mov_b64_e32 v[42:43], v[10:11]
	v_mov_b64_e32 v[40:41], v[8:9]
	v_mov_b64_e32 v[38:39], v[6:7]
	v_mov_b64_e32 v[36:37], v[4:5]
	v_mov_b64_e32 v[34:35], v[2:3]
	v_mov_b64_e32 v[32:33], v[0:1]
	v_mov_b64_e32 v[60:61], v[12:13]
	v_mov_b64_e32 v[58:59], v[10:11]
	v_mov_b64_e32 v[56:57], v[8:9]
	v_mov_b64_e32 v[54:55], v[6:7]
	v_mov_b64_e32 v[52:53], v[4:5]
	v_mov_b64_e32 v[50:51], v[2:3]
	v_mov_b64_e32 v[48:49], v[0:1]
	v_mov_b64_e32 v[76:77], v[12:13]
	v_mov_b64_e32 v[74:75], v[10:11]
	v_mov_b64_e32 v[72:73], v[8:9]
	v_mov_b64_e32 v[70:71], v[6:7]
	v_mov_b64_e32 v[68:69], v[4:5]
	v_mov_b64_e32 v[66:67], v[2:3]
	v_mov_b64_e32 v[64:65], v[0:1]
	v_mov_b64_e32 v[92:93], v[12:13]
	v_mov_b64_e32 v[90:91], v[10:11]
	v_mov_b64_e32 v[88:89], v[8:9]
	v_mov_b64_e32 v[86:87], v[6:7]
	v_mov_b64_e32 v[84:85], v[4:5]
	v_mov_b64_e32 v[82:83], v[2:3]
	v_mov_b64_e32 v[80:81], v[0:1]
	v_mov_b64_e32 v[108:109], v[12:13]
	v_mov_b64_e32 v[106:107], v[10:11]
	v_mov_b64_e32 v[104:105], v[8:9]
	v_mov_b64_e32 v[102:103], v[6:7]
	v_mov_b64_e32 v[100:101], v[4:5]
	v_mov_b64_e32 v[98:99], v[2:3]
	v_mov_b64_e32 v[96:97], v[0:1]
	v_mov_b64_e32 v[124:125], v[12:13]
	v_mov_b64_e32 v[122:123], v[10:11]
	v_mov_b64_e32 v[120:121], v[8:9]
	v_mov_b64_e32 v[118:119], v[6:7]
	v_mov_b64_e32 v[116:117], v[4:5]
	v_mov_b64_e32 v[114:115], v[2:3]
	v_mov_b64_e32 v[112:113], v[0:1]
	s_mov_b32 s11, 0
	s_sub_u32 s22, s22, 0x100000
	s_subb_u32 s23, s23, 0
	s_sub_i32 s10, s10, 1
	s_barrier
	s_branch .LBB0_1856

.LBB0_1856:
	s_cmp_ge_u32 s10, s66
	s_cselect_b64 s[8:9], -1, 0
	v_mov_b32_e32 v204, v176
	s_and_b64 vcc, exec, s[8:9]
	s_cbranch_vccnz .LBB0_1858
	s_add_i32 s100, s14, 63
	s_cmp_le_i32 s100, s68
	s_cbranch_scc1 .LBB0_1858
	s_add_i32 s16, s11, 1
	s_cmp_eq_u32 s16, 3
	s_cselect_b32 s16, 0, s16
	v_mov_b32_e32 v130, s16
	v_lshlrev_b32_e32 v128, 14, v130
	v_add_u32_e32 v131, s36, v128
	v_lshl_add_u64 v[128:129], s[22:23], 0, v[178:179]
	s_add_u32 s16, s22, 0xf00
	v_readfirstlane_b32 s15, v131
	s_mov_b32 s20, m0
	s_mov_b32 m0, s15
	s_nop 0
	global_load_lds_dwordx4 v[128:129], off
	s_mov_b32 m0, s20
	v_lshl_add_u64 v[128:129], s[22:23], 0, v[180:181]
	s_addc_u32 s17, s23, 0
	s_addk_i32 s15, 0x400
	s_mov_b32 s20, m0
	s_mov_b32 m0, s15
	s_nop 0
	global_load_lds_dwordx4 v[128:129], off
	s_mov_b32 m0, s20
	v_lshlrev_b32_e32 v128, 15, v130
	v_add_u32_e32 v130, s37, v128
	v_lshl_add_u64 v[128:129], s[16:17], 0, v[182:183]
	v_readfirstlane_b32 s15, v130
	s_mov_b32 s20, m0
	s_mov_b32 m0, s15
	s_nop 0
	global_load_lds_dwordx4 v[128:129], off
	s_mov_b32 m0, s20
	v_lshl_add_u64 v[128:129], s[16:17], 0, v[184:185]
	s_add_i32 s20, s15, 0x400
	s_mov_b32 s21, m0
	s_mov_b32 m0, s20
	s_nop 0
	global_load_lds_dwordx4 v[128:129], off
	s_mov_b32 m0, s21
	v_lshl_add_u64 v[128:129], s[16:17], 0, v[186:187]
	s_add_i32 s20, s15, 0x800
	s_mov_b32 s21, m0
	s_mov_b32 m0, s20
	s_nop 0
	global_load_lds_dwordx4 v[128:129], off
	s_mov_b32 m0, s21
	v_lshl_add_u64 v[128:129], s[16:17], 0, v[188:189]
	s_addk_i32 s15, 0xc00
	s_mov_b32 s16, m0
	s_mov_b32 m0, s15
	s_nop 0
	global_load_lds_dwordx4 v[128:129], off
	s_mov_b32 m0, s16
.LBB0_1858:
	s_cmp_gt_i32 s14, s69
	s_cbranch_scc1 .LBB0_1869
	s_add_i32 s100, s14, 63
	s_cmp_le_i32 s100, s68
	s_cbranch_scc0 .Latt_slow_7
	v_lshrrev_b32_e32 v246, 8, v220
	s_nop 0
	v_readfirstlane_b32 s100, v246
	s_nop 0
	s_cmp_eq_u32 s100, 0
	s_cbranch_scc1 .Latt_A_7
	s_cmp_eq_u32 s14, 0
	s_cbranch_scc1 .Latt_B0_7
	s_add_i32 s99, s11, 2
	s_sub_i32 s101, s99, 3
	s_cmp_lt_u32 s99, 3
	s_cselect_b32 s99, s99, s101
	s_lshl_b32 s99, s99, 15
	s_add_i32 s99, s99, 0xc000
	v_bfe_u32 v246, v204, 2, 2
	v_bfe_u32 v247, v204, 5, 1
	v_lshl_or_b32 v247, v247, 2, v246
	v_and_b32_e32 v249, 3, v204
	v_and_b32_e32 v254, 16, v204
	v_lshl_or_b32 v249, v249, 2, v254
	v_lshlrev_b32_e32 v249, 1, v249
	v_lshl_add_u32 v247, v247, 9, v249
	v_add_u32_e32 v247, s99, v247
	v_lshlrev_b32_e32 v246, 6, v246
	v_add_u32_e32 v205, v247, v246
	v_xor_b32_e32 v249, 64, v246
	v_add_u32_e32 v218, v247, v249
	v_xor_b32_e32 v249, 0x80, v246
	v_add_u32_e32 v219, v247, v249
	v_xor_b32_e32 v249, 0xc0, v246
	v_add_u32_e32 v221, v247, v249
	s_lshl_b32 s98, s11, 14
	s_lshl_b32 s99, s11, 15
	s_add_i32 s99, s99, 0xc000
	ds_read_b64_tr_b16 v[206:207], v205 offset:16384
	ds_read_b64_tr_b16 v[208:209], v205 offset:20480
	ds_read_b64_tr_b16 v[210:211], v218 offset:16384
	ds_read_b64_tr_b16 v[212:213], v218 offset:20480
	ds_read_b64_tr_b16 v[214:215], v219 offset:16384
	ds_read_b64_tr_b16 v[216:217], v219 offset:20480
	ds_read_b64_tr_b16 v[238:239], v221 offset:16384
	ds_read_b64_tr_b16 v[240:241], v221 offset:20480
	ds_read_b64_tr_b16 v[222:223], v205 offset:16640
	ds_read_b64_tr_b16 v[224:225], v205 offset:20736
	s_waitcnt lgkmcnt(8)
	v_mfma_f32_32x32x16_bf16 v[112:127], v[206:209], v[242:245], v[112:127]
	ds_read_b64_tr_b16 v[206:207], v218 offset:16640
	ds_read_b64_tr_b16 v[208:209], v218 offset:20736
	s_cmp_lg_u64 s[8:9], 0
	s_cbranch_scc1 .Latt_nd0_7B1
	s_add_i32 s100, s11, 1
	s_cmp_eq_u32 s11, 2
	s_cselect_b32 s100, 0, s100
	s_lshl_b32 s101, s100, 14
	s_add_i32 m0, s36, s101
	s_nop 0
	global_load_lds_dwordx4 v178, s[22:23]
.Latt_nd0_7B1:
	s_waitcnt lgkmcnt(8)
	v_mfma_f32_32x32x16_bf16 v[96:111], v[210:213], v[242:245], v[96:111]
	ds_read_b64_tr_b16 v[210:211], v219 offset:16640
	ds_read_b64_tr_b16 v[212:213], v219 offset:20736
	s_cmp_lg_u64 s[8:9], 0
	s_cbranch_scc1 .Latt_nd1_7B1
	s_add_i32 m0, m0, 0x400
	s_nop 0
	global_load_lds_dwordx4 v180, s[22:23]
.Latt_nd1_7B1:
	s_waitcnt lgkmcnt(8)
	v_mfma_f32_32x32x16_bf16 v[80:95], v[214:217], v[242:245], v[80:95]
	ds_read_b64_tr_b16 v[214:215], v221 offset:16640
	ds_read_b64_tr_b16 v[216:217], v221 offset:20736
	s_cmp_lg_u64 s[8:9], 0
	s_cbranch_scc1 .Latt_nd2_7B1
	s_lshl_b32 s101, s100, 15
	s_add_i32 m0, s37, s101
	s_add_u32 s100, s22, 0xf00
	s_addc_u32 s101, s23, 0
	global_load_lds_dwordx4 v182, s[100:101]

.Latt_B0_7:
	s_lshl_b32 s98, s11, 14
	s_lshl_b32 s99, s11, 15
	s_add_i32 s99, s99, 0xc000
	v_add_u32_e32 v206, s98, v196
	ds_read_b128 v[206:209], v206
	v_add_u32_e32 v210, s98, v197
	ds_read_b128 v[210:213], v210
	v_add_u32_e32 v214, s98, v198
	ds_read_b128 v[214:217], v214
	v_add_u32_e32 v238, s98, v199
	ds_read_b128 v[238:241], v238
	v_add_u32_e32 v242, s98, v200
	ds_read_b128 v[242:245], v242
	v_add_u32_e32 v250, s98, v201
	ds_read_b128 v[250:253], v250
	v_add_u32_e32 v222, s98, v202
	ds_read_b128 v[222:225], v222
	v_add_u32_e32 v226, s98, v203
	ds_read_b128 v[226:229], v226
	v_bfe_u32 v246, v204, 2, 2
	v_bfe_u32 v247, v204, 5, 1
	v_lshl_or_b32 v247, v247, 2, v246
	v_and_b32_e32 v249, 3, v204
	v_and_b32_e32 v254, 16, v204
	v_lshl_or_b32 v249, v249, 2, v254
	v_lshlrev_b32_e32 v249, 1, v249
	v_lshl_add_u32 v247, v247, 9, v249
	v_add_u32_e32 v247, s99, v247
	v_lshlrev_b32_e32 v246, 6, v246
	v_add_u32_e32 v205, v247, v246
	v_xor_b32_e32 v249, 64, v246
	v_add_u32_e32 v218, v247, v249
	v_xor_b32_e32 v249, 0x80, v246
	v_add_u32_e32 v219, v247, v249
	v_xor_b32_e32 v249, 0xc0, v246
	v_add_u32_e32 v221, v247, v249
	s_waitcnt lgkmcnt(7)
	v_mfma_f32_32x32x16_bf16 v[128:143], v[206:209], v[144:147], 0
	v_add_u32_e32 v206, s98, v196
	ds_read_b128 v[206:209], v206 offset:8192
	s_cmp_lg_u64 s[8:9], 0
	s_cbranch_scc1 .Latt_nd0_7B0
	s_add_i32 s100, s11, 1
	s_cmp_eq_u32 s11, 2
	s_cselect_b32 s100, 0, s100
	s_lshl_b32 s101, s100, 14
	s_add_i32 m0, s36, s101
	s_nop 0
	global_load_lds_dwordx4 v178, s[22:23]
.Latt_nd0_7B0:
	s_waitcnt lgkmcnt(7)
	v_mfma_f32_32x32x16_bf16 v[128:143], v[210:213], v[148:151], v[128:143]
	v_add_u32_e32 v210, s98, v197
	ds_read_b128 v[210:213], v210 offset:8192
	s_cmp_lg_u64 s[8:9], 0
	s_cbranch_scc1 .Latt_nd1_7B0
	s_add_i32 m0, m0, 0x400
	s_nop 0
	global_load_lds_dwordx4 v180, s[22:23]
.Latt_nd1_7B0:
	s_waitcnt lgkmcnt(7)
	v_mfma_f32_32x32x16_bf16 v[128:143], v[214:217], v[152:155], v[128:143]
	v_add_u32_e32 v214, s98, v198
	ds_read_b128 v[214:217], v214 offset:8192
	s_cmp_lg_u64 s[8:9], 0
	s_cbranch_scc1 .Latt_nd2_7B0
	s_lshl_b32 s101, s100, 15
	s_add_i32 m0, s37, s101
	s_add_u32 s100, s22, 0xf00
	s_addc_u32 s101, s23, 0
	global_load_lds_dwordx4 v182, s[100:101]
